# GEMM mainloops: lgkmcnt(0) wait taken before the cluster-opening barrier (load stage) instead of after it; in-proj loops' duplicate waits removed too
# baseline (speedup 1.0000x reference)
; #define PG8_STAGE(bufoff, gbase, voff) do { _Pragma("unroll") for (int _i = 0; _i < 2; ++_i) \
;         __builtin_amdgcn_global_load_lds((const unsigned*)((const char*)(gbase) + (voff)[_i]), (LAS unsigned*)(lds + (bufoff) + ldsw + _i * 8192), 16, 0, 0); } while (0)
; #define PG8_LDA(dst, b, h) do { _Pragma("unroll") for (int m = 0; m < 4; ++m) _Pragma("unroll") for (int k = 0; k < 2; ++k) dst[m][k] = *(const LAS bf16x8*)(lds + PG8_SA(b, h) + aoff + m * 2048 + k * 1024); } while (0)
; #define PG8_LDB(dst, b, h) do { _Pragma("unroll") for (int n = 0; n < 2; ++n) _Pragma("unroll") for (int k = 0; k < 2; ++k) dst[n][k] = *(const LAS bf16x8*)(lds + PG8_SB(b, h) + boff + n * 2048 + k * 1024); } while (0)
; #define PG8_MMA(ai, bj, At, Bt) do { __builtin_amdgcn_s_setprio(1); _Pragma("unroll") for (int m = 0; m < 4; ++m) _Pragma("unroll") for (int n = 0; n < 2; ++n) _Pragma("unroll") for (int k = 0; k < 2; ++k) \
;         acc[ai][bj][m][n] = __builtin_amdgcn_mfma_f32_16x16x32_bf16(Bt[n][k], At[m][k], acc[ai][bj][m][n], 0, 0, 0); __builtin_amdgcn_s_setprio(0); } while (0)
; #define PG8_WAIT_V(n) asm volatile("s_waitcnt vmcnt(" #n ")" ::: "memory")
; #define PG8_WAIT_L(n) asm volatile("s_waitcnt lgkmcnt(" #n ")" ::: "memory")
; #define PG8_BAR __builtin_amdgcn_s_barrier()
; #define PG8_SCHED __builtin_amdgcn_sched_barrier(0)
; template <class Epi>
; DEVI void gemm_phase(LAS unsigned char* lds, const Gemm g, const Epi& E) {
;     ...
;             PG8_LDB(B0, 0, 0); PG8_SCHED; PG8_LDA(At, 0, 0); PG8_STAGE(PG8_SA(1, 1), a1 + hstepA, voffA);
;             PG8_WAIT_L(8); PG8_BAR; PG8_WAIT_L(0); PG8_MMA(0, 0, At, B0); PG8_BAR; PG8_SCHED;
;             PG8_LDB(B1, 0, 1); PG8_STAGE(PG8_SB(0, 0), b2, voffB);
;             PG8_BAR; PG8_WAIT_L(0); PG8_MMA(0, 1, At, B1); PG8_BAR;
;             PG8_LDA(At, 0, 1); PG8_STAGE(PG8_SA(0, 0), a2, voffA);
;             PG8_BAR; PG8_WAIT_L(0); PG8_MMA(1, 0, At, B0); PG8_BAR; PG8_SCHED;
;             PG8_STAGE(PG8_SB(0, 1), b2 + hstepB, voffB);
;             PG8_WAIT_V(6); PG8_BAR; PG8_MMA(1, 1, At, B1); PG8_BAR;
;             PG8_LDB(B0, 1, 0); PG8_SCHED; PG8_LDA(At, 1, 0); PG8_STAGE(PG8_SA(0, 1), a2 + hstepA, voffA);
.LBB0_187:
	ds_read_b128 v[156:159], v150
	ds_read_b128 v[160:163], v150 offset:1024
	ds_read_b128 v[164:167], v150 offset:2048
	ds_read_b128 v[168:171], v150 offset:3072
	s_add_u32 s26, s0, 0xfffc0080
	s_addc_u32 s27, s1, -1
	s_cmp_eq_u32 s50, 12
	s_cselect_b32 s29, s13, s27
	s_cselect_b32 s28, s15, s26
	s_cselect_b32 s27, s19, s49
	s_cselect_b32 s26, s18, s17
	v_lshl_add_u64 v[204:205], s[0:1], 0, v[138:139]
	s_add_i32 m0, s38, 0xc000
	ds_read_b128 v[172:175], v151
	ds_read_b128 v[176:179], v151 offset:1024
	ds_read_b128 v[180:183], v151 offset:2048
	ds_read_b128 v[184:187], v151 offset:3072
	ds_read_b128 v[188:191], v151 offset:4096
	ds_read_b128 v[192:195], v151 offset:5120
	ds_read_b128 v[196:199], v151 offset:6144
	ds_read_b128 v[200:203], v151 offset:7168
	global_load_lds_dwordx4 v[204:205], off
	s_add_i32 m0, s38, 0xe000
	v_lshl_add_u64 v[204:205], s[0:1], 0, v[140:141]
	global_load_lds_dwordx4 v[204:205], off
	s_waitcnt lgkmcnt(0)
	s_barrier
	v_mfma_f32_16x16x32_bf16 v[124:127], v[156:159], v[172:175], v[124:127]
	v_mfma_f32_16x16x32_bf16 v[120:123], v[164:167], v[172:175], v[120:123]
	v_mfma_f32_16x16x32_bf16 v[116:119], v[156:159], v[180:183], v[116:119]
	v_mfma_f32_16x16x32_bf16 v[108:111], v[164:167], v[180:183], v[108:111]
	v_mfma_f32_16x16x32_bf16 v[100:103], v[156:159], v[188:191], v[100:103]
	v_mfma_f32_16x16x32_bf16 v[96:99], v[164:167], v[188:191], v[96:99]
	v_mfma_f32_16x16x32_bf16 v[84:87], v[156:159], v[196:199], v[84:87]
	v_mfma_f32_16x16x32_bf16 v[80:83], v[164:167], v[196:199], v[80:83]
	v_mfma_f32_16x16x32_bf16 v[124:127], v[160:163], v[176:179], v[124:127]
	v_mfma_f32_16x16x32_bf16 v[120:123], v[168:171], v[176:179], v[120:123]
	v_mfma_f32_16x16x32_bf16 v[116:119], v[160:163], v[184:187], v[116:119]
	v_mfma_f32_16x16x32_bf16 v[108:111], v[168:171], v[184:187], v[108:111]
	v_mfma_f32_16x16x32_bf16 v[100:103], v[160:163], v[192:195], v[100:103]
	v_mfma_f32_16x16x32_bf16 v[96:99], v[168:171], v[192:195], v[96:99]
	v_mfma_f32_16x16x32_bf16 v[84:87], v[160:163], v[200:203], v[84:87]
	v_mfma_f32_16x16x32_bf16 v[80:83], v[168:171], v[200:203], v[80:83]
	s_barrier
	s_add_i32 s51, s46, s35
	v_lshl_add_u64 v[220:221], s[26:27], 0, v[130:131]
	s_mov_b32 m0, s51
	ds_read_b128 v[204:207], v152
	ds_read_b128 v[208:211], v152 offset:1024
	ds_read_b128 v[212:215], v152 offset:2048
	ds_read_b128 v[216:219], v152 offset:3072
	global_load_lds_dwordx4 v[220:221], off
	s_add_i32 m0, s51, 0x2000
	v_lshl_add_u64 v[222:223], s[26:27], 0, v[134:135]
	global_load_lds_dwordx4 v[222:223], off
	s_waitcnt lgkmcnt(0)
	s_barrier
	v_mfma_f32_16x16x32_bf16 v[112:115], v[204:207], v[172:175], v[112:115]
	v_mfma_f32_16x16x32_bf16 v[104:107], v[212:215], v[172:175], v[104:107]
	v_mfma_f32_16x16x32_bf16 v[92:95], v[204:207], v[180:183], v[92:95]
	v_mfma_f32_16x16x32_bf16 v[88:91], v[212:215], v[180:183], v[88:91]
	v_mfma_f32_16x16x32_bf16 v[76:79], v[204:207], v[188:191], v[76:79]
	v_mfma_f32_16x16x32_bf16 v[72:75], v[212:215], v[188:191], v[72:75]
	v_mfma_f32_16x16x32_bf16 v[68:71], v[204:207], v[196:199], v[68:71]
	v_mfma_f32_16x16x32_bf16 v[64:67], v[212:215], v[196:199], v[64:67]
	v_mfma_f32_16x16x32_bf16 v[112:115], v[208:211], v[176:179], v[112:115]
	v_mfma_f32_16x16x32_bf16 v[104:107], v[216:219], v[176:179], v[104:107]
	v_mfma_f32_16x16x32_bf16 v[92:95], v[208:211], v[184:187], v[92:95]
	v_mfma_f32_16x16x32_bf16 v[88:91], v[216:219], v[184:187], v[88:91]
	v_mfma_f32_16x16x32_bf16 v[76:79], v[208:211], v[192:195], v[76:79]
	v_mfma_f32_16x16x32_bf16 v[72:75], v[216:219], v[192:195], v[72:75]
	v_mfma_f32_16x16x32_bf16 v[68:71], v[208:211], v[200:203], v[68:71]
	v_mfma_f32_16x16x32_bf16 v[64:67], v[216:219], v[200:203], v[64:67]
	s_mov_b32 m0, s38
	v_lshl_add_u64 v[224:225], s[28:29], 0, v[128:129]
	s_barrier
	ds_read_b128 v[172:175], v151 offset:16384
	ds_read_b128 v[176:179], v151 offset:17408
	ds_read_b128 v[180:183], v151 offset:18432
	ds_read_b128 v[184:187], v151 offset:19456
	ds_read_b128 v[188:191], v151 offset:20480
	ds_read_b128 v[192:195], v151 offset:21504
	ds_read_b128 v[196:199], v151 offset:22528
	ds_read_b128 v[200:203], v151 offset:23552
	global_load_lds_dwordx4 v[224:225], off
	s_mov_b32 m0, s39
	v_lshl_add_u64 v[226:227], s[28:29], 0, v[132:133]
	global_load_lds_dwordx4 v[226:227], off
	s_waitcnt lgkmcnt(0)
	s_barrier
	v_mfma_f32_16x16x32_bf16 v[60:63], v[156:159], v[172:175], v[60:63]
	v_mfma_f32_16x16x32_bf16 v[56:59], v[164:167], v[172:175], v[56:59]
	v_mfma_f32_16x16x32_bf16 v[52:55], v[156:159], v[180:183], v[52:55]
	v_mfma_f32_16x16x32_bf16 v[48:51], v[164:167], v[180:183], v[48:51]
	v_mfma_f32_16x16x32_bf16 v[36:39], v[156:159], v[188:191], v[36:39]
	v_mfma_f32_16x16x32_bf16 v[32:35], v[164:167], v[188:191], v[32:35]
	v_mfma_f32_16x16x32_bf16 v[20:23], v[156:159], v[196:199], v[20:23]
	v_mfma_f32_16x16x32_bf16 v[16:19], v[164:167], v[196:199], v[16:19]
	v_mfma_f32_16x16x32_bf16 v[60:63], v[160:163], v[176:179], v[60:63]
	v_mfma_f32_16x16x32_bf16 v[56:59], v[168:171], v[176:179], v[56:59]
	v_mfma_f32_16x16x32_bf16 v[52:55], v[160:163], v[184:187], v[52:55]
	v_mfma_f32_16x16x32_bf16 v[48:51], v[168:171], v[184:187], v[48:51]
	v_mfma_f32_16x16x32_bf16 v[36:39], v[160:163], v[192:195], v[36:39]
	v_mfma_f32_16x16x32_bf16 v[32:35], v[168:171], v[192:195], v[32:35]
	v_mfma_f32_16x16x32_bf16 v[20:23], v[160:163], v[200:203], v[20:23]
	v_mfma_f32_16x16x32_bf16 v[16:19], v[168:171], v[200:203], v[16:19]
	s_barrier
	s_add_u32 s52, s26, 0x40000
	s_addc_u32 s53, s27, 0
	s_add_i32 s51, s47, s35
	s_mov_b32 m0, s51
	v_lshl_add_u64 v[156:157], s[52:53], 0, v[130:131]
	global_load_lds_dwordx4 v[156:157], off
	s_add_i32 m0, s51, 0x2000
	v_lshl_add_u64 v[156:157], s[52:53], 0, v[134:135]
	global_load_lds_dwordx4 v[156:157], off
	s_waitcnt vmcnt(6)
	s_barrier
; #define PG8_STAGE(bufoff, gbase, voff) do { _Pragma("unroll") for (int _i = 0; _i < 2; ++_i) \
;         __builtin_amdgcn_global_load_lds((const unsigned*)((const char*)(gbase) + (voff)[_i]), (LAS unsigned*)(lds + (bufoff) + ldsw + _i * 8192), 16, 0, 0); } while (0)
; #define PG8_LDA(dst, b, h) do { _Pragma("unroll") for (int m = 0; m < 4; ++m) _Pragma("unroll") for (int k = 0; k < 2; ++k) dst[m][k] = *(const LAS bf16x8*)(lds + PG8_SA(b, h) + aoff + m * 2048 + k * 1024); } while (0)
; #define PG8_LDB(dst, b, h) do { _Pragma("unroll") for (int n = 0; n < 2; ++n) _Pragma("unroll") for (int k = 0; k < 2; ++k) dst[n][k] = *(const LAS bf16x8*)(lds + PG8_SB(b, h) + boff + n * 2048 + k * 1024); } while (0)
; #define PG8_MMA(ai, bj, At, Bt) do { __builtin_amdgcn_s_setprio(1); _Pragma("unroll") for (int m = 0; m < 4; ++m) _Pragma("unroll") for (int n = 0; n < 2; ++n) _Pragma("unroll") for (int k = 0; k < 2; ++k) \
;         acc[ai][bj][m][n] = __builtin_amdgcn_mfma_f32_16x16x32_bf16(Bt[n][k], At[m][k], acc[ai][bj][m][n], 0, 0, 0); __builtin_amdgcn_s_setprio(0); } while (0)
; #define PG8_WAIT_V(n) asm volatile("s_waitcnt vmcnt(" #n ")" ::: "memory")
; #define PG8_WAIT_L(n) asm volatile("s_waitcnt lgkmcnt(" #n ")" ::: "memory")
; #define PG8_BAR __builtin_amdgcn_s_barrier()
; #define PG8_SCHED __builtin_amdgcn_sched_barrier(0)
; template <class Epi>
; DEVI void gemm_phase(LAS unsigned char* lds, const Gemm g, const Epi& E) {
;     ...
;             PG8_WAIT_V(6); PG8_BAR; PG8_MMA(1, 1, At, B1); PG8_BAR;
;             PG8_LDB(B0, 1, 0); PG8_SCHED; PG8_LDA(At, 1, 0); PG8_STAGE(PG8_SA(0, 1), a2 + hstepA, voffA);
;             PG8_WAIT_L(8); PG8_BAR; PG8_WAIT_L(0); PG8_MMA(0, 0, At, B0); PG8_BAR; PG8_SCHED;
;             PG8_LDB(B1, 1, 1); PG8_STAGE(PG8_SB(1, 0), b3, voffB);
;             PG8_BAR; PG8_WAIT_L(0); PG8_MMA(0, 1, At, B1); PG8_BAR;
;             PG8_LDA(At, 1, 1); PG8_STAGE(PG8_SA(1, 0), a3, voffA);
;             PG8_BAR; PG8_WAIT_L(0); PG8_MMA(1, 0, At, B0); PG8_BAR; PG8_SCHED;
;             PG8_STAGE(PG8_SB(1, 1), b3 + hstepB, voffB);
	v_mfma_f32_16x16x32_bf16 v[44:47], v[204:207], v[172:175], v[44:47]
	v_mfma_f32_16x16x32_bf16 v[40:43], v[212:215], v[172:175], v[40:43]
	v_mfma_f32_16x16x32_bf16 v[28:31], v[204:207], v[180:183], v[28:31]
	v_mfma_f32_16x16x32_bf16 v[24:27], v[212:215], v[180:183], v[24:27]
	v_mfma_f32_16x16x32_bf16 v[12:15], v[204:207], v[188:191], v[12:15]
	v_mfma_f32_16x16x32_bf16 v[8:11], v[212:215], v[188:191], v[8:11]
	v_mfma_f32_16x16x32_bf16 v[4:7], v[204:207], v[196:199], v[4:7]
	v_mfma_f32_16x16x32_bf16 v[0:3], v[212:215], v[196:199], v[0:3]
	v_mfma_f32_16x16x32_bf16 v[44:47], v[208:211], v[176:179], v[44:47]
	v_mfma_f32_16x16x32_bf16 v[40:43], v[216:219], v[176:179], v[40:43]
	v_mfma_f32_16x16x32_bf16 v[28:31], v[208:211], v[184:187], v[28:31]
	v_mfma_f32_16x16x32_bf16 v[24:27], v[216:219], v[184:187], v[24:27]
	v_mfma_f32_16x16x32_bf16 v[12:15], v[208:211], v[192:195], v[12:15]
	v_mfma_f32_16x16x32_bf16 v[8:11], v[216:219], v[192:195], v[8:11]
	v_mfma_f32_16x16x32_bf16 v[4:7], v[208:211], v[200:203], v[4:7]
	v_mfma_f32_16x16x32_bf16 v[0:3], v[216:219], v[200:203], v[0:3]
	s_add_i32 s51, 0, 0x18000
	v_add_u32_e32 v136, s51, v148
	s_barrier
	ds_read_b128 v[156:159], v136
	ds_read_b128 v[160:163], v136 offset:1024
	ds_read_b128 v[164:167], v136 offset:2048
	ds_read_b128 v[168:171], v136 offset:3072
	s_add_u32 s28, s28, 0x40000
	s_addc_u32 s29, s29, 0
	s_mov_b32 m0, s40
	v_lshl_add_u64 v[204:205], s[28:29], 0, v[128:129]
	ds_read_b128 v[172:175], v151 offset:32768
	ds_read_b128 v[176:179], v151 offset:33792
	ds_read_b128 v[180:183], v151 offset:34816
	ds_read_b128 v[184:187], v151 offset:35840
	ds_read_b128 v[188:191], v151 offset:36864
	ds_read_b128 v[192:195], v151 offset:37888
	ds_read_b128 v[196:199], v151 offset:38912
	ds_read_b128 v[200:203], v151 offset:39936
	global_load_lds_dwordx4 v[204:205], off
	s_mov_b32 m0, s41
	v_lshl_add_u64 v[204:205], s[28:29], 0, v[132:133]
	global_load_lds_dwordx4 v[204:205], off
	s_waitcnt lgkmcnt(0)
	s_barrier
	v_mfma_f32_16x16x32_bf16 v[124:127], v[156:159], v[172:175], v[124:127]
	v_mfma_f32_16x16x32_bf16 v[120:123], v[164:167], v[172:175], v[120:123]
	v_mfma_f32_16x16x32_bf16 v[116:119], v[156:159], v[180:183], v[116:119]
	v_mfma_f32_16x16x32_bf16 v[108:111], v[164:167], v[180:183], v[108:111]
	v_mfma_f32_16x16x32_bf16 v[100:103], v[156:159], v[188:191], v[100:103]
	v_mfma_f32_16x16x32_bf16 v[96:99], v[164:167], v[188:191], v[96:99]
	v_mfma_f32_16x16x32_bf16 v[84:87], v[156:159], v[196:199], v[84:87]
	v_mfma_f32_16x16x32_bf16 v[80:83], v[164:167], v[196:199], v[80:83]
	v_mfma_f32_16x16x32_bf16 v[124:127], v[160:163], v[176:179], v[124:127]
	v_mfma_f32_16x16x32_bf16 v[120:123], v[168:171], v[176:179], v[120:123]
	v_mfma_f32_16x16x32_bf16 v[116:119], v[160:163], v[184:187], v[116:119]
	v_mfma_f32_16x16x32_bf16 v[108:111], v[168:171], v[184:187], v[108:111]
	v_mfma_f32_16x16x32_bf16 v[100:103], v[160:163], v[192:195], v[100:103]
	v_mfma_f32_16x16x32_bf16 v[96:99], v[168:171], v[192:195], v[96:99]
	v_mfma_f32_16x16x32_bf16 v[84:87], v[160:163], v[200:203], v[84:87]
	v_mfma_f32_16x16x32_bf16 v[80:83], v[168:171], v[200:203], v[80:83]
	s_barrier
	s_add_i32 s28, 0, 0x1c000
	s_add_i32 s29, s51, s35
	v_add_u32_e32 v136, s28, v148
	v_lshl_add_u64 v[220:221], v[220:221], 0, s[8:9]
	s_mov_b32 m0, s29
	ds_read_b128 v[204:207], v136
	ds_read_b128 v[208:211], v136 offset:1024
	ds_read_b128 v[212:215], v136 offset:2048
	ds_read_b128 v[216:219], v136 offset:3072
	global_load_lds_dwordx4 v[220:221], off
	s_add_i32 m0, s29, 0x2000
	v_lshl_add_u64 v[220:221], v[222:223], 0, s[8:9]
	global_load_lds_dwordx4 v[220:221], off
	s_waitcnt lgkmcnt(0)
	s_barrier
	v_mfma_f32_16x16x32_bf16 v[112:115], v[204:207], v[172:175], v[112:115]
	v_mfma_f32_16x16x32_bf16 v[104:107], v[212:215], v[172:175], v[104:107]
	v_mfma_f32_16x16x32_bf16 v[92:95], v[204:207], v[180:183], v[92:95]
	v_mfma_f32_16x16x32_bf16 v[88:91], v[212:215], v[180:183], v[88:91]
	v_mfma_f32_16x16x32_bf16 v[76:79], v[204:207], v[188:191], v[76:79]
	v_mfma_f32_16x16x32_bf16 v[72:75], v[212:215], v[188:191], v[72:75]
	v_mfma_f32_16x16x32_bf16 v[68:71], v[204:207], v[196:199], v[68:71]
	v_mfma_f32_16x16x32_bf16 v[64:67], v[212:215], v[196:199], v[64:67]
	v_mfma_f32_16x16x32_bf16 v[112:115], v[208:211], v[176:179], v[112:115]
	v_mfma_f32_16x16x32_bf16 v[104:107], v[216:219], v[176:179], v[104:107]
	v_mfma_f32_16x16x32_bf16 v[92:95], v[208:211], v[184:187], v[92:95]
	v_mfma_f32_16x16x32_bf16 v[88:91], v[216:219], v[184:187], v[88:91]
	v_mfma_f32_16x16x32_bf16 v[76:79], v[208:211], v[192:195], v[76:79]
	v_mfma_f32_16x16x32_bf16 v[72:75], v[216:219], v[192:195], v[72:75]
	v_mfma_f32_16x16x32_bf16 v[68:71], v[208:211], v[200:203], v[68:71]
	v_mfma_f32_16x16x32_bf16 v[64:67], v[216:219], v[200:203], v[64:67]
	s_mov_b32 m0, s44
	v_lshl_add_u64 v[220:221], v[224:225], 0, s[8:9]
	s_barrier
	ds_read_b128 v[172:175], v151 offset:49152
	ds_read_b128 v[176:179], v151 offset:50176
	ds_read_b128 v[180:183], v151 offset:51200
	ds_read_b128 v[184:187], v151 offset:52224
	ds_read_b128 v[188:191], v151 offset:53248
	ds_read_b128 v[192:195], v151 offset:54272
	ds_read_b128 v[196:199], v151 offset:55296
	ds_read_b128 v[200:203], v151 offset:56320
	global_load_lds_dwordx4 v[220:221], off
	s_mov_b32 m0, s45
	v_lshl_add_u64 v[220:221], v[226:227], 0, s[8:9]
	global_load_lds_dwordx4 v[220:221], off
	s_waitcnt lgkmcnt(0)
	s_barrier
; #define PG8_STAGE(bufoff, gbase, voff) do { _Pragma("unroll") for (int _i = 0; _i < 2; ++_i) \
;         __builtin_amdgcn_global_load_lds((const unsigned*)((const char*)(gbase) + (voff)[_i]), (LAS unsigned*)(lds + (bufoff) + ldsw + _i * 8192), 16, 0, 0); } while (0)
; #define PG8_LDA(dst, b, h) do { _Pragma("unroll") for (int m = 0; m < 4; ++m) _Pragma("unroll") for (int k = 0; k < 2; ++k) dst[m][k] = *(const LAS bf16x8*)(lds + PG8_SA(b, h) + aoff + m * 2048 + k * 1024); } while (0)
; #define PG8_MMA(ai, bj, At, Bt) do { __builtin_amdgcn_s_setprio(1); _Pragma("unroll") for (int m = 0; m < 4; ++m) _Pragma("unroll") for (int n = 0; n < 2; ++n) _Pragma("unroll") for (int k = 0; k < 2; ++k) \
;         acc[ai][bj][m][n] = __builtin_amdgcn_mfma_f32_16x16x32_bf16(Bt[n][k], At[m][k], acc[ai][bj][m][n], 0, 0, 0); __builtin_amdgcn_s_setprio(0); } while (0)
; #define PG8_WAIT_V(n) asm volatile("s_waitcnt vmcnt(" #n ")" ::: "memory")
; #define PG8_WAIT_L(n) asm volatile("s_waitcnt lgkmcnt(" #n ")" ::: "memory")
; #define PG8_BAR __builtin_amdgcn_s_barrier()
; #define PG8_SCHED __builtin_amdgcn_sched_barrier(0)
; template <class Epi>
; DEVI void gemm_phase(LAS unsigned char* lds, const Gemm g, const Epi& E) {
;     ...
;             PG8_LDA(At, 1, 1); PG8_STAGE(PG8_SA(1, 0), a3, voffA);
;             PG8_BAR; PG8_WAIT_L(0); PG8_MMA(1, 0, At, B0); PG8_BAR; PG8_SCHED;
;             PG8_STAGE(PG8_SB(1, 1), b3 + hstepB, voffB);
;             PG8_WAIT_V(6); PG8_BAR; PG8_MMA(1, 1, At, B1); PG8_BAR;
;         }
	v_mfma_f32_16x16x32_bf16 v[60:63], v[156:159], v[172:175], v[60:63]
	v_mfma_f32_16x16x32_bf16 v[56:59], v[164:167], v[172:175], v[56:59]
	v_mfma_f32_16x16x32_bf16 v[52:55], v[156:159], v[180:183], v[52:55]
	v_mfma_f32_16x16x32_bf16 v[48:51], v[164:167], v[180:183], v[48:51]
	v_mfma_f32_16x16x32_bf16 v[36:39], v[156:159], v[188:191], v[36:39]
	v_mfma_f32_16x16x32_bf16 v[32:35], v[164:167], v[188:191], v[32:35]
	v_mfma_f32_16x16x32_bf16 v[20:23], v[156:159], v[196:199], v[20:23]
	v_mfma_f32_16x16x32_bf16 v[16:19], v[164:167], v[196:199], v[16:19]
	v_mfma_f32_16x16x32_bf16 v[60:63], v[160:163], v[176:179], v[60:63]
	v_mfma_f32_16x16x32_bf16 v[56:59], v[168:171], v[176:179], v[56:59]
	v_mfma_f32_16x16x32_bf16 v[52:55], v[160:163], v[184:187], v[52:55]
	v_mfma_f32_16x16x32_bf16 v[48:51], v[168:171], v[184:187], v[48:51]
	v_mfma_f32_16x16x32_bf16 v[36:39], v[160:163], v[192:195], v[36:39]
	v_mfma_f32_16x16x32_bf16 v[32:35], v[168:171], v[192:195], v[32:35]
	v_mfma_f32_16x16x32_bf16 v[20:23], v[160:163], v[200:203], v[20:23]
	v_mfma_f32_16x16x32_bf16 v[16:19], v[168:171], v[200:203], v[16:19]
	s_barrier
	s_add_u32 s26, s26, 0x40080
	s_addc_u32 s27, s27, 0
	s_add_i32 s28, s28, s35
	s_mov_b32 m0, s28
	v_lshl_add_u64 v[156:157], s[26:27], 0, v[130:131]
	global_load_lds_dwordx4 v[156:157], off
	s_add_i32 m0, s28, 0x2000
	v_lshl_add_u64 v[156:157], s[26:27], 0, v[134:135]
	global_load_lds_dwordx4 v[156:157], off
	s_waitcnt vmcnt(6)
	s_barrier
	v_mfma_f32_16x16x32_bf16 v[44:47], v[204:207], v[172:175], v[44:47]
	v_mfma_f32_16x16x32_bf16 v[40:43], v[212:215], v[172:175], v[40:43]
	v_mfma_f32_16x16x32_bf16 v[28:31], v[204:207], v[180:183], v[28:31]
	v_mfma_f32_16x16x32_bf16 v[24:27], v[212:215], v[180:183], v[24:27]
	v_mfma_f32_16x16x32_bf16 v[12:15], v[204:207], v[188:191], v[12:15]
	v_mfma_f32_16x16x32_bf16 v[8:11], v[212:215], v[188:191], v[8:11]
	v_mfma_f32_16x16x32_bf16 v[4:7], v[204:207], v[196:199], v[4:7]
	v_mfma_f32_16x16x32_bf16 v[0:3], v[212:215], v[196:199], v[0:3]
	v_mfma_f32_16x16x32_bf16 v[44:47], v[208:211], v[176:179], v[44:47]
	v_mfma_f32_16x16x32_bf16 v[40:43], v[216:219], v[176:179], v[40:43]
	v_mfma_f32_16x16x32_bf16 v[28:31], v[208:211], v[184:187], v[28:31]
	v_mfma_f32_16x16x32_bf16 v[24:27], v[216:219], v[184:187], v[24:27]
	v_mfma_f32_16x16x32_bf16 v[12:15], v[208:211], v[192:195], v[12:15]
	v_mfma_f32_16x16x32_bf16 v[8:11], v[216:219], v[192:195], v[8:11]
	v_mfma_f32_16x16x32_bf16 v[4:7], v[208:211], v[200:203], v[4:7]
	v_mfma_f32_16x16x32_bf16 v[0:3], v[216:219], v[200:203], v[0:3]
	s_add_i32 s50, s50, 2
	s_add_u32 s0, s0, 0x100
	s_addc_u32 s1, s1, 0
	s_add_u32 s17, s17, 0x100
	s_addc_u32 s49, s49, 0
	s_cmp_gt_u32 s50, 13
	s_barrier
	s_cbranch_scc0 .LBB0_187
; template <class Epi>
; DEVI void gemm_phase(LAS unsigned char* lds, const Gemm g, const Epi& E) {
;     ...
;                 for (int mm = 0; mm < 2; ++mm) {
;                     const int m = m0 + mm;
;                     const int r = row0 + ai * HALF + m * 16; float rs = 1.f, part = 0.f;
;                     if constexpr (Epi::RS) rs = rsv[ai * 4 + m];
;                     if constexpr (Epi::PAIR) E.pair8(cur.b, r, cur.pn * HALF + wc * 32 + 8 * fq, acc[ai][0][m][0] * rs, acc[ai][0][m][1] * rs, acc[ai][1][m][0] * rs, acc[ai][1][m][1] * rs);
;                     else
; #pragma unroll
;                     for (int bj = 0; bj < 2; ++bj) {
;                         const int c = col0 + bj * HALF; f32x4 v0 = acc[ai][bj][m][0], v1 = acc[ai][bj][m][1];
;                         if constexpr (Epi::RS) { v0 = v0 * rs; v1 = v1 * rs; }
;                         if constexpr (Epi::PRE) part += E.frag_pre8(cur.b, r, c, v0, v1, pre[mm][bj][0], pre[mm][bj][1]);
;                         else if constexpr (Epi::PERM) E.frag8(cur.b, r, c, v0, v1);
;                         else { E.frag(cur.b, r, c, v0); E.frag(cur.b, r, c + 16, v1); }
;                     }
	s_setprio 0
	v_lshl_add_u32 v156, s48, 8, v147
	v_ashrrev_i32_e32 v157, 31, v156
	v_readlane_b32 s2, v252, 39
	v_lshlrev_b64 v[158:159], 11, v[156:157]
	v_lshl_or_b32 v155, s11, 8, v149
	v_mov_b32_e32 v157, s2
	v_readlane_b32 s2, v252, 37
	s_ashr_i32 s11, s10, 31
	v_cmp_gt_i32_e32 vcc, s42, v155
	v_mov_b32_e32 v162, s2
	v_readlane_b32 s2, v252, 38
	s_lshl_b64 s[0:1], s[10:11], 21
	v_cndmask_b32_e32 v161, v157, v162, vcc
	v_mov_b32_e32 v163, s2
	v_readlane_b32 s2, v252, 36
	v_cvt_pk_bf16_f32 v124, v124, v125
	v_cvt_pk_bf16_f32 v125, v126, v127
	v_mov_b32_e32 v164, s2
	v_cndmask_b32_e32 v160, v163, v164, vcc
	v_cvt_pk_bf16_f32 v126, v120, v121
	v_lshl_add_u64 v[120:121], v[160:161], 0, s[0:1]
	v_and_b32_e32 v136, 0x378, v155
	v_cvt_pk_bf16_f32 v127, v122, v123
	v_lshl_add_u64 v[122:123], v[120:121], 0, v[158:159]
	v_lshlrev_b32_e32 v136, 1, v136
	v_lshl_add_u64 v[122:123], v[122:123], 0, v[136:137]
	global_store_dwordx4 v[122:123], v[124:127], off
	v_or_b32_e32 v122, 0x80, v155
	v_cmp_gt_i32_e32 vcc, s42, v122
	v_cvt_pk_bf16_f32 v112, v112, v113
	v_cvt_pk_bf16_f32 v113, v114, v115
	v_cndmask_b32_e32 v123, v157, v162, vcc
	v_cndmask_b32_e32 v122, v163, v164, vcc
	v_lshl_add_u64 v[122:123], v[122:123], 0, s[0:1]
	s_movk_i32 s0, 0x3f8
	v_cvt_pk_bf16_f32 v115, v106, v107
	v_bitop3_b32 v106, v155, s0, v153 bitop3:0xc8
	v_cvt_pk_bf16_f32 v114, v104, v105
	v_lshl_add_u64 v[104:105], v[122:123], 0, v[158:159]
	v_lshlrev_b32_e32 v124, 1, v106
	v_mov_b32_e32 v125, v137
	v_lshl_add_u64 v[104:105], v[104:105], 0, v[124:125]
	global_store_dwordx4 v[104:105], v[112:115], off
	v_or_b32_e32 v104, 16, v156
	v_ashrrev_i32_e32 v105, 31, v104
	v_lshlrev_b64 v[112:113], 11, v[104:105]
	v_cvt_pk_bf16_f32 v106, v108, v109
	v_lshl_add_u64 v[108:109], v[120:121], 0, v[112:113]
	v_cvt_pk_bf16_f32 v92, v92, v93
	v_cvt_pk_bf16_f32 v93, v94, v95
	v_cvt_pk_bf16_f32 v94, v88, v89
	v_lshl_add_u64 v[88:89], v[122:123], 0, v[112:113]
	v_cvt_pk_bf16_f32 v104, v116, v117
	v_cvt_pk_bf16_f32 v105, v118, v119
	v_cvt_pk_bf16_f32 v107, v110, v111
	v_lshl_add_u64 v[108:109], v[108:109], 0, v[136:137]
	v_cvt_pk_bf16_f32 v95, v90, v91
	v_lshl_add_u64 v[88:89], v[88:89], 0, v[124:125]
	global_store_dwordx4 v[108:109], v[104:107], off
	global_store_dwordx4 v[88:89], v[92:95], off
	v_or_b32_e32 v88, 32, v156
	v_ashrrev_i32_e32 v89, 31, v88
	v_lshlrev_b64 v[92:93], 11, v[88:89]
	v_lshl_add_u64 v[94:95], v[120:121], 0, v[92:93]
	v_cvt_pk_bf16_f32 v76, v76, v77
	v_cvt_pk_bf16_f32 v77, v78, v79
	v_cvt_pk_bf16_f32 v78, v72, v73
	v_lshl_add_u64 v[72:73], v[122:123], 0, v[92:93]
	v_cvt_pk_bf16_f32 v88, v100, v101
	v_cvt_pk_bf16_f32 v89, v102, v103
	v_cvt_pk_bf16_f32 v90, v96, v97
	v_cvt_pk_bf16_f32 v91, v98, v99
	v_lshl_add_u64 v[94:95], v[94:95], 0, v[136:137]
	v_cvt_pk_bf16_f32 v79, v74, v75
	v_lshl_add_u64 v[72:73], v[72:73], 0, v[124:125]
	global_store_dwordx4 v[94:95], v[88:91], off
	global_store_dwordx4 v[72:73], v[76:79], off
	v_or_b32_e32 v72, 48, v156
	v_ashrrev_i32_e32 v73, 31, v72
	v_lshlrev_b64 v[76:77], 11, v[72:73]
	v_lshl_add_u64 v[78:79], v[120:121], 0, v[76:77]
	v_cvt_pk_bf16_f32 v68, v68, v69
	v_cvt_pk_bf16_f32 v69, v70, v71
	v_cvt_pk_bf16_f32 v70, v64, v65
	v_lshl_add_u64 v[64:65], v[122:123], 0, v[76:77]
	v_cvt_pk_bf16_f32 v72, v84, v85
	v_cvt_pk_bf16_f32 v73, v86, v87
	v_cvt_pk_bf16_f32 v74, v80, v81
	v_cvt_pk_bf16_f32 v75, v82, v83
	v_lshl_add_u64 v[78:79], v[78:79], 0, v[136:137]
	v_cvt_pk_bf16_f32 v71, v66, v67
	v_lshl_add_u64 v[64:65], v[64:65], 0, v[124:125]
	s_mov_b64 s[0:1], 0x40000
	global_store_dwordx4 v[78:79], v[72:75], off
	global_store_dwordx4 v[64:65], v[68:71], off
	v_lshl_add_u64 v[64:65], v[158:159], 0, s[0:1]
	v_cvt_pk_bf16_f32 v60, v60, v61
	v_cvt_pk_bf16_f32 v61, v62, v63
	v_cvt_pk_bf16_f32 v62, v56, v57
	v_lshl_add_u64 v[56:57], v[120:121], 0, v[64:65]
	v_cvt_pk_bf16_f32 v44, v44, v45
	v_cvt_pk_bf16_f32 v45, v46, v47
	v_cvt_pk_bf16_f32 v46, v40, v41
	v_lshl_add_u64 v[40:41], v[122:123], 0, v[64:65]
	v_cvt_pk_bf16_f32 v63, v58, v59
	v_lshl_add_u64 v[56:57], v[56:57], 0, v[136:137]
	v_cvt_pk_bf16_f32 v47, v42, v43
	v_lshl_add_u64 v[40:41], v[40:41], 0, v[124:125]
	s_mov_b64 s[0:1], 0x48000
	global_store_dwordx4 v[56:57], v[60:63], off
	global_store_dwordx4 v[40:41], v[44:47], off
	v_cvt_pk_bf16_f32 v28, v28, v29
	v_cvt_pk_bf16_f32 v29, v30, v31
	v_lshl_add_u64 v[44:45], v[158:159], 0, s[0:1]
	v_lshl_add_u64 v[46:47], v[120:121], 0, v[44:45]
	v_cvt_pk_bf16_f32 v30, v24, v25
	v_lshl_add_u64 v[24:25], v[122:123], 0, v[44:45]
	v_cvt_pk_bf16_f32 v40, v52, v53
	v_cvt_pk_bf16_f32 v41, v54, v55
	v_cvt_pk_bf16_f32 v42, v48, v49
	v_cvt_pk_bf16_f32 v43, v50, v51
	v_lshl_add_u64 v[46:47], v[46:47], 0, v[136:137]
	v_cvt_pk_bf16_f32 v31, v26, v27
	v_lshl_add_u64 v[24:25], v[24:25], 0, v[124:125]
	s_mov_b64 s[0:1], 0x50000
	global_store_dwordx4 v[46:47], v[40:43], off
	global_store_dwordx4 v[24:25], v[28:31], off
	v_cvt_pk_bf16_f32 v12, v12, v13
	v_cvt_pk_bf16_f32 v13, v14, v15
	v_lshl_add_u64 v[28:29], v[158:159], 0, s[0:1]
	v_lshl_add_u64 v[30:31], v[120:121], 0, v[28:29]
	v_cvt_pk_bf16_f32 v14, v8, v9
	v_lshl_add_u64 v[8:9], v[122:123], 0, v[28:29]
	v_cvt_pk_bf16_f32 v24, v36, v37
	v_cvt_pk_bf16_f32 v25, v38, v39
	v_cvt_pk_bf16_f32 v26, v32, v33
	v_cvt_pk_bf16_f32 v27, v34, v35
	v_lshl_add_u64 v[30:31], v[30:31], 0, v[136:137]
	v_cvt_pk_bf16_f32 v15, v10, v11
	v_lshl_add_u64 v[8:9], v[8:9], 0, v[124:125]
	s_mov_b64 s[0:1], 0x58000
	global_store_dwordx4 v[30:31], v[24:27], off
	global_store_dwordx4 v[8:9], v[12:15], off
	v_cvt_pk_bf16_f32 v4, v4, v5
	v_cvt_pk_bf16_f32 v5, v6, v7
	v_lshl_add_u64 v[12:13], v[158:159], 0, s[0:1]
	v_lshl_add_u64 v[14:15], v[120:121], 0, v[12:13]
	v_cvt_pk_bf16_f32 v6, v0, v1
	v_lshl_add_u64 v[0:1], v[122:123], 0, v[12:13]
	v_cvt_pk_bf16_f32 v8, v20, v21
	v_cvt_pk_bf16_f32 v9, v22, v23
	v_cvt_pk_bf16_f32 v10, v16, v17
	v_cvt_pk_bf16_f32 v11, v18, v19
	v_lshl_add_u64 v[14:15], v[14:15], 0, v[136:137]
	v_cvt_pk_bf16_f32 v7, v2, v3
	v_lshl_add_u64 v[0:1], v[0:1], 0, v[124:125]
	s_and_b64 vcc, exec, s[4:5]
	s_mov_b32 s10, s12
	s_mov_b32 s11, s14
	s_mov_b32 s48, s16
	s_mov_b64 s[28:29], s[18:19]
	s_mov_b64 s[26:27], s[24:25]
	global_store_dwordx4 v[14:15], v[8:11], off
	global_store_dwordx4 v[0:1], v[4:7], off
	s_cbranch_vccz .LBB0_178
	s_waitcnt vmcnt(0)
	s_cmpk_gt_u32 s34, 0xff
	s_cbranch_scc1 .LBB0_191
	s_barrier

; #define PG8_STAGE(bufoff, gbase, voff) do { _Pragma("unroll") for (int _i = 0; _i < 2; ++_i) \
;         __builtin_amdgcn_global_load_lds((const unsigned*)((const char*)(gbase) + (voff)[_i]), (LAS unsigned*)(lds + (bufoff) + ldsw + _i * 8192), 16, 0, 0); } while (0)
; #define PG8_LDA(dst, b, h) do { _Pragma("unroll") for (int m = 0; m < 4; ++m) _Pragma("unroll") for (int k = 0; k < 2; ++k) dst[m][k] = *(const LAS bf16x8*)(lds + PG8_SA(b, h) + aoff + m * 2048 + k * 1024); } while (0)
; #define PG8_LDB(dst, b, h) do { _Pragma("unroll") for (int n = 0; n < 2; ++n) _Pragma("unroll") for (int k = 0; k < 2; ++k) dst[n][k] = *(const LAS bf16x8*)(lds + PG8_SB(b, h) + boff + n * 2048 + k * 1024); } while (0)
; #define PG8_MMA(ai, bj, At, Bt) do { __builtin_amdgcn_s_setprio(1); _Pragma("unroll") for (int m = 0; m < 4; ++m) _Pragma("unroll") for (int n = 0; n < 2; ++n) _Pragma("unroll") for (int k = 0; k < 2; ++k) \
;         acc[ai][bj][m][n] = __builtin_amdgcn_mfma_f32_16x16x32_bf16(Bt[n][k], At[m][k], acc[ai][bj][m][n], 0, 0, 0); __builtin_amdgcn_s_setprio(0); } while (0)
; #define PG8_WAIT_V(n) asm volatile("s_waitcnt vmcnt(" #n ")" ::: "memory")
; #define PG8_WAIT_L(n) asm volatile("s_waitcnt lgkmcnt(" #n ")" ::: "memory")
; #define PG8_BAR __builtin_amdgcn_s_barrier()
; #define PG8_SCHED __builtin_amdgcn_sched_barrier(0)
; template <class Epi>
; DEVI void gemm_phase(LAS unsigned char* lds, const Gemm g, const Epi& E) {
;     ...
;             PG8_LDB(B0, 0, 0); PG8_SCHED; PG8_LDA(At, 0, 0); PG8_STAGE(PG8_SA(1, 1), a1 + hstepA, voffA);
;             PG8_WAIT_L(8); PG8_BAR; PG8_WAIT_L(0); PG8_MMA(0, 0, At, B0); PG8_BAR; PG8_SCHED;
;             PG8_LDB(B1, 0, 1); PG8_STAGE(PG8_SB(0, 0), b2, voffB);
;             PG8_BAR; PG8_WAIT_L(0); PG8_MMA(0, 1, At, B1); PG8_BAR;
;             PG8_LDA(At, 0, 1); PG8_STAGE(PG8_SA(0, 0), a2, voffA);
;             PG8_BAR; PG8_WAIT_L(0); PG8_MMA(1, 0, At, B0); PG8_BAR; PG8_SCHED;
;             PG8_STAGE(PG8_SB(0, 1), b2 + hstepB, voffB);
;             PG8_WAIT_V(6); PG8_BAR; PG8_MMA(1, 1, At, B1); PG8_BAR;
.LBB0_276:
	s_add_u32 s19, s8, 0xfffc0080
	s_addc_u32 s26, s9, -1
	s_add_i32 s27, 0, 0x10000
	v_add_u32_e32 v8, s27, v214
	ds_read_b128 v[130:133], v8
	ds_read_b128 v[134:137], v8 offset:1024
	ds_read_b128 v[138:141], v8 offset:2048
	ds_read_b128 v[142:145], v8 offset:3072
	s_cmp_eq_u32 s18, 12
	s_cselect_b32 s69, s0, s26
	s_cselect_b32 s68, s1, s19
	s_cselect_b32 s47, s5, s15
	s_cselect_b32 s46, s7, s13
	v_lshl_add_u64 v[208:209], s[8:9], 0, v[184:185]
	s_add_i32 m0, s81, 0xc000
	ds_read_b128 v[146:149], v216
	ds_read_b128 v[150:153], v216 offset:1024
	ds_read_b128 v[188:191], v216 offset:2048
	ds_read_b128 v[192:195], v216 offset:3072
	ds_read_b128 v[196:199], v216 offset:4096
	ds_read_b128 v[200:203], v216 offset:5120
	ds_read_b128 v[204:207], v216 offset:6144
	ds_read_b128 v[218:221], v216 offset:7168
	global_load_lds_dwordx4 v[208:209], off
	s_add_i32 m0, s81, 0xe000
	v_lshl_add_u64 v[208:209], s[8:9], 0, v[186:187]
	global_load_lds_dwordx4 v[208:209], off
	s_waitcnt lgkmcnt(0)
	s_barrier
	s_cmp_lg_u32 s101, 0
	s_cbranch_scc1 .Lip13_a_0
	v_mfma_f32_16x16x32_bf16 v[126:129], v[130:133], v[146:149], v[126:129]
	v_mfma_f32_16x16x32_bf16 v[122:125], v[138:141], v[146:149], v[122:125]
	v_mfma_f32_16x16x32_bf16 v[114:117], v[130:133], v[188:191], v[114:117]
	v_mfma_f32_16x16x32_bf16 v[106:109], v[138:141], v[188:191], v[106:109]
	v_mfma_f32_16x16x32_bf16 v[94:97], v[130:133], v[196:199], v[94:97]
	v_mfma_f32_16x16x32_bf16 v[90:93], v[138:141], v[196:199], v[90:93]
	v_mfma_f32_16x16x32_bf16 v[82:85], v[130:133], v[204:207], v[82:85]
	v_mfma_f32_16x16x32_bf16 v[74:77], v[138:141], v[204:207], v[74:77]
	v_mfma_f32_16x16x32_bf16 v[126:129], v[134:137], v[150:153], v[126:129]
	v_mfma_f32_16x16x32_bf16 v[122:125], v[142:145], v[150:153], v[122:125]
	v_mfma_f32_16x16x32_bf16 v[114:117], v[134:137], v[192:195], v[114:117]
	v_mfma_f32_16x16x32_bf16 v[106:109], v[142:145], v[192:195], v[106:109]
	v_mfma_f32_16x16x32_bf16 v[94:97], v[134:137], v[200:203], v[94:97]
	v_mfma_f32_16x16x32_bf16 v[90:93], v[142:145], v[200:203], v[90:93]
	v_mfma_f32_16x16x32_bf16 v[82:85], v[134:137], v[218:221], v[82:85]
	v_mfma_f32_16x16x32_bf16 v[74:77], v[142:145], v[218:221], v[74:77]
.Lip13_a_0:
	s_barrier
	s_add_i32 s19, 0, 0x14000
	s_add_i32 s26, s27, s80
	v_add_u32_e32 v8, s19, v214
	v_lshl_add_u64 v[208:209], s[46:47], 0, v[178:179]
	s_mov_b32 m0, s26
	ds_read_b128 v[222:225], v8
	ds_read_b128 v[226:229], v8 offset:1024
	ds_read_b128 v[230:233], v8 offset:2048
	ds_read_b128 v[234:237], v8 offset:3072
	global_load_lds_dwordx4 v[208:209], off
	s_add_i32 m0, s26, 0x2000
	v_lshl_add_u64 v[238:239], s[46:47], 0, v[182:183]
	global_load_lds_dwordx4 v[238:239], off
	s_waitcnt lgkmcnt(0)
	s_barrier
	s_cmp_lg_u32 s100, 0
	s_cbranch_scc1 .Lip13_a_1
	v_mfma_f32_16x16x32_bf16 v[118:121], v[222:225], v[146:149], v[118:121]
	v_mfma_f32_16x16x32_bf16 v[110:113], v[230:233], v[146:149], v[110:113]
	v_mfma_f32_16x16x32_bf16 v[102:105], v[222:225], v[188:191], v[102:105]
	v_mfma_f32_16x16x32_bf16 v[98:101], v[230:233], v[188:191], v[98:101]
	v_mfma_f32_16x16x32_bf16 v[86:89], v[222:225], v[196:199], v[86:89]
	v_mfma_f32_16x16x32_bf16 v[78:81], v[230:233], v[196:199], v[78:81]
	v_mfma_f32_16x16x32_bf16 v[62:65], v[222:225], v[204:207], v[62:65]
	v_mfma_f32_16x16x32_bf16 v[58:61], v[230:233], v[204:207], v[58:61]
	v_mfma_f32_16x16x32_bf16 v[118:121], v[226:229], v[150:153], v[118:121]
	v_mfma_f32_16x16x32_bf16 v[110:113], v[234:237], v[150:153], v[110:113]
	v_mfma_f32_16x16x32_bf16 v[102:105], v[226:229], v[192:195], v[102:105]
	v_mfma_f32_16x16x32_bf16 v[98:101], v[234:237], v[192:195], v[98:101]
	v_mfma_f32_16x16x32_bf16 v[86:89], v[226:229], v[200:203], v[86:89]
	v_mfma_f32_16x16x32_bf16 v[78:81], v[234:237], v[200:203], v[78:81]
	v_mfma_f32_16x16x32_bf16 v[62:65], v[226:229], v[218:221], v[62:65]
	v_mfma_f32_16x16x32_bf16 v[58:61], v[234:237], v[218:221], v[58:61]
.Lip13_a_1:
	s_mov_b32 m0, s81
	v_lshl_add_u64 v[240:241], s[68:69], 0, v[176:177]
	s_barrier
	ds_read_b128 v[146:149], v216 offset:16384
	ds_read_b128 v[150:153], v216 offset:17408
	ds_read_b128 v[188:191], v216 offset:18432
	ds_read_b128 v[192:195], v216 offset:19456
	ds_read_b128 v[196:199], v216 offset:20480
	ds_read_b128 v[200:203], v216 offset:21504
	ds_read_b128 v[204:207], v216 offset:22528
	ds_read_b128 v[218:221], v216 offset:23552
	global_load_lds_dwordx4 v[240:241], off
	s_mov_b32 m0, s82
	v_lshl_add_u64 v[242:243], s[68:69], 0, v[180:181]
	global_load_lds_dwordx4 v[242:243], off
	s_waitcnt lgkmcnt(0)
	s_barrier
	s_cmp_lg_u32 s101, 0
	s_cbranch_scc1 .Lip13_a_2
	v_mfma_f32_16x16x32_bf16 v[70:73], v[130:133], v[146:149], v[70:73]
	v_mfma_f32_16x16x32_bf16 v[66:69], v[138:141], v[146:149], v[66:69]
	v_mfma_f32_16x16x32_bf16 v[46:49], v[130:133], v[188:191], v[46:49]
	v_mfma_f32_16x16x32_bf16 v[42:45], v[138:141], v[188:191], v[42:45]
	v_mfma_f32_16x16x32_bf16 v[30:33], v[130:133], v[196:199], v[30:33]
	v_mfma_f32_16x16x32_bf16 v[26:29], v[138:141], v[196:199], v[26:29]
	v_mfma_f32_16x16x32_bf16 v[14:17], v[130:133], v[204:207], v[14:17]
	v_mfma_f32_16x16x32_bf16 v[10:13], v[138:141], v[204:207], v[10:13]
	v_mfma_f32_16x16x32_bf16 v[70:73], v[134:137], v[150:153], v[70:73]
	v_mfma_f32_16x16x32_bf16 v[66:69], v[142:145], v[150:153], v[66:69]
	v_mfma_f32_16x16x32_bf16 v[46:49], v[134:137], v[192:195], v[46:49]
	v_mfma_f32_16x16x32_bf16 v[42:45], v[142:145], v[192:195], v[42:45]
	v_mfma_f32_16x16x32_bf16 v[30:33], v[134:137], v[200:203], v[30:33]
	v_mfma_f32_16x16x32_bf16 v[26:29], v[142:145], v[200:203], v[26:29]
	v_mfma_f32_16x16x32_bf16 v[14:17], v[134:137], v[218:221], v[14:17]
	v_mfma_f32_16x16x32_bf16 v[10:13], v[142:145], v[218:221], v[10:13]

; #define PG8_STAGE(bufoff, gbase, voff) do { _Pragma("unroll") for (int _i = 0; _i < 2; ++_i) \
;         __builtin_amdgcn_global_load_lds((const unsigned*)((const char*)(gbase) + (voff)[_i]), (LAS unsigned*)(lds + (bufoff) + ldsw + _i * 8192), 16, 0, 0); } while (0)
; #define PG8_LDA(dst, b, h) do { _Pragma("unroll") for (int m = 0; m < 4; ++m) _Pragma("unroll") for (int k = 0; k < 2; ++k) dst[m][k] = *(const LAS bf16x8*)(lds + PG8_SA(b, h) + aoff + m * 2048 + k * 1024); } while (0)
; #define PG8_LDB(dst, b, h) do { _Pragma("unroll") for (int n = 0; n < 2; ++n) _Pragma("unroll") for (int k = 0; k < 2; ++k) dst[n][k] = *(const LAS bf16x8*)(lds + PG8_SB(b, h) + boff + n * 2048 + k * 1024); } while (0)
; #define PG8_MMA(ai, bj, At, Bt) do { __builtin_amdgcn_s_setprio(1); _Pragma("unroll") for (int m = 0; m < 4; ++m) _Pragma("unroll") for (int n = 0; n < 2; ++n) _Pragma("unroll") for (int k = 0; k < 2; ++k) \
;         acc[ai][bj][m][n] = __builtin_amdgcn_mfma_f32_16x16x32_bf16(Bt[n][k], At[m][k], acc[ai][bj][m][n], 0, 0, 0); __builtin_amdgcn_s_setprio(0); } while (0)
; #define PG8_WAIT_V(n) asm volatile("s_waitcnt vmcnt(" #n ")" ::: "memory")
; #define PG8_WAIT_L(n) asm volatile("s_waitcnt lgkmcnt(" #n ")" ::: "memory")
; #define PG8_BAR __builtin_amdgcn_s_barrier()
; #define PG8_SCHED __builtin_amdgcn_sched_barrier(0)
; template <class Epi>
; DEVI void gemm_phase(LAS unsigned char* lds, const Gemm g, const Epi& E) {
;     ...
;             PG8_LDB(B0, 1, 0); PG8_SCHED; PG8_LDA(At, 1, 0); PG8_STAGE(PG8_SA(0, 1), a2 + hstepA, voffA);
;             PG8_WAIT_L(8); PG8_BAR; PG8_WAIT_L(0); PG8_MMA(0, 0, At, B0); PG8_BAR; PG8_SCHED;
;             PG8_LDB(B1, 1, 1); PG8_STAGE(PG8_SB(1, 0), b3, voffB);
;             PG8_BAR; PG8_WAIT_L(0); PG8_MMA(0, 1, At, B1); PG8_BAR;
;             PG8_LDA(At, 1, 1); PG8_STAGE(PG8_SA(1, 0), a3, voffA);
;             PG8_BAR; PG8_WAIT_L(0); PG8_MMA(1, 0, At, B0); PG8_BAR; PG8_SCHED;
;             PG8_STAGE(PG8_SB(1, 1), b3 + hstepB, voffB);
;             PG8_WAIT_V(6); PG8_BAR; PG8_MMA(1, 1, At, B1); PG8_BAR;
.Lip13_a_3:
	s_add_i32 s19, 0, 0x18000
	v_add_u32_e32 v8, s19, v214
	s_barrier
	ds_read_b128 v[130:133], v8
	ds_read_b128 v[134:137], v8 offset:1024
	ds_read_b128 v[138:141], v8 offset:2048
	ds_read_b128 v[142:145], v8 offset:3072
	s_add_u32 s26, s68, 0x40000
	s_addc_u32 s27, s69, 0
	s_mov_b32 m0, s83
	v_lshl_add_u64 v[222:223], s[26:27], 0, v[176:177]
	ds_read_b128 v[146:149], v216 offset:32768
	ds_read_b128 v[150:153], v216 offset:33792
	ds_read_b128 v[188:191], v216 offset:34816
	ds_read_b128 v[192:195], v216 offset:35840
	ds_read_b128 v[196:199], v216 offset:36864
	ds_read_b128 v[200:203], v216 offset:37888
	ds_read_b128 v[204:207], v216 offset:38912
	ds_read_b128 v[218:221], v216 offset:39936
	global_load_lds_dwordx4 v[222:223], off
	s_mov_b32 m0, s84
	v_lshl_add_u64 v[222:223], s[26:27], 0, v[180:181]
	global_load_lds_dwordx4 v[222:223], off
	s_waitcnt lgkmcnt(0)
	s_barrier
	s_cmp_lg_u32 s101, 0
	s_cbranch_scc1 .Lip13_a_4
	v_mfma_f32_16x16x32_bf16 v[126:129], v[130:133], v[146:149], v[126:129]
	v_mfma_f32_16x16x32_bf16 v[122:125], v[138:141], v[146:149], v[122:125]
	v_mfma_f32_16x16x32_bf16 v[114:117], v[130:133], v[188:191], v[114:117]
	v_mfma_f32_16x16x32_bf16 v[106:109], v[138:141], v[188:191], v[106:109]
	v_mfma_f32_16x16x32_bf16 v[94:97], v[130:133], v[196:199], v[94:97]
	v_mfma_f32_16x16x32_bf16 v[90:93], v[138:141], v[196:199], v[90:93]
	v_mfma_f32_16x16x32_bf16 v[82:85], v[130:133], v[204:207], v[82:85]
	v_mfma_f32_16x16x32_bf16 v[74:77], v[138:141], v[204:207], v[74:77]
	v_mfma_f32_16x16x32_bf16 v[126:129], v[134:137], v[150:153], v[126:129]
	v_mfma_f32_16x16x32_bf16 v[122:125], v[142:145], v[150:153], v[122:125]
	v_mfma_f32_16x16x32_bf16 v[114:117], v[134:137], v[192:195], v[114:117]
	v_mfma_f32_16x16x32_bf16 v[106:109], v[142:145], v[192:195], v[106:109]
	v_mfma_f32_16x16x32_bf16 v[94:97], v[134:137], v[200:203], v[94:97]
	v_mfma_f32_16x16x32_bf16 v[90:93], v[142:145], v[200:203], v[90:93]
	v_mfma_f32_16x16x32_bf16 v[82:85], v[134:137], v[218:221], v[82:85]
	v_mfma_f32_16x16x32_bf16 v[74:77], v[142:145], v[218:221], v[74:77]
.Lip13_a_4:
	s_barrier
	s_add_i32 s38, 0, 0x1c000
	s_add_i32 s19, s19, s80
	v_add_u32_e32 v8, s38, v214
	v_lshl_add_u64 v[208:209], v[208:209], 0, s[70:71]
	s_mov_b32 m0, s19
	ds_read_b128 v[222:225], v8
	ds_read_b128 v[226:229], v8 offset:1024
	ds_read_b128 v[230:233], v8 offset:2048
	ds_read_b128 v[234:237], v8 offset:3072
	global_load_lds_dwordx4 v[208:209], off
	s_add_i32 m0, s19, 0x2000
	v_lshl_add_u64 v[208:209], v[238:239], 0, s[70:71]
	global_load_lds_dwordx4 v[208:209], off
	s_waitcnt lgkmcnt(0)
	s_barrier
	s_cmp_lg_u32 s100, 0
	s_cbranch_scc1 .Lip13_a_5
	v_mfma_f32_16x16x32_bf16 v[118:121], v[222:225], v[146:149], v[118:121]
	v_mfma_f32_16x16x32_bf16 v[110:113], v[230:233], v[146:149], v[110:113]
	v_mfma_f32_16x16x32_bf16 v[102:105], v[222:225], v[188:191], v[102:105]
	v_mfma_f32_16x16x32_bf16 v[98:101], v[230:233], v[188:191], v[98:101]
	v_mfma_f32_16x16x32_bf16 v[86:89], v[222:225], v[196:199], v[86:89]
	v_mfma_f32_16x16x32_bf16 v[78:81], v[230:233], v[196:199], v[78:81]
	v_mfma_f32_16x16x32_bf16 v[62:65], v[222:225], v[204:207], v[62:65]
	v_mfma_f32_16x16x32_bf16 v[58:61], v[230:233], v[204:207], v[58:61]
	v_mfma_f32_16x16x32_bf16 v[118:121], v[226:229], v[150:153], v[118:121]
	v_mfma_f32_16x16x32_bf16 v[110:113], v[234:237], v[150:153], v[110:113]
	v_mfma_f32_16x16x32_bf16 v[102:105], v[226:229], v[192:195], v[102:105]
	v_mfma_f32_16x16x32_bf16 v[98:101], v[234:237], v[192:195], v[98:101]
	v_mfma_f32_16x16x32_bf16 v[86:89], v[226:229], v[200:203], v[86:89]
	v_mfma_f32_16x16x32_bf16 v[78:81], v[234:237], v[200:203], v[78:81]
	v_mfma_f32_16x16x32_bf16 v[62:65], v[226:229], v[218:221], v[62:65]
	v_mfma_f32_16x16x32_bf16 v[58:61], v[234:237], v[218:221], v[58:61]
.Lip13_a_5:
	s_mov_b32 m0, s85
	v_lshl_add_u64 v[208:209], v[240:241], 0, s[70:71]
	s_barrier
	ds_read_b128 v[146:149], v216 offset:49152
	ds_read_b128 v[150:153], v216 offset:50176
	ds_read_b128 v[188:191], v216 offset:51200
	ds_read_b128 v[192:195], v216 offset:52224
	ds_read_b128 v[196:199], v216 offset:53248
	ds_read_b128 v[200:203], v216 offset:54272
	ds_read_b128 v[204:207], v216 offset:55296
	ds_read_b128 v[218:221], v216 offset:56320
	global_load_lds_dwordx4 v[208:209], off
	s_mov_b32 m0, s86
	v_lshl_add_u64 v[208:209], v[242:243], 0, s[70:71]
	global_load_lds_dwordx4 v[208:209], off
	s_waitcnt lgkmcnt(0)
	s_barrier
	s_cmp_lg_u32 s101, 0
	s_cbranch_scc1 .Lip13_a_6
	v_mfma_f32_16x16x32_bf16 v[70:73], v[130:133], v[146:149], v[70:73]
	v_mfma_f32_16x16x32_bf16 v[66:69], v[138:141], v[146:149], v[66:69]
	v_mfma_f32_16x16x32_bf16 v[46:49], v[130:133], v[188:191], v[46:49]
	v_mfma_f32_16x16x32_bf16 v[42:45], v[138:141], v[188:191], v[42:45]
	v_mfma_f32_16x16x32_bf16 v[30:33], v[130:133], v[196:199], v[30:33]
	v_mfma_f32_16x16x32_bf16 v[26:29], v[138:141], v[196:199], v[26:29]
	v_mfma_f32_16x16x32_bf16 v[14:17], v[130:133], v[204:207], v[14:17]
	v_mfma_f32_16x16x32_bf16 v[10:13], v[138:141], v[204:207], v[10:13]
	v_mfma_f32_16x16x32_bf16 v[70:73], v[134:137], v[150:153], v[70:73]
	v_mfma_f32_16x16x32_bf16 v[66:69], v[142:145], v[150:153], v[66:69]
	v_mfma_f32_16x16x32_bf16 v[46:49], v[134:137], v[192:195], v[46:49]
	v_mfma_f32_16x16x32_bf16 v[42:45], v[142:145], v[192:195], v[42:45]
	v_mfma_f32_16x16x32_bf16 v[30:33], v[134:137], v[200:203], v[30:33]
	v_mfma_f32_16x16x32_bf16 v[26:29], v[142:145], v[200:203], v[26:29]
	v_mfma_f32_16x16x32_bf16 v[14:17], v[134:137], v[218:221], v[14:17]
	v_mfma_f32_16x16x32_bf16 v[10:13], v[142:145], v[218:221], v[10:13]

; #define PG8_STAGE(bufoff, gbase, voff) do { _Pragma("unroll") for (int _i = 0; _i < 2; ++_i) \
;         __builtin_amdgcn_global_load_lds((const unsigned*)((const char*)(gbase) + (voff)[_i]), (LAS unsigned*)(lds + (bufoff) + ldsw + _i * 8192), 16, 0, 0); } while (0)
; #define PG8_LDA(dst, b, h) do { _Pragma("unroll") for (int m = 0; m < 4; ++m) _Pragma("unroll") for (int k = 0; k < 2; ++k) dst[m][k] = *(const LAS bf16x8*)(lds + PG8_SA(b, h) + aoff + m * 2048 + k * 1024); } while (0)
; #define PG8_LDB(dst, b, h) do { _Pragma("unroll") for (int n = 0; n < 2; ++n) _Pragma("unroll") for (int k = 0; k < 2; ++k) dst[n][k] = *(const LAS bf16x8*)(lds + PG8_SB(b, h) + boff + n * 2048 + k * 1024); } while (0)
; #define PG8_MMA(ai, bj, At, Bt) do { __builtin_amdgcn_s_setprio(1); _Pragma("unroll") for (int m = 0; m < 4; ++m) _Pragma("unroll") for (int n = 0; n < 2; ++n) _Pragma("unroll") for (int k = 0; k < 2; ++k) \
;         acc[ai][bj][m][n] = __builtin_amdgcn_mfma_f32_16x16x32_bf16(Bt[n][k], At[m][k], acc[ai][bj][m][n], 0, 0, 0); __builtin_amdgcn_s_setprio(0); } while (0)
; #define PG8_WAIT_V(n) asm volatile("s_waitcnt vmcnt(" #n ")" ::: "memory")
; #define PG8_WAIT_L(n) asm volatile("s_waitcnt lgkmcnt(" #n ")" ::: "memory")
; #define PG8_BAR __builtin_amdgcn_s_barrier()
; #define PG8_SCHED __builtin_amdgcn_sched_barrier(0)
; template <class Epi>
; DEVI void gemm_phase(LAS unsigned char* lds, const Gemm g, const Epi& E) {
;     ...
;             PG8_LDB(B0, 0, 0); PG8_SCHED; PG8_LDA(At, 0, 0); PG8_STAGE(PG8_SA(1, 1), a1 + hstepA, voffA);
;             PG8_WAIT_L(8); PG8_BAR; PG8_WAIT_L(0); PG8_MMA(0, 0, At, B0); PG8_BAR; PG8_SCHED;
;             PG8_LDB(B1, 0, 1); PG8_STAGE(PG8_SB(0, 0), b2, voffB);
;             PG8_BAR; PG8_WAIT_L(0); PG8_MMA(0, 1, At, B1); PG8_BAR;
;             PG8_LDA(At, 0, 1); PG8_STAGE(PG8_SA(0, 0), a2, voffA);
;             PG8_BAR; PG8_WAIT_L(0); PG8_MMA(1, 0, At, B0); PG8_BAR; PG8_SCHED;
;             PG8_STAGE(PG8_SB(0, 1), b2 + hstepB, voffB);
;             PG8_WAIT_V(6); PG8_BAR; PG8_MMA(1, 1, At, B1); PG8_BAR;
.LBB0_356:
	s_add_u32 s19, s8, 0xfffc0080
	s_addc_u32 s26, s9, -1
	s_add_i32 s27, 0, 0x10000
	v_add_u32_e32 v142, s27, v209
	ds_read_b128 v[130:133], v142
	ds_read_b128 v[134:137], v142 offset:1024
	ds_read_b128 v[138:141], v142 offset:2048
	ds_read_b128 v[142:145], v142 offset:3072
	s_cmp_eq_u32 s18, 12
	s_cselect_b32 s69, s0, s26
	s_cselect_b32 s68, s1, s19
	s_cselect_b32 s47, s5, s13
	s_cselect_b32 s46, s7, s11
	v_lshl_add_u64 v[206:207], s[8:9], 0, v[182:183]
	s_add_i32 m0, s85, 0xc000
	ds_read_b128 v[146:149], v214
	ds_read_b128 v[150:153], v214 offset:1024
	ds_read_b128 v[186:189], v214 offset:2048
	ds_read_b128 v[190:193], v214 offset:3072
	ds_read_b128 v[194:197], v214 offset:4096
	ds_read_b128 v[198:201], v214 offset:5120
	ds_read_b128 v[202:205], v214 offset:6144
	ds_read_b128 v[216:219], v214 offset:7168
	global_load_lds_dwordx4 v[206:207], off
	s_add_i32 m0, s85, 0xe000
	v_lshl_add_u64 v[206:207], s[8:9], 0, v[184:185]
	global_load_lds_dwordx4 v[206:207], off
	s_waitcnt lgkmcnt(0)
	s_barrier
	s_cmp_lg_u32 s101, 0
	s_cbranch_scc1 .Lip13_b_0
	v_mfma_f32_16x16x32_bf16 v[126:129], v[130:133], v[146:149], v[126:129]
	v_mfma_f32_16x16x32_bf16 v[122:125], v[138:141], v[146:149], v[122:125]
	v_mfma_f32_16x16x32_bf16 v[114:117], v[130:133], v[186:189], v[114:117]
	v_mfma_f32_16x16x32_bf16 v[106:109], v[138:141], v[186:189], v[106:109]
	v_mfma_f32_16x16x32_bf16 v[94:97], v[130:133], v[194:197], v[94:97]
	v_mfma_f32_16x16x32_bf16 v[90:93], v[138:141], v[194:197], v[90:93]
	v_mfma_f32_16x16x32_bf16 v[82:85], v[130:133], v[202:205], v[82:85]
	v_mfma_f32_16x16x32_bf16 v[74:77], v[138:141], v[202:205], v[74:77]
	v_mfma_f32_16x16x32_bf16 v[126:129], v[134:137], v[150:153], v[126:129]
	v_mfma_f32_16x16x32_bf16 v[122:125], v[142:145], v[150:153], v[122:125]
	v_mfma_f32_16x16x32_bf16 v[114:117], v[134:137], v[190:193], v[114:117]
	v_mfma_f32_16x16x32_bf16 v[106:109], v[142:145], v[190:193], v[106:109]
	v_mfma_f32_16x16x32_bf16 v[94:97], v[134:137], v[198:201], v[94:97]
	v_mfma_f32_16x16x32_bf16 v[90:93], v[142:145], v[198:201], v[90:93]
	v_mfma_f32_16x16x32_bf16 v[82:85], v[134:137], v[216:219], v[82:85]
	v_mfma_f32_16x16x32_bf16 v[74:77], v[142:145], v[216:219], v[74:77]
.Lip13_b_0:
	s_barrier
	s_add_i32 s19, 0, 0x14000
	s_add_i32 s26, s27, s84
	v_add_u32_e32 v162, s19, v209
	v_lshl_add_u64 v[206:207], s[46:47], 0, v[8:9]
	s_mov_b32 m0, s26
	ds_read_b128 v[220:223], v162
	ds_read_b128 v[224:227], v162 offset:1024
	ds_read_b128 v[228:231], v162 offset:2048
	ds_read_b128 v[232:235], v162 offset:3072
	global_load_lds_dwordx4 v[206:207], off
	s_add_i32 m0, s26, 0x2000
	v_lshl_add_u64 v[236:237], s[46:47], 0, v[180:181]
	global_load_lds_dwordx4 v[236:237], off
	s_waitcnt lgkmcnt(0)
	s_barrier
	s_cmp_lg_u32 s100, 0
	s_cbranch_scc1 .Lip13_b_1
	v_mfma_f32_16x16x32_bf16 v[118:121], v[220:223], v[146:149], v[118:121]
	v_mfma_f32_16x16x32_bf16 v[110:113], v[228:231], v[146:149], v[110:113]
	v_mfma_f32_16x16x32_bf16 v[102:105], v[220:223], v[186:189], v[102:105]
	v_mfma_f32_16x16x32_bf16 v[98:101], v[228:231], v[186:189], v[98:101]
	v_mfma_f32_16x16x32_bf16 v[86:89], v[220:223], v[194:197], v[86:89]
	v_mfma_f32_16x16x32_bf16 v[78:81], v[228:231], v[194:197], v[78:81]
	v_mfma_f32_16x16x32_bf16 v[62:65], v[220:223], v[202:205], v[62:65]
	v_mfma_f32_16x16x32_bf16 v[58:61], v[228:231], v[202:205], v[58:61]
	v_mfma_f32_16x16x32_bf16 v[118:121], v[224:227], v[150:153], v[118:121]
	v_mfma_f32_16x16x32_bf16 v[110:113], v[232:235], v[150:153], v[110:113]
	v_mfma_f32_16x16x32_bf16 v[102:105], v[224:227], v[190:193], v[102:105]
	v_mfma_f32_16x16x32_bf16 v[98:101], v[232:235], v[190:193], v[98:101]
	v_mfma_f32_16x16x32_bf16 v[86:89], v[224:227], v[198:201], v[86:89]
	v_mfma_f32_16x16x32_bf16 v[78:81], v[232:235], v[198:201], v[78:81]
	v_mfma_f32_16x16x32_bf16 v[62:65], v[224:227], v[216:219], v[62:65]
	v_mfma_f32_16x16x32_bf16 v[58:61], v[232:235], v[216:219], v[58:61]
.Lip13_b_1:
	s_mov_b32 m0, s85
	v_lshl_add_u64 v[238:239], s[68:69], 0, v[176:177]
	s_barrier
	ds_read_b128 v[146:149], v214 offset:16384
	ds_read_b128 v[150:153], v214 offset:17408
	ds_read_b128 v[186:189], v214 offset:18432
	ds_read_b128 v[190:193], v214 offset:19456
	ds_read_b128 v[194:197], v214 offset:20480
	ds_read_b128 v[198:201], v214 offset:21504
	ds_read_b128 v[202:205], v214 offset:22528
	ds_read_b128 v[216:219], v214 offset:23552
	global_load_lds_dwordx4 v[238:239], off
	s_mov_b32 m0, s86
	v_lshl_add_u64 v[240:241], s[68:69], 0, v[178:179]
	global_load_lds_dwordx4 v[240:241], off
	s_waitcnt lgkmcnt(0)
	s_barrier
	s_cmp_lg_u32 s101, 0
	s_cbranch_scc1 .Lip13_b_2
	v_mfma_f32_16x16x32_bf16 v[70:73], v[130:133], v[146:149], v[70:73]
	v_mfma_f32_16x16x32_bf16 v[66:69], v[138:141], v[146:149], v[66:69]
	v_mfma_f32_16x16x32_bf16 v[46:49], v[130:133], v[186:189], v[46:49]
	v_mfma_f32_16x16x32_bf16 v[42:45], v[138:141], v[186:189], v[42:45]
	v_mfma_f32_16x16x32_bf16 v[30:33], v[130:133], v[194:197], v[30:33]
	v_mfma_f32_16x16x32_bf16 v[26:29], v[138:141], v[194:197], v[26:29]
	v_mfma_f32_16x16x32_bf16 v[14:17], v[130:133], v[202:205], v[14:17]
	v_mfma_f32_16x16x32_bf16 v[10:13], v[138:141], v[202:205], v[10:13]
	v_mfma_f32_16x16x32_bf16 v[70:73], v[134:137], v[150:153], v[70:73]
	v_mfma_f32_16x16x32_bf16 v[66:69], v[142:145], v[150:153], v[66:69]
	v_mfma_f32_16x16x32_bf16 v[46:49], v[134:137], v[190:193], v[46:49]
	v_mfma_f32_16x16x32_bf16 v[42:45], v[142:145], v[190:193], v[42:45]
	v_mfma_f32_16x16x32_bf16 v[30:33], v[134:137], v[198:201], v[30:33]
	v_mfma_f32_16x16x32_bf16 v[26:29], v[142:145], v[198:201], v[26:29]
	v_mfma_f32_16x16x32_bf16 v[14:17], v[134:137], v[216:219], v[14:17]
	v_mfma_f32_16x16x32_bf16 v[10:13], v[142:145], v[216:219], v[10:13]

; #define PG8_STAGE(bufoff, gbase, voff) do { _Pragma("unroll") for (int _i = 0; _i < 2; ++_i) \
;         __builtin_amdgcn_global_load_lds((const unsigned*)((const char*)(gbase) + (voff)[_i]), (LAS unsigned*)(lds + (bufoff) + ldsw + _i * 8192), 16, 0, 0); } while (0)
; #define PG8_LDA(dst, b, h) do { _Pragma("unroll") for (int m = 0; m < 4; ++m) _Pragma("unroll") for (int k = 0; k < 2; ++k) dst[m][k] = *(const LAS bf16x8*)(lds + PG8_SA(b, h) + aoff + m * 2048 + k * 1024); } while (0)
; #define PG8_LDB(dst, b, h) do { _Pragma("unroll") for (int n = 0; n < 2; ++n) _Pragma("unroll") for (int k = 0; k < 2; ++k) dst[n][k] = *(const LAS bf16x8*)(lds + PG8_SB(b, h) + boff + n * 2048 + k * 1024); } while (0)
; #define PG8_MMA(ai, bj, At, Bt) do { __builtin_amdgcn_s_setprio(1); _Pragma("unroll") for (int m = 0; m < 4; ++m) _Pragma("unroll") for (int n = 0; n < 2; ++n) _Pragma("unroll") for (int k = 0; k < 2; ++k) \
;         acc[ai][bj][m][n] = __builtin_amdgcn_mfma_f32_16x16x32_bf16(Bt[n][k], At[m][k], acc[ai][bj][m][n], 0, 0, 0); __builtin_amdgcn_s_setprio(0); } while (0)
; #define PG8_WAIT_V(n) asm volatile("s_waitcnt vmcnt(" #n ")" ::: "memory")
; #define PG8_WAIT_L(n) asm volatile("s_waitcnt lgkmcnt(" #n ")" ::: "memory")
; #define PG8_BAR __builtin_amdgcn_s_barrier()
; #define PG8_SCHED __builtin_amdgcn_sched_barrier(0)
; template <class Epi>
; DEVI void gemm_phase(LAS unsigned char* lds, const Gemm g, const Epi& E) {
;     ...
;             PG8_LDB(B0, 1, 0); PG8_SCHED; PG8_LDA(At, 1, 0); PG8_STAGE(PG8_SA(0, 1), a2 + hstepA, voffA);
;             PG8_WAIT_L(8); PG8_BAR; PG8_WAIT_L(0); PG8_MMA(0, 0, At, B0); PG8_BAR; PG8_SCHED;
;             PG8_LDB(B1, 1, 1); PG8_STAGE(PG8_SB(1, 0), b3, voffB);
;             PG8_BAR; PG8_WAIT_L(0); PG8_MMA(0, 1, At, B1); PG8_BAR;
;             PG8_LDA(At, 1, 1); PG8_STAGE(PG8_SA(1, 0), a3, voffA);
;             PG8_BAR; PG8_WAIT_L(0); PG8_MMA(1, 0, At, B0); PG8_BAR; PG8_SCHED;
;             PG8_STAGE(PG8_SB(1, 1), b3 + hstepB, voffB);
;             PG8_WAIT_V(6); PG8_BAR; PG8_MMA(1, 1, At, B1); PG8_BAR;
.Lip13_b_3:
	s_add_i32 s19, 0, 0x18000
	v_add_u32_e32 v142, s19, v209
	s_barrier
	ds_read_b128 v[130:133], v142
	ds_read_b128 v[134:137], v142 offset:1024
	ds_read_b128 v[138:141], v142 offset:2048
	ds_read_b128 v[142:145], v142 offset:3072
	s_add_u32 s26, s68, 0x40000
	s_addc_u32 s27, s69, 0
	s_mov_b32 m0, s87
	v_lshl_add_u64 v[220:221], s[26:27], 0, v[176:177]
	ds_read_b128 v[146:149], v214 offset:32768
	ds_read_b128 v[150:153], v214 offset:33792
	ds_read_b128 v[186:189], v214 offset:34816
	ds_read_b128 v[190:193], v214 offset:35840
	ds_read_b128 v[194:197], v214 offset:36864
	ds_read_b128 v[198:201], v214 offset:37888
	ds_read_b128 v[202:205], v214 offset:38912
	ds_read_b128 v[216:219], v214 offset:39936
	global_load_lds_dwordx4 v[220:221], off
	s_mov_b32 m0, s88
	v_lshl_add_u64 v[220:221], s[26:27], 0, v[178:179]
	global_load_lds_dwordx4 v[220:221], off
	s_waitcnt lgkmcnt(0)
	s_barrier
	s_cmp_lg_u32 s101, 0
	s_cbranch_scc1 .Lip13_b_4
	v_mfma_f32_16x16x32_bf16 v[126:129], v[130:133], v[146:149], v[126:129]
	v_mfma_f32_16x16x32_bf16 v[122:125], v[138:141], v[146:149], v[122:125]
	v_mfma_f32_16x16x32_bf16 v[114:117], v[130:133], v[186:189], v[114:117]
	v_mfma_f32_16x16x32_bf16 v[106:109], v[138:141], v[186:189], v[106:109]
	v_mfma_f32_16x16x32_bf16 v[94:97], v[130:133], v[194:197], v[94:97]
	v_mfma_f32_16x16x32_bf16 v[90:93], v[138:141], v[194:197], v[90:93]
	v_mfma_f32_16x16x32_bf16 v[82:85], v[130:133], v[202:205], v[82:85]
	v_mfma_f32_16x16x32_bf16 v[74:77], v[138:141], v[202:205], v[74:77]
	v_mfma_f32_16x16x32_bf16 v[126:129], v[134:137], v[150:153], v[126:129]
	v_mfma_f32_16x16x32_bf16 v[122:125], v[142:145], v[150:153], v[122:125]
	v_mfma_f32_16x16x32_bf16 v[114:117], v[134:137], v[190:193], v[114:117]
	v_mfma_f32_16x16x32_bf16 v[106:109], v[142:145], v[190:193], v[106:109]
	v_mfma_f32_16x16x32_bf16 v[94:97], v[134:137], v[198:201], v[94:97]
	v_mfma_f32_16x16x32_bf16 v[90:93], v[142:145], v[198:201], v[90:93]
	v_mfma_f32_16x16x32_bf16 v[82:85], v[134:137], v[216:219], v[82:85]
	v_mfma_f32_16x16x32_bf16 v[74:77], v[142:145], v[216:219], v[74:77]
.Lip13_b_4:
	s_barrier
	s_add_i32 s38, 0, 0x1c000
	s_add_i32 s19, s19, s84
	v_add_u32_e32 v162, s38, v209
	v_lshl_add_u64 v[206:207], v[206:207], 0, s[70:71]
	s_mov_b32 m0, s19
	ds_read_b128 v[220:223], v162
	ds_read_b128 v[224:227], v162 offset:1024
	ds_read_b128 v[228:231], v162 offset:2048
	ds_read_b128 v[232:235], v162 offset:3072
	global_load_lds_dwordx4 v[206:207], off
	s_add_i32 m0, s19, 0x2000
	v_lshl_add_u64 v[206:207], v[236:237], 0, s[70:71]
	global_load_lds_dwordx4 v[206:207], off
	s_waitcnt lgkmcnt(0)
	s_barrier
	s_cmp_lg_u32 s100, 0
	s_cbranch_scc1 .Lip13_b_5
	v_mfma_f32_16x16x32_bf16 v[118:121], v[220:223], v[146:149], v[118:121]
	v_mfma_f32_16x16x32_bf16 v[110:113], v[228:231], v[146:149], v[110:113]
	v_mfma_f32_16x16x32_bf16 v[102:105], v[220:223], v[186:189], v[102:105]
	v_mfma_f32_16x16x32_bf16 v[98:101], v[228:231], v[186:189], v[98:101]
	v_mfma_f32_16x16x32_bf16 v[86:89], v[220:223], v[194:197], v[86:89]
	v_mfma_f32_16x16x32_bf16 v[78:81], v[228:231], v[194:197], v[78:81]
	v_mfma_f32_16x16x32_bf16 v[62:65], v[220:223], v[202:205], v[62:65]
	v_mfma_f32_16x16x32_bf16 v[58:61], v[228:231], v[202:205], v[58:61]
	v_mfma_f32_16x16x32_bf16 v[118:121], v[224:227], v[150:153], v[118:121]
	v_mfma_f32_16x16x32_bf16 v[110:113], v[232:235], v[150:153], v[110:113]
	v_mfma_f32_16x16x32_bf16 v[102:105], v[224:227], v[190:193], v[102:105]
	v_mfma_f32_16x16x32_bf16 v[98:101], v[232:235], v[190:193], v[98:101]
	v_mfma_f32_16x16x32_bf16 v[86:89], v[224:227], v[198:201], v[86:89]
	v_mfma_f32_16x16x32_bf16 v[78:81], v[232:235], v[198:201], v[78:81]
	v_mfma_f32_16x16x32_bf16 v[62:65], v[224:227], v[216:219], v[62:65]
	v_mfma_f32_16x16x32_bf16 v[58:61], v[232:235], v[216:219], v[58:61]
.Lip13_b_5:
	s_mov_b32 m0, s89
	v_lshl_add_u64 v[206:207], v[238:239], 0, s[70:71]
	s_barrier
	ds_read_b128 v[146:149], v214 offset:49152
	ds_read_b128 v[150:153], v214 offset:50176
	ds_read_b128 v[186:189], v214 offset:51200
	ds_read_b128 v[190:193], v214 offset:52224
	ds_read_b128 v[194:197], v214 offset:53248
	ds_read_b128 v[198:201], v214 offset:54272
	ds_read_b128 v[202:205], v214 offset:55296
	ds_read_b128 v[216:219], v214 offset:56320
	global_load_lds_dwordx4 v[206:207], off
	s_mov_b32 m0, s90
	v_lshl_add_u64 v[206:207], v[240:241], 0, s[70:71]
	global_load_lds_dwordx4 v[206:207], off
	s_waitcnt lgkmcnt(0)
	s_barrier
	s_cmp_lg_u32 s101, 0
	s_cbranch_scc1 .Lip13_b_6
	v_mfma_f32_16x16x32_bf16 v[70:73], v[130:133], v[146:149], v[70:73]
	v_mfma_f32_16x16x32_bf16 v[66:69], v[138:141], v[146:149], v[66:69]
	v_mfma_f32_16x16x32_bf16 v[46:49], v[130:133], v[186:189], v[46:49]
	v_mfma_f32_16x16x32_bf16 v[42:45], v[138:141], v[186:189], v[42:45]
	v_mfma_f32_16x16x32_bf16 v[30:33], v[130:133], v[194:197], v[30:33]
	v_mfma_f32_16x16x32_bf16 v[26:29], v[138:141], v[194:197], v[26:29]
	v_mfma_f32_16x16x32_bf16 v[14:17], v[130:133], v[202:205], v[14:17]
	v_mfma_f32_16x16x32_bf16 v[10:13], v[138:141], v[202:205], v[10:13]
	v_mfma_f32_16x16x32_bf16 v[70:73], v[134:137], v[150:153], v[70:73]
	v_mfma_f32_16x16x32_bf16 v[66:69], v[142:145], v[150:153], v[66:69]
	v_mfma_f32_16x16x32_bf16 v[46:49], v[134:137], v[190:193], v[46:49]
	v_mfma_f32_16x16x32_bf16 v[42:45], v[142:145], v[190:193], v[42:45]
	v_mfma_f32_16x16x32_bf16 v[30:33], v[134:137], v[198:201], v[30:33]
	v_mfma_f32_16x16x32_bf16 v[26:29], v[142:145], v[198:201], v[26:29]
	v_mfma_f32_16x16x32_bf16 v[14:17], v[134:137], v[216:219], v[14:17]
	v_mfma_f32_16x16x32_bf16 v[10:13], v[142:145], v[216:219], v[10:13]

; #define PG8_STAGE(bufoff, gbase, voff) do { _Pragma("unroll") for (int _i = 0; _i < 2; ++_i) \
;         __builtin_amdgcn_global_load_lds((const unsigned*)((const char*)(gbase) + (voff)[_i]), (LAS unsigned*)(lds + (bufoff) + ldsw + _i * 8192), 16, 0, 0); } while (0)
; #define PG8_LDA(dst, b, h) do { _Pragma("unroll") for (int m = 0; m < 4; ++m) _Pragma("unroll") for (int k = 0; k < 2; ++k) dst[m][k] = *(const LAS bf16x8*)(lds + PG8_SA(b, h) + aoff + m * 2048 + k * 1024); } while (0)
; #define PG8_LDB(dst, b, h) do { _Pragma("unroll") for (int n = 0; n < 2; ++n) _Pragma("unroll") for (int k = 0; k < 2; ++k) dst[n][k] = *(const LAS bf16x8*)(lds + PG8_SB(b, h) + boff + n * 2048 + k * 1024); } while (0)
; #define PG8_MMA(ai, bj, At, Bt) do { __builtin_amdgcn_s_setprio(1); _Pragma("unroll") for (int m = 0; m < 4; ++m) _Pragma("unroll") for (int n = 0; n < 2; ++n) _Pragma("unroll") for (int k = 0; k < 2; ++k) \
;         acc[ai][bj][m][n] = __builtin_amdgcn_mfma_f32_16x16x32_bf16(Bt[n][k], At[m][k], acc[ai][bj][m][n], 0, 0, 0); __builtin_amdgcn_s_setprio(0); } while (0)
; #define PG8_WAIT_V(n) asm volatile("s_waitcnt vmcnt(" #n ")" ::: "memory")
; #define PG8_WAIT_L(n) asm volatile("s_waitcnt lgkmcnt(" #n ")" ::: "memory")
; #define PG8_BAR __builtin_amdgcn_s_barrier()
; #define PG8_SCHED __builtin_amdgcn_sched_barrier(0)
; template <class Epi>
; DEVI void gemm_phase(LAS unsigned char* lds, const Gemm g, const Epi& E) {
;     ...
;             PG8_LDB(B0, 0, 0); PG8_SCHED; PG8_LDA(At, 0, 0); PG8_STAGE(PG8_SA(1, 1), a1 + hstepA, voffA);
;             PG8_WAIT_L(8); PG8_BAR; PG8_WAIT_L(0); PG8_MMA(0, 0, At, B0); PG8_BAR; PG8_SCHED;
;             PG8_LDB(B1, 0, 1); PG8_STAGE(PG8_SB(0, 0), b2, voffB);
;             PG8_BAR; PG8_WAIT_L(0); PG8_MMA(0, 1, At, B1); PG8_BAR;
;             PG8_LDA(At, 0, 1); PG8_STAGE(PG8_SA(0, 0), a2, voffA);
;             PG8_BAR; PG8_WAIT_L(0); PG8_MMA(1, 0, At, B0); PG8_BAR; PG8_SCHED;
;             PG8_STAGE(PG8_SB(0, 1), b2 + hstepB, voffB);
;             PG8_WAIT_V(6); PG8_BAR; PG8_MMA(1, 1, At, B1); PG8_BAR;
;             PG8_LDB(B0, 1, 0); PG8_SCHED; PG8_LDA(At, 1, 0); PG8_STAGE(PG8_SA(0, 1), a2 + hstepA, voffA);
.LBB0_968:
	s_add_u32 s26, s68, 0xfffc0080
	s_addc_u32 s27, s69, -1
	s_add_i32 s38, 0, 0x10000
	v_add_u32_e32 v142, s38, v193
	ds_read_b128 v[130:133], v142
	ds_read_b128 v[134:137], v142 offset:1024
	ds_read_b128 v[138:141], v142 offset:2048
	ds_read_b128 v[142:145], v142 offset:3072
	s_cmp_eq_u32 s19, 12
	s_cselect_b32 s83, s0, s27
	s_cselect_b32 s82, s1, s26
	s_cselect_b32 s81, s9, s18
	s_cselect_b32 s80, s13, s15
	v_lshl_add_u64 v[162:163], s[68:69], 0, v[178:179]
	s_add_i32 m0, s85, 0xc000
	ds_read_b128 v[146:149], v198
	ds_read_b128 v[182:185], v198 offset:1024
	ds_read_b128 v[186:189], v198 offset:2048
	ds_read_b128 v[200:203], v198 offset:3072
	ds_read_b128 v[204:207], v198 offset:4096
	ds_read_b128 v[214:217], v198 offset:5120
	ds_read_b128 v[218:221], v198 offset:6144
	ds_read_b128 v[222:225], v198 offset:7168
	global_load_lds_dwordx4 v[162:163], off
	s_add_i32 m0, s85, 0xe000
	v_lshl_add_u64 v[162:163], s[68:69], 0, v[180:181]
	global_load_lds_dwordx4 v[162:163], off
	s_waitcnt lgkmcnt(0)
	s_barrier
	v_mfma_f32_16x16x32_bf16 v[126:129], v[130:133], v[146:149], v[126:129]
	v_mfma_f32_16x16x32_bf16 v[122:125], v[138:141], v[146:149], v[122:125]
	v_mfma_f32_16x16x32_bf16 v[110:113], v[130:133], v[186:189], v[110:113]
	v_mfma_f32_16x16x32_bf16 v[106:109], v[138:141], v[186:189], v[106:109]
	v_mfma_f32_16x16x32_bf16 v[94:97], v[130:133], v[204:207], v[94:97]
	v_mfma_f32_16x16x32_bf16 v[90:93], v[138:141], v[204:207], v[90:93]
	v_mfma_f32_16x16x32_bf16 v[78:81], v[130:133], v[218:221], v[78:81]
	v_mfma_f32_16x16x32_bf16 v[74:77], v[138:141], v[218:221], v[74:77]
	v_mfma_f32_16x16x32_bf16 v[126:129], v[134:137], v[182:185], v[126:129]
	v_mfma_f32_16x16x32_bf16 v[122:125], v[142:145], v[182:185], v[122:125]
	v_mfma_f32_16x16x32_bf16 v[110:113], v[134:137], v[200:203], v[110:113]
	v_mfma_f32_16x16x32_bf16 v[106:109], v[142:145], v[200:203], v[106:109]
	v_mfma_f32_16x16x32_bf16 v[94:97], v[134:137], v[214:217], v[94:97]
	v_mfma_f32_16x16x32_bf16 v[90:93], v[142:145], v[214:217], v[90:93]
	v_mfma_f32_16x16x32_bf16 v[78:81], v[134:137], v[222:225], v[78:81]
	v_mfma_f32_16x16x32_bf16 v[74:77], v[142:145], v[222:225], v[74:77]
	s_barrier
	s_add_i32 s39, 0, 0x14000
	v_add_u32_e32 v162, s39, v193
	s_add_i32 s26, s38, s84
	ds_read_b128 v[226:229], v162
	ds_read_b128 v[230:233], v162 offset:1024
	ds_read_b128 v[234:237], v162 offset:2048
	ds_read_b128 v[238:241], v162 offset:3072
	v_lshl_add_u64 v[162:163], s[80:81], 0, v[8:9]
	s_mov_b32 m0, s26
	v_lshl_add_u64 v[164:165], s[80:81], 0, v[176:177]
	global_load_lds_dwordx4 v[162:163], off
	s_add_i32 m0, s26, 0x2000
	s_nop 0
	global_load_lds_dwordx4 v[164:165], off
	s_waitcnt lgkmcnt(0)
	s_barrier
	v_mfma_f32_16x16x32_bf16 v[118:121], v[226:229], v[146:149], v[118:121]
	v_mfma_f32_16x16x32_bf16 v[114:117], v[234:237], v[146:149], v[114:117]
	v_mfma_f32_16x16x32_bf16 v[102:105], v[226:229], v[186:189], v[102:105]
	v_mfma_f32_16x16x32_bf16 v[98:101], v[234:237], v[186:189], v[98:101]
	v_mfma_f32_16x16x32_bf16 v[86:89], v[226:229], v[204:207], v[86:89]
	v_mfma_f32_16x16x32_bf16 v[82:85], v[234:237], v[204:207], v[82:85]
	v_mfma_f32_16x16x32_bf16 v[70:73], v[226:229], v[218:221], v[70:73]
	v_mfma_f32_16x16x32_bf16 v[66:69], v[234:237], v[218:221], v[66:69]
	v_mfma_f32_16x16x32_bf16 v[118:121], v[230:233], v[182:185], v[118:121]
	v_mfma_f32_16x16x32_bf16 v[114:117], v[238:241], v[182:185], v[114:117]
	v_mfma_f32_16x16x32_bf16 v[102:105], v[230:233], v[200:203], v[102:105]
	v_mfma_f32_16x16x32_bf16 v[98:101], v[238:241], v[200:203], v[98:101]
	v_mfma_f32_16x16x32_bf16 v[86:89], v[230:233], v[214:217], v[86:89]
	v_mfma_f32_16x16x32_bf16 v[82:85], v[238:241], v[214:217], v[82:85]
	v_mfma_f32_16x16x32_bf16 v[70:73], v[230:233], v[222:225], v[70:73]
	v_mfma_f32_16x16x32_bf16 v[66:69], v[238:241], v[222:225], v[66:69]
	s_mov_b32 m0, s85
	v_lshl_add_u64 v[190:191], s[82:83], 0, v[150:151]
	s_barrier
	ds_read_b128 v[146:149], v198 offset:16384
	ds_read_b128 v[182:185], v198 offset:17408
	ds_read_b128 v[186:189], v198 offset:18432
	ds_read_b128 v[200:203], v198 offset:19456
	ds_read_b128 v[204:207], v198 offset:20480
	ds_read_b128 v[214:217], v198 offset:21504
	ds_read_b128 v[218:221], v198 offset:22528
	ds_read_b128 v[222:225], v198 offset:23552
	global_load_lds_dwordx4 v[190:191], off
	s_mov_b32 m0, s86
	v_lshl_add_u64 v[208:209], s[82:83], 0, v[152:153]
	global_load_lds_dwordx4 v[208:209], off
	s_waitcnt lgkmcnt(0)
	s_barrier
	v_mfma_f32_16x16x32_bf16 v[62:65], v[130:133], v[146:149], v[62:65]
	v_mfma_f32_16x16x32_bf16 v[58:61], v[138:141], v[146:149], v[58:61]
	v_mfma_f32_16x16x32_bf16 v[46:49], v[130:133], v[186:189], v[46:49]
	v_mfma_f32_16x16x32_bf16 v[42:45], v[138:141], v[186:189], v[42:45]
	v_mfma_f32_16x16x32_bf16 v[30:33], v[130:133], v[204:207], v[30:33]
	v_mfma_f32_16x16x32_bf16 v[26:29], v[138:141], v[204:207], v[26:29]
	v_mfma_f32_16x16x32_bf16 v[14:17], v[130:133], v[218:221], v[14:17]
	v_mfma_f32_16x16x32_bf16 v[10:13], v[138:141], v[218:221], v[10:13]
	v_mfma_f32_16x16x32_bf16 v[62:65], v[134:137], v[182:185], v[62:65]
	v_mfma_f32_16x16x32_bf16 v[58:61], v[142:145], v[182:185], v[58:61]
	v_mfma_f32_16x16x32_bf16 v[46:49], v[134:137], v[200:203], v[46:49]
	v_mfma_f32_16x16x32_bf16 v[42:45], v[142:145], v[200:203], v[42:45]
	v_mfma_f32_16x16x32_bf16 v[30:33], v[134:137], v[214:217], v[30:33]
	v_mfma_f32_16x16x32_bf16 v[26:29], v[142:145], v[214:217], v[26:29]
	v_mfma_f32_16x16x32_bf16 v[14:17], v[134:137], v[222:225], v[14:17]
	v_mfma_f32_16x16x32_bf16 v[10:13], v[142:145], v[222:225], v[10:13]
	s_barrier
; #define PG8_STAGE(bufoff, gbase, voff) do { _Pragma("unroll") for (int _i = 0; _i < 2; ++_i) \
;         __builtin_amdgcn_global_load_lds((const unsigned*)((const char*)(gbase) + (voff)[_i]), (LAS unsigned*)(lds + (bufoff) + ldsw + _i * 8192), 16, 0, 0); } while (0)
; #define PG8_LDA(dst, b, h) do { _Pragma("unroll") for (int m = 0; m < 4; ++m) _Pragma("unroll") for (int k = 0; k < 2; ++k) dst[m][k] = *(const LAS bf16x8*)(lds + PG8_SA(b, h) + aoff + m * 2048 + k * 1024); } while (0)
; #define PG8_LDB(dst, b, h) do { _Pragma("unroll") for (int n = 0; n < 2; ++n) _Pragma("unroll") for (int k = 0; k < 2; ++k) dst[n][k] = *(const LAS bf16x8*)(lds + PG8_SB(b, h) + boff + n * 2048 + k * 1024); } while (0)
; #define PG8_MMA(ai, bj, At, Bt) do { __builtin_amdgcn_s_setprio(1); _Pragma("unroll") for (int m = 0; m < 4; ++m) _Pragma("unroll") for (int n = 0; n < 2; ++n) _Pragma("unroll") for (int k = 0; k < 2; ++k) \
;         acc[ai][bj][m][n] = __builtin_amdgcn_mfma_f32_16x16x32_bf16(Bt[n][k], At[m][k], acc[ai][bj][m][n], 0, 0, 0); __builtin_amdgcn_s_setprio(0); } while (0)
; #define PG8_WAIT_V(n) asm volatile("s_waitcnt vmcnt(" #n ")" ::: "memory")
; #define PG8_WAIT_L(n) asm volatile("s_waitcnt lgkmcnt(" #n ")" ::: "memory")
; #define PG8_BAR __builtin_amdgcn_s_barrier()
; #define PG8_SCHED __builtin_amdgcn_sched_barrier(0)
; template <class Epi>
; DEVI void gemm_phase(LAS unsigned char* lds, const Gemm g, const Epi& E) {
;     ...
;             PG8_WAIT_V(6); PG8_BAR; PG8_MMA(1, 1, At, B1); PG8_BAR;
;             PG8_LDB(B0, 1, 0); PG8_SCHED; PG8_LDA(At, 1, 0); PG8_STAGE(PG8_SA(0, 1), a2 + hstepA, voffA);
;             PG8_WAIT_L(8); PG8_BAR; PG8_WAIT_L(0); PG8_MMA(0, 0, At, B0); PG8_BAR; PG8_SCHED;
;             PG8_LDB(B1, 1, 1); PG8_STAGE(PG8_SB(1, 0), b3, voffB);
;             PG8_BAR; PG8_WAIT_L(0); PG8_MMA(0, 1, At, B1); PG8_BAR;
;             PG8_LDA(At, 1, 1); PG8_STAGE(PG8_SA(1, 0), a3, voffA);
;             PG8_BAR; PG8_WAIT_L(0); PG8_MMA(1, 0, At, B0); PG8_BAR; PG8_SCHED;
;             PG8_STAGE(PG8_SB(1, 1), b3 + hstepB, voffB);
	s_add_u32 s26, s80, 0x40000
	s_addc_u32 s27, s81, 0
	s_add_i32 s38, s39, s84
	s_mov_b32 m0, s38
	v_lshl_add_u64 v[130:131], s[26:27], 0, v[8:9]
	global_load_lds_dwordx4 v[130:131], off
	s_add_i32 m0, s38, 0x2000
	v_lshl_add_u64 v[130:131], s[26:27], 0, v[176:177]
	global_load_lds_dwordx4 v[130:131], off
	s_waitcnt vmcnt(6)
	s_barrier
	v_mfma_f32_16x16x32_bf16 v[54:57], v[226:229], v[146:149], v[54:57]
	v_mfma_f32_16x16x32_bf16 v[50:53], v[234:237], v[146:149], v[50:53]
	v_mfma_f32_16x16x32_bf16 v[38:41], v[226:229], v[186:189], v[38:41]
	v_mfma_f32_16x16x32_bf16 v[34:37], v[234:237], v[186:189], v[34:37]
	v_mfma_f32_16x16x32_bf16 v[22:25], v[226:229], v[204:207], v[22:25]
	v_mfma_f32_16x16x32_bf16 v[18:21], v[234:237], v[204:207], v[18:21]
	v_mfma_f32_16x16x32_bf16 v[4:7], v[226:229], v[218:221], v[4:7]
	v_mfma_f32_16x16x32_bf16 v[0:3], v[234:237], v[218:221], v[0:3]
	v_mfma_f32_16x16x32_bf16 v[54:57], v[230:233], v[182:185], v[54:57]
	v_mfma_f32_16x16x32_bf16 v[50:53], v[238:241], v[182:185], v[50:53]
	v_mfma_f32_16x16x32_bf16 v[38:41], v[230:233], v[200:203], v[38:41]
	v_mfma_f32_16x16x32_bf16 v[34:37], v[238:241], v[200:203], v[34:37]
	v_mfma_f32_16x16x32_bf16 v[22:25], v[230:233], v[214:217], v[22:25]
	v_mfma_f32_16x16x32_bf16 v[18:21], v[238:241], v[214:217], v[18:21]
	v_mfma_f32_16x16x32_bf16 v[4:7], v[230:233], v[222:225], v[4:7]
	v_mfma_f32_16x16x32_bf16 v[0:3], v[238:241], v[222:225], v[0:3]
	s_add_i32 s38, 0, 0x18000
	v_add_u32_e32 v142, s38, v193
	s_barrier
	ds_read_b128 v[130:133], v142
	ds_read_b128 v[134:137], v142 offset:1024
	ds_read_b128 v[138:141], v142 offset:2048
	ds_read_b128 v[142:145], v142 offset:3072
	s_add_u32 s26, s82, 0x40000
	s_addc_u32 s27, s83, 0
	s_mov_b32 m0, s87
	v_lshl_add_u64 v[226:227], s[26:27], 0, v[150:151]
	ds_read_b128 v[146:149], v198 offset:32768
	ds_read_b128 v[182:185], v198 offset:33792
	ds_read_b128 v[186:189], v198 offset:34816
	ds_read_b128 v[200:203], v198 offset:35840
	ds_read_b128 v[204:207], v198 offset:36864
	ds_read_b128 v[214:217], v198 offset:37888
	ds_read_b128 v[218:221], v198 offset:38912
	ds_read_b128 v[222:225], v198 offset:39936
	global_load_lds_dwordx4 v[226:227], off
	s_mov_b32 m0, s88
	v_lshl_add_u64 v[226:227], s[26:27], 0, v[152:153]
	global_load_lds_dwordx4 v[226:227], off
	s_waitcnt lgkmcnt(0)
	s_barrier
	v_mfma_f32_16x16x32_bf16 v[126:129], v[130:133], v[146:149], v[126:129]
	v_mfma_f32_16x16x32_bf16 v[122:125], v[138:141], v[146:149], v[122:125]
	v_mfma_f32_16x16x32_bf16 v[110:113], v[130:133], v[186:189], v[110:113]
	v_mfma_f32_16x16x32_bf16 v[106:109], v[138:141], v[186:189], v[106:109]
	v_mfma_f32_16x16x32_bf16 v[94:97], v[130:133], v[204:207], v[94:97]
	v_mfma_f32_16x16x32_bf16 v[90:93], v[138:141], v[204:207], v[90:93]
	v_mfma_f32_16x16x32_bf16 v[78:81], v[130:133], v[218:221], v[78:81]
	v_mfma_f32_16x16x32_bf16 v[74:77], v[138:141], v[218:221], v[74:77]
	v_mfma_f32_16x16x32_bf16 v[126:129], v[134:137], v[182:185], v[126:129]
	v_mfma_f32_16x16x32_bf16 v[122:125], v[142:145], v[182:185], v[122:125]
	v_mfma_f32_16x16x32_bf16 v[110:113], v[134:137], v[200:203], v[110:113]
	v_mfma_f32_16x16x32_bf16 v[106:109], v[142:145], v[200:203], v[106:109]
	v_mfma_f32_16x16x32_bf16 v[94:97], v[134:137], v[214:217], v[94:97]
	v_mfma_f32_16x16x32_bf16 v[90:93], v[142:145], v[214:217], v[90:93]
	v_mfma_f32_16x16x32_bf16 v[78:81], v[134:137], v[222:225], v[78:81]
	v_mfma_f32_16x16x32_bf16 v[74:77], v[142:145], v[222:225], v[74:77]
	s_barrier
	s_add_i32 s39, 0, 0x1c000
	s_add_i32 s26, s38, s84
	v_add_u32_e32 v199, s39, v193
	v_lshl_add_u64 v[162:163], v[162:163], 0, s[70:71]
	s_mov_b32 m0, s26
	ds_read_b128 v[226:229], v199
	ds_read_b128 v[230:233], v199 offset:1024
	ds_read_b128 v[234:237], v199 offset:2048
	ds_read_b128 v[238:241], v199 offset:3072
	global_load_lds_dwordx4 v[162:163], off
	s_add_i32 m0, s26, 0x2000
	v_lshl_add_u64 v[162:163], v[164:165], 0, s[70:71]
	global_load_lds_dwordx4 v[162:163], off
	s_waitcnt lgkmcnt(0)
	s_barrier
	v_mfma_f32_16x16x32_bf16 v[118:121], v[226:229], v[146:149], v[118:121]
	v_mfma_f32_16x16x32_bf16 v[114:117], v[234:237], v[146:149], v[114:117]
	v_mfma_f32_16x16x32_bf16 v[102:105], v[226:229], v[186:189], v[102:105]
	v_mfma_f32_16x16x32_bf16 v[98:101], v[234:237], v[186:189], v[98:101]
	v_mfma_f32_16x16x32_bf16 v[86:89], v[226:229], v[204:207], v[86:89]
	v_mfma_f32_16x16x32_bf16 v[82:85], v[234:237], v[204:207], v[82:85]
	v_mfma_f32_16x16x32_bf16 v[70:73], v[226:229], v[218:221], v[70:73]
	v_mfma_f32_16x16x32_bf16 v[66:69], v[234:237], v[218:221], v[66:69]
	v_mfma_f32_16x16x32_bf16 v[118:121], v[230:233], v[182:185], v[118:121]
	v_mfma_f32_16x16x32_bf16 v[114:117], v[238:241], v[182:185], v[114:117]
	v_mfma_f32_16x16x32_bf16 v[102:105], v[230:233], v[200:203], v[102:105]
	v_mfma_f32_16x16x32_bf16 v[98:101], v[238:241], v[200:203], v[98:101]
	v_mfma_f32_16x16x32_bf16 v[86:89], v[230:233], v[214:217], v[86:89]
	v_mfma_f32_16x16x32_bf16 v[82:85], v[238:241], v[214:217], v[82:85]
	v_mfma_f32_16x16x32_bf16 v[70:73], v[230:233], v[222:225], v[70:73]
	v_mfma_f32_16x16x32_bf16 v[66:69], v[238:241], v[222:225], v[66:69]
	s_mov_b32 m0, s89
	v_lshl_add_u64 v[162:163], v[190:191], 0, s[70:71]
	s_barrier
	ds_read_b128 v[146:149], v198 offset:49152
	ds_read_b128 v[182:185], v198 offset:50176
	ds_read_b128 v[186:189], v198 offset:51200
	ds_read_b128 v[200:203], v198 offset:52224
	ds_read_b128 v[204:207], v198 offset:53248
	ds_read_b128 v[214:217], v198 offset:54272
	ds_read_b128 v[218:221], v198 offset:55296
	ds_read_b128 v[222:225], v198 offset:56320
	global_load_lds_dwordx4 v[162:163], off
	s_mov_b32 m0, s90
	v_lshl_add_u64 v[162:163], v[208:209], 0, s[70:71]
	global_load_lds_dwordx4 v[162:163], off
	s_waitcnt lgkmcnt(0)
	s_barrier
; #define LAS __attribute__((address_space(3)))
; #define PG8_WAIT_V(n) asm volatile("s_waitcnt vmcnt(" #n ")" ::: "memory")
; #define PG8_WAIT_L(n) asm volatile("s_waitcnt lgkmcnt(" #n ")" ::: "memory")
; template <class Epi>
; DEVI void gemm_phase(LAS unsigned char* lds, const Gemm g, const Epi& E) {
;     ...
;             PG8_LDA(At, 1, 1); PG8_STAGE(PG8_SA(1, 0), a3, voffA);
;             PG8_BAR; PG8_WAIT_L(0); PG8_MMA(1, 0, At, B0); PG8_BAR; PG8_SCHED;
;             PG8_STAGE(PG8_SB(1, 1), b3 + hstepB, voffB);
;             PG8_WAIT_V(6); PG8_BAR; PG8_MMA(1, 1, At, B1); PG8_BAR;
;         }
;     ...
;             for (int am = 0; am < 4; ++am) {
;                 const int ai = am >> 1, m0 = (am & 1) * 2;
;                 f32x4 pre[2][2][2];
;                 if constexpr (Epi::PRE) {
; #pragma unroll
;                     for (int m = 0; m < 2; ++m)
; #pragma unroll
;                         for (int bj = 0; bj < 2; ++bj)
; #pragma unroll
;                             for (int n = 0; n < 2; ++n) pre[m][bj][n] = E.load(row0 + ai * HALF + (m0 + m) * 16, col0 + bj * HALF + n * NST);
;                 }
; #pragma unroll
;                 for (int mm = 0; mm < 2; ++mm) {
;                     const int m = m0 + mm;
;                     const int r = row0 + ai * HALF + m * 16; float rs = 1.f, part = 0.f;
;                     if constexpr (Epi::RS) rs = rsv[ai * 4 + m];
;                     if constexpr (Epi::PAIR) E.pair8(cur.b, r, cur.pn * HALF + wc * 32 + 8 * fq, acc[ai][0][m][0] * rs, acc[ai][0][m][1] * rs, acc[ai][1][m][0] * rs, acc[ai][1][m][1] * rs);
;                     else
; #pragma unroll
;                     for (int bj = 0; bj < 2; ++bj) {
;                         const int c = col0 + bj * HALF; f32x4 v0 = acc[ai][bj][m][0], v1 = acc[ai][bj][m][1];
;                         if constexpr (Epi::RS) { v0 = v0 * rs; v1 = v1 * rs; }
;                         if constexpr (Epi::PRE) part += E.frag_pre8(cur.b, r, c, v0, v1, pre[mm][bj][0], pre[mm][bj][1]);
;                         else if constexpr (Epi::PERM) E.frag8(cur.b, r, c, v0, v1);
;                         else { E.frag(cur.b, r, c, v0); E.frag(cur.b, r, c + 16, v1); }
;                     }
;                     if constexpr (Epi::SSQ) { part += __shfl_xor(part, 16); part += __shfl_xor(part, 32); if (fq == 0) ((LAS float*)(lds + 131072))[(wr * 4 + wc) * 128 + ai * 64 + m * 16 + fr] = part; }
	v_mfma_f32_16x16x32_bf16 v[62:65], v[130:133], v[146:149], v[62:65]
	v_mfma_f32_16x16x32_bf16 v[58:61], v[138:141], v[146:149], v[58:61]
	v_mfma_f32_16x16x32_bf16 v[46:49], v[130:133], v[186:189], v[46:49]
	v_mfma_f32_16x16x32_bf16 v[42:45], v[138:141], v[186:189], v[42:45]
	v_mfma_f32_16x16x32_bf16 v[30:33], v[130:133], v[204:207], v[30:33]
	v_mfma_f32_16x16x32_bf16 v[26:29], v[138:141], v[204:207], v[26:29]
	v_mfma_f32_16x16x32_bf16 v[14:17], v[130:133], v[218:221], v[14:17]
	v_mfma_f32_16x16x32_bf16 v[10:13], v[138:141], v[218:221], v[10:13]
	v_mfma_f32_16x16x32_bf16 v[62:65], v[134:137], v[182:185], v[62:65]
	v_mfma_f32_16x16x32_bf16 v[58:61], v[142:145], v[182:185], v[58:61]
	v_mfma_f32_16x16x32_bf16 v[46:49], v[134:137], v[200:203], v[46:49]
	v_mfma_f32_16x16x32_bf16 v[42:45], v[142:145], v[200:203], v[42:45]
	v_mfma_f32_16x16x32_bf16 v[30:33], v[134:137], v[214:217], v[30:33]
	v_mfma_f32_16x16x32_bf16 v[26:29], v[142:145], v[214:217], v[26:29]
	v_mfma_f32_16x16x32_bf16 v[14:17], v[134:137], v[222:225], v[14:17]
	v_mfma_f32_16x16x32_bf16 v[10:13], v[142:145], v[222:225], v[10:13]
	s_barrier
	s_add_u32 s26, s80, 0x40080
	s_addc_u32 s27, s81, 0
	s_add_i32 s38, s39, s84
	s_mov_b32 m0, s38
	v_lshl_add_u64 v[130:131], s[26:27], 0, v[8:9]
	global_load_lds_dwordx4 v[130:131], off
	s_add_i32 m0, s38, 0x2000
	v_lshl_add_u64 v[130:131], s[26:27], 0, v[176:177]
	global_load_lds_dwordx4 v[130:131], off
	s_waitcnt vmcnt(6)
	s_barrier
	v_mfma_f32_16x16x32_bf16 v[54:57], v[226:229], v[146:149], v[54:57]
	v_mfma_f32_16x16x32_bf16 v[50:53], v[234:237], v[146:149], v[50:53]
	v_mfma_f32_16x16x32_bf16 v[38:41], v[226:229], v[186:189], v[38:41]
	v_mfma_f32_16x16x32_bf16 v[34:37], v[234:237], v[186:189], v[34:37]
	v_mfma_f32_16x16x32_bf16 v[22:25], v[226:229], v[204:207], v[22:25]
	v_mfma_f32_16x16x32_bf16 v[18:21], v[234:237], v[204:207], v[18:21]
	v_mfma_f32_16x16x32_bf16 v[4:7], v[226:229], v[218:221], v[4:7]
	v_mfma_f32_16x16x32_bf16 v[0:3], v[234:237], v[218:221], v[0:3]
	v_mfma_f32_16x16x32_bf16 v[54:57], v[230:233], v[182:185], v[54:57]
	v_mfma_f32_16x16x32_bf16 v[50:53], v[238:241], v[182:185], v[50:53]
	v_mfma_f32_16x16x32_bf16 v[38:41], v[230:233], v[200:203], v[38:41]
	v_mfma_f32_16x16x32_bf16 v[34:37], v[238:241], v[200:203], v[34:37]
	v_mfma_f32_16x16x32_bf16 v[22:25], v[230:233], v[214:217], v[22:25]
	v_mfma_f32_16x16x32_bf16 v[18:21], v[238:241], v[214:217], v[18:21]
	v_mfma_f32_16x16x32_bf16 v[4:7], v[230:233], v[222:225], v[4:7]
	v_mfma_f32_16x16x32_bf16 v[0:3], v[238:241], v[222:225], v[0:3]
	s_add_i32 s19, s19, 2
	s_add_u32 s68, s68, 0x100
	s_addc_u32 s69, s69, 0
	s_add_u32 s15, s15, 0x100
	s_addc_u32 s18, s18, 0
	s_cmp_gt_u32 s19, 13
	s_barrier
	s_cbranch_scc0 .LBB0_968
	s_setprio 0
	v_and_b32_e32 v131, 64, v155
	v_xor_b32_e32 v130, 16, v155
	v_add_u32_e32 v131, 64, v131
	v_cmp_lt_i32_e32 vcc, v130, v131
	s_lshl_b32 s9, s46, 8
	v_add_u32_e32 v186, s9, v192
	v_cndmask_b32_e32 v130, v155, v130, vcc
	v_lshlrev_b32_e32 v200, 2, v130
	v_xor_b32_e32 v130, 32, v155
	v_cmp_lt_i32_e32 vcc, v130, v131
	v_lshl_or_b32 v184, s8, 8, v197
	v_ashrrev_i32_e32 v187, 31, v186
	v_cndmask_b32_e32 v130, v155, v130, vcc
	v_lshlrev_b32_e32 v199, 2, v130
	v_lshlrev_b64 v[130:131], 12, v[186:187]
	v_ashrrev_i32_e32 v185, 31, v184
	v_lshl_add_u64 v[130:131], s[78:79], 0, v[130:131]
	v_lshlrev_b64 v[188:189], 2, v[184:185]
	v_lshl_add_u64 v[130:131], v[130:131], 0, v[188:189]
	global_load_dwordx4 v[202:205], v[130:131], off offset:16
	global_load_dwordx4 v[206:209], v[130:131], off
	global_load_dwordx4 v[146:149], v[130:131], off offset:528
	global_load_dwordx4 v[214:217], v[130:131], off offset:512
	v_or_b32_e32 v190, 16, v186
	v_ashrrev_i32_e32 v191, 31, v190
	v_lshlrev_b64 v[130:131], 12, v[190:191]
	v_lshl_add_u64 v[130:131], s[78:79], 0, v[130:131]
	v_lshl_add_u64 v[134:135], v[130:131], 0, v[188:189]
	global_load_dwordx4 v[138:141], v[134:135], off offset:16
	global_load_dwordx4 v[142:145], v[134:135], off
	global_load_dwordx4 v[130:133], v[134:135], off offset:528
	s_nop 0
	global_load_dwordx4 v[134:137], v[134:135], off offset:512
	v_lshlrev_b64 v[162:163], 10, v[186:187]
	v_lshl_add_u64 v[164:165], v[162:163], 0, v[184:185]
	v_or_b32_e32 v182, 0x80, v184
	v_ashrrev_i32_e32 v183, 31, v182
	s_waitcnt vmcnt(0)
	v_pk_add_f32 v[122:123], v[122:123], v[202:203]
	v_pk_add_f32 v[128:129], v[128:129], v[208:209]
	v_pk_add_f32 v[126:127], v[126:127], v[206:207]
	v_lshl_add_u64 v[206:207], v[164:165], 2, s[30:31]
	v_pk_add_f32 v[124:125], v[124:125], v[204:205]
	global_store_dwordx4 v[206:207], v[126:129], off
	global_store_dwordx4 v[206:207], v[122:125], off offset:16
	v_cvt_pk_bf16_f32 v202, v126, v127
	v_cvt_pk_bf16_f32 v204, v122, v123
	v_mul_f32_e32 v127, v127, v127
	v_mul_f32_e32 v123, v123, v123
	v_fmac_f32_e32 v127, v126, v126
	v_mul_f32_e32 v126, v129, v129
	v_fmac_f32_e32 v123, v122, v122
	v_mul_f32_e32 v122, v125, v125
	v_fmac_f32_e32 v126, v128, v128
	v_fmac_f32_e32 v122, v124, v124
	v_cvt_pk_bf16_f32 v203, v128, v129
	v_cvt_pk_bf16_f32 v205, v124, v125
	v_lshl_add_u64 v[164:165], v[164:165], 1, s[28:29]
	v_add_f32_e32 v126, v127, v126
	v_add_f32_e32 v122, v123, v122
	v_pk_add_f32 v[120:121], v[120:121], v[216:217]
	v_pk_add_f32 v[118:119], v[118:119], v[214:215]
	v_pk_add_f32 v[114:115], v[114:115], v[146:147]
	global_store_dwordx4 v[164:165], v[202:205], off
	v_add_f32_e32 v128, v126, v122
	v_pk_add_f32 v[116:117], v[116:117], v[148:149]
	global_store_dwordx4 v[206:207], v[118:121], off offset:512
	global_store_dwordx4 v[206:207], v[114:117], off offset:528
	v_cvt_pk_bf16_f32 v122, v118, v119
	v_cvt_pk_bf16_f32 v124, v114, v115
	v_mul_f32_e32 v119, v119, v119
	v_mul_f32_e32 v115, v115, v115
	v_fmac_f32_e32 v119, v118, v118
	v_mul_f32_e32 v118, v121, v121
	v_fmac_f32_e32 v115, v114, v114
	v_mul_f32_e32 v114, v117, v117
	v_fmac_f32_e32 v118, v120, v120
	v_fmac_f32_e32 v114, v116, v116
	v_add_f32_e32 v118, v119, v118
	v_add_f32_e32 v114, v115, v114
	v_add_f32_e32 v114, v118, v114
	v_add_f32_e32 v114, v128, v114
	ds_bpermute_b32 v115, v200, v114
	v_lshl_add_u64 v[126:127], v[162:163], 0, v[182:183]
	v_cvt_pk_bf16_f32 v123, v120, v121
	v_cvt_pk_bf16_f32 v125, v116, v117
	v_lshl_add_u64 v[126:127], v[126:127], 1, s[28:29]
	s_waitcnt lgkmcnt(0)
	v_add_f32_e32 v114, v114, v115
	ds_bpermute_b32 v115, v199, v114
	global_store_dwordx4 v[126:127], v[122:125], off
	s_and_saveexec_b64 s[46:47], s[2:3]
	s_cbranch_execz .LBB0_971
	s_waitcnt lgkmcnt(0)
	v_add_f32_e32 v114, v114, v115
	ds_write_b32 v194, v114

; #define PG8_STAGE(bufoff, gbase, voff) do { _Pragma("unroll") for (int _i = 0; _i < 2; ++_i) \
;         __builtin_amdgcn_global_load_lds((const unsigned*)((const char*)(gbase) + (voff)[_i]), (LAS unsigned*)(lds + (bufoff) + ldsw + _i * 8192), 16, 0, 0); } while (0)
; #define PG8_LDA(dst, b, h) do { _Pragma("unroll") for (int m = 0; m < 4; ++m) _Pragma("unroll") for (int k = 0; k < 2; ++k) dst[m][k] = *(const LAS bf16x8*)(lds + PG8_SA(b, h) + aoff + m * 2048 + k * 1024); } while (0)
; #define PG8_LDB(dst, b, h) do { _Pragma("unroll") for (int n = 0; n < 2; ++n) _Pragma("unroll") for (int k = 0; k < 2; ++k) dst[n][k] = *(const LAS bf16x8*)(lds + PG8_SB(b, h) + boff + n * 2048 + k * 1024); } while (0)
; #define PG8_MMA(ai, bj, At, Bt) do { __builtin_amdgcn_s_setprio(1); _Pragma("unroll") for (int m = 0; m < 4; ++m) _Pragma("unroll") for (int n = 0; n < 2; ++n) _Pragma("unroll") for (int k = 0; k < 2; ++k) \
;         acc[ai][bj][m][n] = __builtin_amdgcn_mfma_f32_16x16x32_bf16(Bt[n][k], At[m][k], acc[ai][bj][m][n], 0, 0, 0); __builtin_amdgcn_s_setprio(0); } while (0)
; #define PG8_WAIT_V(n) asm volatile("s_waitcnt vmcnt(" #n ")" ::: "memory")
; #define PG8_WAIT_L(n) asm volatile("s_waitcnt lgkmcnt(" #n ")" ::: "memory")
; #define PG8_BAR __builtin_amdgcn_s_barrier()
; #define PG8_SCHED __builtin_amdgcn_sched_barrier(0)
; template <class Epi>
; DEVI void gemm_phase(LAS unsigned char* lds, const Gemm g, const Epi& E) {
;     ...
;             PG8_LDB(B0, 0, 0); PG8_SCHED; PG8_LDA(At, 0, 0); PG8_STAGE(PG8_SA(1, 1), a1 + hstepA, voffA);
;             PG8_WAIT_L(8); PG8_BAR; PG8_WAIT_L(0); PG8_MMA(0, 0, At, B0); PG8_BAR; PG8_SCHED;
;             PG8_LDB(B1, 0, 1); PG8_STAGE(PG8_SB(0, 0), b2, voffB);
;             PG8_BAR; PG8_WAIT_L(0); PG8_MMA(0, 1, At, B1); PG8_BAR;
;             PG8_LDA(At, 0, 1); PG8_STAGE(PG8_SA(0, 0), a2, voffA);
;             PG8_BAR; PG8_WAIT_L(0); PG8_MMA(1, 0, At, B0); PG8_BAR; PG8_SCHED;
;             PG8_STAGE(PG8_SB(0, 1), b2 + hstepB, voffB);
;             PG8_WAIT_V(6); PG8_BAR; PG8_MMA(1, 1, At, B1); PG8_BAR;
;             PG8_LDB(B0, 1, 0); PG8_SCHED; PG8_LDA(At, 1, 0); PG8_STAGE(PG8_SA(0, 1), a2 + hstepA, voffA);
.LBB0_1007:
	s_add_u32 s16, s14, 0xfffc0080
	s_addc_u32 s17, s15, -1
	s_add_i32 s26, 0, 0x10000
	v_add_u32_e32 v8, s26, v199
	ds_read_b128 v[130:133], v8
	ds_read_b128 v[134:137], v8 offset:1024
	ds_read_b128 v[138:141], v8 offset:2048
	ds_read_b128 v[142:145], v8 offset:3072
	s_cmp_eq_u32 s19, 12
	s_cselect_b32 s37, s0, s17
	s_cselect_b32 s36, s1, s16
	s_cselect_b32 s17, s5, s18
	s_cselect_b32 s16, s7, s9
	v_lshl_add_u64 v[162:163], s[14:15], 0, v[180:181]
	s_add_i32 m0, s66, 0xc000
	ds_read_b128 v[184:187], v204
	ds_read_b128 v[188:191], v204 offset:1024
	ds_read_b128 v[192:195], v204 offset:2048
	ds_read_b128 v[206:209], v204 offset:3072
	ds_read_b128 v[214:217], v204 offset:4096
	ds_read_b128 v[218:221], v204 offset:5120
	ds_read_b128 v[222:225], v204 offset:6144
	ds_read_b128 v[226:229], v204 offset:7168
	global_load_lds_dwordx4 v[162:163], off
	s_add_i32 m0, s66, 0xe000
	v_lshl_add_u64 v[162:163], s[14:15], 0, v[182:183]
	global_load_lds_dwordx4 v[162:163], off
	s_waitcnt lgkmcnt(0)
	s_barrier
	v_mfma_f32_16x16x32_bf16 v[126:129], v[130:133], v[184:187], v[126:129]
	v_mfma_f32_16x16x32_bf16 v[122:125], v[138:141], v[184:187], v[122:125]
	v_mfma_f32_16x16x32_bf16 v[114:117], v[130:133], v[192:195], v[114:117]
	v_mfma_f32_16x16x32_bf16 v[106:109], v[138:141], v[192:195], v[106:109]
	v_mfma_f32_16x16x32_bf16 v[102:105], v[130:133], v[214:217], v[102:105]
	v_mfma_f32_16x16x32_bf16 v[94:97], v[138:141], v[214:217], v[94:97]
	v_mfma_f32_16x16x32_bf16 v[82:85], v[130:133], v[222:225], v[82:85]
	v_mfma_f32_16x16x32_bf16 v[74:77], v[138:141], v[222:225], v[74:77]
	v_mfma_f32_16x16x32_bf16 v[126:129], v[134:137], v[188:191], v[126:129]
	v_mfma_f32_16x16x32_bf16 v[122:125], v[142:145], v[188:191], v[122:125]
	v_mfma_f32_16x16x32_bf16 v[114:117], v[134:137], v[206:209], v[114:117]
	v_mfma_f32_16x16x32_bf16 v[106:109], v[142:145], v[206:209], v[106:109]
	v_mfma_f32_16x16x32_bf16 v[102:105], v[134:137], v[218:221], v[102:105]
	v_mfma_f32_16x16x32_bf16 v[94:97], v[142:145], v[218:221], v[94:97]
	v_mfma_f32_16x16x32_bf16 v[82:85], v[134:137], v[226:229], v[82:85]
	v_mfma_f32_16x16x32_bf16 v[74:77], v[142:145], v[226:229], v[74:77]
	s_barrier
	s_add_i32 s38, 0, 0x14000
	s_add_i32 s26, s26, s47
	v_add_u32_e32 v8, s38, v199
	v_lshl_add_u64 v[162:163], s[16:17], 0, v[148:149]
	s_mov_b32 m0, s26
	ds_read_b128 v[230:233], v8
	ds_read_b128 v[234:237], v8 offset:1024
	ds_read_b128 v[238:241], v8 offset:2048
	ds_read_b128 v[242:245], v8 offset:3072
	global_load_lds_dwordx4 v[162:163], off
	s_add_i32 m0, s26, 0x2000
	v_lshl_add_u64 v[164:165], s[16:17], 0, v[152:153]
	global_load_lds_dwordx4 v[164:165], off
	s_waitcnt lgkmcnt(0)
	s_barrier
	v_mfma_f32_16x16x32_bf16 v[118:121], v[230:233], v[184:187], v[118:121]
	v_mfma_f32_16x16x32_bf16 v[110:113], v[238:241], v[184:187], v[110:113]
	v_mfma_f32_16x16x32_bf16 v[98:101], v[230:233], v[192:195], v[98:101]
	v_mfma_f32_16x16x32_bf16 v[90:93], v[238:241], v[192:195], v[90:93]
	v_mfma_f32_16x16x32_bf16 v[86:89], v[230:233], v[214:217], v[86:89]
	v_mfma_f32_16x16x32_bf16 v[78:81], v[238:241], v[214:217], v[78:81]
	v_mfma_f32_16x16x32_bf16 v[54:57], v[230:233], v[222:225], v[54:57]
	v_mfma_f32_16x16x32_bf16 v[34:37], v[238:241], v[222:225], v[34:37]
	v_mfma_f32_16x16x32_bf16 v[118:121], v[234:237], v[188:191], v[118:121]
	v_mfma_f32_16x16x32_bf16 v[110:113], v[242:245], v[188:191], v[110:113]
	v_mfma_f32_16x16x32_bf16 v[98:101], v[234:237], v[206:209], v[98:101]
	v_mfma_f32_16x16x32_bf16 v[90:93], v[242:245], v[206:209], v[90:93]
	v_mfma_f32_16x16x32_bf16 v[86:89], v[234:237], v[218:221], v[86:89]
	v_mfma_f32_16x16x32_bf16 v[78:81], v[242:245], v[218:221], v[78:81]
	v_mfma_f32_16x16x32_bf16 v[54:57], v[234:237], v[226:229], v[54:57]
	v_mfma_f32_16x16x32_bf16 v[34:37], v[242:245], v[226:229], v[34:37]
	s_mov_b32 m0, s66
	v_lshl_add_u64 v[202:203], s[36:37], 0, v[146:147]
	s_barrier
	ds_read_b128 v[184:187], v204 offset:16384
	ds_read_b128 v[188:191], v204 offset:17408
	ds_read_b128 v[192:195], v204 offset:18432
	ds_read_b128 v[206:209], v204 offset:19456
	ds_read_b128 v[214:217], v204 offset:20480
	ds_read_b128 v[218:221], v204 offset:21504
	ds_read_b128 v[222:225], v204 offset:22528
	ds_read_b128 v[226:229], v204 offset:23552
	global_load_lds_dwordx4 v[202:203], off
	s_mov_b32 m0, s68
	v_lshl_add_u64 v[246:247], s[36:37], 0, v[150:151]
	global_load_lds_dwordx4 v[246:247], off
	s_waitcnt lgkmcnt(0)
	s_barrier
	v_mfma_f32_16x16x32_bf16 v[58:61], v[130:133], v[184:187], v[58:61]
	v_mfma_f32_16x16x32_bf16 v[62:65], v[138:141], v[184:187], v[62:65]
	v_mfma_f32_16x16x32_bf16 v[38:41], v[130:133], v[192:195], v[38:41]
	v_mfma_f32_16x16x32_bf16 v[42:45], v[138:141], v[192:195], v[42:45]
	v_mfma_f32_16x16x32_bf16 v[18:21], v[130:133], v[214:217], v[18:21]
	v_mfma_f32_16x16x32_bf16 v[22:25], v[138:141], v[214:217], v[22:25]
	v_mfma_f32_16x16x32_bf16 v[0:3], v[130:133], v[222:225], v[0:3]
	v_mfma_f32_16x16x32_bf16 v[4:7], v[138:141], v[222:225], v[4:7]
	v_mfma_f32_16x16x32_bf16 v[58:61], v[134:137], v[188:191], v[58:61]
	v_mfma_f32_16x16x32_bf16 v[62:65], v[142:145], v[188:191], v[62:65]
	v_mfma_f32_16x16x32_bf16 v[38:41], v[134:137], v[206:209], v[38:41]
	v_mfma_f32_16x16x32_bf16 v[42:45], v[142:145], v[206:209], v[42:45]
	v_mfma_f32_16x16x32_bf16 v[18:21], v[134:137], v[218:221], v[18:21]
	v_mfma_f32_16x16x32_bf16 v[22:25], v[142:145], v[218:221], v[22:25]
	v_mfma_f32_16x16x32_bf16 v[0:3], v[134:137], v[226:229], v[0:3]
	v_mfma_f32_16x16x32_bf16 v[4:7], v[142:145], v[226:229], v[4:7]
	s_barrier
; #define PG8_STAGE(bufoff, gbase, voff) do { _Pragma("unroll") for (int _i = 0; _i < 2; ++_i) \
;         __builtin_amdgcn_global_load_lds((const unsigned*)((const char*)(gbase) + (voff)[_i]), (LAS unsigned*)(lds + (bufoff) + ldsw + _i * 8192), 16, 0, 0); } while (0)
; #define PG8_LDA(dst, b, h) do { _Pragma("unroll") for (int m = 0; m < 4; ++m) _Pragma("unroll") for (int k = 0; k < 2; ++k) dst[m][k] = *(const LAS bf16x8*)(lds + PG8_SA(b, h) + aoff + m * 2048 + k * 1024); } while (0)
; #define PG8_LDB(dst, b, h) do { _Pragma("unroll") for (int n = 0; n < 2; ++n) _Pragma("unroll") for (int k = 0; k < 2; ++k) dst[n][k] = *(const LAS bf16x8*)(lds + PG8_SB(b, h) + boff + n * 2048 + k * 1024); } while (0)
; #define PG8_MMA(ai, bj, At, Bt) do { __builtin_amdgcn_s_setprio(1); _Pragma("unroll") for (int m = 0; m < 4; ++m) _Pragma("unroll") for (int n = 0; n < 2; ++n) _Pragma("unroll") for (int k = 0; k < 2; ++k) \
;         acc[ai][bj][m][n] = __builtin_amdgcn_mfma_f32_16x16x32_bf16(Bt[n][k], At[m][k], acc[ai][bj][m][n], 0, 0, 0); __builtin_amdgcn_s_setprio(0); } while (0)
; #define PG8_WAIT_V(n) asm volatile("s_waitcnt vmcnt(" #n ")" ::: "memory")
; #define PG8_WAIT_L(n) asm volatile("s_waitcnt lgkmcnt(" #n ")" ::: "memory")
; #define PG8_BAR __builtin_amdgcn_s_barrier()
; #define PG8_SCHED __builtin_amdgcn_sched_barrier(0)
; template <class Epi>
; DEVI void gemm_phase(LAS unsigned char* lds, const Gemm g, const Epi& E) {
;     ...
;             PG8_WAIT_V(6); PG8_BAR; PG8_MMA(1, 1, At, B1); PG8_BAR;
;             PG8_LDB(B0, 1, 0); PG8_SCHED; PG8_LDA(At, 1, 0); PG8_STAGE(PG8_SA(0, 1), a2 + hstepA, voffA);
;             PG8_WAIT_L(8); PG8_BAR; PG8_WAIT_L(0); PG8_MMA(0, 0, At, B0); PG8_BAR; PG8_SCHED;
;             PG8_LDB(B1, 1, 1); PG8_STAGE(PG8_SB(1, 0), b3, voffB);
;             PG8_BAR; PG8_WAIT_L(0); PG8_MMA(0, 1, At, B1); PG8_BAR;
;             PG8_LDA(At, 1, 1); PG8_STAGE(PG8_SA(1, 0), a3, voffA);
;             PG8_BAR; PG8_WAIT_L(0); PG8_MMA(1, 0, At, B0); PG8_BAR; PG8_SCHED;
;             PG8_STAGE(PG8_SB(1, 1), b3 + hstepB, voffB);
	s_add_u32 s26, s16, 0x40000
	s_addc_u32 s27, s17, 0
	s_add_i32 s38, s38, s47
	s_mov_b32 m0, s38
	v_lshl_add_u64 v[130:131], s[26:27], 0, v[148:149]
	global_load_lds_dwordx4 v[130:131], off
	s_add_i32 m0, s38, 0x2000
	v_lshl_add_u64 v[130:131], s[26:27], 0, v[152:153]
	global_load_lds_dwordx4 v[130:131], off
	s_waitcnt vmcnt(6)
	s_barrier
	v_mfma_f32_16x16x32_bf16 v[66:69], v[230:233], v[184:187], v[66:69]
	v_mfma_f32_16x16x32_bf16 v[70:73], v[238:241], v[184:187], v[70:73]
	v_mfma_f32_16x16x32_bf16 v[46:49], v[230:233], v[192:195], v[46:49]
	v_mfma_f32_16x16x32_bf16 v[50:53], v[238:241], v[192:195], v[50:53]
	v_mfma_f32_16x16x32_bf16 v[26:29], v[230:233], v[214:217], v[26:29]
	v_mfma_f32_16x16x32_bf16 v[30:33], v[238:241], v[214:217], v[30:33]
	v_mfma_f32_16x16x32_bf16 v[10:13], v[230:233], v[222:225], v[10:13]
	v_mfma_f32_16x16x32_bf16 v[14:17], v[238:241], v[222:225], v[14:17]
	v_mfma_f32_16x16x32_bf16 v[66:69], v[234:237], v[188:191], v[66:69]
	v_mfma_f32_16x16x32_bf16 v[70:73], v[242:245], v[188:191], v[70:73]
	v_mfma_f32_16x16x32_bf16 v[46:49], v[234:237], v[206:209], v[46:49]
	v_mfma_f32_16x16x32_bf16 v[50:53], v[242:245], v[206:209], v[50:53]
	v_mfma_f32_16x16x32_bf16 v[26:29], v[234:237], v[218:221], v[26:29]
	v_mfma_f32_16x16x32_bf16 v[30:33], v[242:245], v[218:221], v[30:33]
	v_mfma_f32_16x16x32_bf16 v[10:13], v[234:237], v[226:229], v[10:13]
	v_mfma_f32_16x16x32_bf16 v[14:17], v[242:245], v[226:229], v[14:17]
	s_add_i32 s38, 0, 0x18000
	v_add_u32_e32 v8, s38, v199
	s_barrier
	ds_read_b128 v[130:133], v8
	ds_read_b128 v[134:137], v8 offset:1024
	ds_read_b128 v[138:141], v8 offset:2048
	ds_read_b128 v[142:145], v8 offset:3072
	s_add_u32 s26, s36, 0x40000
	s_addc_u32 s27, s37, 0
	s_mov_b32 m0, s69
	v_lshl_add_u64 v[230:231], s[26:27], 0, v[146:147]
	ds_read_b128 v[184:187], v204 offset:32768
	ds_read_b128 v[188:191], v204 offset:33792
	ds_read_b128 v[192:195], v204 offset:34816
	ds_read_b128 v[206:209], v204 offset:35840
	ds_read_b128 v[214:217], v204 offset:36864
	ds_read_b128 v[218:221], v204 offset:37888
	ds_read_b128 v[222:225], v204 offset:38912
	ds_read_b128 v[226:229], v204 offset:39936
	global_load_lds_dwordx4 v[230:231], off
	s_mov_b32 m0, s80
	v_lshl_add_u64 v[230:231], s[26:27], 0, v[150:151]
	global_load_lds_dwordx4 v[230:231], off
	s_waitcnt lgkmcnt(0)
	s_barrier
	v_mfma_f32_16x16x32_bf16 v[126:129], v[130:133], v[184:187], v[126:129]
	v_mfma_f32_16x16x32_bf16 v[122:125], v[138:141], v[184:187], v[122:125]
	v_mfma_f32_16x16x32_bf16 v[114:117], v[130:133], v[192:195], v[114:117]
	v_mfma_f32_16x16x32_bf16 v[106:109], v[138:141], v[192:195], v[106:109]
	v_mfma_f32_16x16x32_bf16 v[102:105], v[130:133], v[214:217], v[102:105]
	v_mfma_f32_16x16x32_bf16 v[94:97], v[138:141], v[214:217], v[94:97]
	v_mfma_f32_16x16x32_bf16 v[82:85], v[130:133], v[222:225], v[82:85]
	v_mfma_f32_16x16x32_bf16 v[74:77], v[138:141], v[222:225], v[74:77]
	v_mfma_f32_16x16x32_bf16 v[126:129], v[134:137], v[188:191], v[126:129]
	v_mfma_f32_16x16x32_bf16 v[122:125], v[142:145], v[188:191], v[122:125]
	v_mfma_f32_16x16x32_bf16 v[114:117], v[134:137], v[206:209], v[114:117]
	v_mfma_f32_16x16x32_bf16 v[106:109], v[142:145], v[206:209], v[106:109]
	v_mfma_f32_16x16x32_bf16 v[102:105], v[134:137], v[218:221], v[102:105]
	v_mfma_f32_16x16x32_bf16 v[94:97], v[142:145], v[218:221], v[94:97]
	v_mfma_f32_16x16x32_bf16 v[82:85], v[134:137], v[226:229], v[82:85]
	v_mfma_f32_16x16x32_bf16 v[74:77], v[142:145], v[226:229], v[74:77]
	s_barrier
	s_add_i32 s26, 0, 0x1c000
	s_add_i32 s27, s38, s47
	v_add_u32_e32 v8, s26, v199
	v_lshl_add_u64 v[162:163], v[162:163], 0, s[70:71]
	s_mov_b32 m0, s27
	ds_read_b128 v[230:233], v8
	ds_read_b128 v[234:237], v8 offset:1024
	ds_read_b128 v[238:241], v8 offset:2048
	ds_read_b128 v[242:245], v8 offset:3072
	global_load_lds_dwordx4 v[162:163], off
	s_add_i32 m0, s27, 0x2000
	v_lshl_add_u64 v[162:163], v[164:165], 0, s[70:71]
	global_load_lds_dwordx4 v[162:163], off
	s_waitcnt lgkmcnt(0)
	s_barrier
	v_mfma_f32_16x16x32_bf16 v[118:121], v[230:233], v[184:187], v[118:121]
	v_mfma_f32_16x16x32_bf16 v[110:113], v[238:241], v[184:187], v[110:113]
	v_mfma_f32_16x16x32_bf16 v[98:101], v[230:233], v[192:195], v[98:101]
	v_mfma_f32_16x16x32_bf16 v[90:93], v[238:241], v[192:195], v[90:93]
	v_mfma_f32_16x16x32_bf16 v[86:89], v[230:233], v[214:217], v[86:89]
	v_mfma_f32_16x16x32_bf16 v[78:81], v[238:241], v[214:217], v[78:81]
	v_mfma_f32_16x16x32_bf16 v[54:57], v[230:233], v[222:225], v[54:57]
	v_mfma_f32_16x16x32_bf16 v[34:37], v[238:241], v[222:225], v[34:37]
	v_mfma_f32_16x16x32_bf16 v[118:121], v[234:237], v[188:191], v[118:121]
	v_mfma_f32_16x16x32_bf16 v[110:113], v[242:245], v[188:191], v[110:113]
	v_mfma_f32_16x16x32_bf16 v[98:101], v[234:237], v[206:209], v[98:101]
	v_mfma_f32_16x16x32_bf16 v[90:93], v[242:245], v[206:209], v[90:93]
	v_mfma_f32_16x16x32_bf16 v[86:89], v[234:237], v[218:221], v[86:89]
	v_mfma_f32_16x16x32_bf16 v[78:81], v[242:245], v[218:221], v[78:81]
	v_mfma_f32_16x16x32_bf16 v[54:57], v[234:237], v[226:229], v[54:57]
	v_mfma_f32_16x16x32_bf16 v[34:37], v[242:245], v[226:229], v[34:37]
	s_mov_b32 m0, s81
	v_lshl_add_u64 v[162:163], v[202:203], 0, s[70:71]
	s_barrier
	ds_read_b128 v[184:187], v204 offset:49152
	ds_read_b128 v[188:191], v204 offset:50176
	ds_read_b128 v[192:195], v204 offset:51200
	ds_read_b128 v[206:209], v204 offset:52224
	ds_read_b128 v[214:217], v204 offset:53248
	ds_read_b128 v[218:221], v204 offset:54272
	ds_read_b128 v[222:225], v204 offset:55296
	ds_read_b128 v[226:229], v204 offset:56320
	global_load_lds_dwordx4 v[162:163], off
	s_mov_b32 m0, s82
	v_lshl_add_u64 v[162:163], v[246:247], 0, s[70:71]
	global_load_lds_dwordx4 v[162:163], off
	s_waitcnt lgkmcnt(0)
	s_barrier
; #define PG8_STAGE(bufoff, gbase, voff) do { _Pragma("unroll") for (int _i = 0; _i < 2; ++_i) \
;         __builtin_amdgcn_global_load_lds((const unsigned*)((const char*)(gbase) + (voff)[_i]), (LAS unsigned*)(lds + (bufoff) + ldsw + _i * 8192), 16, 0, 0); } while (0)
; #define PG8_LDA(dst, b, h) do { _Pragma("unroll") for (int m = 0; m < 4; ++m) _Pragma("unroll") for (int k = 0; k < 2; ++k) dst[m][k] = *(const LAS bf16x8*)(lds + PG8_SA(b, h) + aoff + m * 2048 + k * 1024); } while (0)
; #define PG8_MMA(ai, bj, At, Bt) do { __builtin_amdgcn_s_setprio(1); _Pragma("unroll") for (int m = 0; m < 4; ++m) _Pragma("unroll") for (int n = 0; n < 2; ++n) _Pragma("unroll") for (int k = 0; k < 2; ++k) \
;         acc[ai][bj][m][n] = __builtin_amdgcn_mfma_f32_16x16x32_bf16(Bt[n][k], At[m][k], acc[ai][bj][m][n], 0, 0, 0); __builtin_amdgcn_s_setprio(0); } while (0)
; #define PG8_WAIT_V(n) asm volatile("s_waitcnt vmcnt(" #n ")" ::: "memory")
; #define PG8_WAIT_L(n) asm volatile("s_waitcnt lgkmcnt(" #n ")" ::: "memory")
; #define PG8_BAR __builtin_amdgcn_s_barrier()
; #define PG8_SCHED __builtin_amdgcn_sched_barrier(0)
; template <class Epi>
; DEVI void gemm_phase(LAS unsigned char* lds, const Gemm g, const Epi& E) {
;     ...
;             PG8_LDA(At, 1, 1); PG8_STAGE(PG8_SA(1, 0), a3, voffA);
;             PG8_BAR; PG8_WAIT_L(0); PG8_MMA(1, 0, At, B0); PG8_BAR; PG8_SCHED;
;             PG8_STAGE(PG8_SB(1, 1), b3 + hstepB, voffB);
;             PG8_WAIT_V(6); PG8_BAR; PG8_MMA(1, 1, At, B1); PG8_BAR;
;         }
;         {
;             const int row0 = cur.pm * BM + wr * 64 + fr, col0 = cur.pn * BM + wc * 32 + (Epi::PERM ? 8 : 4) * fq; constexpr int NST = Epi::PERM ? 4 : 16;
;             float rsv[8];
;             if constexpr (Epi::RS) { f32x4 q4[8];
; #pragma unroll
;                 for (int i = 0; i < 8; ++i) q4[i] = *(const f32x4*)(E.ssq_in + (size_t)(row0 + (i >> 2) * HALF + (i & 3) * 16) * 4);
; #pragma unroll
;                 for (int i = 0; i < 8; ++i) rsv[i] = rsqrtf((((q4[i][0] + q4[i][1]) + q4[i][2]) + q4[i][3]) * (1.f / DM) + 1e-6f); }
	v_mfma_f32_16x16x32_bf16 v[58:61], v[130:133], v[184:187], v[58:61]
	v_mfma_f32_16x16x32_bf16 v[62:65], v[138:141], v[184:187], v[62:65]
	v_mfma_f32_16x16x32_bf16 v[38:41], v[130:133], v[192:195], v[38:41]
	v_mfma_f32_16x16x32_bf16 v[42:45], v[138:141], v[192:195], v[42:45]
	v_mfma_f32_16x16x32_bf16 v[18:21], v[130:133], v[214:217], v[18:21]
	v_mfma_f32_16x16x32_bf16 v[22:25], v[138:141], v[214:217], v[22:25]
	v_mfma_f32_16x16x32_bf16 v[0:3], v[130:133], v[222:225], v[0:3]
	v_mfma_f32_16x16x32_bf16 v[4:7], v[138:141], v[222:225], v[4:7]
	v_mfma_f32_16x16x32_bf16 v[58:61], v[134:137], v[188:191], v[58:61]
	v_mfma_f32_16x16x32_bf16 v[62:65], v[142:145], v[188:191], v[62:65]
	v_mfma_f32_16x16x32_bf16 v[38:41], v[134:137], v[206:209], v[38:41]
	v_mfma_f32_16x16x32_bf16 v[42:45], v[142:145], v[206:209], v[42:45]
	v_mfma_f32_16x16x32_bf16 v[18:21], v[134:137], v[218:221], v[18:21]
	v_mfma_f32_16x16x32_bf16 v[22:25], v[142:145], v[218:221], v[22:25]
	v_mfma_f32_16x16x32_bf16 v[0:3], v[134:137], v[226:229], v[0:3]
	v_mfma_f32_16x16x32_bf16 v[4:7], v[142:145], v[226:229], v[4:7]
	s_barrier
	s_add_u32 s16, s16, 0x40080
	s_addc_u32 s17, s17, 0
	s_add_i32 s26, s26, s47
	s_mov_b32 m0, s26
	v_lshl_add_u64 v[130:131], s[16:17], 0, v[148:149]
	global_load_lds_dwordx4 v[130:131], off
	s_add_i32 m0, s26, 0x2000
	v_lshl_add_u64 v[130:131], s[16:17], 0, v[152:153]
	global_load_lds_dwordx4 v[130:131], off
	s_waitcnt vmcnt(6)
	s_barrier
	v_mfma_f32_16x16x32_bf16 v[66:69], v[230:233], v[184:187], v[66:69]
	v_mfma_f32_16x16x32_bf16 v[70:73], v[238:241], v[184:187], v[70:73]
	v_mfma_f32_16x16x32_bf16 v[46:49], v[230:233], v[192:195], v[46:49]
	v_mfma_f32_16x16x32_bf16 v[50:53], v[238:241], v[192:195], v[50:53]
	v_mfma_f32_16x16x32_bf16 v[26:29], v[230:233], v[214:217], v[26:29]
	v_mfma_f32_16x16x32_bf16 v[30:33], v[238:241], v[214:217], v[30:33]
	v_mfma_f32_16x16x32_bf16 v[10:13], v[230:233], v[222:225], v[10:13]
	v_mfma_f32_16x16x32_bf16 v[14:17], v[238:241], v[222:225], v[14:17]
	v_mfma_f32_16x16x32_bf16 v[66:69], v[234:237], v[188:191], v[66:69]
	v_mfma_f32_16x16x32_bf16 v[70:73], v[242:245], v[188:191], v[70:73]
	v_mfma_f32_16x16x32_bf16 v[46:49], v[234:237], v[206:209], v[46:49]
	v_mfma_f32_16x16x32_bf16 v[50:53], v[242:245], v[206:209], v[50:53]
	v_mfma_f32_16x16x32_bf16 v[26:29], v[234:237], v[218:221], v[26:29]
	v_mfma_f32_16x16x32_bf16 v[30:33], v[242:245], v[218:221], v[30:33]
	v_mfma_f32_16x16x32_bf16 v[10:13], v[234:237], v[226:229], v[10:13]
	v_mfma_f32_16x16x32_bf16 v[14:17], v[242:245], v[226:229], v[14:17]
	s_add_i32 s19, s19, 2
	s_add_u32 s14, s14, 0x100
	s_addc_u32 s15, s15, 0
	s_add_u32 s9, s9, 0x100
	s_addc_u32 s18, s18, 0
	s_cmp_gt_u32 s19, 13
	s_barrier
	s_cbranch_scc0 .LBB0_1007
	s_setprio 0
	v_lshl_add_u32 v194, s4, 8, v197
	v_add_u32_e32 v184, 0xb0, v194
	v_ashrrev_i32_e32 v195, 31, v194
	v_ashrrev_i32_e32 v185, 31, v184
	v_lshl_add_u64 v[130:131], v[194:195], 4, s[76:77]
	v_lshl_add_u64 v[134:135], v[184:185], 4, s[76:77]
	global_load_dwordx4 v[206:209], v[130:131], off
	v_or_b32_e32 v192, 48, v194
	global_load_dwordx4 v[134:137], v[134:135], off
	v_or_b32_e32 v130, 16, v194
	v_ashrrev_i32_e32 v131, 31, v130
	v_lshl_add_u64 v[130:131], v[130:131], 4, s[76:77]
	global_load_dwordx4 v[214:217], v[130:131], off
	v_or_b32_e32 v130, 32, v194
	v_ashrrev_i32_e32 v131, 31, v130
	v_lshl_add_u64 v[130:131], v[130:131], 4, s[76:77]
	v_ashrrev_i32_e32 v193, 31, v192
	global_load_dwordx4 v[218:221], v[130:131], off
	v_lshl_add_u64 v[130:131], v[192:193], 4, s[76:77]
	global_load_dwordx4 v[222:225], v[130:131], off
	v_add_u32_e32 v190, 0x80, v194
	v_ashrrev_i32_e32 v191, 31, v190
	v_add_u32_e32 v188, 0x90, v194
	v_lshl_add_u64 v[130:131], v[190:191], 4, s[76:77]
	v_ashrrev_i32_e32 v189, 31, v188
	global_load_dwordx4 v[138:141], v[130:131], off
	v_lshl_add_u64 v[130:131], v[188:189], 4, s[76:77]
	global_load_dwordx4 v[142:145], v[130:131], off
	v_add_u32_e32 v186, 0xa0, v194
	v_ashrrev_i32_e32 v187, 31, v186
	v_lshl_add_u64 v[130:131], v[186:187], 4, s[76:77]
	global_load_dwordx4 v[130:133], v[130:131], off
	s_mov_b32 s0, 0x358637bd
	v_mov_b64_e32 v[202:203], s[0:1]
	s_mov_b64 s[16:17], s[12:13]
	s_mov_b64 s[14:15], s[10:11]
	s_waitcnt vmcnt(0)
	v_mov_b32_e32 v163, v206
	v_mov_b32_e32 v165, v208
	v_mov_b32_e32 v162, v214
	v_mov_b32_e32 v206, v215
	v_pk_add_f32 v[162:163], v[162:163], v[206:207]
	v_mov_b32_e32 v164, v216
	v_pk_add_f32 v[162:163], v[164:165], v[162:163]
	v_mov_b32_e32 v208, v217
	v_pk_add_f32 v[162:163], v[208:209], v[162:163]
	v_mov_b32_e32 v164, v224
	v_pk_fma_f32 v[162:163], v[162:163], s[72:73], v[202:203] op_sel_hi:[1,0,0]
	v_mov_b32_e32 v165, v220
	v_mul_f32_e32 v8, 0x4b800000, v163
	v_cmp_gt_f32_e64 s[4:5], s94, v163
	v_cmp_gt_f32_e32 vcc, s94, v162
	v_mov_b32_e32 v220, v225
	v_cndmask_b32_e64 v8, v163, v8, s[4:5]
	v_rsq_f32_e32 v8, v8
	s_nop 0
	v_mul_f32_e32 v163, 0x45800000, v8
	v_cndmask_b32_e64 v198, v8, v163, s[4:5]
	v_mul_f32_e32 v8, 0x4b800000, v162
	v_cndmask_b32_e32 v8, v162, v8, vcc
	v_rsq_f32_e32 v8, v8
	v_mov_b32_e32 v163, v218
	v_mov_b32_e32 v218, v223
	v_pk_mul_f32 v[128:129], v[128:129], v[198:199] op_sel_hi:[1,0]
	v_mul_f32_e32 v162, 0x45800000, v8
	v_cndmask_b32_e32 v8, v8, v162, vcc
	v_mov_b32_e32 v162, v222
	v_pk_add_f32 v[162:163], v[162:163], v[218:219]
	v_pk_mul_f32 v[126:127], v[126:127], v[198:199] op_sel_hi:[1,0]
	v_pk_add_f32 v[162:163], v[164:165], v[162:163]
	v_pk_mul_f32 v[122:123], v[122:123], v[198:199] op_sel_hi:[1,0]
	v_pk_add_f32 v[162:163], v[220:221], v[162:163]
	v_pk_mul_f32 v[120:121], v[120:121], v[198:199] op_sel_hi:[1,0]
	v_pk_fma_f32 v[162:163], v[162:163], s[72:73], v[202:203] op_sel_hi:[1,0,0]
; template <class Epi>
; DEVI void gemm_phase(LAS unsigned char* lds, const Gemm g, const Epi& E) {
;     ...
;                 for (int i = 0; i < 8; ++i) q4[i] = *(const f32x4*)(E.ssq_in + (size_t)(row0 + (i >> 2) * HALF + (i & 3) * 16) * 4);
; #pragma unroll
;                 for (int i = 0; i < 8; ++i) rsv[i] = rsqrtf((((q4[i][0] + q4[i][1]) + q4[i][2]) + q4[i][3]) * (1.f / DM) + 1e-6f); }
;     ...
;                 for (int mm = 0; mm < 2; ++mm) {
;                     const int m = m0 + mm;
;                     const int r = row0 + ai * HALF + m * 16; float rs = 1.f, part = 0.f;
;                     if constexpr (Epi::RS) rs = rsv[ai * 4 + m];
;                     if constexpr (Epi::PAIR) E.pair8(cur.b, r, cur.pn * HALF + wc * 32 + 8 * fq, acc[ai][0][m][0] * rs, acc[ai][0][m][1] * rs, acc[ai][1][m][0] * rs, acc[ai][1][m][1] * rs);
;                     else
; #pragma unroll
;                     for (int bj = 0; bj < 2; ++bj) {
;                         const int c = col0 + bj * HALF; f32x4 v0 = acc[ai][bj][m][0], v1 = acc[ai][bj][m][1];
;                         if constexpr (Epi::RS) { v0 = v0 * rs; v1 = v1 * rs; }
;                         if constexpr (Epi::PRE) part += E.frag_pre8(cur.b, r, c, v0, v1, pre[mm][bj][0], pre[mm][bj][1]);
;                         else if constexpr (Epi::PERM) E.frag8(cur.b, r, c, v0, v1);
;                         else { E.frag(cur.b, r, c, v0); E.frag(cur.b, r, c + 16, v1); }
	v_pk_mul_f32 v[118:119], v[118:119], v[198:199] op_sel_hi:[1,0]
	v_mul_f32_e32 v164, 0x4b800000, v163
	v_cmp_gt_f32_e64 s[4:5], s94, v163
	v_cmp_gt_f32_e32 vcc, s94, v162
	v_pk_mul_f32 v[110:111], v[110:111], v[198:199] op_sel_hi:[1,0]
	v_cndmask_b32_e64 v163, v163, v164, s[4:5]
	v_rsq_f32_e32 v163, v163
	v_cvt_pk_bf16_f32 v118, v118, v119
	v_cvt_pk_bf16_f32 v119, v120, v121
	v_cvt_pk_bf16_f32 v120, v110, v111
	v_mul_f32_e32 v164, 0x45800000, v163
	v_cndmask_b32_e64 v200, v163, v164, s[4:5]
	v_mul_f32_e32 v163, 0x4b800000, v162
	v_cndmask_b32_e32 v162, v162, v163, vcc
	v_rsq_f32_e32 v162, v162
	v_pk_mul_f32 v[112:113], v[112:113], v[198:199] op_sel_hi:[1,0]
	v_pk_mul_f32 v[114:115], v[114:115], v[8:9] op_sel_hi:[1,0]
	v_cvt_pk_bf16_f32 v121, v112, v113
	v_mul_f32_e32 v163, 0x45800000, v162
	v_cndmask_b32_e32 v196, v162, v163, vcc
	v_mov_b32_e32 v162, v142
	v_mov_b32_e32 v163, v138
	v_mov_b32_e32 v138, v143
	v_pk_add_f32 v[138:139], v[162:163], v[138:139]
	v_mov_b32_e32 v142, v144
	v_mov_b32_e32 v143, v140
	v_pk_add_f32 v[138:139], v[142:143], v[138:139]
	v_mov_b32_e32 v140, v145
	v_pk_add_f32 v[138:139], v[140:141], v[138:139]
	v_mov_b32_e32 v142, v134
	v_pk_fma_f32 v[140:141], v[138:139], s[72:73], v[202:203] op_sel_hi:[1,0,0]
	v_mov_b32_e32 v143, v130
	v_mul_f32_e32 v138, 0x4b800000, v141
	v_cmp_gt_f32_e64 s[4:5], s94, v141
	v_mov_b32_e32 v130, v135
	v_pk_add_f32 v[130:131], v[142:143], v[130:131]
	v_cndmask_b32_e64 v138, v141, v138, s[4:5]
	v_rsq_f32_e32 v138, v138
	v_mov_b32_e32 v134, v136
	v_mov_b32_e32 v135, v132
	v_pk_add_f32 v[130:131], v[134:135], v[130:131]
	v_mov_b32_e32 v132, v137
	v_pk_add_f32 v[130:131], v[132:133], v[130:131]
	v_mul_f32_e32 v139, 0x45800000, v138
	v_pk_fma_f32 v[130:131], v[130:131], s[72:73], v[202:203] op_sel_hi:[1,0,0]
	v_cmp_gt_f32_e32 vcc, s94, v140
	v_cndmask_b32_e64 v138, v138, v139, s[4:5]
	v_mul_f32_e32 v139, 0x4b800000, v140
	v_mul_f32_e32 v132, 0x4b800000, v131
	v_cmp_gt_f32_e64 s[4:5], s94, v131
	v_cndmask_b32_e32 v139, v140, v139, vcc
	v_rsq_f32_e32 v139, v139
	v_cndmask_b32_e64 v131, v131, v132, s[4:5]
	v_rsq_f32_e32 v131, v131
	v_pk_mul_f32 v[136:137], v[124:125], v[198:199] op_sel_hi:[1,0]
	v_mul_f32_e32 v140, 0x45800000, v139
	v_cndmask_b32_e32 v140, v139, v140, vcc
	v_mul_f32_e32 v132, 0x45800000, v131
	v_cmp_gt_f32_e32 vcc, s94, v130
	v_cndmask_b32_e64 v132, v131, v132, s[4:5]
	v_mul_f32_e32 v131, 0x4b800000, v130
	v_cndmask_b32_e32 v130, v130, v131, vcc
	v_rsq_f32_e32 v130, v130
	v_cvt_pk_bf16_f32 v125, v128, v129
	v_ashrrev_i32_e32 v134, 5, v194
	v_ashrrev_i32_e32 v135, 31, v134
	v_mul_f32_e32 v131, 0x45800000, v130
	v_cndmask_b32_e32 v130, v130, v131, vcc
	v_lshl_or_b32 v131, s84, 8, v201
	v_ashrrev_i32_e32 v128, 4, v131
	v_ashrrev_i32_e32 v129, 31, v128
	v_cvt_pk_bf16_f32 v124, v126, v127
	v_cvt_pk_bf16_f32 v126, v122, v123
	v_lshlrev_b64 v[122:123], 10, v[128:129]
	v_or_b32_e32 v110, 8, v128
	v_cvt_pk_bf16_f32 v127, v136, v137
	v_lshl_add_u64 v[136:137], v[122:123], 0, v[134:135]
	v_ashrrev_i32_e32 v111, 31, v110
	v_mad_u64_u32 v[142:143], s[0:1], v136, s34, v[178:179]
	v_lshlrev_b64 v[110:111], 10, v[110:111]
	v_mad_i32_i24 v143, v137, s34, v143
	v_lshl_add_u64 v[112:113], v[110:111], 0, v[134:135]
	global_store_dwordx4 v[142:143], v[124:127], off
	v_pk_mul_f32 v[100:101], v[100:101], v[8:9] op_sel_hi:[1,0]
	v_pk_mul_f32 v[98:99], v[98:99], v[8:9] op_sel_hi:[1,0]
	v_mad_u64_u32 v[124:125], s[0:1], v112, s34, v[178:179]
	v_mad_i32_i24 v125, v113, s34, v125
	v_pk_mul_f32 v[112:113], v[116:117], v[8:9] op_sel_hi:[1,0]
	v_pk_mul_f32 v[116:117], v[108:109], v[8:9] op_sel_hi:[1,0]
	v_pk_mul_f32 v[108:109], v[106:107], v[8:9] op_sel_hi:[1,0]
	v_cvt_pk_bf16_f32 v106, v114, v115
	v_cvt_pk_bf16_f32 v107, v112, v113
	v_cvt_pk_bf16_f32 v108, v108, v109
	v_cvt_pk_bf16_f32 v109, v116, v117
	global_store_dwordx4 v[142:143], v[106:109], off offset:512
	v_pk_mul_f32 v[94:95], v[94:95], v[200:201] op_sel_hi:[1,0]
	v_pk_mul_f32 v[96:97], v[96:97], v[200:201] op_sel_hi:[1,0]
	v_pk_mul_f32 v[106:107], v[92:93], v[8:9] op_sel_hi:[1,0]
	v_pk_mul_f32 v[92:93], v[90:91], v[8:9] op_sel_hi:[1,0]
	v_cvt_pk_bf16_f32 v90, v98, v99
	v_cvt_pk_bf16_f32 v91, v100, v101
	v_cvt_pk_bf16_f32 v92, v92, v93
	v_cvt_pk_bf16_f32 v93, v106, v107
	v_or_b32_e32 v98, 1, v134
	global_store_dwordx4 v[124:125], v[90:93], off offset:512
	v_ashrrev_i32_e32 v99, 31, v98
	v_pk_mul_f32 v[86:87], v[86:87], v[200:201] op_sel_hi:[1,0]
	v_pk_mul_f32 v[92:93], v[104:105], v[200:201] op_sel_hi:[1,0]
	v_pk_mul_f32 v[90:91], v[102:103], v[200:201] op_sel_hi:[1,0]
	v_pk_mul_f32 v[88:89], v[88:89], v[200:201] op_sel_hi:[1,0]
	v_cvt_pk_bf16_f32 v90, v90, v91
	v_cvt_pk_bf16_f32 v91, v92, v93
	v_cvt_pk_bf16_f32 v92, v94, v95
	v_lshl_add_u64 v[94:95], v[122:123], 0, v[98:99]
	v_cvt_pk_bf16_f32 v93, v96, v97
	v_mad_u64_u32 v[96:97], s[0:1], v94, s34, v[178:179]
	v_mad_i32_i24 v97, v95, s34, v97
	global_store_dwordx4 v[96:97], v[90:93], off
	v_lshlrev_b32_e32 v8, 5, v192
	v_and_b32_e32 v8, 0x3e0, v8
	v_pk_mul_f32 v[90:91], v[80:81], v[200:201] op_sel_hi:[1,0]
	v_pk_mul_f32 v[80:81], v[78:79], v[200:201] op_sel_hi:[1,0]
	v_cvt_pk_bf16_f32 v78, v86, v87
	v_lshl_add_u64 v[86:87], v[110:111], 0, v[98:99]
	v_cvt_pk_bf16_f32 v79, v88, v89
	v_mad_u64_u32 v[88:89], s[0:1], v86, s34, v[178:179]
	v_cvt_pk_bf16_f32 v80, v80, v81
	v_cvt_pk_bf16_f32 v81, v90, v91
	v_mad_i32_i24 v89, v87, s34, v89
	global_store_dwordx4 v[88:89], v[78:81], off
	v_pk_mul_f32 v[82:83], v[82:83], v[196:197] op_sel_hi:[1,0]
	v_pk_mul_f32 v[84:85], v[84:85], v[196:197] op_sel_hi:[1,0]
	v_ashrrev_i32_e32 v78, 5, v192
	v_ashrrev_i32_e32 v79, 31, v78
	v_lshl_add_u64 v[80:81], v[176:177], 0, v[8:9]
; #define PG8_WAIT_V(n) asm volatile("s_waitcnt vmcnt(" #n ")" ::: "memory")
; #define PG8_BAR __builtin_amdgcn_s_barrier()
; template <class Epi>
; DEVI void gemm_phase(LAS unsigned char* lds, const Gemm g, const Epi& E) {
;     ...
;                     for (int bj = 0; bj < 2; ++bj) {
;                         const int c = col0 + bj * HALF; f32x4 v0 = acc[ai][bj][m][0], v1 = acc[ai][bj][m][1];
;                         if constexpr (Epi::RS) { v0 = v0 * rs; v1 = v1 * rs; }
;                         if constexpr (Epi::PRE) part += E.frag_pre8(cur.b, r, c, v0, v1, pre[mm][bj][0], pre[mm][bj][1]);
;                         else if constexpr (Epi::PERM) E.frag8(cur.b, r, c, v0, v1);
;                         else { E.frag(cur.b, r, c, v0); E.frag(cur.b, r, c + 16, v1); }
;     ...
;         if (!has_next) break;
; #pragma unroll
;         for (int a = 0; a < 2; ++a)
; #pragma unroll
;             for (int b = 0; b < 2; ++b)
; #pragma unroll
;                 for (int m = 0; m < 4; ++m)
; #pragma unroll
;                     for (int n = 0; n < 2; ++n) acc[a][b][m][n] = (f32x4){0.f, 0.f, 0.f, 0.f};
;         cur = nxt; cA = nA; cB = nB; ++ui;
;     }
;     PG8_WAIT_V(0);
;     if (wr == 0) PG8_BAR;
;     PG8_BAR;
	v_pk_mul_f32 v[86:87], v[76:77], v[196:197] op_sel_hi:[1,0]
	v_pk_mul_f32 v[76:77], v[74:75], v[196:197] op_sel_hi:[1,0]
	v_cvt_pk_bf16_f32 v74, v82, v83
	v_lshl_add_u64 v[82:83], v[122:123], 0, v[78:79]
	v_cvt_pk_bf16_f32 v75, v84, v85
	v_mad_u64_u32 v[84:85], s[0:1], v82, s34, v[80:81]
	v_cvt_pk_bf16_f32 v76, v76, v77
	v_cvt_pk_bf16_f32 v77, v86, v87
	v_mad_i32_i24 v85, v83, s34, v85
	v_pk_mul_f32 v[54:55], v[54:55], v[196:197] op_sel_hi:[1,0]
	global_store_dwordx4 v[124:125], v[118:121], off
	global_store_dwordx4 v[84:85], v[74:77], off
	v_pk_mul_f32 v[56:57], v[56:57], v[196:197] op_sel_hi:[1,0]
	v_lshlrev_b32_e32 v8, 5, v188
	v_pk_mul_f32 v[74:75], v[36:37], v[196:197] op_sel_hi:[1,0]
	v_pk_mul_f32 v[36:37], v[34:35], v[196:197] op_sel_hi:[1,0]
	v_cvt_pk_bf16_f32 v34, v54, v55
	v_lshl_add_u64 v[54:55], v[110:111], 0, v[78:79]
	v_cvt_pk_bf16_f32 v35, v56, v57
	v_mad_u64_u32 v[56:57], s[0:1], v54, s34, v[80:81]
	v_cvt_pk_bf16_f32 v36, v36, v37
	v_cvt_pk_bf16_f32 v37, v74, v75
	v_mad_i32_i24 v57, v55, s34, v57
	v_ashrrev_i32_e32 v54, 5, v190
	global_store_dwordx4 v[56:57], v[34:37], off
	v_ashrrev_i32_e32 v55, 31, v54
	v_pk_mul_f32 v[56:57], v[64:65], v[138:139] op_sel_hi:[1,0]
	v_pk_mul_f32 v[36:37], v[60:61], v[138:139] op_sel_hi:[1,0]
	v_pk_mul_f32 v[34:35], v[58:59], v[138:139] op_sel_hi:[1,0]
	v_pk_mul_f32 v[58:59], v[62:63], v[138:139] op_sel_hi:[1,0]
	v_cvt_pk_bf16_f32 v34, v34, v35
	v_cvt_pk_bf16_f32 v35, v36, v37
	v_cvt_pk_bf16_f32 v37, v56, v57
	v_lshl_add_u64 v[56:57], v[122:123], 0, v[54:55]
	v_cvt_pk_bf16_f32 v36, v58, v59
	v_mad_u64_u32 v[58:59], s[0:1], v56, s34, v[178:179]
	v_mad_i32_i24 v59, v57, s34, v59
	global_store_dwordx4 v[58:59], v[34:37], off
	v_pk_mul_f32 v[56:57], v[72:73], v[138:139] op_sel_hi:[1,0]
	v_lshl_add_u64 v[54:55], v[110:111], 0, v[54:55]
	v_pk_mul_f32 v[36:37], v[68:69], v[138:139] op_sel_hi:[1,0]
	v_pk_mul_f32 v[34:35], v[66:67], v[138:139] op_sel_hi:[1,0]
	v_pk_mul_f32 v[58:59], v[70:71], v[138:139] op_sel_hi:[1,0]
	v_cvt_pk_bf16_f32 v34, v34, v35
	v_cvt_pk_bf16_f32 v35, v36, v37
	v_cvt_pk_bf16_f32 v37, v56, v57
	v_mad_u64_u32 v[56:57], s[0:1], v54, s34, v[178:179]
	v_cvt_pk_bf16_f32 v36, v58, v59
	v_mad_i32_i24 v57, v55, s34, v57
	v_ashrrev_i32_e32 v54, 5, v188
	global_store_dwordx4 v[56:57], v[34:37], off
	v_ashrrev_i32_e32 v55, 31, v54
	v_and_b32_e32 v8, 0x3e0, v8
	v_pk_mul_f32 v[36:37], v[40:41], v[140:141] op_sel_hi:[1,0]
	v_pk_mul_f32 v[34:35], v[38:39], v[140:141] op_sel_hi:[1,0]
	v_pk_mul_f32 v[38:39], v[44:45], v[140:141] op_sel_hi:[1,0]
	v_lshl_add_u64 v[56:57], v[176:177], 0, v[8:9]
	v_pk_mul_f32 v[40:41], v[42:43], v[140:141] op_sel_hi:[1,0]
	v_cvt_pk_bf16_f32 v34, v34, v35
	v_cvt_pk_bf16_f32 v35, v36, v37
	v_cvt_pk_bf16_f32 v37, v38, v39
	v_lshl_add_u64 v[38:39], v[122:123], 0, v[54:55]
	v_cvt_pk_bf16_f32 v36, v40, v41
	v_mad_u64_u32 v[40:41], s[0:1], v38, s34, v[56:57]
	v_mad_i32_i24 v41, v39, s34, v41
	global_store_dwordx4 v[40:41], v[34:37], off
	v_pk_mul_f32 v[38:39], v[52:53], v[140:141] op_sel_hi:[1,0]
	v_pk_mul_f32 v[40:41], v[50:51], v[140:141] op_sel_hi:[1,0]
	v_pk_mul_f32 v[36:37], v[48:49], v[140:141] op_sel_hi:[1,0]
	v_pk_mul_f32 v[34:35], v[46:47], v[140:141] op_sel_hi:[1,0]
	v_pk_mul_f32 v[20:21], v[20:21], v[132:133] op_sel_hi:[1,0]
	v_cvt_pk_bf16_f32 v34, v34, v35
	v_cvt_pk_bf16_f32 v35, v36, v37
	v_cvt_pk_bf16_f32 v37, v38, v39
	v_lshl_add_u64 v[38:39], v[110:111], 0, v[54:55]
	v_cvt_pk_bf16_f32 v36, v40, v41
	v_mad_u64_u32 v[40:41], s[0:1], v38, s34, v[56:57]
	v_mad_i32_i24 v41, v39, s34, v41
	global_store_dwordx4 v[40:41], v[34:37], off
	v_pk_mul_f32 v[18:19], v[18:19], v[132:133] op_sel_hi:[1,0]
	v_pk_mul_f32 v[22:23], v[22:23], v[132:133] op_sel_hi:[1,0]
	v_ashrrev_i32_e32 v34, 5, v186
	v_ashrrev_i32_e32 v35, 31, v34
	v_pk_mul_f32 v[24:25], v[24:25], v[132:133] op_sel_hi:[1,0]
	v_cvt_pk_bf16_f32 v18, v18, v19
	v_cvt_pk_bf16_f32 v19, v20, v21
	v_cvt_pk_bf16_f32 v20, v22, v23
	v_lshl_add_u64 v[22:23], v[122:123], 0, v[34:35]
	v_cvt_pk_bf16_f32 v21, v24, v25
	v_mad_u64_u32 v[24:25], s[0:1], v22, s34, v[178:179]
	v_mad_i32_i24 v25, v23, s34, v25
	global_store_dwordx4 v[24:25], v[18:21], off
	v_pk_mul_f32 v[22:23], v[32:33], v[132:133] op_sel_hi:[1,0]
	v_pk_mul_f32 v[24:25], v[30:31], v[132:133] op_sel_hi:[1,0]
	v_pk_mul_f32 v[20:21], v[28:29], v[132:133] op_sel_hi:[1,0]
	v_pk_mul_f32 v[18:19], v[26:27], v[132:133] op_sel_hi:[1,0]
	v_lshlrev_b32_e32 v8, 5, v184
	v_cvt_pk_bf16_f32 v18, v18, v19
	v_cvt_pk_bf16_f32 v19, v20, v21
	v_cvt_pk_bf16_f32 v21, v22, v23
	v_lshl_add_u64 v[22:23], v[110:111], 0, v[34:35]
	v_cvt_pk_bf16_f32 v20, v24, v25
	v_mad_u64_u32 v[24:25], s[0:1], v22, s34, v[178:179]
	v_mad_i32_i24 v25, v23, s34, v25
	global_store_dwordx4 v[24:25], v[18:21], off
	v_and_b32_e32 v8, 0x3e0, v8
	v_pk_mul_f32 v[2:3], v[2:3], v[130:131] op_sel_hi:[1,0]
	v_ashrrev_i32_e32 v18, 5, v184
	v_ashrrev_i32_e32 v19, 31, v18
	v_pk_mul_f32 v[0:1], v[0:1], v[130:131] op_sel_hi:[1,0]
	v_pk_mul_f32 v[4:5], v[4:5], v[130:131] op_sel_hi:[1,0]
	v_lshl_add_u64 v[20:21], v[176:177], 0, v[8:9]
	v_pk_mul_f32 v[6:7], v[6:7], v[130:131] op_sel_hi:[1,0]
	v_cvt_pk_bf16_f32 v0, v0, v1
	v_cvt_pk_bf16_f32 v1, v2, v3
	v_cvt_pk_bf16_f32 v2, v4, v5
	v_lshl_add_u64 v[4:5], v[122:123], 0, v[18:19]
	v_cvt_pk_bf16_f32 v3, v6, v7
	v_mad_u64_u32 v[6:7], s[0:1], v4, s34, v[20:21]
	v_mad_i32_i24 v7, v5, s34, v7
	global_store_dwordx4 v[6:7], v[0:3], off
	v_pk_mul_f32 v[4:5], v[16:17], v[130:131] op_sel_hi:[1,0]
	v_pk_mul_f32 v[6:7], v[14:15], v[130:131] op_sel_hi:[1,0]
	v_pk_mul_f32 v[2:3], v[12:13], v[130:131] op_sel_hi:[1,0]
	v_pk_mul_f32 v[0:1], v[10:11], v[130:131] op_sel_hi:[1,0]
	s_and_b64 vcc, exec, s[2:3]
	v_cvt_pk_bf16_f32 v0, v0, v1
	v_cvt_pk_bf16_f32 v1, v2, v3
	v_cvt_pk_bf16_f32 v3, v4, v5
	v_lshl_add_u64 v[4:5], v[110:111], 0, v[18:19]
	v_cvt_pk_bf16_f32 v2, v6, v7
	v_mad_u64_u32 v[6:7], s[0:1], v4, s34, v[20:21]
	v_mad_i32_i24 v7, v5, s34, v7
	s_mov_b32 s84, s8
	s_mov_b32 s4, s6
	global_store_dwordx4 v[6:7], v[0:3], off
	s_cbranch_vccz .LBB0_1000
	s_waitcnt vmcnt(0)
	s_cmpk_gt_u32 s46, 0xff
	s_cbranch_scc1 .LBB0_1011
	s_barrier

; #define PG8_STAGE(bufoff, gbase, voff) do { _Pragma("unroll") for (int _i = 0; _i < 2; ++_i) \
;         __builtin_amdgcn_global_load_lds((const unsigned*)((const char*)(gbase) + (voff)[_i]), (LAS unsigned*)(lds + (bufoff) + ldsw + _i * 8192), 16, 0, 0); } while (0)
; #define PG8_LDA(dst, b, h) do { _Pragma("unroll") for (int m = 0; m < 4; ++m) _Pragma("unroll") for (int k = 0; k < 2; ++k) dst[m][k] = *(const LAS bf16x8*)(lds + PG8_SA(b, h) + aoff + m * 2048 + k * 1024); } while (0)
; #define PG8_LDB(dst, b, h) do { _Pragma("unroll") for (int n = 0; n < 2; ++n) _Pragma("unroll") for (int k = 0; k < 2; ++k) dst[n][k] = *(const LAS bf16x8*)(lds + PG8_SB(b, h) + boff + n * 2048 + k * 1024); } while (0)
; #define PG8_MMA(ai, bj, At, Bt) do { __builtin_amdgcn_s_setprio(1); _Pragma("unroll") for (int m = 0; m < 4; ++m) _Pragma("unroll") for (int n = 0; n < 2; ++n) _Pragma("unroll") for (int k = 0; k < 2; ++k) \
;         acc[ai][bj][m][n] = __builtin_amdgcn_mfma_f32_16x16x32_bf16(Bt[n][k], At[m][k], acc[ai][bj][m][n], 0, 0, 0); __builtin_amdgcn_s_setprio(0); } while (0)
; template <class Epi>
; DEVI void gemm_phase(LAS unsigned char* lds, const Gemm g, const Epi& E) {
;     ...
;         for (int t = 0; t < nt; t += 2) {
;             const bool last = (t == nt - 2);
;             const char* a1 = cA + (size_t)(t + 1) * kstep;
;             const char* a2 = last ? nA : cA + (size_t)(t + 2) * kstep; const char* b2 = last ? nB : cB + (size_t)(t + 2) * kstep;
;             const char* a3 = a2 + kstep; const char* b3 = b2 + kstep;
;             PG8_LDB(B0, 0, 0); PG8_SCHED; PG8_LDA(At, 0, 0); PG8_STAGE(PG8_SA(1, 1), a1 + hstepA, voffA);
;             PG8_WAIT_L(8); PG8_BAR; PG8_WAIT_L(0); PG8_MMA(0, 0, At, B0); PG8_BAR; PG8_SCHED;
;             PG8_LDB(B1, 0, 1); PG8_STAGE(PG8_SB(0, 0), b2, voffB);
;             PG8_BAR; PG8_WAIT_L(0); PG8_MMA(0, 1, At, B1); PG8_BAR;
;             PG8_LDA(At, 0, 1); PG8_STAGE(PG8_SA(0, 0), a2, voffA);
;             PG8_BAR; PG8_WAIT_L(0); PG8_MMA(1, 0, At, B0); PG8_BAR; PG8_SCHED;
;             PG8_STAGE(PG8_SB(0, 1), b2 + hstepB, voffB);
;             PG8_WAIT_V(6); PG8_BAR; PG8_MMA(1, 1, At, B1); PG8_BAR;
;             PG8_LDB(B0, 1, 0); PG8_SCHED; PG8_LDA(At, 1, 0); PG8_STAGE(PG8_SA(0, 1), a2 + hstepA, voffA);
;             PG8_WAIT_L(8); PG8_BAR; PG8_WAIT_L(0); PG8_MMA(0, 0, At, B0); PG8_BAR; PG8_SCHED;
.LBB0_1127:
	s_add_u32 s14, s12, 0x100
	s_addc_u32 s15, s13, 0
	s_add_i32 s48, 0, 0x10000
	v_add_u32_e32 v81, s48, v79
	ds_read_b128 v[82:85], v81
	ds_read_b128 v[86:89], v81 offset:1024
	ds_read_b128 v[90:93], v81 offset:2048
	ds_read_b128 v[94:97], v81 offset:3072
	s_cmp_eq_u32 s47, 4
	s_cselect_b32 s37, s9, s15
	s_cselect_b32 s36, s8, s14
	s_cselect_b32 s17, s11, s7
	s_cselect_b32 s16, s10, s5
	v_lshl_add_u64 v[130:131], s[12:13], 0, v[74:75]
	s_add_i32 m0, s18, 0xc000
	ds_read_b128 v[98:101], v80
	ds_read_b128 v[102:105], v80 offset:1024
	ds_read_b128 v[106:109], v80 offset:2048
	ds_read_b128 v[110:113], v80 offset:3072
	ds_read_b128 v[114:117], v80 offset:4096
	ds_read_b128 v[118:121], v80 offset:5120
	ds_read_b128 v[122:125], v80 offset:6144
	ds_read_b128 v[126:129], v80 offset:7168
	global_load_lds_dwordx4 v[130:131], off
	s_add_i32 m0, s18, 0xe000
	v_lshl_add_u64 v[130:131], s[12:13], 0, v[76:77]
	global_load_lds_dwordx4 v[130:131], off
	s_waitcnt lgkmcnt(0)
	s_barrier
	v_mfma_f32_16x16x32_bf16 v[62:65], v[82:85], v[98:101], v[62:65]
	v_mfma_f32_16x16x32_bf16 v[58:61], v[90:93], v[98:101], v[58:61]
	v_mfma_f32_16x16x32_bf16 v[54:57], v[82:85], v[106:109], v[54:57]
	v_mfma_f32_16x16x32_bf16 v[50:53], v[90:93], v[106:109], v[50:53]
	v_mfma_f32_16x16x32_bf16 v[46:49], v[82:85], v[114:117], v[46:49]
	v_mfma_f32_16x16x32_bf16 v[42:45], v[90:93], v[114:117], v[42:45]
	v_mfma_f32_16x16x32_bf16 v[38:41], v[82:85], v[122:125], v[38:41]
	v_mfma_f32_16x16x32_bf16 v[34:37], v[90:93], v[122:125], v[34:37]
	v_mfma_f32_16x16x32_bf16 v[62:65], v[86:89], v[102:105], v[62:65]
	v_mfma_f32_16x16x32_bf16 v[58:61], v[94:97], v[102:105], v[58:61]
	v_mfma_f32_16x16x32_bf16 v[54:57], v[86:89], v[110:113], v[54:57]
	v_mfma_f32_16x16x32_bf16 v[50:53], v[94:97], v[110:113], v[50:53]
	v_mfma_f32_16x16x32_bf16 v[46:49], v[86:89], v[118:121], v[46:49]
	v_mfma_f32_16x16x32_bf16 v[42:45], v[94:97], v[118:121], v[42:45]
	v_mfma_f32_16x16x32_bf16 v[38:41], v[86:89], v[126:129], v[38:41]
	v_mfma_f32_16x16x32_bf16 v[34:37], v[94:97], v[126:129], v[34:37]
	s_barrier
	s_add_i32 s12, s48, s1
	v_lshl_add_u64 v[130:131], s[16:17], 0, v[70:71]
	s_mov_b32 m0, s12
	v_lshl_add_u64 v[132:133], s[16:17], 0, v[66:67]
	global_load_lds_dwordx4 v[130:131], off
	s_add_i32 m0, s12, 0x2000
	s_nop 0
	global_load_lds_dwordx4 v[132:133], off
	s_barrier
	s_waitcnt lgkmcnt(0)
	s_mov_b32 m0, s18
	v_lshl_add_u64 v[134:135], s[36:37], 0, v[72:73]
	s_barrier
	ds_read_b128 v[98:101], v80 offset:16384
	ds_read_b128 v[102:105], v80 offset:17408
	ds_read_b128 v[106:109], v80 offset:18432
	ds_read_b128 v[110:113], v80 offset:19456
	ds_read_b128 v[114:117], v80 offset:20480
	ds_read_b128 v[118:121], v80 offset:21504
	ds_read_b128 v[122:125], v80 offset:22528
	ds_read_b128 v[126:129], v80 offset:23552
	global_load_lds_dwordx4 v[134:135], off
	s_mov_b32 m0, s19
	v_lshl_add_u64 v[136:137], s[36:37], 0, v[68:69]
	global_load_lds_dwordx4 v[136:137], off
	s_waitcnt lgkmcnt(0)
	s_barrier
	v_mfma_f32_16x16x32_bf16 v[30:33], v[82:85], v[98:101], v[30:33]
	v_mfma_f32_16x16x32_bf16 v[26:29], v[90:93], v[98:101], v[26:29]
	v_mfma_f32_16x16x32_bf16 v[22:25], v[82:85], v[106:109], v[22:25]
	v_mfma_f32_16x16x32_bf16 v[18:21], v[90:93], v[106:109], v[18:21]
	v_mfma_f32_16x16x32_bf16 v[14:17], v[82:85], v[114:117], v[14:17]
	v_mfma_f32_16x16x32_bf16 v[10:13], v[90:93], v[114:117], v[10:13]
	v_mfma_f32_16x16x32_bf16 v[4:7], v[82:85], v[122:125], v[4:7]
	v_mfma_f32_16x16x32_bf16 v[0:3], v[90:93], v[122:125], v[0:3]
	v_mfma_f32_16x16x32_bf16 v[30:33], v[86:89], v[102:105], v[30:33]
	v_mfma_f32_16x16x32_bf16 v[26:29], v[94:97], v[102:105], v[26:29]
	v_mfma_f32_16x16x32_bf16 v[22:25], v[86:89], v[110:113], v[22:25]
	v_mfma_f32_16x16x32_bf16 v[18:21], v[94:97], v[110:113], v[18:21]
	v_mfma_f32_16x16x32_bf16 v[14:17], v[86:89], v[118:121], v[14:17]
	v_mfma_f32_16x16x32_bf16 v[10:13], v[94:97], v[118:121], v[10:13]
	v_mfma_f32_16x16x32_bf16 v[4:7], v[86:89], v[126:129], v[4:7]
	v_mfma_f32_16x16x32_bf16 v[0:3], v[94:97], v[126:129], v[0:3]
	s_barrier
	s_add_u32 s12, s16, 0x20000
	s_addc_u32 s13, s17, 0
	s_mov_b32 m0, s26
	v_lshl_add_u64 v[82:83], s[12:13], 0, v[70:71]
	global_load_lds_dwordx4 v[82:83], off
	s_mov_b32 m0, s27
	v_lshl_add_u64 v[82:83], s[12:13], 0, v[66:67]
	global_load_lds_dwordx4 v[82:83], off
	s_waitcnt vmcnt(6)
	s_barrier
	s_add_i32 s48, 0, 0x18000
	v_add_u32_e32 v81, s48, v79
	s_barrier
	ds_read_b128 v[82:85], v81
	ds_read_b128 v[86:89], v81 offset:1024
	ds_read_b128 v[90:93], v81 offset:2048
	ds_read_b128 v[94:97], v81 offset:3072
	s_add_u32 s12, s36, 0x28000
	s_addc_u32 s13, s37, 0
	s_mov_b32 m0, s38
	v_lshl_add_u64 v[138:139], s[12:13], 0, v[72:73]
	ds_read_b128 v[98:101], v80 offset:32768
	ds_read_b128 v[102:105], v80 offset:33792
	ds_read_b128 v[106:109], v80 offset:34816
	ds_read_b128 v[110:113], v80 offset:35840
	ds_read_b128 v[114:117], v80 offset:36864
	ds_read_b128 v[118:121], v80 offset:37888
	ds_read_b128 v[122:125], v80 offset:38912
	ds_read_b128 v[126:129], v80 offset:39936
	global_load_lds_dwordx4 v[138:139], off
	s_mov_b32 m0, s39
	v_lshl_add_u64 v[138:139], s[12:13], 0, v[68:69]
	global_load_lds_dwordx4 v[138:139], off
	s_waitcnt lgkmcnt(0)
	s_barrier
; #define PG8_STAGE(bufoff, gbase, voff) do { _Pragma("unroll") for (int _i = 0; _i < 2; ++_i) \
;         __builtin_amdgcn_global_load_lds((const unsigned*)((const char*)(gbase) + (voff)[_i]), (LAS unsigned*)(lds + (bufoff) + ldsw + _i * 8192), 16, 0, 0); } while (0)
; #define PG8_LDA(dst, b, h) do { _Pragma("unroll") for (int m = 0; m < 4; ++m) _Pragma("unroll") for (int k = 0; k < 2; ++k) dst[m][k] = *(const LAS bf16x8*)(lds + PG8_SA(b, h) + aoff + m * 2048 + k * 1024); } while (0)
; #define PG8_LDB(dst, b, h) do { _Pragma("unroll") for (int n = 0; n < 2; ++n) _Pragma("unroll") for (int k = 0; k < 2; ++k) dst[n][k] = *(const LAS bf16x8*)(lds + PG8_SB(b, h) + boff + n * 2048 + k * 1024); } while (0)
; #define PG8_MMA(ai, bj, At, Bt) do { __builtin_amdgcn_s_setprio(1); _Pragma("unroll") for (int m = 0; m < 4; ++m) _Pragma("unroll") for (int n = 0; n < 2; ++n) _Pragma("unroll") for (int k = 0; k < 2; ++k) \
;         acc[ai][bj][m][n] = __builtin_amdgcn_mfma_f32_16x16x32_bf16(Bt[n][k], At[m][k], acc[ai][bj][m][n], 0, 0, 0); __builtin_amdgcn_s_setprio(0); } while (0)
; #define PG8_WAIT_V(n) asm volatile("s_waitcnt vmcnt(" #n ")" ::: "memory")
; #define PG8_BAR __builtin_amdgcn_s_barrier()
; template <class Epi>
; DEVI void gemm_phase(LAS unsigned char* lds, const Gemm g, const Epi& E) {
;     ...
;             PG8_WAIT_L(8); PG8_BAR; PG8_WAIT_L(0); PG8_MMA(0, 0, At, B0); PG8_BAR; PG8_SCHED;
;             PG8_LDB(B1, 1, 1); PG8_STAGE(PG8_SB(1, 0), b3, voffB);
;             PG8_BAR; PG8_WAIT_L(0); PG8_MMA(0, 1, At, B1); PG8_BAR;
;             PG8_LDA(At, 1, 1); PG8_STAGE(PG8_SA(1, 0), a3, voffA);
;             PG8_BAR; PG8_WAIT_L(0); PG8_MMA(1, 0, At, B0); PG8_BAR; PG8_SCHED;
;             PG8_STAGE(PG8_SB(1, 1), b3 + hstepB, voffB);
;             PG8_WAIT_V(6); PG8_BAR; PG8_MMA(1, 1, At, B1); PG8_BAR;
;         }
;     ...
;                     for (int bj = 0; bj < 2; ++bj) {
;                         const int c = col0 + bj * HALF; f32x4 v0 = acc[ai][bj][m][0], v1 = acc[ai][bj][m][1];
;                         if constexpr (Epi::RS) { v0 = v0 * rs; v1 = v1 * rs; }
;                         if constexpr (Epi::PRE) part += E.frag_pre8(cur.b, r, c, v0, v1, pre[mm][bj][0], pre[mm][bj][1]);
;                         else if constexpr (Epi::PERM) E.frag8(cur.b, r, c, v0, v1);
;                         else { E.frag(cur.b, r, c, v0); E.frag(cur.b, r, c + 16, v1); }
	v_mfma_f32_16x16x32_bf16 v[62:65], v[82:85], v[98:101], v[62:65]
	v_mfma_f32_16x16x32_bf16 v[58:61], v[90:93], v[98:101], v[58:61]
	v_mfma_f32_16x16x32_bf16 v[54:57], v[82:85], v[106:109], v[54:57]
	v_mfma_f32_16x16x32_bf16 v[50:53], v[90:93], v[106:109], v[50:53]
	v_mfma_f32_16x16x32_bf16 v[46:49], v[82:85], v[114:117], v[46:49]
	v_mfma_f32_16x16x32_bf16 v[42:45], v[90:93], v[114:117], v[42:45]
	v_mfma_f32_16x16x32_bf16 v[38:41], v[82:85], v[122:125], v[38:41]
	v_mfma_f32_16x16x32_bf16 v[34:37], v[90:93], v[122:125], v[34:37]
	v_mfma_f32_16x16x32_bf16 v[62:65], v[86:89], v[102:105], v[62:65]
	v_mfma_f32_16x16x32_bf16 v[58:61], v[94:97], v[102:105], v[58:61]
	v_mfma_f32_16x16x32_bf16 v[54:57], v[86:89], v[110:113], v[54:57]
	v_mfma_f32_16x16x32_bf16 v[50:53], v[94:97], v[110:113], v[50:53]
	v_mfma_f32_16x16x32_bf16 v[46:49], v[86:89], v[118:121], v[46:49]
	v_mfma_f32_16x16x32_bf16 v[42:45], v[94:97], v[118:121], v[42:45]
	v_mfma_f32_16x16x32_bf16 v[38:41], v[86:89], v[126:129], v[38:41]
	v_mfma_f32_16x16x32_bf16 v[34:37], v[94:97], v[126:129], v[34:37]
	s_barrier
	s_add_i32 s12, s48, s1
	s_mov_b32 m0, s12
	v_lshl_add_u64 v[98:99], v[130:131], 0, s[70:71]
	global_load_lds_dwordx4 v[98:99], off
	s_add_i32 m0, s12, 0x2000
	v_lshl_add_u64 v[98:99], v[132:133], 0, s[70:71]
	global_load_lds_dwordx4 v[98:99], off
	s_barrier
	s_waitcnt lgkmcnt(0)
	s_mov_b32 m0, s41
	v_lshl_add_u64 v[130:131], v[134:135], 0, s[70:71]
	s_barrier
	ds_read_b128 v[98:101], v80 offset:49152
	ds_read_b128 v[102:105], v80 offset:50176
	ds_read_b128 v[106:109], v80 offset:51200
	ds_read_b128 v[110:113], v80 offset:52224
	ds_read_b128 v[114:117], v80 offset:53248
	ds_read_b128 v[118:121], v80 offset:54272
	ds_read_b128 v[122:125], v80 offset:55296
	ds_read_b128 v[126:129], v80 offset:56320
	global_load_lds_dwordx4 v[130:131], off
	s_mov_b32 m0, s42
	v_lshl_add_u64 v[130:131], v[136:137], 0, s[70:71]
	global_load_lds_dwordx4 v[130:131], off
	s_waitcnt lgkmcnt(0)
	s_barrier
	v_mfma_f32_16x16x32_bf16 v[30:33], v[82:85], v[98:101], v[30:33]
	v_mfma_f32_16x16x32_bf16 v[26:29], v[90:93], v[98:101], v[26:29]
	v_mfma_f32_16x16x32_bf16 v[22:25], v[82:85], v[106:109], v[22:25]
	v_mfma_f32_16x16x32_bf16 v[18:21], v[90:93], v[106:109], v[18:21]
	v_mfma_f32_16x16x32_bf16 v[14:17], v[82:85], v[114:117], v[14:17]
	v_mfma_f32_16x16x32_bf16 v[10:13], v[90:93], v[114:117], v[10:13]
	v_mfma_f32_16x16x32_bf16 v[4:7], v[82:85], v[122:125], v[4:7]
	v_mfma_f32_16x16x32_bf16 v[0:3], v[90:93], v[122:125], v[0:3]
	v_mfma_f32_16x16x32_bf16 v[30:33], v[86:89], v[102:105], v[30:33]
	v_mfma_f32_16x16x32_bf16 v[26:29], v[94:97], v[102:105], v[26:29]
	v_mfma_f32_16x16x32_bf16 v[22:25], v[86:89], v[110:113], v[22:25]
	v_mfma_f32_16x16x32_bf16 v[18:21], v[94:97], v[110:113], v[18:21]
	v_mfma_f32_16x16x32_bf16 v[14:17], v[86:89], v[118:121], v[14:17]
	v_mfma_f32_16x16x32_bf16 v[10:13], v[94:97], v[118:121], v[10:13]
	v_mfma_f32_16x16x32_bf16 v[4:7], v[86:89], v[126:129], v[4:7]
	v_mfma_f32_16x16x32_bf16 v[0:3], v[94:97], v[126:129], v[0:3]
	s_barrier
	s_add_u32 s12, s16, 0x20080
	s_addc_u32 s13, s17, 0
	s_mov_b32 m0, s43
	v_lshl_add_u64 v[82:83], s[12:13], 0, v[70:71]
	global_load_lds_dwordx4 v[82:83], off
	s_mov_b32 m0, s44
	v_lshl_add_u64 v[82:83], s[12:13], 0, v[66:67]
	global_load_lds_dwordx4 v[82:83], off
	s_waitcnt vmcnt(6)
	s_barrier
	s_add_i32 s47, s47, 2
	s_add_u32 s5, s5, 0x100
	s_addc_u32 s7, s7, 0
	s_cmp_gt_u32 s47, 5
	s_mov_b64 s[12:13], s[14:15]
	s_barrier
	s_cbranch_scc0 .LBB0_1127
	s_setprio 0
	s_ashr_i32 s5, s4, 31
	v_lshl_add_u32 v82, s40, 8, v78
	s_lshl_b64 s[4:5], s[4:5], 19
	v_readlane_b32 s7, v253, 50
	s_add_u32 s4, s7, s4
	v_readlane_b32 s7, v253, 51
	v_ashrrev_i32_e32 v83, 31, v82
	s_addc_u32 s5, s7, s5
	v_lshlrev_b64 v[84:85], 9, v[82:83]
	v_lshl_add_u64 v[84:85], s[4:5], 0, v[84:85]
	v_lshl_add_u64 v[84:85], v[84:85], 0, v[8:9]
	global_store_dwordx4 v[84:85], v[62:65], off
	global_store_dwordx4 v[84:85], v[58:61], off offset:64
	s_mov_b32 s40, s46
	s_mov_b64 s[14:15], s[10:11]
	v_or_b32_e32 v58, 16, v82
	v_ashrrev_i32_e32 v59, 31, v58
	v_lshlrev_b64 v[58:59], 9, v[58:59]
	v_lshl_add_u64 v[58:59], s[4:5], 0, v[58:59]
	v_lshl_add_u64 v[58:59], v[58:59], 0, v[8:9]
	global_store_dwordx4 v[58:59], v[54:57], off
	global_store_dwordx4 v[58:59], v[50:53], off offset:64
	s_mov_b64 s[12:13], s[8:9]
	s_nop 0
	v_or_b32_e32 v50, 32, v82
	v_ashrrev_i32_e32 v51, 31, v50
	v_lshlrev_b64 v[50:51], 9, v[50:51]
	v_lshl_add_u64 v[50:51], s[4:5], 0, v[50:51]
	v_lshl_add_u64 v[50:51], v[50:51], 0, v[8:9]
	global_store_dwordx4 v[50:51], v[46:49], off
	global_store_dwordx4 v[50:51], v[42:45], off offset:64
	s_nop 1
	v_or_b32_e32 v42, 48, v82
	v_ashrrev_i32_e32 v43, 31, v42
	v_lshlrev_b64 v[42:43], 9, v[42:43]
	v_lshl_add_u64 v[42:43], s[4:5], 0, v[42:43]
	v_lshl_add_u64 v[42:43], v[42:43], 0, v[8:9]
	s_mov_b64 s[4:5], 0x10000
	global_store_dwordx4 v[42:43], v[38:41], off
	global_store_dwordx4 v[42:43], v[34:37], off offset:64
	s_nop 1
	v_lshl_add_u64 v[34:35], v[84:85], 0, s[4:5]
	s_mov_b32 s4, 0x10000
	v_add_co_u32_e32 v36, vcc, s4, v84
	s_mov_b64 s[4:5], 0x12000
	s_nop 0
	v_addc_co_u32_e32 v37, vcc, 0, v85, vcc
	global_store_dwordx4 v[36:37], v[30:33], off
	global_store_dwordx4 v[34:35], v[26:29], off offset:64
	s_nop 1
	v_lshl_add_u64 v[26:27], v[84:85], 0, s[4:5]
	s_mov_b32 s4, 0x12000
	v_add_co_u32_e32 v28, vcc, s4, v84
	s_mov_b64 s[4:5], 0x14000
	s_nop 0
	v_addc_co_u32_e32 v29, vcc, 0, v85, vcc
	global_store_dwordx4 v[28:29], v[22:25], off
	global_store_dwordx4 v[26:27], v[18:21], off offset:64
	s_nop 1
	v_add_co_u32_e32 v20, vcc, 0x14000, v84
	v_lshl_add_u64 v[18:19], v[84:85], 0, s[4:5]
	s_nop 0
	v_addc_co_u32_e32 v21, vcc, 0, v85, vcc
	global_store_dwordx4 v[20:21], v[14:17], off
	global_store_dwordx4 v[18:19], v[10:13], off offset:64
	s_mov_b64 s[4:5], 0x16000
	s_nop 0
	v_add_co_u32_e32 v12, vcc, 0x16000, v84
	v_lshl_add_u64 v[10:11], v[84:85], 0, s[4:5]
	s_nop 0
	v_addc_co_u32_e32 v13, vcc, 0, v85, vcc
	s_and_b64 vcc, exec, s[2:3]
	s_mov_b32 s4, s6
	global_store_dwordx4 v[12:13], v[4:7], off
	global_store_dwordx4 v[10:11], v[0:3], off offset:64
	s_cbranch_vccz .LBB0_1122
	s_branch .LBB0_1131

; #define PG8_STAGE(bufoff, gbase, voff) do { _Pragma("unroll") for (int _i = 0; _i < 2; ++_i) \
;         __builtin_amdgcn_global_load_lds((const unsigned*)((const char*)(gbase) + (voff)[_i]), (LAS unsigned*)(lds + (bufoff) + ldsw + _i * 8192), 16, 0, 0); } while (0)
; #define PG8_LDA(dst, b, h) do { _Pragma("unroll") for (int m = 0; m < 4; ++m) _Pragma("unroll") for (int k = 0; k < 2; ++k) dst[m][k] = *(const LAS bf16x8*)(lds + PG8_SA(b, h) + aoff + m * 2048 + k * 1024); } while (0)
; #define PG8_LDB(dst, b, h) do { _Pragma("unroll") for (int n = 0; n < 2; ++n) _Pragma("unroll") for (int k = 0; k < 2; ++k) dst[n][k] = *(const LAS bf16x8*)(lds + PG8_SB(b, h) + boff + n * 2048 + k * 1024); } while (0)
; #define PG8_MMA(ai, bj, At, Bt) do { __builtin_amdgcn_s_setprio(1); _Pragma("unroll") for (int m = 0; m < 4; ++m) _Pragma("unroll") for (int n = 0; n < 2; ++n) _Pragma("unroll") for (int k = 0; k < 2; ++k) \
;         acc[ai][bj][m][n] = __builtin_amdgcn_mfma_f32_16x16x32_bf16(Bt[n][k], At[m][k], acc[ai][bj][m][n], 0, 0, 0); __builtin_amdgcn_s_setprio(0); } while (0)
; #define PG8_WAIT_V(n) asm volatile("s_waitcnt vmcnt(" #n ")" ::: "memory")
; #define PG8_WAIT_L(n) asm volatile("s_waitcnt lgkmcnt(" #n ")" ::: "memory")
; #define PG8_BAR __builtin_amdgcn_s_barrier()
; #define PG8_SCHED __builtin_amdgcn_sched_barrier(0)
; template <class Epi>
; DEVI void gemm_phase(LAS unsigned char* lds, const Gemm g, const Epi& E) {
;     ...
;             PG8_LDB(B0, 0, 0); PG8_SCHED; PG8_LDA(At, 0, 0); PG8_STAGE(PG8_SA(1, 1), a1 + hstepA, voffA);
;             PG8_WAIT_L(8); PG8_BAR; PG8_WAIT_L(0); PG8_MMA(0, 0, At, B0); PG8_BAR; PG8_SCHED;
;             PG8_LDB(B1, 0, 1); PG8_STAGE(PG8_SB(0, 0), b2, voffB);
;             PG8_BAR; PG8_WAIT_L(0); PG8_MMA(0, 1, At, B1); PG8_BAR;
;             PG8_LDA(At, 0, 1); PG8_STAGE(PG8_SA(0, 0), a2, voffA);
;             PG8_BAR; PG8_WAIT_L(0); PG8_MMA(1, 0, At, B0); PG8_BAR; PG8_SCHED;
;             PG8_STAGE(PG8_SB(0, 1), b2 + hstepB, voffB);
;             PG8_WAIT_V(6); PG8_BAR; PG8_MMA(1, 1, At, B1); PG8_BAR;
.LBB0_1278:
	s_add_u32 s12, s10, 0x100
	s_addc_u32 s13, s11, 0
	s_add_i32 s38, 0, 0x10000
	v_add_u32_e32 v146, s38, v149
	ds_read_b128 v[142:145], v146
	ds_read_b128 v[176:179], v146 offset:1024
	ds_read_b128 v[180:183], v146 offset:2048
	ds_read_b128 v[184:187], v146 offset:3072
	s_cmp_eq_u32 s27, 6
	s_cselect_b32 s17, s5, s13
	s_cselect_b32 s16, s4, s12
	s_cselect_b32 s15, s7, s26
	s_cselect_b32 s14, s6, s19
	v_lshl_add_u64 v[146:147], s[10:11], 0, v[138:139]
	s_add_i32 m0, s46, 0xc000
	ds_read_b128 v[188:191], v151
	ds_read_b128 v[192:195], v151 offset:1024
	ds_read_b128 v[196:199], v151 offset:2048
	ds_read_b128 v[200:203], v151 offset:3072
	ds_read_b128 v[204:207], v151 offset:4096
	ds_read_b128 v[214:217], v151 offset:5120
	ds_read_b128 v[218:221], v151 offset:6144
	ds_read_b128 v[222:225], v151 offset:7168
	global_load_lds_dwordx4 v[146:147], off
	s_add_i32 m0, s46, 0xe000
	v_lshl_add_u64 v[146:147], s[10:11], 0, v[140:141]
	global_load_lds_dwordx4 v[146:147], off
	s_waitcnt lgkmcnt(0)
	s_barrier
	v_mfma_f32_16x16x32_bf16 v[126:129], v[142:145], v[188:191], v[126:129]
	v_mfma_f32_16x16x32_bf16 v[122:125], v[180:183], v[188:191], v[122:125]
	v_mfma_f32_16x16x32_bf16 v[110:113], v[142:145], v[196:199], v[110:113]
	v_mfma_f32_16x16x32_bf16 v[106:109], v[180:183], v[196:199], v[106:109]
	v_mfma_f32_16x16x32_bf16 v[94:97], v[142:145], v[204:207], v[94:97]
	v_mfma_f32_16x16x32_bf16 v[90:93], v[180:183], v[204:207], v[90:93]
	v_mfma_f32_16x16x32_bf16 v[78:81], v[142:145], v[218:221], v[78:81]
	v_mfma_f32_16x16x32_bf16 v[74:77], v[180:183], v[218:221], v[74:77]
	v_mfma_f32_16x16x32_bf16 v[126:129], v[176:179], v[192:195], v[126:129]
	v_mfma_f32_16x16x32_bf16 v[122:125], v[184:187], v[192:195], v[122:125]
	v_mfma_f32_16x16x32_bf16 v[110:113], v[176:179], v[200:203], v[110:113]
	v_mfma_f32_16x16x32_bf16 v[106:109], v[184:187], v[200:203], v[106:109]
	v_mfma_f32_16x16x32_bf16 v[94:97], v[176:179], v[214:217], v[94:97]
	v_mfma_f32_16x16x32_bf16 v[90:93], v[184:187], v[214:217], v[90:93]
	v_mfma_f32_16x16x32_bf16 v[78:81], v[176:179], v[222:225], v[78:81]
	v_mfma_f32_16x16x32_bf16 v[74:77], v[184:187], v[222:225], v[74:77]
	s_barrier
	s_add_i32 s39, 0, 0x14000
	v_add_u32_e32 v146, s39, v149
	s_add_i32 s10, s38, s37
	ds_read_b128 v[226:229], v146
	ds_read_b128 v[230:233], v146 offset:1024
	ds_read_b128 v[234:237], v146 offset:2048
	ds_read_b128 v[238:241], v146 offset:3072
	v_lshl_add_u64 v[146:147], s[14:15], 0, v[8:9]
	s_mov_b32 m0, s10
	v_lshl_add_u64 v[152:153], s[14:15], 0, v[130:131]
	global_load_lds_dwordx4 v[146:147], off
	s_add_i32 m0, s10, 0x2000
	s_nop 0
	global_load_lds_dwordx4 v[152:153], off
	s_waitcnt lgkmcnt(0)
	s_barrier
	v_mfma_f32_16x16x32_bf16 v[118:121], v[226:229], v[188:191], v[118:121]
	v_mfma_f32_16x16x32_bf16 v[114:117], v[234:237], v[188:191], v[114:117]
	v_mfma_f32_16x16x32_bf16 v[102:105], v[226:229], v[196:199], v[102:105]
	v_mfma_f32_16x16x32_bf16 v[98:101], v[234:237], v[196:199], v[98:101]
	v_mfma_f32_16x16x32_bf16 v[86:89], v[226:229], v[204:207], v[86:89]
	v_mfma_f32_16x16x32_bf16 v[82:85], v[234:237], v[204:207], v[82:85]
	v_mfma_f32_16x16x32_bf16 v[70:73], v[226:229], v[218:221], v[70:73]
	v_mfma_f32_16x16x32_bf16 v[66:69], v[234:237], v[218:221], v[66:69]
	v_mfma_f32_16x16x32_bf16 v[118:121], v[230:233], v[192:195], v[118:121]
	v_mfma_f32_16x16x32_bf16 v[114:117], v[238:241], v[192:195], v[114:117]
	v_mfma_f32_16x16x32_bf16 v[102:105], v[230:233], v[200:203], v[102:105]
	v_mfma_f32_16x16x32_bf16 v[98:101], v[238:241], v[200:203], v[98:101]
	v_mfma_f32_16x16x32_bf16 v[86:89], v[230:233], v[214:217], v[86:89]
	v_mfma_f32_16x16x32_bf16 v[82:85], v[238:241], v[214:217], v[82:85]
	v_mfma_f32_16x16x32_bf16 v[70:73], v[230:233], v[222:225], v[70:73]
	v_mfma_f32_16x16x32_bf16 v[66:69], v[238:241], v[222:225], v[66:69]
	s_mov_b32 m0, s46
	v_lshl_add_u64 v[162:163], s[16:17], 0, v[134:135]
	s_barrier
	ds_read_b128 v[188:191], v151 offset:16384
	ds_read_b128 v[192:195], v151 offset:17408
	ds_read_b128 v[196:199], v151 offset:18432
	ds_read_b128 v[200:203], v151 offset:19456
	ds_read_b128 v[204:207], v151 offset:20480
	ds_read_b128 v[214:217], v151 offset:21504
	ds_read_b128 v[218:221], v151 offset:22528
	ds_read_b128 v[222:225], v151 offset:23552
	global_load_lds_dwordx4 v[162:163], off
	s_mov_b32 m0, s47
	v_lshl_add_u64 v[164:165], s[16:17], 0, v[132:133]
	global_load_lds_dwordx4 v[164:165], off
	s_waitcnt lgkmcnt(0)
	s_barrier
	v_mfma_f32_16x16x32_bf16 v[62:65], v[142:145], v[188:191], v[62:65]
	v_mfma_f32_16x16x32_bf16 v[58:61], v[180:183], v[188:191], v[58:61]
	v_mfma_f32_16x16x32_bf16 v[46:49], v[142:145], v[196:199], v[46:49]
	v_mfma_f32_16x16x32_bf16 v[42:45], v[180:183], v[196:199], v[42:45]
	v_mfma_f32_16x16x32_bf16 v[30:33], v[142:145], v[204:207], v[30:33]
	v_mfma_f32_16x16x32_bf16 v[26:29], v[180:183], v[204:207], v[26:29]
	v_mfma_f32_16x16x32_bf16 v[14:17], v[142:145], v[218:221], v[14:17]
	v_mfma_f32_16x16x32_bf16 v[10:13], v[180:183], v[218:221], v[10:13]
	v_mfma_f32_16x16x32_bf16 v[62:65], v[176:179], v[192:195], v[62:65]
	v_mfma_f32_16x16x32_bf16 v[58:61], v[184:187], v[192:195], v[58:61]
	v_mfma_f32_16x16x32_bf16 v[46:49], v[176:179], v[200:203], v[46:49]
	v_mfma_f32_16x16x32_bf16 v[42:45], v[184:187], v[200:203], v[42:45]
	v_mfma_f32_16x16x32_bf16 v[30:33], v[176:179], v[214:217], v[30:33]
	v_mfma_f32_16x16x32_bf16 v[26:29], v[184:187], v[214:217], v[26:29]
	v_mfma_f32_16x16x32_bf16 v[14:17], v[176:179], v[222:225], v[14:17]
	v_mfma_f32_16x16x32_bf16 v[10:13], v[184:187], v[222:225], v[10:13]
	s_barrier
; #define PG8_STAGE(bufoff, gbase, voff) do { _Pragma("unroll") for (int _i = 0; _i < 2; ++_i) \
;         __builtin_amdgcn_global_load_lds((const unsigned*)((const char*)(gbase) + (voff)[_i]), (LAS unsigned*)(lds + (bufoff) + ldsw + _i * 8192), 16, 0, 0); } while (0)
; #define PG8_LDA(dst, b, h) do { _Pragma("unroll") for (int m = 0; m < 4; ++m) _Pragma("unroll") for (int k = 0; k < 2; ++k) dst[m][k] = *(const LAS bf16x8*)(lds + PG8_SA(b, h) + aoff + m * 2048 + k * 1024); } while (0)
; #define PG8_LDB(dst, b, h) do { _Pragma("unroll") for (int n = 0; n < 2; ++n) _Pragma("unroll") for (int k = 0; k < 2; ++k) dst[n][k] = *(const LAS bf16x8*)(lds + PG8_SB(b, h) + boff + n * 2048 + k * 1024); } while (0)
; #define PG8_MMA(ai, bj, At, Bt) do { __builtin_amdgcn_s_setprio(1); _Pragma("unroll") for (int m = 0; m < 4; ++m) _Pragma("unroll") for (int n = 0; n < 2; ++n) _Pragma("unroll") for (int k = 0; k < 2; ++k) \
;         acc[ai][bj][m][n] = __builtin_amdgcn_mfma_f32_16x16x32_bf16(Bt[n][k], At[m][k], acc[ai][bj][m][n], 0, 0, 0); __builtin_amdgcn_s_setprio(0); } while (0)
; #define PG8_WAIT_V(n) asm volatile("s_waitcnt vmcnt(" #n ")" ::: "memory")
; #define PG8_WAIT_L(n) asm volatile("s_waitcnt lgkmcnt(" #n ")" ::: "memory")
; #define PG8_BAR __builtin_amdgcn_s_barrier()
; #define PG8_SCHED __builtin_amdgcn_sched_barrier(0)
; template <class Epi>
; DEVI void gemm_phase(LAS unsigned char* lds, const Gemm g, const Epi& E) {
;     ...
;             PG8_WAIT_V(6); PG8_BAR; PG8_MMA(1, 1, At, B1); PG8_BAR;
;             PG8_LDB(B0, 1, 0); PG8_SCHED; PG8_LDA(At, 1, 0); PG8_STAGE(PG8_SA(0, 1), a2 + hstepA, voffA);
;             PG8_WAIT_L(8); PG8_BAR; PG8_WAIT_L(0); PG8_MMA(0, 0, At, B0); PG8_BAR; PG8_SCHED;
;             PG8_LDB(B1, 1, 1); PG8_STAGE(PG8_SB(1, 0), b3, voffB);
;             PG8_BAR; PG8_WAIT_L(0); PG8_MMA(0, 1, At, B1); PG8_BAR;
;             PG8_LDA(At, 1, 1); PG8_STAGE(PG8_SA(1, 0), a3, voffA);
;             PG8_BAR; PG8_WAIT_L(0); PG8_MMA(1, 0, At, B0); PG8_BAR; PG8_SCHED;
	s_add_u32 s10, s14, 0x28000
	s_addc_u32 s11, s15, 0
	s_add_i32 s38, s39, s37
	s_mov_b32 m0, s38
	v_lshl_add_u64 v[142:143], s[10:11], 0, v[8:9]
	global_load_lds_dwordx4 v[142:143], off
	s_add_i32 m0, s38, 0x2000
	v_lshl_add_u64 v[142:143], s[10:11], 0, v[130:131]
	global_load_lds_dwordx4 v[142:143], off
	s_waitcnt vmcnt(6)
	s_barrier
	v_mfma_f32_16x16x32_bf16 v[54:57], v[226:229], v[188:191], v[54:57]
	v_mfma_f32_16x16x32_bf16 v[50:53], v[234:237], v[188:191], v[50:53]
	v_mfma_f32_16x16x32_bf16 v[38:41], v[226:229], v[196:199], v[38:41]
	v_mfma_f32_16x16x32_bf16 v[34:37], v[234:237], v[196:199], v[34:37]
	v_mfma_f32_16x16x32_bf16 v[22:25], v[226:229], v[204:207], v[22:25]
	v_mfma_f32_16x16x32_bf16 v[18:21], v[234:237], v[204:207], v[18:21]
	v_mfma_f32_16x16x32_bf16 v[4:7], v[226:229], v[218:221], v[4:7]
	v_mfma_f32_16x16x32_bf16 v[0:3], v[234:237], v[218:221], v[0:3]
	v_mfma_f32_16x16x32_bf16 v[54:57], v[230:233], v[192:195], v[54:57]
	v_mfma_f32_16x16x32_bf16 v[50:53], v[238:241], v[192:195], v[50:53]
	v_mfma_f32_16x16x32_bf16 v[38:41], v[230:233], v[200:203], v[38:41]
	v_mfma_f32_16x16x32_bf16 v[34:37], v[238:241], v[200:203], v[34:37]
	v_mfma_f32_16x16x32_bf16 v[22:25], v[230:233], v[214:217], v[22:25]
	v_mfma_f32_16x16x32_bf16 v[18:21], v[238:241], v[214:217], v[18:21]
	v_mfma_f32_16x16x32_bf16 v[4:7], v[230:233], v[222:225], v[4:7]
	v_mfma_f32_16x16x32_bf16 v[0:3], v[238:241], v[222:225], v[0:3]
	s_add_i32 s38, 0, 0x18000
	v_add_u32_e32 v184, s38, v149
	s_barrier
	ds_read_b128 v[142:145], v184
	ds_read_b128 v[176:179], v184 offset:1024
	ds_read_b128 v[180:183], v184 offset:2048
	ds_read_b128 v[184:187], v184 offset:3072
	s_add_u32 s10, s16, 0x28000
	s_addc_u32 s11, s17, 0
	s_mov_b32 m0, s66
	v_lshl_add_u64 v[208:209], s[10:11], 0, v[134:135]
	ds_read_b128 v[188:191], v151 offset:32768
	ds_read_b128 v[192:195], v151 offset:33792
	ds_read_b128 v[196:199], v151 offset:34816
	ds_read_b128 v[200:203], v151 offset:35840
	ds_read_b128 v[204:207], v151 offset:36864
	ds_read_b128 v[214:217], v151 offset:37888
	ds_read_b128 v[218:221], v151 offset:38912
	ds_read_b128 v[222:225], v151 offset:39936
	global_load_lds_dwordx4 v[208:209], off
	s_mov_b32 m0, s68
	v_lshl_add_u64 v[208:209], s[10:11], 0, v[132:133]
	global_load_lds_dwordx4 v[208:209], off
	s_waitcnt lgkmcnt(0)
	s_barrier
	v_mfma_f32_16x16x32_bf16 v[126:129], v[142:145], v[188:191], v[126:129]
	v_mfma_f32_16x16x32_bf16 v[122:125], v[180:183], v[188:191], v[122:125]
	v_mfma_f32_16x16x32_bf16 v[110:113], v[142:145], v[196:199], v[110:113]
	v_mfma_f32_16x16x32_bf16 v[106:109], v[180:183], v[196:199], v[106:109]
	v_mfma_f32_16x16x32_bf16 v[94:97], v[142:145], v[204:207], v[94:97]
	v_mfma_f32_16x16x32_bf16 v[90:93], v[180:183], v[204:207], v[90:93]
	v_mfma_f32_16x16x32_bf16 v[78:81], v[142:145], v[218:221], v[78:81]
	v_mfma_f32_16x16x32_bf16 v[74:77], v[180:183], v[218:221], v[74:77]
	v_mfma_f32_16x16x32_bf16 v[126:129], v[176:179], v[192:195], v[126:129]
	v_mfma_f32_16x16x32_bf16 v[122:125], v[184:187], v[192:195], v[122:125]
	v_mfma_f32_16x16x32_bf16 v[110:113], v[176:179], v[200:203], v[110:113]
	v_mfma_f32_16x16x32_bf16 v[106:109], v[184:187], v[200:203], v[106:109]
	v_mfma_f32_16x16x32_bf16 v[94:97], v[176:179], v[214:217], v[94:97]
	v_mfma_f32_16x16x32_bf16 v[90:93], v[184:187], v[214:217], v[90:93]
	v_mfma_f32_16x16x32_bf16 v[78:81], v[176:179], v[222:225], v[78:81]
	v_mfma_f32_16x16x32_bf16 v[74:77], v[184:187], v[222:225], v[74:77]
	s_barrier
	s_add_i32 s16, 0, 0x1c000
	s_add_i32 s10, s38, s37
	v_add_u32_e32 v208, s16, v149
	v_lshl_add_u64 v[146:147], v[146:147], 0, s[70:71]
	s_mov_b32 m0, s10
	ds_read_b128 v[226:229], v208
	ds_read_b128 v[230:233], v208 offset:1024
	ds_read_b128 v[234:237], v208 offset:2048
	ds_read_b128 v[238:241], v208 offset:3072
	global_load_lds_dwordx4 v[146:147], off
	s_add_i32 m0, s10, 0x2000
	v_lshl_add_u64 v[146:147], v[152:153], 0, s[70:71]
	global_load_lds_dwordx4 v[146:147], off
	s_waitcnt lgkmcnt(0)
	s_barrier
	v_mfma_f32_16x16x32_bf16 v[118:121], v[226:229], v[188:191], v[118:121]
	v_mfma_f32_16x16x32_bf16 v[114:117], v[234:237], v[188:191], v[114:117]
	v_mfma_f32_16x16x32_bf16 v[102:105], v[226:229], v[196:199], v[102:105]
	v_mfma_f32_16x16x32_bf16 v[98:101], v[234:237], v[196:199], v[98:101]
	v_mfma_f32_16x16x32_bf16 v[86:89], v[226:229], v[204:207], v[86:89]
	v_mfma_f32_16x16x32_bf16 v[82:85], v[234:237], v[204:207], v[82:85]
	v_mfma_f32_16x16x32_bf16 v[70:73], v[226:229], v[218:221], v[70:73]
	v_mfma_f32_16x16x32_bf16 v[66:69], v[234:237], v[218:221], v[66:69]
	v_mfma_f32_16x16x32_bf16 v[118:121], v[230:233], v[192:195], v[118:121]
	v_mfma_f32_16x16x32_bf16 v[114:117], v[238:241], v[192:195], v[114:117]
	v_mfma_f32_16x16x32_bf16 v[102:105], v[230:233], v[200:203], v[102:105]
	v_mfma_f32_16x16x32_bf16 v[98:101], v[238:241], v[200:203], v[98:101]
	v_mfma_f32_16x16x32_bf16 v[86:89], v[230:233], v[214:217], v[86:89]
	v_mfma_f32_16x16x32_bf16 v[82:85], v[238:241], v[214:217], v[82:85]
	v_mfma_f32_16x16x32_bf16 v[70:73], v[230:233], v[222:225], v[70:73]
	v_mfma_f32_16x16x32_bf16 v[66:69], v[238:241], v[222:225], v[66:69]
	s_mov_b32 m0, s69
	v_lshl_add_u64 v[146:147], v[162:163], 0, s[70:71]
	s_barrier
	ds_read_b128 v[188:191], v151 offset:49152
	ds_read_b128 v[192:195], v151 offset:50176
	ds_read_b128 v[196:199], v151 offset:51200
	ds_read_b128 v[200:203], v151 offset:52224
	ds_read_b128 v[204:207], v151 offset:53248
	ds_read_b128 v[214:217], v151 offset:54272
	ds_read_b128 v[218:221], v151 offset:55296
	ds_read_b128 v[222:225], v151 offset:56320
	global_load_lds_dwordx4 v[146:147], off
	s_mov_b32 m0, s80
	v_lshl_add_u64 v[146:147], v[164:165], 0, s[70:71]
	global_load_lds_dwordx4 v[146:147], off
	s_waitcnt lgkmcnt(0)
	s_barrier
; #define PG8_STAGE(bufoff, gbase, voff) do { _Pragma("unroll") for (int _i = 0; _i < 2; ++_i) \
;         __builtin_amdgcn_global_load_lds((const unsigned*)((const char*)(gbase) + (voff)[_i]), (LAS unsigned*)(lds + (bufoff) + ldsw + _i * 8192), 16, 0, 0); } while (0)
; #define PG8_MMA(ai, bj, At, Bt) do { __builtin_amdgcn_s_setprio(1); _Pragma("unroll") for (int m = 0; m < 4; ++m) _Pragma("unroll") for (int n = 0; n < 2; ++n) _Pragma("unroll") for (int k = 0; k < 2; ++k) \
;         acc[ai][bj][m][n] = __builtin_amdgcn_mfma_f32_16x16x32_bf16(Bt[n][k], At[m][k], acc[ai][bj][m][n], 0, 0, 0); __builtin_amdgcn_s_setprio(0); } while (0)
; #define PG8_WAIT_V(n) asm volatile("s_waitcnt vmcnt(" #n ")" ::: "memory")
; #define PG8_WAIT_L(n) asm volatile("s_waitcnt lgkmcnt(" #n ")" ::: "memory")
; #define PG8_BAR __builtin_amdgcn_s_barrier()
; #define PG8_SCHED __builtin_amdgcn_sched_barrier(0)
; template <class Epi>
; DEVI void gemm_phase(LAS unsigned char* lds, const Gemm g, const Epi& E) {
;     ...
;             PG8_BAR; PG8_WAIT_L(0); PG8_MMA(1, 0, At, B0); PG8_BAR; PG8_SCHED;
;             PG8_STAGE(PG8_SB(1, 1), b3 + hstepB, voffB);
;             PG8_WAIT_V(6); PG8_BAR; PG8_MMA(1, 1, At, B1); PG8_BAR;
;         }
	v_mfma_f32_16x16x32_bf16 v[62:65], v[142:145], v[188:191], v[62:65]
	v_mfma_f32_16x16x32_bf16 v[58:61], v[180:183], v[188:191], v[58:61]
	v_mfma_f32_16x16x32_bf16 v[46:49], v[142:145], v[196:199], v[46:49]
	v_mfma_f32_16x16x32_bf16 v[42:45], v[180:183], v[196:199], v[42:45]
	v_mfma_f32_16x16x32_bf16 v[30:33], v[142:145], v[204:207], v[30:33]
	v_mfma_f32_16x16x32_bf16 v[26:29], v[180:183], v[204:207], v[26:29]
	v_mfma_f32_16x16x32_bf16 v[14:17], v[142:145], v[218:221], v[14:17]
	v_mfma_f32_16x16x32_bf16 v[10:13], v[180:183], v[218:221], v[10:13]
	v_mfma_f32_16x16x32_bf16 v[62:65], v[176:179], v[192:195], v[62:65]
	v_mfma_f32_16x16x32_bf16 v[58:61], v[184:187], v[192:195], v[58:61]
	v_mfma_f32_16x16x32_bf16 v[46:49], v[176:179], v[200:203], v[46:49]
	v_mfma_f32_16x16x32_bf16 v[42:45], v[184:187], v[200:203], v[42:45]
	v_mfma_f32_16x16x32_bf16 v[30:33], v[176:179], v[214:217], v[30:33]
	v_mfma_f32_16x16x32_bf16 v[26:29], v[184:187], v[214:217], v[26:29]
	v_mfma_f32_16x16x32_bf16 v[14:17], v[176:179], v[222:225], v[14:17]
	v_mfma_f32_16x16x32_bf16 v[10:13], v[184:187], v[222:225], v[10:13]
	s_barrier
	s_add_u32 s10, s14, 0x28080
	s_addc_u32 s11, s15, 0
	s_add_i32 s14, s16, s37
	s_mov_b32 m0, s14
	v_lshl_add_u64 v[142:143], s[10:11], 0, v[8:9]
	global_load_lds_dwordx4 v[142:143], off
	s_add_i32 m0, s14, 0x2000
	v_lshl_add_u64 v[142:143], s[10:11], 0, v[130:131]
	global_load_lds_dwordx4 v[142:143], off
	s_waitcnt vmcnt(6)
	s_barrier
	v_mfma_f32_16x16x32_bf16 v[54:57], v[226:229], v[188:191], v[54:57]
	v_mfma_f32_16x16x32_bf16 v[50:53], v[234:237], v[188:191], v[50:53]
	v_mfma_f32_16x16x32_bf16 v[38:41], v[226:229], v[196:199], v[38:41]
	v_mfma_f32_16x16x32_bf16 v[34:37], v[234:237], v[196:199], v[34:37]
	v_mfma_f32_16x16x32_bf16 v[22:25], v[226:229], v[204:207], v[22:25]
	v_mfma_f32_16x16x32_bf16 v[18:21], v[234:237], v[204:207], v[18:21]
	v_mfma_f32_16x16x32_bf16 v[4:7], v[226:229], v[218:221], v[4:7]
	v_mfma_f32_16x16x32_bf16 v[0:3], v[234:237], v[218:221], v[0:3]
	v_mfma_f32_16x16x32_bf16 v[54:57], v[230:233], v[192:195], v[54:57]
	v_mfma_f32_16x16x32_bf16 v[50:53], v[238:241], v[192:195], v[50:53]
	v_mfma_f32_16x16x32_bf16 v[38:41], v[230:233], v[200:203], v[38:41]
	v_mfma_f32_16x16x32_bf16 v[34:37], v[238:241], v[200:203], v[34:37]
	v_mfma_f32_16x16x32_bf16 v[22:25], v[230:233], v[214:217], v[22:25]
	v_mfma_f32_16x16x32_bf16 v[18:21], v[238:241], v[214:217], v[18:21]
	v_mfma_f32_16x16x32_bf16 v[4:7], v[230:233], v[222:225], v[4:7]
	v_mfma_f32_16x16x32_bf16 v[0:3], v[238:241], v[222:225], v[0:3]
	s_add_i32 s27, s27, 2
	s_add_u32 s19, s19, 0x100
	s_addc_u32 s26, s26, 0
	s_cmp_gt_u32 s27, 7
	s_mov_b64 s[10:11], s[12:13]
	s_barrier
	s_cbranch_scc0 .LBB0_1278
	s_setprio 0
	v_lshl_add_u32 v144, s18, 8, v148
	v_ashrrev_i32_e32 v145, 31, v144
	v_lshlrev_b64 v[142:143], 16, v[144:145]
	v_mul_f32_e32 v145, 0x3d372713, v126
	v_mul_f32_e32 v145, v126, v145
	v_fma_f32 v145, v126, v145, v126
	v_mul_f32_e32 v145, 0x3f4c422a, v145
	v_add_f32_e32 v145, v145, v145
	v_mul_f32_e32 v145, 0xbfb8aa3b, v145
	v_exp_f32_e32 v145, v145
	v_lshl_or_b32 v164, s1, 8, v150
	s_lshl_b32 s0, s0, 4
	s_ashr_i32 s1, s0, 31
	v_add_f32_e32 v145, 1.0, v145
	v_rcp_f32_e32 v152, v145
	v_mul_f32_e32 v145, 0x3d372713, v122
	v_mul_f32_e32 v145, v122, v145
	v_fma_f32 v145, v122, v145, v122
	v_mul_f32_e32 v145, 0x3f4c422a, v145
	v_add_f32_e32 v145, v145, v145
	v_mul_f32_e32 v145, 0xbfb8aa3b, v145
	v_exp_f32_e32 v145, v145
	v_lshl_add_u64 v[146:147], s[0:1], 1, v[136:137]
	v_lshl_add_u64 v[142:143], v[146:147], 0, v[142:143]
	s_mov_b64 s[0:1], 0x800000
	v_add_f32_e32 v145, 1.0, v145
	v_rcp_f32_e32 v162, v145
	v_mul_f32_e32 v145, 0x3d372713, v127
	v_mul_f32_e32 v145, v127, v145
	v_fma_f32 v145, v127, v145, v127
	v_mul_f32_e32 v145, 0x3f4c422a, v145
	v_add_f32_e32 v145, v145, v145
	v_mul_f32_e32 v145, 0xbfb8aa3b, v145
	v_exp_f32_e32 v145, v145
	s_and_b64 vcc, exec, s[2:3]
	s_mov_b32 s18, s82
	s_mov_b64 s[12:13], s[6:7]
	v_add_f32_e32 v145, 1.0, v145
	v_rcp_f32_e32 v153, v145
	v_mul_f32_e32 v145, 0x3d372713, v123
	v_mul_f32_e32 v145, v123, v145
	v_fma_f32 v145, v123, v145, v123
	v_mul_f32_e32 v145, 0x3f4c422a, v145
	v_add_f32_e32 v145, v145, v145
	v_mul_f32_e32 v145, 0xbfb8aa3b, v145
	v_exp_f32_e32 v145, v145
	v_pk_mul_f32 v[126:127], v[126:127], v[152:153]
	s_mov_b64 s[10:11], s[4:5]
	v_add_f32_e32 v145, 1.0, v145
	v_rcp_f32_e32 v163, v145
	v_mul_f32_e32 v145, 0x3d372713, v128
	v_mul_f32_e32 v145, v128, v145
	v_fma_f32 v145, v128, v145, v128
	v_mul_f32_e32 v145, 0x3f4c422a, v145
	v_add_f32_e32 v145, v145, v145
	v_mul_f32_e32 v145, 0xbfb8aa3b, v145
	v_exp_f32_e32 v145, v145
	v_pk_mul_f32 v[122:123], v[122:123], v[162:163]
	v_add_f32_e32 v145, 1.0, v145
	v_rcp_f32_e32 v152, v145
	v_mul_f32_e32 v145, 0x3d372713, v124
	v_mul_f32_e32 v145, v124, v145
	v_fma_f32 v145, v124, v145, v124
	v_mul_f32_e32 v145, 0x3f4c422a, v145
	v_add_f32_e32 v145, v145, v145
	v_mul_f32_e32 v145, 0xbfb8aa3b, v145
	v_exp_f32_e32 v145, v145
	s_nop 0
	v_add_f32_e32 v145, 1.0, v145
	v_rcp_f32_e32 v162, v145
	v_mul_f32_e32 v145, 0x3d372713, v129
	v_mul_f32_e32 v145, v129, v145
	v_fma_f32 v145, v129, v145, v129
	v_mul_f32_e32 v145, 0x3f4c422a, v145
	v_add_f32_e32 v145, v145, v145
	v_mul_f32_e32 v145, 0xbfb8aa3b, v145
	v_exp_f32_e32 v145, v145
	s_nop 0
	v_add_f32_e32 v145, 1.0, v145
	v_rcp_f32_e32 v153, v145
	v_mul_f32_e32 v145, 0x3d372713, v125
	v_mul_f32_e32 v145, v125, v145
	v_fma_f32 v145, v125, v145, v125
	v_mul_f32_e32 v145, 0x3f4c422a, v145
	v_add_f32_e32 v145, v145, v145
	v_mul_f32_e32 v145, 0xbfb8aa3b, v145
	v_exp_f32_e32 v145, v145
	v_pk_mul_f32 v[128:129], v[128:129], v[152:153]
	v_add_f32_e32 v145, 1.0, v145
; DEVI float sigmoidf_(float x) { return __builtin_amdgcn_rcpf(1.f + __expf(-x)); }
; DEVI float siluf_(float x) { return x * __builtin_amdgcn_rcpf(1.f + __expf(-x)); }
; DEVI float logsigf_(float x) { return fminf(x, 0.f) - __logf(1.f + __expf(-fabsf(x))); }
	v_rcp_f32_e32 v163, v145
	s_nop 0
	v_pk_mul_f32 v[152:153], v[124:125], v[162:163]
	v_cvt_pk_bf16_f32 v125, v128, v129
	v_ashrrev_i32_e32 v128, 4, v164
	v_ashrrev_i32_e32 v129, 31, v128
	v_cvt_pk_bf16_f32 v124, v126, v127
	v_cvt_pk_bf16_f32 v126, v122, v123
	v_lshlrev_b64 v[122:123], 11, v[128:129]
	v_cvt_pk_bf16_f32 v127, v152, v153
	v_lshl_add_u64 v[152:153], v[142:143], 0, v[122:123]
	global_store_dwordx4 v[152:153], v[124:127], off
	s_nop 1
	v_mul_f32_e32 v125, 0x3d372713, v114
	v_mul_f32_e32 v125, v114, v125
	v_fma_f32 v125, v114, v125, v114
	v_mul_f32_e32 v125, 0x3f4c422a, v125
	v_add_f32_e32 v125, v125, v125
	v_mul_f32_e32 v125, 0xbfb8aa3b, v125
	v_exp_f32_e32 v125, v125
	v_mul_f32_e32 v124, 0x3d372713, v118
	v_mul_f32_e32 v124, v118, v124
	v_fma_f32 v124, v118, v124, v118
	v_add_f32_e32 v125, 1.0, v125
	v_rcp_f32_e32 v126, v125
	v_mul_f32_e32 v125, 0x3d372713, v119
	v_mul_f32_e32 v125, v119, v125
	v_fma_f32 v125, v119, v125, v119
	v_mul_f32_e32 v124, 0x3f4c422a, v124
	v_mul_f32_e32 v125, 0x3f4c422a, v125
	v_add_f32_e32 v124, v124, v124
	v_add_f32_e32 v125, v125, v125
	v_mul_f32_e32 v124, 0xbfb8aa3b, v124
	v_mul_f32_e32 v125, 0xbfb8aa3b, v125
	v_exp_f32_e32 v124, v124
	v_exp_f32_e32 v125, v125
	v_add_f32_e32 v124, 1.0, v124
	v_add_f32_e32 v125, 1.0, v125
	v_rcp_f32_e32 v124, v124
	v_rcp_f32_e32 v125, v125
	s_nop 0
	v_pk_mul_f32 v[118:119], v[118:119], v[124:125]
	v_mul_f32_e32 v124, 0x3d372713, v115
	v_mul_f32_e32 v124, v115, v124
	v_fma_f32 v124, v115, v124, v115
	v_mul_f32_e32 v124, 0x3f4c422a, v124
	v_add_f32_e32 v124, v124, v124
	v_mul_f32_e32 v125, 0x3d372713, v116
	v_mul_f32_e32 v124, 0xbfb8aa3b, v124
	v_mul_f32_e32 v125, v116, v125
	v_exp_f32_e32 v124, v124
	v_fma_f32 v125, v116, v125, v116
	v_mul_f32_e32 v125, 0x3f4c422a, v125
	v_add_f32_e32 v125, v125, v125
	v_mul_f32_e32 v125, 0xbfb8aa3b, v125
	v_add_f32_e32 v124, 1.0, v124
	v_exp_f32_e32 v125, v125
	v_rcp_f32_e32 v127, v124
	v_mul_f32_e32 v124, 0x3d372713, v120
	v_mul_f32_e32 v124, v120, v124
	v_add_f32_e32 v125, 1.0, v125
	v_pk_mul_f32 v[114:115], v[114:115], v[126:127]
	v_rcp_f32_e32 v126, v125
	v_mul_f32_e32 v125, 0x3d372713, v121
	v_mul_f32_e32 v125, v121, v125
	v_fma_f32 v124, v120, v124, v120
	v_fma_f32 v125, v121, v125, v121
	v_mul_f32_e32 v124, 0x3f4c422a, v124
	v_mul_f32_e32 v125, 0x3f4c422a, v125
	v_add_f32_e32 v124, v124, v124
	v_add_f32_e32 v125, v125, v125
	v_mul_f32_e32 v124, 0xbfb8aa3b, v124
	v_mul_f32_e32 v125, 0xbfb8aa3b, v125
	v_exp_f32_e32 v124, v124
	v_exp_f32_e32 v125, v125
	v_add_f32_e32 v124, 1.0, v124
	v_add_f32_e32 v125, 1.0, v125
	v_rcp_f32_e32 v124, v124
	v_rcp_f32_e32 v125, v125
	s_nop 0
	v_pk_mul_f32 v[120:121], v[120:121], v[124:125]
	v_mul_f32_e32 v124, 0x3d372713, v117
	v_mul_f32_e32 v124, v117, v124
	v_fma_f32 v124, v117, v124, v117
	v_mul_f32_e32 v124, 0x3f4c422a, v124
	v_add_f32_e32 v124, v124, v124
	v_mul_f32_e32 v124, 0xbfb8aa3b, v124
	v_exp_f32_e32 v124, v124
	s_nop 0
	v_add_f32_e32 v124, 1.0, v124
	v_rcp_f32_e32 v127, v124
	s_nop 0
	v_pk_mul_f32 v[124:125], v[116:117], v[126:127]
	v_cvt_pk_bf16_f32 v116, v118, v119
	v_cvt_pk_bf16_f32 v118, v114, v115
	v_or_b32_e32 v114, 8, v128
	v_ashrrev_i32_e32 v115, 31, v114
	v_lshlrev_b64 v[114:115], 11, v[114:115]
	v_cvt_pk_bf16_f32 v117, v120, v121
	v_cvt_pk_bf16_f32 v119, v124, v125
	v_lshl_add_u64 v[120:121], v[142:143], 0, v[114:115]
	global_store_dwordx4 v[120:121], v[116:119], off
	s_nop 1
	v_mul_f32_e32 v119, 0x3d372713, v106
	v_mul_f32_e32 v119, v106, v119
	v_fma_f32 v119, v106, v119, v106
	v_mul_f32_e32 v119, 0x3f4c422a, v119
	v_add_f32_e32 v119, v119, v119
	v_mul_f32_e32 v119, 0xbfb8aa3b, v119
	v_exp_f32_e32 v119, v119
	v_mul_f32_e32 v118, 0x3d372713, v110
	v_mul_f32_e32 v118, v110, v118
	v_fma_f32 v118, v110, v118, v110
	v_add_f32_e32 v119, 1.0, v119
	v_rcp_f32_e32 v120, v119
	v_mul_f32_e32 v119, 0x3d372713, v111
	v_mul_f32_e32 v119, v111, v119
	v_fma_f32 v119, v111, v119, v111
	v_mul_f32_e32 v118, 0x3f4c422a, v118
	v_mul_f32_e32 v119, 0x3f4c422a, v119
	v_add_f32_e32 v118, v118, v118
	v_add_f32_e32 v119, v119, v119
	v_mul_f32_e32 v118, 0xbfb8aa3b, v118
	v_mul_f32_e32 v119, 0xbfb8aa3b, v119
	v_exp_f32_e32 v118, v118
	v_exp_f32_e32 v119, v119
	v_or_b32_e32 v116, 16, v144
	v_ashrrev_i32_e32 v117, 31, v116
	v_add_f32_e32 v118, 1.0, v118
	v_add_f32_e32 v119, 1.0, v119
	v_rcp_f32_e32 v118, v118
	v_rcp_f32_e32 v119, v119
	v_lshlrev_b64 v[116:117], 16, v[116:117]
	v_lshl_add_u64 v[116:117], v[146:147], 0, v[116:117]
	v_pk_mul_f32 v[110:111], v[110:111], v[118:119]
	v_mul_f32_e32 v118, 0x3d372713, v107
	v_mul_f32_e32 v118, v107, v118
	v_fma_f32 v118, v107, v118, v107
	v_mul_f32_e32 v118, 0x3f4c422a, v118
	v_add_f32_e32 v118, v118, v118
	v_mul_f32_e32 v118, 0xbfb8aa3b, v118
	v_exp_f32_e32 v118, v118
	s_nop 0
	v_add_f32_e32 v118, 1.0, v118
	v_rcp_f32_e32 v121, v118
	s_nop 0
	v_pk_mul_f32 v[118:119], v[106:107], v[120:121]
	v_mul_f32_e32 v107, 0x3d372713, v108
	v_mul_f32_e32 v107, v108, v107
	v_fma_f32 v107, v108, v107, v108
	v_mul_f32_e32 v107, 0x3f4c422a, v107
	v_add_f32_e32 v107, v107, v107
	v_mul_f32_e32 v107, 0xbfb8aa3b, v107
	v_exp_f32_e32 v107, v107
	v_mul_f32_e32 v106, 0x3d372713, v112
	v_mul_f32_e32 v106, v112, v106
	v_fma_f32 v106, v112, v106, v112
	v_add_f32_e32 v107, 1.0, v107
	v_rcp_f32_e32 v120, v107
	v_mul_f32_e32 v107, 0x3d372713, v113
	v_mul_f32_e32 v107, v113, v107
	v_fma_f32 v107, v113, v107, v113
	v_mul_f32_e32 v106, 0x3f4c422a, v106
	v_mul_f32_e32 v107, 0x3f4c422a, v107
	v_add_f32_e32 v106, v106, v106
	v_add_f32_e32 v107, v107, v107
	v_mul_f32_e32 v106, 0xbfb8aa3b, v106
	v_mul_f32_e32 v107, 0xbfb8aa3b, v107
	v_exp_f32_e32 v106, v106
	v_exp_f32_e32 v107, v107
; DEVI float sigmoidf_(float x) { return __builtin_amdgcn_rcpf(1.f + __expf(-x)); }
; DEVI float siluf_(float x) { return x * __builtin_amdgcn_rcpf(1.f + __expf(-x)); }
; DEVI float logsigf_(float x) { return fminf(x, 0.f) - __logf(1.f + __expf(-fabsf(x))); }
	v_add_f32_e32 v106, 1.0, v106
	v_add_f32_e32 v107, 1.0, v107
	v_rcp_f32_e32 v106, v106
	v_rcp_f32_e32 v107, v107
	s_nop 0
	v_pk_mul_f32 v[112:113], v[112:113], v[106:107]
	v_mul_f32_e32 v106, 0x3d372713, v109
	v_mul_f32_e32 v106, v109, v106
	v_fma_f32 v106, v109, v106, v109
	v_mul_f32_e32 v106, 0x3f4c422a, v106
	v_add_f32_e32 v106, v106, v106
	v_mul_f32_e32 v106, 0xbfb8aa3b, v106
	v_exp_f32_e32 v106, v106
	v_cvt_pk_bf16_f32 v107, v112, v113
	v_add_f32_e32 v106, 1.0, v106
	v_rcp_f32_e32 v121, v106
	v_cvt_pk_bf16_f32 v106, v110, v111
	v_lshl_add_u64 v[110:111], v[116:117], 0, v[122:123]
	v_pk_mul_f32 v[120:121], v[108:109], v[120:121]
	v_cvt_pk_bf16_f32 v108, v118, v119
	v_cvt_pk_bf16_f32 v109, v120, v121
	global_store_dwordx4 v[110:111], v[106:109], off
	s_nop 1
	v_mul_f32_e32 v107, 0x3d372713, v98
	v_mul_f32_e32 v107, v98, v107
	v_fma_f32 v107, v98, v107, v98
	v_mul_f32_e32 v107, 0x3f4c422a, v107
	v_add_f32_e32 v107, v107, v107
	v_mul_f32_e32 v107, 0xbfb8aa3b, v107
	v_exp_f32_e32 v107, v107
	v_mul_f32_e32 v106, 0x3d372713, v102
	v_mul_f32_e32 v106, v102, v106
	v_fma_f32 v106, v102, v106, v102
	v_add_f32_e32 v107, 1.0, v107
	v_rcp_f32_e32 v108, v107
	v_mul_f32_e32 v107, 0x3d372713, v103
	v_mul_f32_e32 v107, v103, v107
	v_fma_f32 v107, v103, v107, v103
	v_mul_f32_e32 v106, 0x3f4c422a, v106
	v_mul_f32_e32 v107, 0x3f4c422a, v107
	v_add_f32_e32 v106, v106, v106
	v_add_f32_e32 v107, v107, v107
	v_mul_f32_e32 v106, 0xbfb8aa3b, v106
	v_mul_f32_e32 v107, 0xbfb8aa3b, v107
	v_exp_f32_e32 v106, v106
	v_exp_f32_e32 v107, v107
	v_add_f32_e32 v106, 1.0, v106
	v_add_f32_e32 v107, 1.0, v107
	v_rcp_f32_e32 v106, v106
	v_rcp_f32_e32 v107, v107
	s_nop 0
	v_pk_mul_f32 v[102:103], v[102:103], v[106:107]
	v_mul_f32_e32 v106, 0x3d372713, v99
	v_mul_f32_e32 v106, v99, v106
	v_fma_f32 v106, v99, v106, v99
	v_mul_f32_e32 v106, 0x3f4c422a, v106
	v_add_f32_e32 v106, v106, v106
	v_mul_f32_e32 v106, 0xbfb8aa3b, v106
	v_exp_f32_e32 v106, v106
	s_nop 0
	v_add_f32_e32 v106, 1.0, v106
	v_rcp_f32_e32 v109, v106
	s_nop 0
	v_pk_mul_f32 v[106:107], v[98:99], v[108:109]
	v_mul_f32_e32 v99, 0x3d372713, v100
	v_mul_f32_e32 v99, v100, v99
	v_fma_f32 v99, v100, v99, v100
	v_mul_f32_e32 v99, 0x3f4c422a, v99
	v_add_f32_e32 v99, v99, v99
	v_mul_f32_e32 v99, 0xbfb8aa3b, v99
	v_exp_f32_e32 v99, v99
	v_mul_f32_e32 v98, 0x3d372713, v104
	v_mul_f32_e32 v98, v104, v98
	v_fma_f32 v98, v104, v98, v104
	v_add_f32_e32 v99, 1.0, v99
	v_rcp_f32_e32 v108, v99
	v_mul_f32_e32 v99, 0x3d372713, v105
	v_mul_f32_e32 v99, v105, v99
	v_fma_f32 v99, v105, v99, v105
	v_mul_f32_e32 v98, 0x3f4c422a, v98
	v_mul_f32_e32 v99, 0x3f4c422a, v99
	v_add_f32_e32 v98, v98, v98
	v_add_f32_e32 v99, v99, v99
	v_mul_f32_e32 v98, 0xbfb8aa3b, v98
	v_mul_f32_e32 v99, 0xbfb8aa3b, v99
	v_exp_f32_e32 v98, v98
	v_exp_f32_e32 v99, v99
	v_add_f32_e32 v98, 1.0, v98
	v_add_f32_e32 v99, 1.0, v99
	v_rcp_f32_e32 v98, v98
	v_rcp_f32_e32 v99, v99
	s_nop 0
	v_pk_mul_f32 v[104:105], v[104:105], v[98:99]
	v_mul_f32_e32 v98, 0x3d372713, v101
	v_mul_f32_e32 v98, v101, v98
	v_fma_f32 v98, v101, v98, v101
	v_mul_f32_e32 v98, 0x3f4c422a, v98
	v_add_f32_e32 v98, v98, v98
	v_mul_f32_e32 v98, 0xbfb8aa3b, v98
	v_exp_f32_e32 v98, v98
	v_cvt_pk_bf16_f32 v99, v104, v105
	v_add_f32_e32 v98, 1.0, v98
	v_rcp_f32_e32 v109, v98
	v_cvt_pk_bf16_f32 v98, v102, v103
	v_lshl_add_u64 v[102:103], v[116:117], 0, v[114:115]
	v_pk_mul_f32 v[108:109], v[100:101], v[108:109]
	v_cvt_pk_bf16_f32 v100, v106, v107
	v_cvt_pk_bf16_f32 v101, v108, v109
	global_store_dwordx4 v[102:103], v[98:101], off
	s_nop 1
	v_mul_f32_e32 v101, 0x3d372713, v90
	v_mul_f32_e32 v101, v90, v101
	v_fma_f32 v101, v90, v101, v90
	v_mul_f32_e32 v101, 0x3f4c422a, v101
	v_add_f32_e32 v101, v101, v101
	v_mul_f32_e32 v101, 0xbfb8aa3b, v101
	v_exp_f32_e32 v101, v101
	v_mul_f32_e32 v100, 0x3d372713, v94
	v_mul_f32_e32 v100, v94, v100
	v_fma_f32 v100, v94, v100, v94
	v_add_f32_e32 v101, 1.0, v101
	v_rcp_f32_e32 v102, v101
	v_mul_f32_e32 v101, 0x3d372713, v95
	v_mul_f32_e32 v101, v95, v101
	v_fma_f32 v101, v95, v101, v95
	v_mul_f32_e32 v100, 0x3f4c422a, v100
	v_mul_f32_e32 v101, 0x3f4c422a, v101
	v_add_f32_e32 v100, v100, v100
	v_add_f32_e32 v101, v101, v101
	v_mul_f32_e32 v100, 0xbfb8aa3b, v100
	v_mul_f32_e32 v101, 0xbfb8aa3b, v101
	v_exp_f32_e32 v100, v100
	v_exp_f32_e32 v101, v101
	v_or_b32_e32 v98, 32, v144
	v_ashrrev_i32_e32 v99, 31, v98
	v_add_f32_e32 v100, 1.0, v100
	v_add_f32_e32 v101, 1.0, v101
	v_rcp_f32_e32 v100, v100
	v_rcp_f32_e32 v101, v101
	v_lshlrev_b64 v[98:99], 16, v[98:99]
	v_lshl_add_u64 v[98:99], v[146:147], 0, v[98:99]
	v_pk_mul_f32 v[94:95], v[94:95], v[100:101]
	v_mul_f32_e32 v100, 0x3d372713, v91
	v_mul_f32_e32 v100, v91, v100
	v_fma_f32 v100, v91, v100, v91
	v_mul_f32_e32 v100, 0x3f4c422a, v100
	v_add_f32_e32 v100, v100, v100
	v_mul_f32_e32 v100, 0xbfb8aa3b, v100
	v_exp_f32_e32 v100, v100
	s_nop 0
	v_add_f32_e32 v100, 1.0, v100
	v_rcp_f32_e32 v103, v100
	s_nop 0
	v_pk_mul_f32 v[100:101], v[90:91], v[102:103]
	v_mul_f32_e32 v91, 0x3d372713, v92
	v_mul_f32_e32 v91, v92, v91
	v_fma_f32 v91, v92, v91, v92
	v_mul_f32_e32 v91, 0x3f4c422a, v91
	v_add_f32_e32 v91, v91, v91
	v_mul_f32_e32 v91, 0xbfb8aa3b, v91
	v_exp_f32_e32 v91, v91
	v_mul_f32_e32 v90, 0x3d372713, v96
	v_mul_f32_e32 v90, v96, v90
	v_fma_f32 v90, v96, v90, v96
	v_add_f32_e32 v91, 1.0, v91
	v_rcp_f32_e32 v102, v91
	v_mul_f32_e32 v91, 0x3d372713, v97
	v_mul_f32_e32 v91, v97, v91
	v_fma_f32 v91, v97, v91, v97
	v_mul_f32_e32 v90, 0x3f4c422a, v90
	v_mul_f32_e32 v91, 0x3f4c422a, v91
	v_add_f32_e32 v90, v90, v90
	v_add_f32_e32 v91, v91, v91
	v_mul_f32_e32 v90, 0xbfb8aa3b, v90
	v_mul_f32_e32 v91, 0xbfb8aa3b, v91
	v_exp_f32_e32 v90, v90
; DEVI float sigmoidf_(float x) { return __builtin_amdgcn_rcpf(1.f + __expf(-x)); }
; DEVI float siluf_(float x) { return x * __builtin_amdgcn_rcpf(1.f + __expf(-x)); }
; DEVI float logsigf_(float x) { return fminf(x, 0.f) - __logf(1.f + __expf(-fabsf(x))); }
	v_exp_f32_e32 v91, v91
	v_add_f32_e32 v90, 1.0, v90
	v_add_f32_e32 v91, 1.0, v91
	v_rcp_f32_e32 v90, v90
	v_rcp_f32_e32 v91, v91
	s_nop 0
	v_pk_mul_f32 v[96:97], v[96:97], v[90:91]
	v_mul_f32_e32 v90, 0x3d372713, v93
	v_mul_f32_e32 v90, v93, v90
	v_fma_f32 v90, v93, v90, v93
	v_mul_f32_e32 v90, 0x3f4c422a, v90
	v_add_f32_e32 v90, v90, v90
	v_mul_f32_e32 v90, 0xbfb8aa3b, v90
	v_exp_f32_e32 v90, v90
	v_cvt_pk_bf16_f32 v91, v96, v97
	v_add_f32_e32 v90, 1.0, v90
	v_rcp_f32_e32 v103, v90
	v_cvt_pk_bf16_f32 v90, v94, v95
	v_lshl_add_u64 v[94:95], v[98:99], 0, v[122:123]
	v_pk_mul_f32 v[102:103], v[92:93], v[102:103]
	v_cvt_pk_bf16_f32 v92, v100, v101
	v_cvt_pk_bf16_f32 v93, v102, v103
	global_store_dwordx4 v[94:95], v[90:93], off
	s_nop 1
	v_mul_f32_e32 v91, 0x3d372713, v82
	v_mul_f32_e32 v91, v82, v91
	v_fma_f32 v91, v82, v91, v82
	v_mul_f32_e32 v91, 0x3f4c422a, v91
	v_add_f32_e32 v91, v91, v91
	v_mul_f32_e32 v91, 0xbfb8aa3b, v91
	v_exp_f32_e32 v91, v91
	v_mul_f32_e32 v90, 0x3d372713, v86
	v_mul_f32_e32 v90, v86, v90
	v_fma_f32 v90, v86, v90, v86
	v_add_f32_e32 v91, 1.0, v91
	v_rcp_f32_e32 v92, v91
	v_mul_f32_e32 v91, 0x3d372713, v87
	v_mul_f32_e32 v91, v87, v91
	v_fma_f32 v91, v87, v91, v87
	v_mul_f32_e32 v90, 0x3f4c422a, v90
	v_mul_f32_e32 v91, 0x3f4c422a, v91
	v_add_f32_e32 v90, v90, v90
	v_add_f32_e32 v91, v91, v91
	v_mul_f32_e32 v90, 0xbfb8aa3b, v90
	v_mul_f32_e32 v91, 0xbfb8aa3b, v91
	v_exp_f32_e32 v90, v90
	v_exp_f32_e32 v91, v91
	v_add_f32_e32 v90, 1.0, v90
	v_add_f32_e32 v91, 1.0, v91
	v_rcp_f32_e32 v90, v90
	v_rcp_f32_e32 v91, v91
	s_nop 0
	v_pk_mul_f32 v[86:87], v[86:87], v[90:91]
	v_mul_f32_e32 v90, 0x3d372713, v83
	v_mul_f32_e32 v90, v83, v90
	v_fma_f32 v90, v83, v90, v83
	v_mul_f32_e32 v90, 0x3f4c422a, v90
	v_add_f32_e32 v90, v90, v90
	v_mul_f32_e32 v90, 0xbfb8aa3b, v90
	v_exp_f32_e32 v90, v90
	s_nop 0
	v_add_f32_e32 v90, 1.0, v90
	v_rcp_f32_e32 v93, v90
	s_nop 0
	v_pk_mul_f32 v[90:91], v[82:83], v[92:93]
	v_mul_f32_e32 v83, 0x3d372713, v84
	v_mul_f32_e32 v83, v84, v83
	v_fma_f32 v83, v84, v83, v84
	v_mul_f32_e32 v83, 0x3f4c422a, v83
	v_add_f32_e32 v83, v83, v83
	v_mul_f32_e32 v83, 0xbfb8aa3b, v83
	v_exp_f32_e32 v83, v83
	v_mul_f32_e32 v82, 0x3d372713, v88
	v_mul_f32_e32 v82, v88, v82
	v_fma_f32 v82, v88, v82, v88
	v_add_f32_e32 v83, 1.0, v83
	v_rcp_f32_e32 v92, v83
	v_mul_f32_e32 v83, 0x3d372713, v89
	v_mul_f32_e32 v83, v89, v83
	v_fma_f32 v83, v89, v83, v89
	v_mul_f32_e32 v82, 0x3f4c422a, v82
	v_mul_f32_e32 v83, 0x3f4c422a, v83
	v_add_f32_e32 v82, v82, v82
	v_add_f32_e32 v83, v83, v83
	v_mul_f32_e32 v82, 0xbfb8aa3b, v82
	v_mul_f32_e32 v83, 0xbfb8aa3b, v83
	v_exp_f32_e32 v82, v82
	v_exp_f32_e32 v83, v83
	v_add_f32_e32 v82, 1.0, v82
	v_add_f32_e32 v83, 1.0, v83
	v_rcp_f32_e32 v82, v82
	v_rcp_f32_e32 v83, v83
	s_nop 0
	v_pk_mul_f32 v[88:89], v[88:89], v[82:83]
	v_mul_f32_e32 v82, 0x3d372713, v85
	v_mul_f32_e32 v82, v85, v82
	v_fma_f32 v82, v85, v82, v85
	v_mul_f32_e32 v82, 0x3f4c422a, v82
	v_add_f32_e32 v82, v82, v82
	v_mul_f32_e32 v82, 0xbfb8aa3b, v82
	v_exp_f32_e32 v82, v82
	v_cvt_pk_bf16_f32 v83, v88, v89
	v_add_f32_e32 v82, 1.0, v82
	v_rcp_f32_e32 v93, v82
	v_cvt_pk_bf16_f32 v82, v86, v87
	v_lshl_add_u64 v[86:87], v[98:99], 0, v[114:115]
	v_pk_mul_f32 v[92:93], v[84:85], v[92:93]
	v_cvt_pk_bf16_f32 v84, v90, v91
	v_cvt_pk_bf16_f32 v85, v92, v93
	global_store_dwordx4 v[86:87], v[82:85], off
	s_nop 1
	v_mul_f32_e32 v85, 0x3d372713, v74
	v_mul_f32_e32 v85, v74, v85
	v_fma_f32 v85, v74, v85, v74
	v_mul_f32_e32 v85, 0x3f4c422a, v85
	v_add_f32_e32 v85, v85, v85
	v_mul_f32_e32 v85, 0xbfb8aa3b, v85
	v_exp_f32_e32 v85, v85
	v_mul_f32_e32 v84, 0x3d372713, v78
	v_mul_f32_e32 v84, v78, v84
	v_fma_f32 v84, v78, v84, v78
	v_add_f32_e32 v85, 1.0, v85
	v_rcp_f32_e32 v86, v85
	v_mul_f32_e32 v85, 0x3d372713, v79
	v_mul_f32_e32 v85, v79, v85
	v_fma_f32 v85, v79, v85, v79
	v_mul_f32_e32 v84, 0x3f4c422a, v84
	v_mul_f32_e32 v85, 0x3f4c422a, v85
	v_add_f32_e32 v84, v84, v84
	v_add_f32_e32 v85, v85, v85
	v_mul_f32_e32 v84, 0xbfb8aa3b, v84
	v_mul_f32_e32 v85, 0xbfb8aa3b, v85
	v_exp_f32_e32 v84, v84
	v_exp_f32_e32 v85, v85
	v_or_b32_e32 v82, 48, v144
	v_ashrrev_i32_e32 v83, 31, v82
	v_add_f32_e32 v84, 1.0, v84
	v_add_f32_e32 v85, 1.0, v85
	v_rcp_f32_e32 v84, v84
	v_rcp_f32_e32 v85, v85
	v_lshlrev_b64 v[82:83], 16, v[82:83]
	v_lshl_add_u64 v[82:83], v[146:147], 0, v[82:83]
	v_pk_mul_f32 v[78:79], v[78:79], v[84:85]
	v_mul_f32_e32 v84, 0x3d372713, v75
	v_mul_f32_e32 v84, v75, v84
	v_fma_f32 v84, v75, v84, v75
	v_mul_f32_e32 v84, 0x3f4c422a, v84
	v_add_f32_e32 v84, v84, v84
	v_mul_f32_e32 v84, 0xbfb8aa3b, v84
	v_exp_f32_e32 v84, v84
	s_nop 0
	v_add_f32_e32 v84, 1.0, v84
	v_rcp_f32_e32 v87, v84
	s_nop 0
	v_pk_mul_f32 v[84:85], v[74:75], v[86:87]
	v_mul_f32_e32 v75, 0x3d372713, v76
	v_mul_f32_e32 v75, v76, v75
	v_fma_f32 v75, v76, v75, v76
	v_mul_f32_e32 v75, 0x3f4c422a, v75
	v_add_f32_e32 v75, v75, v75
	v_mul_f32_e32 v75, 0xbfb8aa3b, v75
	v_exp_f32_e32 v75, v75
	v_mul_f32_e32 v74, 0x3d372713, v80
	v_mul_f32_e32 v74, v80, v74
	v_fma_f32 v74, v80, v74, v80
	v_add_f32_e32 v75, 1.0, v75
	v_rcp_f32_e32 v86, v75
	v_mul_f32_e32 v75, 0x3d372713, v81
	v_mul_f32_e32 v75, v81, v75
	v_fma_f32 v75, v81, v75, v81
	v_mul_f32_e32 v74, 0x3f4c422a, v74
	v_mul_f32_e32 v75, 0x3f4c422a, v75
	v_add_f32_e32 v74, v74, v74
	v_add_f32_e32 v75, v75, v75
	v_mul_f32_e32 v74, 0xbfb8aa3b, v74
	v_mul_f32_e32 v75, 0xbfb8aa3b, v75
	v_exp_f32_e32 v74, v74
	v_exp_f32_e32 v75, v75
	v_add_f32_e32 v74, 1.0, v74
	v_add_f32_e32 v75, 1.0, v75
	v_rcp_f32_e32 v74, v74
	v_rcp_f32_e32 v75, v75
	s_nop 0
	v_pk_mul_f32 v[80:81], v[80:81], v[74:75]
	v_mul_f32_e32 v74, 0x3d372713, v77
	v_mul_f32_e32 v74, v77, v74
; DEVI float sigmoidf_(float x) { return __builtin_amdgcn_rcpf(1.f + __expf(-x)); }
; DEVI float siluf_(float x) { return x * __builtin_amdgcn_rcpf(1.f + __expf(-x)); }
; DEVI float logsigf_(float x) { return fminf(x, 0.f) - __logf(1.f + __expf(-fabsf(x))); }
	v_fma_f32 v74, v77, v74, v77
	v_mul_f32_e32 v74, 0x3f4c422a, v74
	v_add_f32_e32 v74, v74, v74
	v_mul_f32_e32 v74, 0xbfb8aa3b, v74
	v_exp_f32_e32 v74, v74
	v_cvt_pk_bf16_f32 v75, v80, v81
	v_add_f32_e32 v74, 1.0, v74
	v_rcp_f32_e32 v87, v74
	v_cvt_pk_bf16_f32 v74, v78, v79
	v_lshl_add_u64 v[78:79], v[82:83], 0, v[122:123]
	v_pk_mul_f32 v[86:87], v[76:77], v[86:87]
	v_cvt_pk_bf16_f32 v76, v84, v85
	v_cvt_pk_bf16_f32 v77, v86, v87
	global_store_dwordx4 v[78:79], v[74:77], off
	s_nop 1
	v_mul_f32_e32 v75, 0x3d372713, v66
	v_mul_f32_e32 v75, v66, v75
	v_fma_f32 v75, v66, v75, v66
	v_mul_f32_e32 v75, 0x3f4c422a, v75
	v_add_f32_e32 v75, v75, v75
	v_mul_f32_e32 v75, 0xbfb8aa3b, v75
	v_exp_f32_e32 v75, v75
	v_mul_f32_e32 v74, 0x3d372713, v70
	v_mul_f32_e32 v74, v70, v74
	v_fma_f32 v74, v70, v74, v70
	v_add_f32_e32 v75, 1.0, v75
	v_rcp_f32_e32 v76, v75
	v_mul_f32_e32 v75, 0x3d372713, v71
	v_mul_f32_e32 v75, v71, v75
	v_fma_f32 v75, v71, v75, v71
	v_mul_f32_e32 v74, 0x3f4c422a, v74
	v_mul_f32_e32 v75, 0x3f4c422a, v75
	v_add_f32_e32 v74, v74, v74
	v_add_f32_e32 v75, v75, v75
	v_mul_f32_e32 v74, 0xbfb8aa3b, v74
	v_mul_f32_e32 v75, 0xbfb8aa3b, v75
	v_exp_f32_e32 v74, v74
	v_exp_f32_e32 v75, v75
	v_add_f32_e32 v74, 1.0, v74
	v_add_f32_e32 v75, 1.0, v75
	v_rcp_f32_e32 v74, v74
	v_rcp_f32_e32 v75, v75
	s_nop 0
	v_pk_mul_f32 v[70:71], v[70:71], v[74:75]
	v_mul_f32_e32 v74, 0x3d372713, v67
	v_mul_f32_e32 v74, v67, v74
	v_fma_f32 v74, v67, v74, v67
	v_mul_f32_e32 v74, 0x3f4c422a, v74
	v_add_f32_e32 v74, v74, v74
	v_mul_f32_e32 v74, 0xbfb8aa3b, v74
	v_exp_f32_e32 v74, v74
	s_nop 0
	v_add_f32_e32 v74, 1.0, v74
	v_rcp_f32_e32 v77, v74
	s_nop 0
	v_pk_mul_f32 v[74:75], v[66:67], v[76:77]
	v_mul_f32_e32 v67, 0x3d372713, v68
	v_mul_f32_e32 v67, v68, v67
	v_fma_f32 v67, v68, v67, v68
	v_mul_f32_e32 v67, 0x3f4c422a, v67
	v_add_f32_e32 v67, v67, v67
	v_mul_f32_e32 v67, 0xbfb8aa3b, v67
	v_exp_f32_e32 v67, v67
	v_mul_f32_e32 v66, 0x3d372713, v72
	v_mul_f32_e32 v66, v72, v66
	v_fma_f32 v66, v72, v66, v72
	v_add_f32_e32 v67, 1.0, v67
	v_rcp_f32_e32 v76, v67
	v_mul_f32_e32 v67, 0x3d372713, v73
	v_mul_f32_e32 v67, v73, v67
	v_fma_f32 v67, v73, v67, v73
	v_mul_f32_e32 v66, 0x3f4c422a, v66
	v_mul_f32_e32 v67, 0x3f4c422a, v67
	v_add_f32_e32 v66, v66, v66
	v_add_f32_e32 v67, v67, v67
	v_mul_f32_e32 v66, 0xbfb8aa3b, v66
	v_mul_f32_e32 v67, 0xbfb8aa3b, v67
	v_exp_f32_e32 v66, v66
	v_exp_f32_e32 v67, v67
	v_add_f32_e32 v66, 1.0, v66
	v_add_f32_e32 v67, 1.0, v67
	v_rcp_f32_e32 v66, v66
	v_rcp_f32_e32 v67, v67
	s_nop 0
	v_pk_mul_f32 v[72:73], v[72:73], v[66:67]
	v_mul_f32_e32 v66, 0x3d372713, v69
	v_mul_f32_e32 v66, v69, v66
	v_fma_f32 v66, v69, v66, v69
	v_mul_f32_e32 v66, 0x3f4c422a, v66
	v_add_f32_e32 v66, v66, v66
	v_mul_f32_e32 v66, 0xbfb8aa3b, v66
	v_exp_f32_e32 v66, v66
	v_cvt_pk_bf16_f32 v67, v72, v73
	v_add_f32_e32 v66, 1.0, v66
	v_rcp_f32_e32 v77, v66
	v_cvt_pk_bf16_f32 v66, v70, v71
	v_lshl_add_u64 v[70:71], v[82:83], 0, v[114:115]
	v_pk_mul_f32 v[76:77], v[68:69], v[76:77]
	v_cvt_pk_bf16_f32 v68, v74, v75
	v_cvt_pk_bf16_f32 v69, v76, v77
	global_store_dwordx4 v[70:71], v[66:69], off
	s_nop 1
	v_mul_f32_e32 v69, 0x3d372713, v58
	v_mul_f32_e32 v69, v58, v69
	v_fma_f32 v69, v58, v69, v58
	v_mul_f32_e32 v69, 0x3f4c422a, v69
	v_add_f32_e32 v69, v69, v69
	v_mul_f32_e32 v69, 0xbfb8aa3b, v69
	v_exp_f32_e32 v69, v69
	v_mul_f32_e32 v68, 0x3d372713, v62
	v_mul_f32_e32 v68, v62, v68
	v_fma_f32 v68, v62, v68, v62
	v_add_f32_e32 v69, 1.0, v69
	v_rcp_f32_e32 v70, v69
	v_mul_f32_e32 v69, 0x3d372713, v63
	v_mul_f32_e32 v69, v63, v69
	v_fma_f32 v69, v63, v69, v63
	v_mul_f32_e32 v68, 0x3f4c422a, v68
	v_mul_f32_e32 v69, 0x3f4c422a, v69
	v_add_f32_e32 v68, v68, v68
	v_add_f32_e32 v69, v69, v69
	v_mul_f32_e32 v68, 0xbfb8aa3b, v68
	v_mul_f32_e32 v69, 0xbfb8aa3b, v69
	v_exp_f32_e32 v68, v68
	v_exp_f32_e32 v69, v69
	v_lshl_add_u64 v[66:67], v[142:143], 0, s[0:1]
	s_mov_b64 s[0:1], 0x900000
	v_add_f32_e32 v68, 1.0, v68
	v_add_f32_e32 v69, 1.0, v69
	v_rcp_f32_e32 v68, v68
	v_rcp_f32_e32 v69, v69
	s_nop 0
	v_pk_mul_f32 v[62:63], v[62:63], v[68:69]
	v_mul_f32_e32 v68, 0x3d372713, v59
	v_mul_f32_e32 v68, v59, v68
	v_fma_f32 v68, v59, v68, v59
	v_mul_f32_e32 v68, 0x3f4c422a, v68
	v_add_f32_e32 v68, v68, v68
	v_mul_f32_e32 v68, 0xbfb8aa3b, v68
	v_exp_f32_e32 v68, v68
	s_nop 0
	v_add_f32_e32 v68, 1.0, v68
	v_rcp_f32_e32 v71, v68
	s_nop 0
	v_pk_mul_f32 v[68:69], v[58:59], v[70:71]
	v_mul_f32_e32 v59, 0x3d372713, v60
	v_mul_f32_e32 v59, v60, v59
	v_fma_f32 v59, v60, v59, v60
	v_mul_f32_e32 v59, 0x3f4c422a, v59
	v_add_f32_e32 v59, v59, v59
	v_mul_f32_e32 v59, 0xbfb8aa3b, v59
	v_exp_f32_e32 v59, v59
	v_mul_f32_e32 v58, 0x3d372713, v64
	v_mul_f32_e32 v58, v64, v58
	v_fma_f32 v58, v64, v58, v64
	v_add_f32_e32 v59, 1.0, v59
	v_rcp_f32_e32 v70, v59
	v_mul_f32_e32 v59, 0x3d372713, v65
	v_mul_f32_e32 v59, v65, v59
	v_fma_f32 v59, v65, v59, v65
	v_mul_f32_e32 v58, 0x3f4c422a, v58
	v_mul_f32_e32 v59, 0x3f4c422a, v59
	v_add_f32_e32 v58, v58, v58
	v_add_f32_e32 v59, v59, v59
	v_mul_f32_e32 v58, 0xbfb8aa3b, v58
	v_mul_f32_e32 v59, 0xbfb8aa3b, v59
	v_exp_f32_e32 v58, v58
	v_exp_f32_e32 v59, v59
	v_add_f32_e32 v58, 1.0, v58
	v_add_f32_e32 v59, 1.0, v59
	v_rcp_f32_e32 v58, v58
	v_rcp_f32_e32 v59, v59
	s_nop 0
	v_pk_mul_f32 v[64:65], v[64:65], v[58:59]
	v_mul_f32_e32 v58, 0x3d372713, v61
	v_mul_f32_e32 v58, v61, v58
	v_fma_f32 v58, v61, v58, v61
	v_mul_f32_e32 v58, 0x3f4c422a, v58
	v_add_f32_e32 v58, v58, v58
	v_mul_f32_e32 v58, 0xbfb8aa3b, v58
	v_exp_f32_e32 v58, v58
	v_cvt_pk_bf16_f32 v59, v64, v65
	v_add_f32_e32 v58, 1.0, v58
	v_rcp_f32_e32 v71, v58
	v_cvt_pk_bf16_f32 v58, v62, v63
	v_lshl_add_u64 v[62:63], v[66:67], 0, v[122:123]
; DEVI float sigmoidf_(float x) { return __builtin_amdgcn_rcpf(1.f + __expf(-x)); }
; DEVI float siluf_(float x) { return x * __builtin_amdgcn_rcpf(1.f + __expf(-x)); }
; DEVI float logsigf_(float x) { return fminf(x, 0.f) - __logf(1.f + __expf(-fabsf(x))); }
	v_pk_mul_f32 v[70:71], v[60:61], v[70:71]
	v_cvt_pk_bf16_f32 v60, v68, v69
	v_cvt_pk_bf16_f32 v61, v70, v71
	global_store_dwordx4 v[62:63], v[58:61], off
	s_nop 1
	v_mul_f32_e32 v59, 0x3d372713, v50
	v_mul_f32_e32 v59, v50, v59
	v_fma_f32 v59, v50, v59, v50
	v_mul_f32_e32 v59, 0x3f4c422a, v59
	v_add_f32_e32 v59, v59, v59
	v_mul_f32_e32 v59, 0xbfb8aa3b, v59
	v_exp_f32_e32 v59, v59
	v_mul_f32_e32 v58, 0x3d372713, v54
	v_mul_f32_e32 v58, v54, v58
	v_fma_f32 v58, v54, v58, v54
	v_add_f32_e32 v59, 1.0, v59
	v_rcp_f32_e32 v60, v59
	v_mul_f32_e32 v59, 0x3d372713, v55
	v_mul_f32_e32 v59, v55, v59
	v_fma_f32 v59, v55, v59, v55
	v_mul_f32_e32 v58, 0x3f4c422a, v58
	v_mul_f32_e32 v59, 0x3f4c422a, v59
	v_add_f32_e32 v58, v58, v58
	v_add_f32_e32 v59, v59, v59
	v_mul_f32_e32 v58, 0xbfb8aa3b, v58
	v_mul_f32_e32 v59, 0xbfb8aa3b, v59
	v_exp_f32_e32 v58, v58
	v_exp_f32_e32 v59, v59
	v_add_f32_e32 v58, 1.0, v58
	v_add_f32_e32 v59, 1.0, v59
	v_rcp_f32_e32 v58, v58
	v_rcp_f32_e32 v59, v59
	s_nop 0
	v_pk_mul_f32 v[54:55], v[54:55], v[58:59]
	v_mul_f32_e32 v58, 0x3d372713, v51
	v_mul_f32_e32 v58, v51, v58
	v_fma_f32 v58, v51, v58, v51
	v_mul_f32_e32 v58, 0x3f4c422a, v58
	v_add_f32_e32 v58, v58, v58
	v_mul_f32_e32 v58, 0xbfb8aa3b, v58
	v_exp_f32_e32 v58, v58
	s_nop 0
	v_add_f32_e32 v58, 1.0, v58
	v_rcp_f32_e32 v61, v58
	s_nop 0
	v_pk_mul_f32 v[58:59], v[50:51], v[60:61]
	v_mul_f32_e32 v51, 0x3d372713, v52
	v_mul_f32_e32 v51, v52, v51
	v_fma_f32 v51, v52, v51, v52
	v_mul_f32_e32 v51, 0x3f4c422a, v51
	v_add_f32_e32 v51, v51, v51
	v_mul_f32_e32 v51, 0xbfb8aa3b, v51
	v_exp_f32_e32 v51, v51
	v_mul_f32_e32 v50, 0x3d372713, v56
	v_mul_f32_e32 v50, v56, v50
	v_fma_f32 v50, v56, v50, v56
	v_add_f32_e32 v51, 1.0, v51
	v_rcp_f32_e32 v60, v51
	v_mul_f32_e32 v51, 0x3d372713, v57
	v_mul_f32_e32 v51, v57, v51
	v_fma_f32 v51, v57, v51, v57
	v_mul_f32_e32 v50, 0x3f4c422a, v50
	v_mul_f32_e32 v51, 0x3f4c422a, v51
	v_add_f32_e32 v50, v50, v50
	v_add_f32_e32 v51, v51, v51
	v_mul_f32_e32 v50, 0xbfb8aa3b, v50
	v_mul_f32_e32 v51, 0xbfb8aa3b, v51
	v_exp_f32_e32 v50, v50
	v_exp_f32_e32 v51, v51
	v_add_f32_e32 v50, 1.0, v50
	v_add_f32_e32 v51, 1.0, v51
	v_rcp_f32_e32 v50, v50
	v_rcp_f32_e32 v51, v51
	s_nop 0
	v_pk_mul_f32 v[56:57], v[56:57], v[50:51]
	v_mul_f32_e32 v50, 0x3d372713, v53
	v_mul_f32_e32 v50, v53, v50
	v_fma_f32 v50, v53, v50, v53
	v_mul_f32_e32 v50, 0x3f4c422a, v50
	v_add_f32_e32 v50, v50, v50
	v_mul_f32_e32 v50, 0xbfb8aa3b, v50
	v_exp_f32_e32 v50, v50
	v_cvt_pk_bf16_f32 v51, v56, v57
	v_add_f32_e32 v50, 1.0, v50
	v_rcp_f32_e32 v61, v50
	v_cvt_pk_bf16_f32 v50, v54, v55
	v_lshl_add_u64 v[54:55], v[66:67], 0, v[114:115]
	v_pk_mul_f32 v[60:61], v[52:53], v[60:61]
	v_cvt_pk_bf16_f32 v52, v58, v59
	v_cvt_pk_bf16_f32 v53, v60, v61
	global_store_dwordx4 v[54:55], v[50:53], off
	s_nop 1
	v_mul_f32_e32 v53, 0x3d372713, v42
	v_mul_f32_e32 v53, v42, v53
	v_fma_f32 v53, v42, v53, v42
	v_mul_f32_e32 v53, 0x3f4c422a, v53
	v_add_f32_e32 v53, v53, v53
	v_mul_f32_e32 v53, 0xbfb8aa3b, v53
	v_exp_f32_e32 v53, v53
	v_mul_f32_e32 v52, 0x3d372713, v46
	v_mul_f32_e32 v52, v46, v52
	v_fma_f32 v52, v46, v52, v46
	v_add_f32_e32 v53, 1.0, v53
	v_rcp_f32_e32 v54, v53
	v_mul_f32_e32 v53, 0x3d372713, v47
	v_mul_f32_e32 v53, v47, v53
	v_fma_f32 v53, v47, v53, v47
	v_mul_f32_e32 v52, 0x3f4c422a, v52
	v_mul_f32_e32 v53, 0x3f4c422a, v53
	v_add_f32_e32 v52, v52, v52
	v_add_f32_e32 v53, v53, v53
	v_mul_f32_e32 v52, 0xbfb8aa3b, v52
	v_mul_f32_e32 v53, 0xbfb8aa3b, v53
	v_exp_f32_e32 v52, v52
	v_exp_f32_e32 v53, v53
	v_lshl_add_u64 v[50:51], v[142:143], 0, s[0:1]
	s_mov_b64 s[0:1], 0xa00000
	v_add_f32_e32 v52, 1.0, v52
	v_add_f32_e32 v53, 1.0, v53
	v_rcp_f32_e32 v52, v52
	v_rcp_f32_e32 v53, v53
	s_nop 0
	v_pk_mul_f32 v[46:47], v[46:47], v[52:53]
	v_mul_f32_e32 v52, 0x3d372713, v43
	v_mul_f32_e32 v52, v43, v52
	v_fma_f32 v52, v43, v52, v43
	v_mul_f32_e32 v52, 0x3f4c422a, v52
	v_add_f32_e32 v52, v52, v52
	v_mul_f32_e32 v52, 0xbfb8aa3b, v52
	v_exp_f32_e32 v52, v52
	s_nop 0
	v_add_f32_e32 v52, 1.0, v52
	v_rcp_f32_e32 v55, v52
	s_nop 0
	v_pk_mul_f32 v[52:53], v[42:43], v[54:55]
	v_mul_f32_e32 v43, 0x3d372713, v44
	v_mul_f32_e32 v43, v44, v43
	v_fma_f32 v43, v44, v43, v44
	v_mul_f32_e32 v43, 0x3f4c422a, v43
	v_add_f32_e32 v43, v43, v43
	v_mul_f32_e32 v43, 0xbfb8aa3b, v43
	v_exp_f32_e32 v43, v43
	v_mul_f32_e32 v42, 0x3d372713, v48
	v_mul_f32_e32 v42, v48, v42
	v_fma_f32 v42, v48, v42, v48
	v_add_f32_e32 v43, 1.0, v43
	v_rcp_f32_e32 v54, v43
	v_mul_f32_e32 v43, 0x3d372713, v49
	v_mul_f32_e32 v43, v49, v43
	v_fma_f32 v43, v49, v43, v49
	v_mul_f32_e32 v42, 0x3f4c422a, v42
	v_mul_f32_e32 v43, 0x3f4c422a, v43
	v_add_f32_e32 v42, v42, v42
	v_add_f32_e32 v43, v43, v43
	v_mul_f32_e32 v42, 0xbfb8aa3b, v42
	v_mul_f32_e32 v43, 0xbfb8aa3b, v43
	v_exp_f32_e32 v42, v42
	v_exp_f32_e32 v43, v43
	v_add_f32_e32 v42, 1.0, v42
	v_add_f32_e32 v43, 1.0, v43
	v_rcp_f32_e32 v42, v42
	v_rcp_f32_e32 v43, v43
	s_nop 0
	v_pk_mul_f32 v[48:49], v[48:49], v[42:43]
	v_mul_f32_e32 v42, 0x3d372713, v45
	v_mul_f32_e32 v42, v45, v42
	v_fma_f32 v42, v45, v42, v45
	v_mul_f32_e32 v42, 0x3f4c422a, v42
	v_add_f32_e32 v42, v42, v42
	v_mul_f32_e32 v42, 0xbfb8aa3b, v42
	v_exp_f32_e32 v42, v42
	v_cvt_pk_bf16_f32 v43, v48, v49
	v_add_f32_e32 v42, 1.0, v42
	v_rcp_f32_e32 v55, v42
	v_cvt_pk_bf16_f32 v42, v46, v47
	v_lshl_add_u64 v[46:47], v[50:51], 0, v[122:123]
	v_pk_mul_f32 v[54:55], v[44:45], v[54:55]
	v_cvt_pk_bf16_f32 v44, v52, v53
	v_cvt_pk_bf16_f32 v45, v54, v55
	global_store_dwordx4 v[46:47], v[42:45], off
	s_nop 1
	v_mul_f32_e32 v43, 0x3d372713, v34
	v_mul_f32_e32 v43, v34, v43
	v_fma_f32 v43, v34, v43, v34
	v_mul_f32_e32 v43, 0x3f4c422a, v43
; DEVI float sigmoidf_(float x) { return __builtin_amdgcn_rcpf(1.f + __expf(-x)); }
; DEVI float siluf_(float x) { return x * __builtin_amdgcn_rcpf(1.f + __expf(-x)); }
; DEVI float logsigf_(float x) { return fminf(x, 0.f) - __logf(1.f + __expf(-fabsf(x))); }
	v_add_f32_e32 v43, v43, v43
	v_mul_f32_e32 v43, 0xbfb8aa3b, v43
	v_exp_f32_e32 v43, v43
	v_mul_f32_e32 v42, 0x3d372713, v38
	v_mul_f32_e32 v42, v38, v42
	v_fma_f32 v42, v38, v42, v38
	v_add_f32_e32 v43, 1.0, v43
	v_rcp_f32_e32 v44, v43
	v_mul_f32_e32 v43, 0x3d372713, v39
	v_mul_f32_e32 v43, v39, v43
	v_fma_f32 v43, v39, v43, v39
	v_mul_f32_e32 v42, 0x3f4c422a, v42
	v_mul_f32_e32 v43, 0x3f4c422a, v43
	v_add_f32_e32 v42, v42, v42
	v_add_f32_e32 v43, v43, v43
	v_mul_f32_e32 v42, 0xbfb8aa3b, v42
	v_mul_f32_e32 v43, 0xbfb8aa3b, v43
	v_exp_f32_e32 v42, v42
	v_exp_f32_e32 v43, v43
	v_add_f32_e32 v42, 1.0, v42
	v_add_f32_e32 v43, 1.0, v43
	v_rcp_f32_e32 v42, v42
	v_rcp_f32_e32 v43, v43
	s_nop 0
	v_pk_mul_f32 v[38:39], v[38:39], v[42:43]
	v_mul_f32_e32 v42, 0x3d372713, v35
	v_mul_f32_e32 v42, v35, v42
	v_fma_f32 v42, v35, v42, v35
	v_mul_f32_e32 v42, 0x3f4c422a, v42
	v_add_f32_e32 v42, v42, v42
	v_mul_f32_e32 v42, 0xbfb8aa3b, v42
	v_exp_f32_e32 v42, v42
	s_nop 0
	v_add_f32_e32 v42, 1.0, v42
	v_rcp_f32_e32 v45, v42
	s_nop 0
	v_pk_mul_f32 v[42:43], v[34:35], v[44:45]
	v_mul_f32_e32 v35, 0x3d372713, v36
	v_mul_f32_e32 v35, v36, v35
	v_fma_f32 v35, v36, v35, v36
	v_mul_f32_e32 v35, 0x3f4c422a, v35
	v_add_f32_e32 v35, v35, v35
	v_mul_f32_e32 v35, 0xbfb8aa3b, v35
	v_exp_f32_e32 v35, v35
	v_mul_f32_e32 v34, 0x3d372713, v40
	v_mul_f32_e32 v34, v40, v34
	v_fma_f32 v34, v40, v34, v40
	v_add_f32_e32 v35, 1.0, v35
	v_rcp_f32_e32 v44, v35
	v_mul_f32_e32 v35, 0x3d372713, v41
	v_mul_f32_e32 v35, v41, v35
	v_fma_f32 v35, v41, v35, v41
	v_mul_f32_e32 v34, 0x3f4c422a, v34
	v_mul_f32_e32 v35, 0x3f4c422a, v35
	v_add_f32_e32 v34, v34, v34
	v_add_f32_e32 v35, v35, v35
	v_mul_f32_e32 v34, 0xbfb8aa3b, v34
	v_mul_f32_e32 v35, 0xbfb8aa3b, v35
	v_exp_f32_e32 v34, v34
	v_exp_f32_e32 v35, v35
	v_add_f32_e32 v34, 1.0, v34
	v_add_f32_e32 v35, 1.0, v35
	v_rcp_f32_e32 v34, v34
	v_rcp_f32_e32 v35, v35
	s_nop 0
	v_pk_mul_f32 v[40:41], v[40:41], v[34:35]
	v_mul_f32_e32 v34, 0x3d372713, v37
	v_mul_f32_e32 v34, v37, v34
	v_fma_f32 v34, v37, v34, v37
	v_mul_f32_e32 v34, 0x3f4c422a, v34
	v_add_f32_e32 v34, v34, v34
	v_mul_f32_e32 v34, 0xbfb8aa3b, v34
	v_exp_f32_e32 v34, v34
	v_cvt_pk_bf16_f32 v35, v40, v41
	v_add_f32_e32 v34, 1.0, v34
	v_rcp_f32_e32 v45, v34
	v_cvt_pk_bf16_f32 v34, v38, v39
	v_lshl_add_u64 v[38:39], v[50:51], 0, v[114:115]
	v_pk_mul_f32 v[44:45], v[36:37], v[44:45]
	v_cvt_pk_bf16_f32 v36, v42, v43
	v_cvt_pk_bf16_f32 v37, v44, v45
	global_store_dwordx4 v[38:39], v[34:37], off
	s_nop 1
	v_mul_f32_e32 v37, 0x3d372713, v26
	v_mul_f32_e32 v37, v26, v37
	v_fma_f32 v37, v26, v37, v26
	v_mul_f32_e32 v37, 0x3f4c422a, v37
	v_add_f32_e32 v37, v37, v37
	v_mul_f32_e32 v37, 0xbfb8aa3b, v37
	v_exp_f32_e32 v37, v37
	v_mul_f32_e32 v36, 0x3d372713, v30
	v_mul_f32_e32 v36, v30, v36
	v_fma_f32 v36, v30, v36, v30
	v_add_f32_e32 v37, 1.0, v37
	v_rcp_f32_e32 v38, v37
	v_mul_f32_e32 v37, 0x3d372713, v31
	v_mul_f32_e32 v37, v31, v37
	v_fma_f32 v37, v31, v37, v31
	v_mul_f32_e32 v36, 0x3f4c422a, v36
	v_mul_f32_e32 v37, 0x3f4c422a, v37
	v_add_f32_e32 v36, v36, v36
	v_add_f32_e32 v37, v37, v37
	v_mul_f32_e32 v36, 0xbfb8aa3b, v36
	v_mul_f32_e32 v37, 0xbfb8aa3b, v37
	v_exp_f32_e32 v36, v36
	v_exp_f32_e32 v37, v37
	v_lshl_add_u64 v[34:35], v[142:143], 0, s[0:1]
	s_mov_b64 s[0:1], 0xb00000
	v_add_f32_e32 v36, 1.0, v36
	v_add_f32_e32 v37, 1.0, v37
	v_rcp_f32_e32 v36, v36
	v_rcp_f32_e32 v37, v37
	s_nop 0
	v_pk_mul_f32 v[30:31], v[30:31], v[36:37]
	v_mul_f32_e32 v36, 0x3d372713, v27
	v_mul_f32_e32 v36, v27, v36
	v_fma_f32 v36, v27, v36, v27
	v_mul_f32_e32 v36, 0x3f4c422a, v36
	v_add_f32_e32 v36, v36, v36
	v_mul_f32_e32 v36, 0xbfb8aa3b, v36
	v_exp_f32_e32 v36, v36
	s_nop 0
	v_add_f32_e32 v36, 1.0, v36
	v_rcp_f32_e32 v39, v36
	s_nop 0
	v_pk_mul_f32 v[36:37], v[26:27], v[38:39]
	v_mul_f32_e32 v27, 0x3d372713, v28
	v_mul_f32_e32 v27, v28, v27
	v_fma_f32 v27, v28, v27, v28
	v_mul_f32_e32 v27, 0x3f4c422a, v27
	v_add_f32_e32 v27, v27, v27
	v_mul_f32_e32 v27, 0xbfb8aa3b, v27
	v_exp_f32_e32 v27, v27
	v_mul_f32_e32 v26, 0x3d372713, v32
	v_mul_f32_e32 v26, v32, v26
	v_fma_f32 v26, v32, v26, v32
	v_add_f32_e32 v27, 1.0, v27
	v_rcp_f32_e32 v38, v27
	v_mul_f32_e32 v27, 0x3d372713, v33
	v_mul_f32_e32 v27, v33, v27
	v_fma_f32 v27, v33, v27, v33
	v_mul_f32_e32 v26, 0x3f4c422a, v26
	v_mul_f32_e32 v27, 0x3f4c422a, v27
	v_add_f32_e32 v26, v26, v26
	v_add_f32_e32 v27, v27, v27
	v_mul_f32_e32 v26, 0xbfb8aa3b, v26
	v_mul_f32_e32 v27, 0xbfb8aa3b, v27
	v_exp_f32_e32 v26, v26
	v_exp_f32_e32 v27, v27
	v_add_f32_e32 v26, 1.0, v26
	v_add_f32_e32 v27, 1.0, v27
	v_rcp_f32_e32 v26, v26
	v_rcp_f32_e32 v27, v27
	s_nop 0
	v_pk_mul_f32 v[32:33], v[32:33], v[26:27]
	v_mul_f32_e32 v26, 0x3d372713, v29
	v_mul_f32_e32 v26, v29, v26
	v_fma_f32 v26, v29, v26, v29
	v_mul_f32_e32 v26, 0x3f4c422a, v26
	v_add_f32_e32 v26, v26, v26
	v_mul_f32_e32 v26, 0xbfb8aa3b, v26
	v_exp_f32_e32 v26, v26
	v_cvt_pk_bf16_f32 v27, v32, v33
	v_add_f32_e32 v26, 1.0, v26
	v_rcp_f32_e32 v39, v26
	v_cvt_pk_bf16_f32 v26, v30, v31
	v_lshl_add_u64 v[30:31], v[34:35], 0, v[122:123]
	v_pk_mul_f32 v[38:39], v[28:29], v[38:39]
	v_cvt_pk_bf16_f32 v28, v36, v37
	v_cvt_pk_bf16_f32 v29, v38, v39
	global_store_dwordx4 v[30:31], v[26:29], off
	s_nop 1
	v_mul_f32_e32 v27, 0x3d372713, v18
	v_mul_f32_e32 v27, v18, v27
	v_fma_f32 v27, v18, v27, v18
	v_mul_f32_e32 v27, 0x3f4c422a, v27
	v_add_f32_e32 v27, v27, v27
	v_mul_f32_e32 v27, 0xbfb8aa3b, v27
	v_exp_f32_e32 v27, v27
	v_mul_f32_e32 v26, 0x3d372713, v22
	v_mul_f32_e32 v26, v22, v26
	v_fma_f32 v26, v22, v26, v22
	v_add_f32_e32 v27, 1.0, v27
	v_rcp_f32_e32 v28, v27
	v_mul_f32_e32 v27, 0x3d372713, v23
	v_mul_f32_e32 v27, v23, v27
; DEVI float sigmoidf_(float x) { return __builtin_amdgcn_rcpf(1.f + __expf(-x)); }
; DEVI float siluf_(float x) { return x * __builtin_amdgcn_rcpf(1.f + __expf(-x)); }
; DEVI float logsigf_(float x) { return fminf(x, 0.f) - __logf(1.f + __expf(-fabsf(x))); }
	v_fma_f32 v27, v23, v27, v23
	v_mul_f32_e32 v26, 0x3f4c422a, v26
	v_mul_f32_e32 v27, 0x3f4c422a, v27
	v_add_f32_e32 v26, v26, v26
	v_add_f32_e32 v27, v27, v27
	v_mul_f32_e32 v26, 0xbfb8aa3b, v26
	v_mul_f32_e32 v27, 0xbfb8aa3b, v27
	v_exp_f32_e32 v26, v26
	v_exp_f32_e32 v27, v27
	v_add_f32_e32 v26, 1.0, v26
	v_add_f32_e32 v27, 1.0, v27
	v_rcp_f32_e32 v26, v26
	v_rcp_f32_e32 v27, v27
	s_nop 0
	v_pk_mul_f32 v[22:23], v[22:23], v[26:27]
	v_mul_f32_e32 v26, 0x3d372713, v19
	v_mul_f32_e32 v26, v19, v26
	v_fma_f32 v26, v19, v26, v19
	v_mul_f32_e32 v26, 0x3f4c422a, v26
	v_add_f32_e32 v26, v26, v26
	v_mul_f32_e32 v26, 0xbfb8aa3b, v26
	v_exp_f32_e32 v26, v26
	s_nop 0
	v_add_f32_e32 v26, 1.0, v26
	v_rcp_f32_e32 v29, v26
	s_nop 0
	v_pk_mul_f32 v[26:27], v[18:19], v[28:29]
	v_mul_f32_e32 v19, 0x3d372713, v20
	v_mul_f32_e32 v19, v20, v19
	v_fma_f32 v19, v20, v19, v20
	v_mul_f32_e32 v19, 0x3f4c422a, v19
	v_add_f32_e32 v19, v19, v19
	v_mul_f32_e32 v19, 0xbfb8aa3b, v19
	v_exp_f32_e32 v19, v19
	v_mul_f32_e32 v18, 0x3d372713, v24
	v_mul_f32_e32 v18, v24, v18
	v_fma_f32 v18, v24, v18, v24
	v_add_f32_e32 v19, 1.0, v19
	v_rcp_f32_e32 v28, v19
	v_mul_f32_e32 v19, 0x3d372713, v25
	v_mul_f32_e32 v19, v25, v19
	v_fma_f32 v19, v25, v19, v25
	v_mul_f32_e32 v18, 0x3f4c422a, v18
	v_mul_f32_e32 v19, 0x3f4c422a, v19
	v_add_f32_e32 v18, v18, v18
	v_add_f32_e32 v19, v19, v19
	v_mul_f32_e32 v18, 0xbfb8aa3b, v18
	v_mul_f32_e32 v19, 0xbfb8aa3b, v19
	v_exp_f32_e32 v18, v18
	v_exp_f32_e32 v19, v19
	v_add_f32_e32 v18, 1.0, v18
	v_add_f32_e32 v19, 1.0, v19
	v_rcp_f32_e32 v18, v18
	v_rcp_f32_e32 v19, v19
	s_nop 0
	v_pk_mul_f32 v[24:25], v[24:25], v[18:19]
	v_mul_f32_e32 v18, 0x3d372713, v21
	v_mul_f32_e32 v18, v21, v18
	v_fma_f32 v18, v21, v18, v21
	v_mul_f32_e32 v18, 0x3f4c422a, v18
	v_add_f32_e32 v18, v18, v18
	v_mul_f32_e32 v18, 0xbfb8aa3b, v18
	v_exp_f32_e32 v18, v18
	v_cvt_pk_bf16_f32 v19, v24, v25
	v_add_f32_e32 v18, 1.0, v18
	v_rcp_f32_e32 v29, v18
	v_cvt_pk_bf16_f32 v18, v22, v23
	v_lshl_add_u64 v[22:23], v[34:35], 0, v[114:115]
	v_pk_mul_f32 v[28:29], v[20:21], v[28:29]
	v_cvt_pk_bf16_f32 v20, v26, v27
	v_cvt_pk_bf16_f32 v21, v28, v29
	global_store_dwordx4 v[22:23], v[18:21], off
	s_nop 1
	v_mul_f32_e32 v21, 0x3d372713, v10
	v_mul_f32_e32 v21, v10, v21
	v_fma_f32 v21, v10, v21, v10
	v_mul_f32_e32 v21, 0x3f4c422a, v21
	v_add_f32_e32 v21, v21, v21
	v_mul_f32_e32 v21, 0xbfb8aa3b, v21
	v_exp_f32_e32 v21, v21
	v_mul_f32_e32 v20, 0x3d372713, v14
	v_mul_f32_e32 v20, v14, v20
	v_fma_f32 v20, v14, v20, v14
	v_add_f32_e32 v21, 1.0, v21
	v_rcp_f32_e32 v22, v21
	v_mul_f32_e32 v21, 0x3d372713, v15
	v_mul_f32_e32 v21, v15, v21
	v_fma_f32 v21, v15, v21, v15
	v_mul_f32_e32 v20, 0x3f4c422a, v20
	v_mul_f32_e32 v21, 0x3f4c422a, v21
	v_add_f32_e32 v20, v20, v20
	v_add_f32_e32 v21, v21, v21
	v_mul_f32_e32 v20, 0xbfb8aa3b, v20
	v_mul_f32_e32 v21, 0xbfb8aa3b, v21
	v_exp_f32_e32 v20, v20
	v_exp_f32_e32 v21, v21
	v_lshl_add_u64 v[18:19], v[142:143], 0, s[0:1]
	s_mov_b32 s0, s8
	v_add_f32_e32 v20, 1.0, v20
	v_add_f32_e32 v21, 1.0, v21
	v_rcp_f32_e32 v20, v20
	v_rcp_f32_e32 v21, v21
	s_mov_b32 s1, s9
	v_pk_mul_f32 v[14:15], v[14:15], v[20:21]
	v_mul_f32_e32 v20, 0x3d372713, v11
	v_mul_f32_e32 v20, v11, v20
	v_fma_f32 v20, v11, v20, v11
	v_mul_f32_e32 v20, 0x3f4c422a, v20
	v_add_f32_e32 v20, v20, v20
	v_mul_f32_e32 v20, 0xbfb8aa3b, v20
	v_exp_f32_e32 v20, v20
	s_nop 0
	v_add_f32_e32 v20, 1.0, v20
	v_rcp_f32_e32 v23, v20
	s_nop 0
	v_pk_mul_f32 v[20:21], v[10:11], v[22:23]
	v_mul_f32_e32 v11, 0x3d372713, v12
	v_mul_f32_e32 v11, v12, v11
	v_fma_f32 v11, v12, v11, v12
	v_mul_f32_e32 v11, 0x3f4c422a, v11
	v_add_f32_e32 v11, v11, v11
	v_mul_f32_e32 v11, 0xbfb8aa3b, v11
	v_exp_f32_e32 v11, v11
	v_mul_f32_e32 v10, 0x3d372713, v16
	v_mul_f32_e32 v10, v16, v10
; #define PG8_WAIT_V(n) asm volatile("s_waitcnt vmcnt(" #n ")" ::: "memory")
; #define PG8_BAR __builtin_amdgcn_s_barrier()
; template <class Epi>
; DEVI void gemm_phase(LAS unsigned char* lds, const Gemm g, const Epi& E) {
;     ...
;         if (!has_next) break;
; #pragma unroll
;         for (int a = 0; a < 2; ++a)
; #pragma unroll
;             for (int b = 0; b < 2; ++b)
; #pragma unroll
;                 for (int m = 0; m < 4; ++m)
; #pragma unroll
;                     for (int n = 0; n < 2; ++n) acc[a][b][m][n] = (f32x4){0.f, 0.f, 0.f, 0.f};
;         cur = nxt; cA = nA; cB = nB; ++ui;
;     }
;     PG8_WAIT_V(0);
;     if (wr == 0) PG8_BAR;
;     PG8_BAR;
	v_fma_f32 v10, v16, v10, v16
	v_add_f32_e32 v11, 1.0, v11
	v_rcp_f32_e32 v22, v11
	v_mul_f32_e32 v11, 0x3d372713, v17
	v_mul_f32_e32 v11, v17, v11
	v_fma_f32 v11, v17, v11, v17
	v_mul_f32_e32 v10, 0x3f4c422a, v10
	v_mul_f32_e32 v11, 0x3f4c422a, v11
	v_add_f32_e32 v10, v10, v10
	v_add_f32_e32 v11, v11, v11
	v_mul_f32_e32 v10, 0xbfb8aa3b, v10
	v_mul_f32_e32 v11, 0xbfb8aa3b, v11
	v_exp_f32_e32 v10, v10
	v_exp_f32_e32 v11, v11
	v_add_f32_e32 v10, 1.0, v10
	v_add_f32_e32 v11, 1.0, v11
	v_rcp_f32_e32 v10, v10
	v_rcp_f32_e32 v11, v11
	s_nop 0
	v_pk_mul_f32 v[16:17], v[16:17], v[10:11]
	v_mul_f32_e32 v10, 0x3d372713, v13
	v_mul_f32_e32 v10, v13, v10
	v_fma_f32 v10, v13, v10, v13
	v_mul_f32_e32 v10, 0x3f4c422a, v10
	v_add_f32_e32 v10, v10, v10
	v_mul_f32_e32 v10, 0xbfb8aa3b, v10
	v_exp_f32_e32 v10, v10
	v_cvt_pk_bf16_f32 v11, v16, v17
	v_add_f32_e32 v10, 1.0, v10
	v_rcp_f32_e32 v23, v10
	v_cvt_pk_bf16_f32 v10, v14, v15
	v_lshl_add_u64 v[14:15], v[18:19], 0, v[122:123]
	v_pk_mul_f32 v[22:23], v[12:13], v[22:23]
	v_cvt_pk_bf16_f32 v12, v20, v21
	v_cvt_pk_bf16_f32 v13, v22, v23
	global_store_dwordx4 v[14:15], v[10:13], off
	s_nop 1
	v_mul_f32_e32 v11, 0x3d372713, v0
	v_mul_f32_e32 v11, v0, v11
	v_fma_f32 v11, v0, v11, v0
	v_mul_f32_e32 v11, 0x3f4c422a, v11
	v_add_f32_e32 v11, v11, v11
	v_mul_f32_e32 v11, 0xbfb8aa3b, v11
	v_exp_f32_e32 v11, v11
	v_mul_f32_e32 v10, 0x3d372713, v4
	v_mul_f32_e32 v10, v4, v10
	v_fma_f32 v10, v4, v10, v4
	v_add_f32_e32 v11, 1.0, v11
	v_rcp_f32_e32 v12, v11
	v_mul_f32_e32 v11, 0x3d372713, v5
	v_mul_f32_e32 v11, v5, v11
	v_fma_f32 v11, v5, v11, v5
	v_mul_f32_e32 v10, 0x3f4c422a, v10
	v_mul_f32_e32 v11, 0x3f4c422a, v11
	v_add_f32_e32 v10, v10, v10
	v_add_f32_e32 v11, v11, v11
	v_mul_f32_e32 v10, 0xbfb8aa3b, v10
	v_mul_f32_e32 v11, 0xbfb8aa3b, v11
	v_exp_f32_e32 v10, v10
	v_exp_f32_e32 v11, v11
	v_add_f32_e32 v10, 1.0, v10
	v_add_f32_e32 v11, 1.0, v11
	v_rcp_f32_e32 v10, v10
	v_rcp_f32_e32 v11, v11
	s_nop 0
	v_pk_mul_f32 v[4:5], v[4:5], v[10:11]
	v_mul_f32_e32 v10, 0x3d372713, v1
	v_mul_f32_e32 v10, v1, v10
	v_fma_f32 v10, v1, v10, v1
	v_mul_f32_e32 v10, 0x3f4c422a, v10
	v_add_f32_e32 v10, v10, v10
	v_mul_f32_e32 v10, 0xbfb8aa3b, v10
	v_exp_f32_e32 v10, v10
	s_nop 0
	v_add_f32_e32 v10, 1.0, v10
	v_rcp_f32_e32 v13, v10
	s_nop 0
	v_pk_mul_f32 v[10:11], v[0:1], v[12:13]
	v_mul_f32_e32 v1, 0x3d372713, v2
	v_mul_f32_e32 v1, v2, v1
	v_fma_f32 v1, v2, v1, v2
	v_mul_f32_e32 v1, 0x3f4c422a, v1
	v_add_f32_e32 v1, v1, v1
	v_mul_f32_e32 v1, 0xbfb8aa3b, v1
	v_exp_f32_e32 v1, v1
	v_mul_f32_e32 v0, 0x3d372713, v6
	v_mul_f32_e32 v0, v6, v0
	v_fma_f32 v0, v6, v0, v6
	v_add_f32_e32 v1, 1.0, v1
	v_rcp_f32_e32 v12, v1
	v_mul_f32_e32 v1, 0x3d372713, v7
	v_mul_f32_e32 v1, v7, v1
	v_fma_f32 v1, v7, v1, v7
	v_mul_f32_e32 v0, 0x3f4c422a, v0
	v_mul_f32_e32 v1, 0x3f4c422a, v1
	v_add_f32_e32 v0, v0, v0
	v_add_f32_e32 v1, v1, v1
	v_mul_f32_e32 v0, 0xbfb8aa3b, v0
	v_mul_f32_e32 v1, 0xbfb8aa3b, v1
	v_exp_f32_e32 v0, v0
	v_exp_f32_e32 v1, v1
	v_add_f32_e32 v0, 1.0, v0
	v_add_f32_e32 v1, 1.0, v1
	v_rcp_f32_e32 v0, v0
	v_rcp_f32_e32 v1, v1
	s_nop 0
	v_pk_mul_f32 v[6:7], v[6:7], v[0:1]
	v_mul_f32_e32 v0, 0x3d372713, v3
	v_mul_f32_e32 v0, v3, v0
	v_fma_f32 v0, v3, v0, v3
	v_mul_f32_e32 v0, 0x3f4c422a, v0
	v_add_f32_e32 v0, v0, v0
	v_mul_f32_e32 v0, 0xbfb8aa3b, v0
	v_exp_f32_e32 v0, v0
	v_cvt_pk_bf16_f32 v1, v6, v7
	v_add_f32_e32 v0, 1.0, v0
	v_rcp_f32_e32 v13, v0
	v_cvt_pk_bf16_f32 v0, v4, v5
	v_lshl_add_u64 v[4:5], v[18:19], 0, v[114:115]
	v_pk_mul_f32 v[12:13], v[2:3], v[12:13]
	v_cvt_pk_bf16_f32 v2, v10, v11
	v_cvt_pk_bf16_f32 v3, v12, v13
	global_store_dwordx4 v[4:5], v[0:3], off
	s_cbranch_vccz .LBB0_1271
	s_waitcnt vmcnt(0)
	s_cmpk_gt_u32 s36, 0xff
	s_cbranch_scc1 .LBB0_1282
	s_barrier

; #define PG8_STAGE(bufoff, gbase, voff) do { _Pragma("unroll") for (int _i = 0; _i < 2; ++_i) \
;         __builtin_amdgcn_global_load_lds((const unsigned*)((const char*)(gbase) + (voff)[_i]), (LAS unsigned*)(lds + (bufoff) + ldsw + _i * 8192), 16, 0, 0); } while (0)
; #define PG8_LDA(dst, b, h) do { _Pragma("unroll") for (int m = 0; m < 4; ++m) _Pragma("unroll") for (int k = 0; k < 2; ++k) dst[m][k] = *(const LAS bf16x8*)(lds + PG8_SA(b, h) + aoff + m * 2048 + k * 1024); } while (0)
; #define PG8_LDB(dst, b, h) do { _Pragma("unroll") for (int n = 0; n < 2; ++n) _Pragma("unroll") for (int k = 0; k < 2; ++k) dst[n][k] = *(const LAS bf16x8*)(lds + PG8_SB(b, h) + boff + n * 2048 + k * 1024); } while (0)
; #define PG8_MMA(ai, bj, At, Bt) do { __builtin_amdgcn_s_setprio(1); _Pragma("unroll") for (int m = 0; m < 4; ++m) _Pragma("unroll") for (int n = 0; n < 2; ++n) _Pragma("unroll") for (int k = 0; k < 2; ++k) \
;         acc[ai][bj][m][n] = __builtin_amdgcn_mfma_f32_16x16x32_bf16(Bt[n][k], At[m][k], acc[ai][bj][m][n], 0, 0, 0); __builtin_amdgcn_s_setprio(0); } while (0)
; #define PG8_WAIT_V(n) asm volatile("s_waitcnt vmcnt(" #n ")" ::: "memory")
; #define PG8_WAIT_L(n) asm volatile("s_waitcnt lgkmcnt(" #n ")" ::: "memory")
; #define PG8_BAR __builtin_amdgcn_s_barrier()
; #define PG8_SCHED __builtin_amdgcn_sched_barrier(0)
; template <class Epi>
; DEVI void gemm_phase(LAS unsigned char* lds, const Gemm g, const Epi& E) {
;     ...
;             PG8_LDB(B0, 0, 0); PG8_SCHED; PG8_LDA(At, 0, 0); PG8_STAGE(PG8_SA(1, 1), a1 + hstepA, voffA);
;             PG8_WAIT_L(8); PG8_BAR; PG8_WAIT_L(0); PG8_MMA(0, 0, At, B0); PG8_BAR; PG8_SCHED;
;             PG8_LDB(B1, 0, 1); PG8_STAGE(PG8_SB(0, 0), b2, voffB);
;             PG8_BAR; PG8_WAIT_L(0); PG8_MMA(0, 1, At, B1); PG8_BAR;
;             PG8_LDA(At, 0, 1); PG8_STAGE(PG8_SA(0, 0), a2, voffA);
;             PG8_BAR; PG8_WAIT_L(0); PG8_MMA(1, 0, At, B0); PG8_BAR; PG8_SCHED;
;             PG8_STAGE(PG8_SB(0, 1), b2 + hstepB, voffB);
;             PG8_WAIT_V(6); PG8_BAR; PG8_MMA(1, 1, At, B1); PG8_BAR;
.LBB0_1346:
	s_add_u32 s14, s12, 0xfffc0080
	s_addc_u32 s15, s13, -1
	s_add_i32 s38, 0, 0x10000
	v_add_u32_e32 v152, s38, v185
	ds_read_b128 v[114:117], v152
	ds_read_b128 v[126:129], v152 offset:1024
	ds_read_b128 v[130:133], v152 offset:2048
	ds_read_b128 v[176:179], v152 offset:3072
	s_cmp_eq_u32 s27, 12
	s_cselect_b32 s17, s1, s15
	s_cselect_b32 s16, s3, s14
	s_cselect_b32 s15, s5, s26
	s_cselect_b32 s14, s18, s19
	v_lshl_add_u64 v[152:153], s[12:13], 0, v[148:149]
	s_add_i32 m0, s11, 0xc000
	ds_read_b128 v[180:183], v187
	ds_read_b128 v[188:191], v187 offset:1024
	ds_read_b128 v[192:195], v187 offset:2048
	ds_read_b128 v[196:199], v187 offset:3072
	ds_read_b128 v[200:203], v187 offset:4096
	ds_read_b128 v[204:207], v187 offset:5120
	ds_read_b128 v[214:217], v187 offset:6144
	ds_read_b128 v[218:221], v187 offset:7168
	global_load_lds_dwordx4 v[152:153], off
	s_add_i32 m0, s11, 0xe000
	v_lshl_add_u64 v[152:153], s[12:13], 0, v[150:151]
	global_load_lds_dwordx4 v[152:153], off
	s_waitcnt lgkmcnt(0)
	s_barrier
	v_mfma_f32_16x16x32_bf16 v[138:141], v[114:117], v[180:183], v[138:141]
	v_mfma_f32_16x16x32_bf16 v[134:137], v[130:133], v[180:183], v[134:137]
	v_mfma_f32_16x16x32_bf16 v[110:113], v[114:117], v[192:195], v[110:113]
	v_mfma_f32_16x16x32_bf16 v[106:109], v[130:133], v[192:195], v[106:109]
	v_mfma_f32_16x16x32_bf16 v[94:97], v[114:117], v[200:203], v[94:97]
	v_mfma_f32_16x16x32_bf16 v[90:93], v[130:133], v[200:203], v[90:93]
	v_mfma_f32_16x16x32_bf16 v[78:81], v[114:117], v[214:217], v[78:81]
	v_mfma_f32_16x16x32_bf16 v[74:77], v[130:133], v[214:217], v[74:77]
	v_mfma_f32_16x16x32_bf16 v[138:141], v[126:129], v[188:191], v[138:141]
	v_mfma_f32_16x16x32_bf16 v[134:137], v[176:179], v[188:191], v[134:137]
	v_mfma_f32_16x16x32_bf16 v[110:113], v[126:129], v[196:199], v[110:113]
	v_mfma_f32_16x16x32_bf16 v[106:109], v[176:179], v[196:199], v[106:109]
	v_mfma_f32_16x16x32_bf16 v[94:97], v[126:129], v[204:207], v[94:97]
	v_mfma_f32_16x16x32_bf16 v[90:93], v[176:179], v[204:207], v[90:93]
	v_mfma_f32_16x16x32_bf16 v[78:81], v[126:129], v[218:221], v[78:81]
	v_mfma_f32_16x16x32_bf16 v[74:77], v[176:179], v[218:221], v[74:77]
	s_barrier
	s_add_i32 s40, 0, 0x14000
	v_add_u32_e32 v152, s40, v185
	s_add_i32 s38, s38, s47
	ds_read_b128 v[222:225], v152
	ds_read_b128 v[226:229], v152 offset:1024
	ds_read_b128 v[230:233], v152 offset:2048
	ds_read_b128 v[234:237], v152 offset:3072
	v_lshl_add_u64 v[152:153], s[14:15], 0, v[8:9]
	s_mov_b32 m0, s38
	v_lshl_add_u64 v[162:163], s[14:15], 0, v[146:147]
	global_load_lds_dwordx4 v[152:153], off
	s_add_i32 m0, s38, 0x2000
	s_nop 0
	global_load_lds_dwordx4 v[162:163], off
	s_waitcnt lgkmcnt(0)
	s_barrier
	v_mfma_f32_16x16x32_bf16 v[122:125], v[222:225], v[180:183], v[122:125]
	v_mfma_f32_16x16x32_bf16 v[118:121], v[230:233], v[180:183], v[118:121]
	v_mfma_f32_16x16x32_bf16 v[102:105], v[222:225], v[192:195], v[102:105]
	v_mfma_f32_16x16x32_bf16 v[98:101], v[230:233], v[192:195], v[98:101]
	v_mfma_f32_16x16x32_bf16 v[86:89], v[222:225], v[200:203], v[86:89]
	v_mfma_f32_16x16x32_bf16 v[82:85], v[230:233], v[200:203], v[82:85]
	v_mfma_f32_16x16x32_bf16 v[70:73], v[222:225], v[214:217], v[70:73]
	v_mfma_f32_16x16x32_bf16 v[66:69], v[230:233], v[214:217], v[66:69]
	v_mfma_f32_16x16x32_bf16 v[122:125], v[226:229], v[188:191], v[122:125]
	v_mfma_f32_16x16x32_bf16 v[118:121], v[234:237], v[188:191], v[118:121]
	v_mfma_f32_16x16x32_bf16 v[102:105], v[226:229], v[196:199], v[102:105]
	v_mfma_f32_16x16x32_bf16 v[98:101], v[234:237], v[196:199], v[98:101]
	v_mfma_f32_16x16x32_bf16 v[86:89], v[226:229], v[204:207], v[86:89]
	v_mfma_f32_16x16x32_bf16 v[82:85], v[234:237], v[204:207], v[82:85]
	v_mfma_f32_16x16x32_bf16 v[70:73], v[226:229], v[218:221], v[70:73]
	v_mfma_f32_16x16x32_bf16 v[66:69], v[234:237], v[218:221], v[66:69]
	s_mov_b32 m0, s11
	v_lshl_add_u64 v[164:165], s[16:17], 0, v[142:143]
	s_barrier
	ds_read_b128 v[180:183], v187 offset:16384
	ds_read_b128 v[188:191], v187 offset:17408
	ds_read_b128 v[192:195], v187 offset:18432
	ds_read_b128 v[196:199], v187 offset:19456
	ds_read_b128 v[200:203], v187 offset:20480
	ds_read_b128 v[204:207], v187 offset:21504
	ds_read_b128 v[214:217], v187 offset:22528
	ds_read_b128 v[218:221], v187 offset:23552
	global_load_lds_dwordx4 v[164:165], off
	s_mov_b32 m0, s66
	v_lshl_add_u64 v[208:209], s[16:17], 0, v[144:145]
	global_load_lds_dwordx4 v[208:209], off
	s_waitcnt lgkmcnt(0)
	s_barrier
	v_mfma_f32_16x16x32_bf16 v[62:65], v[114:117], v[180:183], v[62:65]
	v_mfma_f32_16x16x32_bf16 v[58:61], v[130:133], v[180:183], v[58:61]
	v_mfma_f32_16x16x32_bf16 v[46:49], v[114:117], v[192:195], v[46:49]
	v_mfma_f32_16x16x32_bf16 v[42:45], v[130:133], v[192:195], v[42:45]
	v_mfma_f32_16x16x32_bf16 v[30:33], v[114:117], v[200:203], v[30:33]
	v_mfma_f32_16x16x32_bf16 v[26:29], v[130:133], v[200:203], v[26:29]
	v_mfma_f32_16x16x32_bf16 v[14:17], v[114:117], v[214:217], v[14:17]
	v_mfma_f32_16x16x32_bf16 v[10:13], v[130:133], v[214:217], v[10:13]
	v_mfma_f32_16x16x32_bf16 v[62:65], v[126:129], v[188:191], v[62:65]
	v_mfma_f32_16x16x32_bf16 v[58:61], v[176:179], v[188:191], v[58:61]
	v_mfma_f32_16x16x32_bf16 v[46:49], v[126:129], v[196:199], v[46:49]
	v_mfma_f32_16x16x32_bf16 v[42:45], v[176:179], v[196:199], v[42:45]
	v_mfma_f32_16x16x32_bf16 v[30:33], v[126:129], v[204:207], v[30:33]
	v_mfma_f32_16x16x32_bf16 v[26:29], v[176:179], v[204:207], v[26:29]
	v_mfma_f32_16x16x32_bf16 v[14:17], v[126:129], v[218:221], v[14:17]
	v_mfma_f32_16x16x32_bf16 v[10:13], v[176:179], v[218:221], v[10:13]
	s_barrier
; #define PG8_STAGE(bufoff, gbase, voff) do { _Pragma("unroll") for (int _i = 0; _i < 2; ++_i) \
;         __builtin_amdgcn_global_load_lds((const unsigned*)((const char*)(gbase) + (voff)[_i]), (LAS unsigned*)(lds + (bufoff) + ldsw + _i * 8192), 16, 0, 0); } while (0)
; #define PG8_LDA(dst, b, h) do { _Pragma("unroll") for (int m = 0; m < 4; ++m) _Pragma("unroll") for (int k = 0; k < 2; ++k) dst[m][k] = *(const LAS bf16x8*)(lds + PG8_SA(b, h) + aoff + m * 2048 + k * 1024); } while (0)
; #define PG8_LDB(dst, b, h) do { _Pragma("unroll") for (int n = 0; n < 2; ++n) _Pragma("unroll") for (int k = 0; k < 2; ++k) dst[n][k] = *(const LAS bf16x8*)(lds + PG8_SB(b, h) + boff + n * 2048 + k * 1024); } while (0)
; #define PG8_MMA(ai, bj, At, Bt) do { __builtin_amdgcn_s_setprio(1); _Pragma("unroll") for (int m = 0; m < 4; ++m) _Pragma("unroll") for (int n = 0; n < 2; ++n) _Pragma("unroll") for (int k = 0; k < 2; ++k) \
;         acc[ai][bj][m][n] = __builtin_amdgcn_mfma_f32_16x16x32_bf16(Bt[n][k], At[m][k], acc[ai][bj][m][n], 0, 0, 0); __builtin_amdgcn_s_setprio(0); } while (0)
; #define PG8_WAIT_V(n) asm volatile("s_waitcnt vmcnt(" #n ")" ::: "memory")
; #define PG8_WAIT_L(n) asm volatile("s_waitcnt lgkmcnt(" #n ")" ::: "memory")
; #define PG8_BAR __builtin_amdgcn_s_barrier()
; #define PG8_SCHED __builtin_amdgcn_sched_barrier(0)
; template <class Epi>
; DEVI void gemm_phase(LAS unsigned char* lds, const Gemm g, const Epi& E) {
;     ...
;             PG8_WAIT_V(6); PG8_BAR; PG8_MMA(1, 1, At, B1); PG8_BAR;
;             PG8_LDB(B0, 1, 0); PG8_SCHED; PG8_LDA(At, 1, 0); PG8_STAGE(PG8_SA(0, 1), a2 + hstepA, voffA);
;             PG8_WAIT_L(8); PG8_BAR; PG8_WAIT_L(0); PG8_MMA(0, 0, At, B0); PG8_BAR; PG8_SCHED;
;             PG8_LDB(B1, 1, 1); PG8_STAGE(PG8_SB(1, 0), b3, voffB);
;             PG8_BAR; PG8_WAIT_L(0); PG8_MMA(0, 1, At, B1); PG8_BAR;
;             PG8_LDA(At, 1, 1); PG8_STAGE(PG8_SA(1, 0), a3, voffA);
;             PG8_BAR; PG8_WAIT_L(0); PG8_MMA(1, 0, At, B0); PG8_BAR; PG8_SCHED;
	s_add_u32 s38, s14, 0x40000
	s_addc_u32 s39, s15, 0
	s_add_i32 s40, s40, s47
	s_mov_b32 m0, s40
	v_lshl_add_u64 v[114:115], s[38:39], 0, v[8:9]
	global_load_lds_dwordx4 v[114:115], off
	s_add_i32 m0, s40, 0x2000
	v_lshl_add_u64 v[114:115], s[38:39], 0, v[146:147]
	global_load_lds_dwordx4 v[114:115], off
	s_waitcnt vmcnt(6)
	s_barrier
	v_mfma_f32_16x16x32_bf16 v[54:57], v[222:225], v[180:183], v[54:57]
	v_mfma_f32_16x16x32_bf16 v[50:53], v[230:233], v[180:183], v[50:53]
	v_mfma_f32_16x16x32_bf16 v[38:41], v[222:225], v[192:195], v[38:41]
	v_mfma_f32_16x16x32_bf16 v[34:37], v[230:233], v[192:195], v[34:37]
	v_mfma_f32_16x16x32_bf16 v[22:25], v[222:225], v[200:203], v[22:25]
	v_mfma_f32_16x16x32_bf16 v[18:21], v[230:233], v[200:203], v[18:21]
	v_mfma_f32_16x16x32_bf16 v[4:7], v[222:225], v[214:217], v[4:7]
	v_mfma_f32_16x16x32_bf16 v[0:3], v[230:233], v[214:217], v[0:3]
	v_mfma_f32_16x16x32_bf16 v[54:57], v[226:229], v[188:191], v[54:57]
	v_mfma_f32_16x16x32_bf16 v[50:53], v[234:237], v[188:191], v[50:53]
	v_mfma_f32_16x16x32_bf16 v[38:41], v[226:229], v[196:199], v[38:41]
	v_mfma_f32_16x16x32_bf16 v[34:37], v[234:237], v[196:199], v[34:37]
	v_mfma_f32_16x16x32_bf16 v[22:25], v[226:229], v[204:207], v[22:25]
	v_mfma_f32_16x16x32_bf16 v[18:21], v[234:237], v[204:207], v[18:21]
	v_mfma_f32_16x16x32_bf16 v[4:7], v[226:229], v[218:221], v[4:7]
	v_mfma_f32_16x16x32_bf16 v[0:3], v[234:237], v[218:221], v[0:3]
	s_add_i32 s38, 0, 0x18000
	v_add_u32_e32 v176, s38, v185
	s_barrier
	ds_read_b128 v[114:117], v176
	ds_read_b128 v[126:129], v176 offset:1024
	ds_read_b128 v[130:133], v176 offset:2048
	ds_read_b128 v[176:179], v176 offset:3072
	s_add_u32 s16, s16, 0x40000
	s_addc_u32 s17, s17, 0
	s_mov_b32 m0, s68
	v_lshl_add_u64 v[222:223], s[16:17], 0, v[142:143]
	ds_read_b128 v[180:183], v187 offset:32768
	ds_read_b128 v[188:191], v187 offset:33792
	ds_read_b128 v[192:195], v187 offset:34816
	ds_read_b128 v[196:199], v187 offset:35840
	ds_read_b128 v[200:203], v187 offset:36864
	ds_read_b128 v[204:207], v187 offset:37888
	ds_read_b128 v[214:217], v187 offset:38912
	ds_read_b128 v[218:221], v187 offset:39936
	global_load_lds_dwordx4 v[222:223], off
	s_mov_b32 m0, s69
	v_lshl_add_u64 v[222:223], s[16:17], 0, v[144:145]
	global_load_lds_dwordx4 v[222:223], off
	s_waitcnt lgkmcnt(0)
	s_barrier
	v_mfma_f32_16x16x32_bf16 v[138:141], v[114:117], v[180:183], v[138:141]
	v_mfma_f32_16x16x32_bf16 v[134:137], v[130:133], v[180:183], v[134:137]
	v_mfma_f32_16x16x32_bf16 v[110:113], v[114:117], v[192:195], v[110:113]
	v_mfma_f32_16x16x32_bf16 v[106:109], v[130:133], v[192:195], v[106:109]
	v_mfma_f32_16x16x32_bf16 v[94:97], v[114:117], v[200:203], v[94:97]
	v_mfma_f32_16x16x32_bf16 v[90:93], v[130:133], v[200:203], v[90:93]
	v_mfma_f32_16x16x32_bf16 v[78:81], v[114:117], v[214:217], v[78:81]
	v_mfma_f32_16x16x32_bf16 v[74:77], v[130:133], v[214:217], v[74:77]
	v_mfma_f32_16x16x32_bf16 v[138:141], v[126:129], v[188:191], v[138:141]
	v_mfma_f32_16x16x32_bf16 v[134:137], v[176:179], v[188:191], v[134:137]
	v_mfma_f32_16x16x32_bf16 v[110:113], v[126:129], v[196:199], v[110:113]
	v_mfma_f32_16x16x32_bf16 v[106:109], v[176:179], v[196:199], v[106:109]
	v_mfma_f32_16x16x32_bf16 v[94:97], v[126:129], v[204:207], v[94:97]
	v_mfma_f32_16x16x32_bf16 v[90:93], v[176:179], v[204:207], v[90:93]
	v_mfma_f32_16x16x32_bf16 v[78:81], v[126:129], v[218:221], v[78:81]
	v_mfma_f32_16x16x32_bf16 v[74:77], v[176:179], v[218:221], v[74:77]
	s_barrier
	s_add_i32 s16, 0, 0x1c000
	s_add_i32 s17, s38, s47
	v_add_u32_e32 v213, s16, v185
	v_lshl_add_u64 v[152:153], v[152:153], 0, s[70:71]
	s_mov_b32 m0, s17
	ds_read_b128 v[222:225], v213
	ds_read_b128 v[226:229], v213 offset:1024
	ds_read_b128 v[230:233], v213 offset:2048
	ds_read_b128 v[234:237], v213 offset:3072
	global_load_lds_dwordx4 v[152:153], off
	s_add_i32 m0, s17, 0x2000
	v_lshl_add_u64 v[152:153], v[162:163], 0, s[70:71]
	global_load_lds_dwordx4 v[152:153], off
	s_waitcnt lgkmcnt(0)
	s_barrier
	v_mfma_f32_16x16x32_bf16 v[122:125], v[222:225], v[180:183], v[122:125]
	v_mfma_f32_16x16x32_bf16 v[118:121], v[230:233], v[180:183], v[118:121]
	v_mfma_f32_16x16x32_bf16 v[102:105], v[222:225], v[192:195], v[102:105]
	v_mfma_f32_16x16x32_bf16 v[98:101], v[230:233], v[192:195], v[98:101]
	v_mfma_f32_16x16x32_bf16 v[86:89], v[222:225], v[200:203], v[86:89]
	v_mfma_f32_16x16x32_bf16 v[82:85], v[230:233], v[200:203], v[82:85]
	v_mfma_f32_16x16x32_bf16 v[70:73], v[222:225], v[214:217], v[70:73]
	v_mfma_f32_16x16x32_bf16 v[66:69], v[230:233], v[214:217], v[66:69]
	v_mfma_f32_16x16x32_bf16 v[122:125], v[226:229], v[188:191], v[122:125]
	v_mfma_f32_16x16x32_bf16 v[118:121], v[234:237], v[188:191], v[118:121]
	v_mfma_f32_16x16x32_bf16 v[102:105], v[226:229], v[196:199], v[102:105]
	v_mfma_f32_16x16x32_bf16 v[98:101], v[234:237], v[196:199], v[98:101]
	v_mfma_f32_16x16x32_bf16 v[86:89], v[226:229], v[204:207], v[86:89]
	v_mfma_f32_16x16x32_bf16 v[82:85], v[234:237], v[204:207], v[82:85]
	v_mfma_f32_16x16x32_bf16 v[70:73], v[226:229], v[218:221], v[70:73]
	v_mfma_f32_16x16x32_bf16 v[66:69], v[234:237], v[218:221], v[66:69]
	s_mov_b32 m0, s80
	v_lshl_add_u64 v[152:153], v[164:165], 0, s[70:71]
	s_barrier
	ds_read_b128 v[180:183], v187 offset:49152
	ds_read_b128 v[188:191], v187 offset:50176
	ds_read_b128 v[192:195], v187 offset:51200
	ds_read_b128 v[196:199], v187 offset:52224
	ds_read_b128 v[200:203], v187 offset:53248
	ds_read_b128 v[204:207], v187 offset:54272
	ds_read_b128 v[214:217], v187 offset:55296
	ds_read_b128 v[218:221], v187 offset:56320
	global_load_lds_dwordx4 v[152:153], off
	s_mov_b32 m0, s81
	v_lshl_add_u64 v[152:153], v[208:209], 0, s[70:71]
	global_load_lds_dwordx4 v[152:153], off
	s_waitcnt lgkmcnt(0)
	s_barrier
; #define PG8_STAGE(bufoff, gbase, voff) do { _Pragma("unroll") for (int _i = 0; _i < 2; ++_i) \
;         __builtin_amdgcn_global_load_lds((const unsigned*)((const char*)(gbase) + (voff)[_i]), (LAS unsigned*)(lds + (bufoff) + ldsw + _i * 8192), 16, 0, 0); } while (0)
; #define PG8_MMA(ai, bj, At, Bt) do { __builtin_amdgcn_s_setprio(1); _Pragma("unroll") for (int m = 0; m < 4; ++m) _Pragma("unroll") for (int n = 0; n < 2; ++n) _Pragma("unroll") for (int k = 0; k < 2; ++k) \
;         acc[ai][bj][m][n] = __builtin_amdgcn_mfma_f32_16x16x32_bf16(Bt[n][k], At[m][k], acc[ai][bj][m][n], 0, 0, 0); __builtin_amdgcn_s_setprio(0); } while (0)
; #define PG8_WAIT_V(n) asm volatile("s_waitcnt vmcnt(" #n ")" ::: "memory")
; #define PG8_WAIT_L(n) asm volatile("s_waitcnt lgkmcnt(" #n ")" ::: "memory")
; #define PG8_BAR __builtin_amdgcn_s_barrier()
; #define PG8_SCHED __builtin_amdgcn_sched_barrier(0)
;     DEVI f32x4 load(int r, int c) const { const bf16x4 y = *(const bf16x4*)(Y + (size_t)r * DM + c); return (f32x4){bf2f((u16)y[0]), bf2f((u16)y[1]), bf2f((u16)y[2]), bf2f((u16)y[3])}; }
; template <class Epi>
; DEVI void gemm_phase(LAS unsigned char* lds, const Gemm g, const Epi& E) {
;     ...
;             PG8_BAR; PG8_WAIT_L(0); PG8_MMA(1, 0, At, B0); PG8_BAR; PG8_SCHED;
;             PG8_STAGE(PG8_SB(1, 1), b3 + hstepB, voffB);
;             PG8_WAIT_V(6); PG8_BAR; PG8_MMA(1, 1, At, B1); PG8_BAR;
;         }
;     ...
;                 if constexpr (Epi::PRE) {
; #pragma unroll
;                     for (int m = 0; m < 2; ++m)
; #pragma unroll
;                         for (int bj = 0; bj < 2; ++bj)
; #pragma unroll
;                             for (int n = 0; n < 2; ++n) pre[m][bj][n] = E.load(row0 + ai * HALF + (m0 + m) * 16, col0 + bj * HALF + n * NST);
;                 }
	v_mfma_f32_16x16x32_bf16 v[62:65], v[114:117], v[180:183], v[62:65]
	v_mfma_f32_16x16x32_bf16 v[58:61], v[130:133], v[180:183], v[58:61]
	v_mfma_f32_16x16x32_bf16 v[46:49], v[114:117], v[192:195], v[46:49]
	v_mfma_f32_16x16x32_bf16 v[42:45], v[130:133], v[192:195], v[42:45]
	v_mfma_f32_16x16x32_bf16 v[30:33], v[114:117], v[200:203], v[30:33]
	v_mfma_f32_16x16x32_bf16 v[26:29], v[130:133], v[200:203], v[26:29]
	v_mfma_f32_16x16x32_bf16 v[14:17], v[114:117], v[214:217], v[14:17]
	v_mfma_f32_16x16x32_bf16 v[10:13], v[130:133], v[214:217], v[10:13]
	v_mfma_f32_16x16x32_bf16 v[62:65], v[126:129], v[188:191], v[62:65]
	v_mfma_f32_16x16x32_bf16 v[58:61], v[176:179], v[188:191], v[58:61]
	v_mfma_f32_16x16x32_bf16 v[46:49], v[126:129], v[196:199], v[46:49]
	v_mfma_f32_16x16x32_bf16 v[42:45], v[176:179], v[196:199], v[42:45]
	v_mfma_f32_16x16x32_bf16 v[30:33], v[126:129], v[204:207], v[30:33]
	v_mfma_f32_16x16x32_bf16 v[26:29], v[176:179], v[204:207], v[26:29]
	v_mfma_f32_16x16x32_bf16 v[14:17], v[126:129], v[218:221], v[14:17]
	v_mfma_f32_16x16x32_bf16 v[10:13], v[176:179], v[218:221], v[10:13]
	s_barrier
	s_add_u32 s14, s14, 0x40080
	s_addc_u32 s15, s15, 0
	s_add_i32 s16, s16, s47
	s_mov_b32 m0, s16
	v_lshl_add_u64 v[114:115], s[14:15], 0, v[8:9]
	global_load_lds_dwordx4 v[114:115], off
	s_add_i32 m0, s16, 0x2000
	v_lshl_add_u64 v[114:115], s[14:15], 0, v[146:147]
	global_load_lds_dwordx4 v[114:115], off
	s_waitcnt vmcnt(6)
	s_barrier
	v_mfma_f32_16x16x32_bf16 v[54:57], v[222:225], v[180:183], v[54:57]
	v_mfma_f32_16x16x32_bf16 v[50:53], v[230:233], v[180:183], v[50:53]
	v_mfma_f32_16x16x32_bf16 v[38:41], v[222:225], v[192:195], v[38:41]
	v_mfma_f32_16x16x32_bf16 v[34:37], v[230:233], v[192:195], v[34:37]
	v_mfma_f32_16x16x32_bf16 v[22:25], v[222:225], v[200:203], v[22:25]
	v_mfma_f32_16x16x32_bf16 v[18:21], v[230:233], v[200:203], v[18:21]
	v_mfma_f32_16x16x32_bf16 v[4:7], v[222:225], v[214:217], v[4:7]
	v_mfma_f32_16x16x32_bf16 v[0:3], v[230:233], v[214:217], v[0:3]
	v_mfma_f32_16x16x32_bf16 v[54:57], v[226:229], v[188:191], v[54:57]
	v_mfma_f32_16x16x32_bf16 v[50:53], v[234:237], v[188:191], v[50:53]
	v_mfma_f32_16x16x32_bf16 v[38:41], v[226:229], v[196:199], v[38:41]
	v_mfma_f32_16x16x32_bf16 v[34:37], v[234:237], v[196:199], v[34:37]
	v_mfma_f32_16x16x32_bf16 v[22:25], v[226:229], v[204:207], v[22:25]
	v_mfma_f32_16x16x32_bf16 v[18:21], v[234:237], v[204:207], v[18:21]
	v_mfma_f32_16x16x32_bf16 v[4:7], v[226:229], v[218:221], v[4:7]
	v_mfma_f32_16x16x32_bf16 v[0:3], v[234:237], v[218:221], v[0:3]
	s_add_i32 s27, s27, 2
	s_add_u32 s12, s12, 0x100
	s_addc_u32 s13, s13, 0
	s_add_u32 s19, s19, 0x100
	s_addc_u32 s26, s26, 0
	s_cmp_gt_u32 s27, 13
	s_barrier
	s_cbranch_scc0 .LBB0_1346
	s_setprio 0
	v_lshl_add_u32 v180, s10, 8, v184
	v_lshl_or_b32 v152, s0, 8, v186
	v_ashrrev_i32_e32 v181, 31, v180
	v_lshlrev_b64 v[178:179], 11, v[180:181]
	v_ashrrev_i32_e32 v153, 31, v152
	v_lshl_add_u64 v[114:115], s[24:25], 0, v[178:179]
	v_lshlrev_b64 v[176:177], 1, v[152:153]
	v_lshl_add_u64 v[114:115], v[114:115], 0, v[176:177]
	global_load_dwordx4 v[188:191], v[114:115], off
	global_load_dwordx4 v[130:133], v[114:115], off offset:256
	v_or_b32_e32 v114, 16, v180
	v_ashrrev_i32_e32 v115, 31, v114
	v_lshlrev_b64 v[182:183], 11, v[114:115]
	v_readlane_b32 s48, v251, 40
	v_lshl_add_u64 v[114:115], s[24:25], 0, v[182:183]
	v_readlane_b32 s54, v251, 46
	v_readlane_b32 s55, v251, 47
	v_lshl_add_u64 v[114:115], v[114:115], 0, v[176:177]
	global_load_dwordx4 v[126:129], v[114:115], off
	s_nop 0
	global_load_dwordx4 v[114:117], v[114:115], off offset:256
	v_lshl_add_u64 v[152:153], v[152:153], 2, s[54:55]
	global_load_dwordx4 v[214:217], v[152:153], off
	global_load_dwordx4 v[218:221], v[152:153], off offset:16
	global_load_dwordx4 v[222:225], v[152:153], off offset:512
	global_load_dwordx4 v[226:229], v[152:153], off offset:528
	s_mov_b64 s[0:1], 0x40000
	v_readlane_b32 s52, v251, 44
	v_readlane_b32 s56, v251, 48
	v_readlane_b32 s57, v251, 49
	v_readlane_b32 s58, v251, 50
	v_readlane_b32 s59, v251, 51
	v_readlane_b32 s60, v251, 52
	v_readlane_b32 s61, v251, 53
	v_readlane_b32 s62, v251, 54
	v_readlane_b32 s63, v251, 55
	s_and_b64 vcc, exec, s[36:37]
	s_mov_b32 s10, s2
	s_mov_b64 s[14:15], s[8:9]
	s_mov_b64 s[12:13], s[6:7]
	s_mov_b64 s[56:57], s[42:43]
	s_mov_b64 s[58:59], s[44:45]
	s_mov_b32 s60, s41
	s_mov_b32 s61, s83
	s_mov_b32 s62, s84
	s_mov_b32 s63, s85
	v_readlane_b32 s55, v254, 0
	s_movk_i32 s52, 0x110
	v_readlane_b32 s49, v251, 41
	v_readlane_b32 s50, v251, 42
	v_readlane_b32 s51, v251, 43
	v_readlane_b32 s53, v251, 45
	v_readlane_b32 s40, v254, 1
	s_waitcnt vmcnt(0)
; DEVI float bf2f(u16 b) { return __uint_as_float(((unsigned)b) << 16); }
; template <class Epi>
; DEVI void gemm_phase(LAS unsigned char* lds, const Gemm g, const Epi& E) {
;     ...
;                         for (int bj = 0; bj < 2; ++bj)
; #pragma unroll
;                             for (int n = 0; n < 2; ++n) pre[m][bj][n] = E.load(row0 + ai * HALF + (m0 + m) * 16, col0 + bj * HALF + n * NST);
;                 }
; #pragma unroll
;                 for (int mm = 0; mm < 2; ++mm) {
;                     const int m = m0 + mm;
;                     const int r = row0 + ai * HALF + m * 16; float rs = 1.f, part = 0.f;
;                     if constexpr (Epi::RS) rs = rsv[ai * 4 + m];
;                     if constexpr (Epi::PAIR) E.pair8(cur.b, r, cur.pn * HALF + wc * 32 + 8 * fq, acc[ai][0][m][0] * rs, acc[ai][0][m][1] * rs, acc[ai][1][m][0] * rs, acc[ai][1][m][1] * rs);
;                     else
; #pragma unroll
;                     for (int bj = 0; bj < 2; ++bj) {
;                         const int c = col0 + bj * HALF; f32x4 v0 = acc[ai][bj][m][0], v1 = acc[ai][bj][m][1];
;                         if constexpr (Epi::RS) { v0 = v0 * rs; v1 = v1 * rs; }
;                         if constexpr (Epi::PRE) part += E.frag_pre8(cur.b, r, c, v0, v1, pre[mm][bj][0], pre[mm][bj][1]);
;     DEVI f32x4 load(int r, int c) const { const bf16x4 y = *(const bf16x4*)(Y + (size_t)r * DM + c); return (f32x4){bf2f((u16)y[0]), bf2f((u16)y[1]), bf2f((u16)y[2]), bf2f((u16)y[3])}; }
	v_and_b32_e32 v163, 0xffff0000, v188
	v_lshlrev_b32_e32 v162, 16, v188
	v_add_f32_e32 v134, v134, v218
	v_add_f32_e32 v138, v138, v214
	v_add_f32_e32 v139, v139, v215
	v_mul_f32_e32 v138, 0xbfb8aa3b, v138
	v_mul_f32_e32 v139, 0xbfb8aa3b, v139
	v_add_f32_e32 v135, v135, v219
	v_exp_f32_e32 v138, v138
	v_mul_f32_e32 v134, 0xbfb8aa3b, v134
	v_exp_f32_e32 v139, v139
	v_mul_f32_e32 v135, 0xbfb8aa3b, v135
	v_exp_f32_e32 v134, v134
	v_exp_f32_e32 v135, v135
	v_add_f32_e32 v138, 1.0, v138
	v_add_f32_e32 v139, 1.0, v139
	v_rcp_f32_e32 v138, v138
	v_add_f32_e32 v134, 1.0, v134
	v_rcp_f32_e32 v139, v139
	v_add_f32_e32 v135, 1.0, v135
	v_rcp_f32_e32 v134, v134
	v_rcp_f32_e32 v135, v135
	v_pk_mul_f32 v[138:139], v[138:139], v[162:163]
	v_and_b32_e32 v163, 0xffff0000, v190
	v_lshlrev_b32_e32 v162, 16, v190
	v_pk_mul_f32 v[162:163], v[134:135], v[162:163]
	v_add_f32_e32 v135, v136, v220
	v_mul_f32_e32 v135, 0xbfb8aa3b, v135
	v_exp_f32_e32 v135, v135
	v_add_f32_e32 v134, v140, v216
	v_mul_f32_e32 v134, 0xbfb8aa3b, v134
	v_exp_f32_e32 v134, v134
	v_add_f32_e32 v135, 1.0, v135
	v_rcp_f32_e32 v136, v135
	v_add_f32_e32 v135, v141, v217
	v_mul_f32_e32 v135, 0xbfb8aa3b, v135
	v_exp_f32_e32 v135, v135
	v_add_f32_e32 v134, 1.0, v134
	v_rcp_f32_e32 v134, v134
	v_and_b32_e32 v141, 0xffff0000, v189
	v_add_f32_e32 v135, 1.0, v135
	v_rcp_f32_e32 v135, v135
	v_lshlrev_b32_e32 v140, 16, v189
	v_pk_mul_f32 v[140:141], v[134:135], v[140:141]
	v_add_f32_e32 v134, v137, v221
	v_mul_f32_e32 v134, 0xbfb8aa3b, v134
	v_exp_f32_e32 v134, v134
	v_and_b32_e32 v135, 0xffff0000, v191
	v_add_f32_e32 v134, 1.0, v134
	v_rcp_f32_e32 v137, v134
	v_lshlrev_b32_e32 v134, 16, v191
	v_pk_mul_f32 v[164:165], v[136:137], v[134:135]
	v_cvt_pk_bf16_f32 v134, v138, v139
	v_lshl_add_u64 v[138:139], s[64:65], 0, v[178:179]
	v_cvt_pk_bf16_f32 v135, v140, v141
	v_cvt_pk_bf16_f32 v136, v162, v163
	v_cvt_pk_bf16_f32 v137, v164, v165
	v_lshl_add_u64 v[138:139], v[138:139], 0, v[176:177]
	global_store_dwordx4 v[138:139], v[134:137], off
	s_nop 0
	v_and_b32_e32 v141, 0xffff0000, v130
	v_lshlrev_b32_e32 v140, 16, v130
	v_lshlrev_b32_e32 v130, 16, v133
	v_add_f32_e32 v118, v118, v226
	v_add_f32_e32 v119, v119, v227
	v_add_f32_e32 v122, v122, v222
	v_mul_f32_e32 v118, 0xbfb8aa3b, v118
	v_add_f32_e32 v123, v123, v223
	v_mul_f32_e32 v119, 0xbfb8aa3b, v119
	v_add_f32_e32 v124, v124, v224
	v_add_f32_e32 v120, v120, v228
	v_add_f32_e32 v125, v125, v225
	v_add_f32_e32 v121, v121, v229
	v_mul_f32_e32 v122, 0xbfb8aa3b, v122
	v_exp_f32_e32 v118, v118
	v_mul_f32_e32 v123, 0xbfb8aa3b, v123
	v_exp_f32_e32 v119, v119
	v_mul_f32_e32 v124, 0xbfb8aa3b, v124
	v_mul_f32_e32 v120, 0xbfb8aa3b, v120
	v_mul_f32_e32 v125, 0xbfb8aa3b, v125
	v_mul_f32_e32 v121, 0xbfb8aa3b, v121
	v_exp_f32_e32 v122, v122
	v_exp_f32_e32 v123, v123
	v_exp_f32_e32 v124, v124
	v_exp_f32_e32 v120, v120
	v_exp_f32_e32 v125, v125
	v_exp_f32_e32 v121, v121
	v_add_f32_e32 v118, 1.0, v118
	v_add_f32_e32 v119, 1.0, v119
	v_add_f32_e32 v122, 1.0, v122
	v_rcp_f32_e32 v118, v118
	v_add_f32_e32 v123, 1.0, v123
	v_rcp_f32_e32 v119, v119
	v_add_f32_e32 v124, 1.0, v124
	v_add_f32_e32 v120, 1.0, v120
	v_add_f32_e32 v125, 1.0, v125
	v_add_f32_e32 v121, 1.0, v121
	v_rcp_f32_e32 v122, v122
	v_rcp_f32_e32 v123, v123
	v_rcp_f32_e32 v124, v124
	v_rcp_f32_e32 v120, v120
	v_rcp_f32_e32 v125, v125
	v_rcp_f32_e32 v121, v121
	v_and_b32_e32 v135, 0xffff0000, v132
	v_lshlrev_b32_e32 v134, 16, v132
	v_pk_mul_f32 v[118:119], v[118:119], v[134:135]
	v_and_b32_e32 v135, 0xffff0000, v131
	v_lshlrev_b32_e32 v134, 16, v131
	v_and_b32_e32 v131, 0xffff0000, v133
	v_pk_mul_f32 v[122:123], v[122:123], v[140:141]
	v_pk_mul_f32 v[124:125], v[124:125], v[134:135]
	v_pk_mul_f32 v[130:131], v[120:121], v[130:131]
	v_cvt_pk_bf16_f32 v120, v122, v123
	v_cvt_pk_bf16_f32 v121, v124, v125
	v_cvt_pk_bf16_f32 v122, v118, v119
	v_cvt_pk_bf16_f32 v123, v130, v131
	global_store_dwordx4 v[138:139], v[120:123], off offset:256
	s_nop 0
	v_add_f32_e32 v106, v106, v218
	v_add_f32_e32 v107, v107, v219
	v_mul_f32_e32 v106, 0xbfb8aa3b, v106
	v_mul_f32_e32 v107, 0xbfb8aa3b, v107
	v_exp_f32_e32 v106, v106
	v_exp_f32_e32 v107, v107
	v_and_b32_e32 v119, 0xffff0000, v128
	v_lshlrev_b32_e32 v118, 16, v128
	v_add_f32_e32 v106, 1.0, v106
	v_add_f32_e32 v107, 1.0, v107
	v_rcp_f32_e32 v106, v106
	v_rcp_f32_e32 v107, v107
	v_add_f32_e32 v110, v110, v214
	v_add_f32_e32 v111, v111, v215
	v_mul_f32_e32 v110, 0xbfb8aa3b, v110
	v_pk_mul_f32 v[118:119], v[106:107], v[118:119]
	v_add_f32_e32 v107, v108, v220
	v_mul_f32_e32 v107, 0xbfb8aa3b, v107
	v_exp_f32_e32 v107, v107
	v_add_f32_e32 v106, v112, v216
	v_mul_f32_e32 v106, 0xbfb8aa3b, v106
	v_exp_f32_e32 v106, v106
	v_add_f32_e32 v107, 1.0, v107
	v_rcp_f32_e32 v108, v107
	v_add_f32_e32 v107, v113, v217
	v_mul_f32_e32 v107, 0xbfb8aa3b, v107
	v_exp_f32_e32 v107, v107
	v_add_f32_e32 v106, 1.0, v106
	v_rcp_f32_e32 v106, v106
	v_and_b32_e32 v113, 0xffff0000, v127
	v_add_f32_e32 v107, 1.0, v107
	v_rcp_f32_e32 v107, v107
	v_lshlrev_b32_e32 v112, 16, v127
	v_mul_f32_e32 v111, 0xbfb8aa3b, v111
	v_exp_f32_e32 v110, v110
	v_pk_mul_f32 v[112:113], v[106:107], v[112:113]
	v_add_f32_e32 v106, v109, v221
	v_exp_f32_e32 v111, v111
	v_mul_f32_e32 v106, 0xbfb8aa3b, v106
	v_exp_f32_e32 v106, v106
	v_add_f32_e32 v110, 1.0, v110
	v_add_f32_e32 v111, 1.0, v111
	v_rcp_f32_e32 v110, v110
	v_rcp_f32_e32 v111, v111
	v_add_f32_e32 v106, 1.0, v106
	v_rcp_f32_e32 v109, v106
	v_and_b32_e32 v123, 0xffff0000, v126
	v_lshlrev_b32_e32 v122, 16, v126
	v_pk_mul_f32 v[110:111], v[110:111], v[122:123]
	v_and_b32_e32 v107, 0xffff0000, v129
	v_lshlrev_b32_e32 v106, 16, v129
	v_pk_mul_f32 v[120:121], v[108:109], v[106:107]
; DEVI float bf2f(u16 b) { return __uint_as_float(((unsigned)b) << 16); }
; template <class Epi>
; DEVI void gemm_phase(LAS unsigned char* lds, const Gemm g, const Epi& E) {
;     ...
;                 if constexpr (Epi::PRE) {
; #pragma unroll
;                     for (int m = 0; m < 2; ++m)
; #pragma unroll
;                         for (int bj = 0; bj < 2; ++bj)
; #pragma unroll
;                             for (int n = 0; n < 2; ++n) pre[m][bj][n] = E.load(row0 + ai * HALF + (m0 + m) * 16, col0 + bj * HALF + n * NST);
;                 }
; #pragma unroll
;                 for (int mm = 0; mm < 2; ++mm) {
;                     const int m = m0 + mm;
;                     const int r = row0 + ai * HALF + m * 16; float rs = 1.f, part = 0.f;
;                     if constexpr (Epi::RS) rs = rsv[ai * 4 + m];
;                     if constexpr (Epi::PAIR) E.pair8(cur.b, r, cur.pn * HALF + wc * 32 + 8 * fq, acc[ai][0][m][0] * rs, acc[ai][0][m][1] * rs, acc[ai][1][m][0] * rs, acc[ai][1][m][1] * rs);
;                     else
; #pragma unroll
;                     for (int bj = 0; bj < 2; ++bj) {
;                         const int c = col0 + bj * HALF; f32x4 v0 = acc[ai][bj][m][0], v1 = acc[ai][bj][m][1];
;                         if constexpr (Epi::RS) { v0 = v0 * rs; v1 = v1 * rs; }
;                         if constexpr (Epi::PRE) part += E.frag_pre8(cur.b, r, c, v0, v1, pre[mm][bj][0], pre[mm][bj][1]);
;     DEVI f32x4 load(int r, int c) const { const bf16x4 y = *(const bf16x4*)(Y + (size_t)r * DM + c); return (f32x4){bf2f((u16)y[0]), bf2f((u16)y[1]), bf2f((u16)y[2]), bf2f((u16)y[3])}; }
	v_cvt_pk_bf16_f32 v106, v110, v111
	v_lshl_add_u64 v[110:111], s[64:65], 0, v[182:183]
	v_cvt_pk_bf16_f32 v107, v112, v113
	v_cvt_pk_bf16_f32 v108, v118, v119
	v_cvt_pk_bf16_f32 v109, v120, v121
	v_lshl_add_u64 v[110:111], v[110:111], 0, v[176:177]
	global_store_dwordx4 v[110:111], v[106:109], off
	s_nop 0
	v_and_b32_e32 v113, 0xffff0000, v114
	v_lshlrev_b32_e32 v112, 16, v114
	v_add_f32_e32 v98, v98, v226
	v_add_f32_e32 v99, v99, v227
	v_mul_f32_e32 v98, 0xbfb8aa3b, v98
	v_mul_f32_e32 v99, 0xbfb8aa3b, v99
	v_exp_f32_e32 v98, v98
	v_exp_f32_e32 v99, v99
	v_and_b32_e32 v107, 0xffff0000, v116
	v_lshlrev_b32_e32 v106, 16, v116
	v_add_f32_e32 v98, 1.0, v98
	v_add_f32_e32 v99, 1.0, v99
	v_rcp_f32_e32 v98, v98
	v_rcp_f32_e32 v99, v99
	v_add_f32_e32 v102, v102, v222
	v_add_f32_e32 v103, v103, v223
	v_mul_f32_e32 v102, 0xbfb8aa3b, v102
	v_pk_mul_f32 v[106:107], v[98:99], v[106:107]
	v_add_f32_e32 v99, v100, v228
	v_mul_f32_e32 v99, 0xbfb8aa3b, v99
	v_exp_f32_e32 v99, v99
	v_add_f32_e32 v98, v104, v224
	v_mul_f32_e32 v98, 0xbfb8aa3b, v98
	v_exp_f32_e32 v98, v98
	v_add_f32_e32 v99, 1.0, v99
	v_rcp_f32_e32 v100, v99
	v_add_f32_e32 v99, v105, v225
	v_mul_f32_e32 v99, 0xbfb8aa3b, v99
	v_exp_f32_e32 v99, v99
	v_add_f32_e32 v98, 1.0, v98
	v_rcp_f32_e32 v98, v98
	v_and_b32_e32 v105, 0xffff0000, v115
	v_add_f32_e32 v99, 1.0, v99
	v_rcp_f32_e32 v99, v99
	v_lshlrev_b32_e32 v104, 16, v115
	v_mul_f32_e32 v103, 0xbfb8aa3b, v103
	v_exp_f32_e32 v102, v102
	v_pk_mul_f32 v[104:105], v[98:99], v[104:105]
	v_add_f32_e32 v98, v101, v229
	v_mul_f32_e32 v98, 0xbfb8aa3b, v98
	v_exp_f32_e32 v103, v103
	v_exp_f32_e32 v98, v98
	v_add_f32_e32 v102, 1.0, v102
	v_rcp_f32_e32 v102, v102
	v_add_f32_e32 v103, 1.0, v103
	v_add_f32_e32 v98, 1.0, v98
	v_rcp_f32_e32 v103, v103
	v_rcp_f32_e32 v101, v98
	v_and_b32_e32 v99, 0xffff0000, v117
	v_lshlrev_b32_e32 v98, 16, v117
	v_pk_mul_f32 v[102:103], v[102:103], v[112:113]
	v_pk_mul_f32 v[108:109], v[100:101], v[98:99]
	v_cvt_pk_bf16_f32 v98, v102, v103
	v_cvt_pk_bf16_f32 v99, v104, v105
	v_cvt_pk_bf16_f32 v100, v106, v107
	v_cvt_pk_bf16_f32 v101, v108, v109
	global_store_dwordx4 v[110:111], v[98:101], off offset:256
	s_nop 1
	v_or_b32_e32 v98, 32, v180
	v_ashrrev_i32_e32 v99, 31, v98
	v_lshlrev_b64 v[120:121], 11, v[98:99]
	v_lshl_add_u64 v[98:99], s[24:25], 0, v[120:121]
	v_lshl_add_u64 v[98:99], v[98:99], 0, v[176:177]
	global_load_dwordx4 v[110:113], v[98:99], off
	global_load_dwordx4 v[106:109], v[98:99], off offset:256
	v_or_b32_e32 v98, 48, v180
	v_ashrrev_i32_e32 v99, 31, v98
	v_lshlrev_b64 v[118:119], 11, v[98:99]
	v_lshl_add_u64 v[98:99], s[24:25], 0, v[118:119]
	v_lshl_add_u64 v[98:99], v[98:99], 0, v[176:177]
	global_load_dwordx4 v[102:105], v[98:99], off
	s_nop 0
	global_load_dwordx4 v[98:101], v[98:99], off offset:256
	s_nop 0
	s_waitcnt vmcnt(0)
	v_add_f32_e32 v90, v90, v218
	v_add_f32_e32 v91, v91, v219
	v_mul_f32_e32 v90, 0xbfb8aa3b, v90
	v_mul_f32_e32 v91, 0xbfb8aa3b, v91
	v_exp_f32_e32 v90, v90
	v_exp_f32_e32 v91, v91
	v_and_b32_e32 v115, 0xffff0000, v112
	v_lshlrev_b32_e32 v114, 16, v112
	v_add_f32_e32 v90, 1.0, v90
	v_add_f32_e32 v91, 1.0, v91
	v_rcp_f32_e32 v90, v90
	v_rcp_f32_e32 v91, v91
	v_add_f32_e32 v94, v94, v214
	v_add_f32_e32 v95, v95, v215
	v_mul_f32_e32 v94, 0xbfb8aa3b, v94
	v_pk_mul_f32 v[114:115], v[90:91], v[114:115]
	v_add_f32_e32 v91, v92, v220
	v_mul_f32_e32 v91, 0xbfb8aa3b, v91
	v_exp_f32_e32 v91, v91
	v_add_f32_e32 v90, v96, v216
	v_mul_f32_e32 v90, 0xbfb8aa3b, v90
	v_exp_f32_e32 v90, v90
	v_add_f32_e32 v91, 1.0, v91
	v_rcp_f32_e32 v92, v91
	v_add_f32_e32 v91, v97, v217
	v_mul_f32_e32 v91, 0xbfb8aa3b, v91
	v_exp_f32_e32 v91, v91
	v_add_f32_e32 v90, 1.0, v90
	v_rcp_f32_e32 v90, v90
	v_and_b32_e32 v97, 0xffff0000, v111
	v_add_f32_e32 v91, 1.0, v91
	v_rcp_f32_e32 v91, v91
	v_lshlrev_b32_e32 v96, 16, v111
	v_mul_f32_e32 v95, 0xbfb8aa3b, v95
	v_exp_f32_e32 v94, v94
	v_pk_mul_f32 v[96:97], v[90:91], v[96:97]
	v_add_f32_e32 v90, v93, v221
	v_exp_f32_e32 v95, v95
	v_mul_f32_e32 v90, 0xbfb8aa3b, v90
	v_exp_f32_e32 v90, v90
	v_add_f32_e32 v94, 1.0, v94
	v_add_f32_e32 v95, 1.0, v95
	v_rcp_f32_e32 v94, v94
	v_rcp_f32_e32 v95, v95
	v_add_f32_e32 v90, 1.0, v90
	v_rcp_f32_e32 v93, v90
	v_and_b32_e32 v123, 0xffff0000, v110
	v_lshlrev_b32_e32 v122, 16, v110
	v_pk_mul_f32 v[94:95], v[94:95], v[122:123]
	v_and_b32_e32 v91, 0xffff0000, v113
	v_lshlrev_b32_e32 v90, 16, v113
	v_pk_mul_f32 v[110:111], v[92:93], v[90:91]
	v_cvt_pk_bf16_f32 v90, v94, v95
	v_lshl_add_u64 v[94:95], s[64:65], 0, v[120:121]
	v_cvt_pk_bf16_f32 v91, v96, v97
	v_cvt_pk_bf16_f32 v92, v114, v115
	v_cvt_pk_bf16_f32 v93, v110, v111
	v_lshl_add_u64 v[94:95], v[94:95], 0, v[176:177]
	global_store_dwordx4 v[94:95], v[90:93], off
	s_nop 0
	v_and_b32_e32 v97, 0xffff0000, v106
	v_lshlrev_b32_e32 v96, 16, v106
	v_add_f32_e32 v82, v82, v226
	v_add_f32_e32 v83, v83, v227
	v_mul_f32_e32 v82, 0xbfb8aa3b, v82
	v_mul_f32_e32 v83, 0xbfb8aa3b, v83
	v_add_f32_e32 v88, v88, v224
	v_add_f32_e32 v89, v89, v225
	v_add_f32_e32 v86, v86, v222
	v_exp_f32_e32 v82, v82
	v_add_f32_e32 v87, v87, v223
	v_exp_f32_e32 v83, v83
	v_mul_f32_e32 v88, 0xbfb8aa3b, v88
	v_add_f32_e32 v84, v84, v228
	v_mul_f32_e32 v89, 0xbfb8aa3b, v89
	v_add_f32_e32 v85, v85, v229
	v_mul_f32_e32 v86, 0xbfb8aa3b, v86
	v_mul_f32_e32 v87, 0xbfb8aa3b, v87
	v_exp_f32_e32 v88, v88
	v_mul_f32_e32 v84, 0xbfb8aa3b, v84
	v_exp_f32_e32 v89, v89
	v_mul_f32_e32 v85, 0xbfb8aa3b, v85
	v_exp_f32_e32 v86, v86
	v_exp_f32_e32 v87, v87
	v_exp_f32_e32 v84, v84
	v_exp_f32_e32 v85, v85
	v_add_f32_e32 v82, 1.0, v82
	v_add_f32_e32 v83, 1.0, v83
	v_rcp_f32_e32 v82, v82
	v_rcp_f32_e32 v83, v83
	v_add_f32_e32 v88, 1.0, v88
; DEVI float bf2f(u16 b) { return __uint_as_float(((unsigned)b) << 16); }
; template <class Epi>
; DEVI void gemm_phase(LAS unsigned char* lds, const Gemm g, const Epi& E) {
;     ...
;                 if constexpr (Epi::PRE) {
; #pragma unroll
;                     for (int m = 0; m < 2; ++m)
; #pragma unroll
;                         for (int bj = 0; bj < 2; ++bj)
; #pragma unroll
;                             for (int n = 0; n < 2; ++n) pre[m][bj][n] = E.load(row0 + ai * HALF + (m0 + m) * 16, col0 + bj * HALF + n * NST);
;                 }
; #pragma unroll
;                 for (int mm = 0; mm < 2; ++mm) {
;                     const int m = m0 + mm;
;                     const int r = row0 + ai * HALF + m * 16; float rs = 1.f, part = 0.f;
;                     if constexpr (Epi::RS) rs = rsv[ai * 4 + m];
;                     if constexpr (Epi::PAIR) E.pair8(cur.b, r, cur.pn * HALF + wc * 32 + 8 * fq, acc[ai][0][m][0] * rs, acc[ai][0][m][1] * rs, acc[ai][1][m][0] * rs, acc[ai][1][m][1] * rs);
;                     else
; #pragma unroll
;                     for (int bj = 0; bj < 2; ++bj) {
;                         const int c = col0 + bj * HALF; f32x4 v0 = acc[ai][bj][m][0], v1 = acc[ai][bj][m][1];
;                         if constexpr (Epi::RS) { v0 = v0 * rs; v1 = v1 * rs; }
;                         if constexpr (Epi::PRE) part += E.frag_pre8(cur.b, r, c, v0, v1, pre[mm][bj][0], pre[mm][bj][1]);
;     DEVI f32x4 load(int r, int c) const { const bf16x4 y = *(const bf16x4*)(Y + (size_t)r * DM + c); return (f32x4){bf2f((u16)y[0]), bf2f((u16)y[1]), bf2f((u16)y[2]), bf2f((u16)y[3])}; }
	v_add_f32_e32 v89, 1.0, v89
	v_add_f32_e32 v86, 1.0, v86
	v_add_f32_e32 v87, 1.0, v87
	v_rcp_f32_e32 v88, v88
	v_add_f32_e32 v84, 1.0, v84
	v_rcp_f32_e32 v89, v89
	v_add_f32_e32 v85, 1.0, v85
	v_rcp_f32_e32 v86, v86
	v_rcp_f32_e32 v87, v87
	v_rcp_f32_e32 v84, v84
	v_rcp_f32_e32 v85, v85
	v_and_b32_e32 v91, 0xffff0000, v108
	v_lshlrev_b32_e32 v90, 16, v108
	v_pk_mul_f32 v[82:83], v[82:83], v[90:91]
	v_and_b32_e32 v91, 0xffff0000, v107
	v_lshlrev_b32_e32 v90, 16, v107
	v_pk_mul_f32 v[88:89], v[88:89], v[90:91]
	v_and_b32_e32 v91, 0xffff0000, v109
	v_lshlrev_b32_e32 v90, 16, v109
	v_pk_mul_f32 v[86:87], v[86:87], v[96:97]
	v_pk_mul_f32 v[90:91], v[84:85], v[90:91]
	v_cvt_pk_bf16_f32 v84, v86, v87
	v_cvt_pk_bf16_f32 v85, v88, v89
	v_cvt_pk_bf16_f32 v86, v82, v83
	v_cvt_pk_bf16_f32 v87, v90, v91
	global_store_dwordx4 v[94:95], v[84:87], off offset:256
	s_nop 0
	v_add_f32_e32 v74, v74, v218
	v_add_f32_e32 v75, v75, v219
	v_mul_f32_e32 v74, 0xbfb8aa3b, v74
	v_mul_f32_e32 v75, 0xbfb8aa3b, v75
	v_exp_f32_e32 v74, v74
	v_exp_f32_e32 v75, v75
	v_and_b32_e32 v83, 0xffff0000, v104
	v_lshlrev_b32_e32 v82, 16, v104
	v_add_f32_e32 v74, 1.0, v74
	v_add_f32_e32 v75, 1.0, v75
	v_rcp_f32_e32 v74, v74
	v_rcp_f32_e32 v75, v75
	v_add_f32_e32 v78, v78, v214
	v_add_f32_e32 v79, v79, v215
	v_mul_f32_e32 v78, 0xbfb8aa3b, v78
	v_pk_mul_f32 v[82:83], v[74:75], v[82:83]
	v_add_f32_e32 v75, v76, v220
	v_mul_f32_e32 v75, 0xbfb8aa3b, v75
	v_exp_f32_e32 v75, v75
	v_add_f32_e32 v74, v80, v216
	v_mul_f32_e32 v74, 0xbfb8aa3b, v74
	v_exp_f32_e32 v74, v74
	v_add_f32_e32 v75, 1.0, v75
	v_rcp_f32_e32 v76, v75
	v_add_f32_e32 v75, v81, v217
	v_mul_f32_e32 v75, 0xbfb8aa3b, v75
	v_exp_f32_e32 v75, v75
	v_add_f32_e32 v74, 1.0, v74
	v_rcp_f32_e32 v74, v74
	v_and_b32_e32 v81, 0xffff0000, v103
	v_add_f32_e32 v75, 1.0, v75
	v_rcp_f32_e32 v75, v75
	v_lshlrev_b32_e32 v80, 16, v103
	v_mul_f32_e32 v79, 0xbfb8aa3b, v79
	v_exp_f32_e32 v78, v78
	v_pk_mul_f32 v[80:81], v[74:75], v[80:81]
	v_add_f32_e32 v74, v77, v221
	v_exp_f32_e32 v79, v79
	v_mul_f32_e32 v74, 0xbfb8aa3b, v74
	v_exp_f32_e32 v74, v74
	v_add_f32_e32 v78, 1.0, v78
	v_add_f32_e32 v79, 1.0, v79
	v_rcp_f32_e32 v78, v78
	v_rcp_f32_e32 v79, v79
	v_add_f32_e32 v74, 1.0, v74
	v_rcp_f32_e32 v77, v74
	v_and_b32_e32 v87, 0xffff0000, v102
	v_lshlrev_b32_e32 v86, 16, v102
	v_pk_mul_f32 v[78:79], v[78:79], v[86:87]
	v_and_b32_e32 v75, 0xffff0000, v105
	v_lshlrev_b32_e32 v74, 16, v105
	v_pk_mul_f32 v[84:85], v[76:77], v[74:75]
	v_cvt_pk_bf16_f32 v74, v78, v79
	v_lshl_add_u64 v[78:79], s[64:65], 0, v[118:119]
	v_cvt_pk_bf16_f32 v75, v80, v81
	v_cvt_pk_bf16_f32 v76, v82, v83
	v_cvt_pk_bf16_f32 v77, v84, v85
	v_lshl_add_u64 v[78:79], v[78:79], 0, v[176:177]
	global_store_dwordx4 v[78:79], v[74:77], off
	s_nop 0
	v_lshl_add_u64 v[88:89], v[178:179], 0, s[0:1]
	s_mov_b64 s[0:1], 0x48000
	v_lshl_add_u64 v[86:87], v[178:179], 0, s[0:1]
	s_mov_b64 s[0:1], 0x50000
	v_add_f32_e32 v66, v66, v226
	v_add_f32_e32 v67, v67, v227
	v_mul_f32_e32 v66, 0xbfb8aa3b, v66
	v_mul_f32_e32 v67, 0xbfb8aa3b, v67
	v_exp_f32_e32 v66, v66
	v_exp_f32_e32 v67, v67
	v_and_b32_e32 v75, 0xffff0000, v100
	v_lshlrev_b32_e32 v74, 16, v100
	v_add_f32_e32 v66, 1.0, v66
	v_add_f32_e32 v67, 1.0, v67
	v_rcp_f32_e32 v66, v66
	v_rcp_f32_e32 v67, v67
	v_add_f32_e32 v70, v70, v222
	v_add_f32_e32 v71, v71, v223
	v_mul_f32_e32 v70, 0xbfb8aa3b, v70
	v_pk_mul_f32 v[74:75], v[66:67], v[74:75]
	v_add_f32_e32 v67, v68, v228
	v_mul_f32_e32 v67, 0xbfb8aa3b, v67
	v_exp_f32_e32 v67, v67
	v_add_f32_e32 v66, v72, v224
	v_mul_f32_e32 v66, 0xbfb8aa3b, v66
	v_exp_f32_e32 v66, v66
	v_add_f32_e32 v67, 1.0, v67
	v_rcp_f32_e32 v68, v67
	v_add_f32_e32 v67, v73, v225
	v_mul_f32_e32 v67, 0xbfb8aa3b, v67
	v_exp_f32_e32 v67, v67
	v_add_f32_e32 v66, 1.0, v66
	v_rcp_f32_e32 v66, v66
	v_and_b32_e32 v73, 0xffff0000, v99
	v_add_f32_e32 v67, 1.0, v67
	v_rcp_f32_e32 v67, v67
	v_lshlrev_b32_e32 v72, 16, v99
	v_mul_f32_e32 v71, 0xbfb8aa3b, v71
	v_exp_f32_e32 v70, v70
	v_pk_mul_f32 v[72:73], v[66:67], v[72:73]
	v_add_f32_e32 v66, v69, v229
	v_mul_f32_e32 v66, 0xbfb8aa3b, v66
	v_exp_f32_e32 v71, v71
	v_exp_f32_e32 v66, v66
	v_add_f32_e32 v70, 1.0, v70
	v_rcp_f32_e32 v70, v70
	v_add_f32_e32 v71, 1.0, v71
	v_add_f32_e32 v66, 1.0, v66
	v_rcp_f32_e32 v71, v71
	v_rcp_f32_e32 v69, v66
	v_and_b32_e32 v81, 0xffff0000, v98
	v_lshlrev_b32_e32 v80, 16, v98
	v_and_b32_e32 v67, 0xffff0000, v101
	v_lshlrev_b32_e32 v66, 16, v101
	v_pk_mul_f32 v[70:71], v[70:71], v[80:81]
	v_pk_mul_f32 v[76:77], v[68:69], v[66:67]
	v_cvt_pk_bf16_f32 v66, v70, v71
	v_cvt_pk_bf16_f32 v67, v72, v73
	v_cvt_pk_bf16_f32 v68, v74, v75
	v_cvt_pk_bf16_f32 v69, v76, v77
	global_store_dwordx4 v[78:79], v[66:69], off offset:256
	s_nop 1
	v_lshl_add_u64 v[66:67], s[24:25], 0, v[88:89]
	v_lshl_add_u64 v[66:67], v[66:67], 0, v[176:177]
	global_load_dwordx4 v[78:81], v[66:67], off
	global_load_dwordx4 v[74:77], v[66:67], off offset:256
	v_lshl_add_u64 v[66:67], s[24:25], 0, v[86:87]
	v_lshl_add_u64 v[66:67], v[66:67], 0, v[176:177]
	global_load_dwordx4 v[70:73], v[66:67], off
	s_nop 0
	global_load_dwordx4 v[66:69], v[66:67], off offset:256
	s_nop 0
	s_waitcnt vmcnt(0)
; DEVI float bf2f(u16 b) { return __uint_as_float(((unsigned)b) << 16); }
; template <class Epi>
; DEVI void gemm_phase(LAS unsigned char* lds, const Gemm g, const Epi& E) {
;     ...
;                 if constexpr (Epi::PRE) {
; #pragma unroll
;                     for (int m = 0; m < 2; ++m)
; #pragma unroll
;                         for (int bj = 0; bj < 2; ++bj)
; #pragma unroll
;                             for (int n = 0; n < 2; ++n) pre[m][bj][n] = E.load(row0 + ai * HALF + (m0 + m) * 16, col0 + bj * HALF + n * NST);
;                 }
; #pragma unroll
;                 for (int mm = 0; mm < 2; ++mm) {
;                     const int m = m0 + mm;
;                     const int r = row0 + ai * HALF + m * 16; float rs = 1.f, part = 0.f;
;                     if constexpr (Epi::RS) rs = rsv[ai * 4 + m];
;                     if constexpr (Epi::PAIR) E.pair8(cur.b, r, cur.pn * HALF + wc * 32 + 8 * fq, acc[ai][0][m][0] * rs, acc[ai][0][m][1] * rs, acc[ai][1][m][0] * rs, acc[ai][1][m][1] * rs);
;                     else
; #pragma unroll
;                     for (int bj = 0; bj < 2; ++bj) {
;                         const int c = col0 + bj * HALF; f32x4 v0 = acc[ai][bj][m][0], v1 = acc[ai][bj][m][1];
;                         if constexpr (Epi::RS) { v0 = v0 * rs; v1 = v1 * rs; }
;                         if constexpr (Epi::PRE) part += E.frag_pre8(cur.b, r, c, v0, v1, pre[mm][bj][0], pre[mm][bj][1]);
;     DEVI f32x4 load(int r, int c) const { const bf16x4 y = *(const bf16x4*)(Y + (size_t)r * DM + c); return (f32x4){bf2f((u16)y[0]), bf2f((u16)y[1]), bf2f((u16)y[2]), bf2f((u16)y[3])}; }
	v_add_f32_e32 v58, v58, v218
	v_add_f32_e32 v59, v59, v219
	v_mul_f32_e32 v58, 0xbfb8aa3b, v58
	v_mul_f32_e32 v59, 0xbfb8aa3b, v59
	v_exp_f32_e32 v58, v58
	v_exp_f32_e32 v59, v59
	v_and_b32_e32 v83, 0xffff0000, v80
	v_lshlrev_b32_e32 v82, 16, v80
	v_add_f32_e32 v58, 1.0, v58
	v_add_f32_e32 v59, 1.0, v59
	v_rcp_f32_e32 v58, v58
	v_rcp_f32_e32 v59, v59
	v_add_f32_e32 v62, v62, v214
	v_add_f32_e32 v63, v63, v215
	v_mul_f32_e32 v62, 0xbfb8aa3b, v62
	v_pk_mul_f32 v[82:83], v[58:59], v[82:83]
	v_add_f32_e32 v59, v60, v220
	v_mul_f32_e32 v59, 0xbfb8aa3b, v59
	v_exp_f32_e32 v59, v59
	v_add_f32_e32 v58, v64, v216
	v_mul_f32_e32 v58, 0xbfb8aa3b, v58
	v_exp_f32_e32 v58, v58
	v_add_f32_e32 v59, 1.0, v59
	v_rcp_f32_e32 v60, v59
	v_add_f32_e32 v59, v65, v217
	v_mul_f32_e32 v59, 0xbfb8aa3b, v59
	v_exp_f32_e32 v59, v59
	v_add_f32_e32 v58, 1.0, v58
	v_rcp_f32_e32 v58, v58
	v_and_b32_e32 v65, 0xffff0000, v79
	v_add_f32_e32 v59, 1.0, v59
	v_rcp_f32_e32 v59, v59
	v_lshlrev_b32_e32 v64, 16, v79
	v_mul_f32_e32 v63, 0xbfb8aa3b, v63
	v_exp_f32_e32 v62, v62
	v_pk_mul_f32 v[64:65], v[58:59], v[64:65]
	v_add_f32_e32 v58, v61, v221
	v_exp_f32_e32 v63, v63
	v_mul_f32_e32 v58, 0xbfb8aa3b, v58
	v_exp_f32_e32 v58, v58
	v_add_f32_e32 v62, 1.0, v62
	v_add_f32_e32 v63, 1.0, v63
	v_rcp_f32_e32 v62, v62
	v_rcp_f32_e32 v63, v63
	v_add_f32_e32 v58, 1.0, v58
	v_rcp_f32_e32 v61, v58
	v_and_b32_e32 v91, 0xffff0000, v78
	v_lshlrev_b32_e32 v90, 16, v78
	v_pk_mul_f32 v[62:63], v[62:63], v[90:91]
	v_and_b32_e32 v59, 0xffff0000, v81
	v_lshlrev_b32_e32 v58, 16, v81
	v_pk_mul_f32 v[78:79], v[60:61], v[58:59]
	v_cvt_pk_bf16_f32 v58, v62, v63
	v_lshl_add_u64 v[62:63], s[64:65], 0, v[88:89]
	v_cvt_pk_bf16_f32 v59, v64, v65
	v_cvt_pk_bf16_f32 v60, v82, v83
	v_cvt_pk_bf16_f32 v61, v78, v79
	v_lshl_add_u64 v[62:63], v[62:63], 0, v[176:177]
	global_store_dwordx4 v[62:63], v[58:61], off
	s_nop 0
	v_and_b32_e32 v65, 0xffff0000, v74
	v_lshlrev_b32_e32 v64, 16, v74
	v_add_f32_e32 v50, v50, v226
	v_add_f32_e32 v51, v51, v227
	v_mul_f32_e32 v50, 0xbfb8aa3b, v50
	v_mul_f32_e32 v51, 0xbfb8aa3b, v51
	v_add_f32_e32 v56, v56, v224
	v_add_f32_e32 v57, v57, v225
	v_add_f32_e32 v54, v54, v222
	v_exp_f32_e32 v50, v50
	v_add_f32_e32 v55, v55, v223
	v_exp_f32_e32 v51, v51
	v_mul_f32_e32 v56, 0xbfb8aa3b, v56
	v_add_f32_e32 v52, v52, v228
	v_mul_f32_e32 v57, 0xbfb8aa3b, v57
	v_add_f32_e32 v53, v53, v229
	v_mul_f32_e32 v54, 0xbfb8aa3b, v54
	v_mul_f32_e32 v55, 0xbfb8aa3b, v55
	v_exp_f32_e32 v56, v56
	v_mul_f32_e32 v52, 0xbfb8aa3b, v52
	v_exp_f32_e32 v57, v57
	v_mul_f32_e32 v53, 0xbfb8aa3b, v53
	v_exp_f32_e32 v54, v54
	v_exp_f32_e32 v55, v55
	v_exp_f32_e32 v52, v52
	v_exp_f32_e32 v53, v53
	v_add_f32_e32 v50, 1.0, v50
	v_add_f32_e32 v51, 1.0, v51
	v_rcp_f32_e32 v50, v50
	v_rcp_f32_e32 v51, v51
	v_add_f32_e32 v56, 1.0, v56
	v_add_f32_e32 v57, 1.0, v57
	v_add_f32_e32 v54, 1.0, v54
	v_add_f32_e32 v55, 1.0, v55
	v_rcp_f32_e32 v56, v56
	v_add_f32_e32 v52, 1.0, v52
	v_rcp_f32_e32 v57, v57
	v_add_f32_e32 v53, 1.0, v53
	v_rcp_f32_e32 v54, v54
	v_rcp_f32_e32 v55, v55
	v_rcp_f32_e32 v52, v52
	v_rcp_f32_e32 v53, v53
	v_and_b32_e32 v59, 0xffff0000, v76
	v_lshlrev_b32_e32 v58, 16, v76
	v_pk_mul_f32 v[50:51], v[50:51], v[58:59]
	v_and_b32_e32 v59, 0xffff0000, v75
	v_lshlrev_b32_e32 v58, 16, v75
	v_pk_mul_f32 v[56:57], v[56:57], v[58:59]
	v_and_b32_e32 v59, 0xffff0000, v77
	v_lshlrev_b32_e32 v58, 16, v77
	v_pk_mul_f32 v[54:55], v[54:55], v[64:65]
	v_pk_mul_f32 v[58:59], v[52:53], v[58:59]
	v_cvt_pk_bf16_f32 v52, v54, v55
	v_cvt_pk_bf16_f32 v53, v56, v57
	v_cvt_pk_bf16_f32 v54, v50, v51
	v_cvt_pk_bf16_f32 v55, v58, v59
	global_store_dwordx4 v[62:63], v[52:55], off offset:256
	s_nop 0
	v_add_f32_e32 v42, v42, v218
	v_add_f32_e32 v43, v43, v219
	v_mul_f32_e32 v42, 0xbfb8aa3b, v42
	v_mul_f32_e32 v43, 0xbfb8aa3b, v43
	v_exp_f32_e32 v42, v42
	v_exp_f32_e32 v43, v43
	v_and_b32_e32 v51, 0xffff0000, v72
	v_lshlrev_b32_e32 v50, 16, v72
	v_add_f32_e32 v42, 1.0, v42
	v_add_f32_e32 v43, 1.0, v43
	v_rcp_f32_e32 v42, v42
	v_rcp_f32_e32 v43, v43
	v_add_f32_e32 v46, v46, v214
	v_add_f32_e32 v47, v47, v215
	v_mul_f32_e32 v46, 0xbfb8aa3b, v46
	v_pk_mul_f32 v[50:51], v[42:43], v[50:51]
	v_add_f32_e32 v43, v44, v220
	v_mul_f32_e32 v43, 0xbfb8aa3b, v43
	v_exp_f32_e32 v43, v43
	v_add_f32_e32 v42, v48, v216
	v_mul_f32_e32 v42, 0xbfb8aa3b, v42
	v_exp_f32_e32 v42, v42
	v_add_f32_e32 v43, 1.0, v43
	v_rcp_f32_e32 v44, v43
	v_add_f32_e32 v43, v49, v217
	v_mul_f32_e32 v43, 0xbfb8aa3b, v43
	v_exp_f32_e32 v43, v43
	v_add_f32_e32 v42, 1.0, v42
	v_rcp_f32_e32 v42, v42
	v_and_b32_e32 v49, 0xffff0000, v71
	v_add_f32_e32 v43, 1.0, v43
	v_rcp_f32_e32 v43, v43
	v_lshlrev_b32_e32 v48, 16, v71
	v_mul_f32_e32 v47, 0xbfb8aa3b, v47
	v_exp_f32_e32 v46, v46
	v_pk_mul_f32 v[48:49], v[42:43], v[48:49]
	v_add_f32_e32 v42, v45, v221
	v_exp_f32_e32 v47, v47
	v_mul_f32_e32 v42, 0xbfb8aa3b, v42
	v_exp_f32_e32 v42, v42
	v_add_f32_e32 v46, 1.0, v46
	v_add_f32_e32 v47, 1.0, v47
	v_rcp_f32_e32 v46, v46
	v_rcp_f32_e32 v47, v47
	v_add_f32_e32 v42, 1.0, v42
	v_rcp_f32_e32 v45, v42
	v_and_b32_e32 v55, 0xffff0000, v70
	v_lshlrev_b32_e32 v54, 16, v70
	v_pk_mul_f32 v[46:47], v[46:47], v[54:55]
	v_and_b32_e32 v43, 0xffff0000, v73
	v_lshlrev_b32_e32 v42, 16, v73
	v_pk_mul_f32 v[52:53], v[44:45], v[42:43]
	v_cvt_pk_bf16_f32 v42, v46, v47
	v_lshl_add_u64 v[46:47], s[64:65], 0, v[86:87]
	v_cvt_pk_bf16_f32 v43, v48, v49
	v_cvt_pk_bf16_f32 v44, v50, v51
	v_cvt_pk_bf16_f32 v45, v52, v53
	v_lshl_add_u64 v[46:47], v[46:47], 0, v[176:177]
	global_store_dwordx4 v[46:47], v[42:45], off
	s_nop 0
	v_lshl_add_u64 v[56:57], v[178:179], 0, s[0:1]
	s_mov_b64 s[0:1], 0x58000
	v_lshl_add_u64 v[54:55], v[178:179], 0, s[0:1]
; DEVI float bf2f(u16 b) { return __uint_as_float(((unsigned)b) << 16); }
; template <class Epi>
; DEVI void gemm_phase(LAS unsigned char* lds, const Gemm g, const Epi& E) {
;     ...
;                             for (int n = 0; n < 2; ++n) pre[m][bj][n] = E.load(row0 + ai * HALF + (m0 + m) * 16, col0 + bj * HALF + n * NST);
;                 }
; #pragma unroll
;                 for (int mm = 0; mm < 2; ++mm) {
;                     const int m = m0 + mm;
;                     const int r = row0 + ai * HALF + m * 16; float rs = 1.f, part = 0.f;
;                     if constexpr (Epi::RS) rs = rsv[ai * 4 + m];
;                     if constexpr (Epi::PAIR) E.pair8(cur.b, r, cur.pn * HALF + wc * 32 + 8 * fq, acc[ai][0][m][0] * rs, acc[ai][0][m][1] * rs, acc[ai][1][m][0] * rs, acc[ai][1][m][1] * rs);
;                     else
; #pragma unroll
;                     for (int bj = 0; bj < 2; ++bj) {
;                         const int c = col0 + bj * HALF; f32x4 v0 = acc[ai][bj][m][0], v1 = acc[ai][bj][m][1];
;                         if constexpr (Epi::RS) { v0 = v0 * rs; v1 = v1 * rs; }
;                         if constexpr (Epi::PRE) part += E.frag_pre8(cur.b, r, c, v0, v1, pre[mm][bj][0], pre[mm][bj][1]);
;     DEVI f32x4 load(int r, int c) const { const bf16x4 y = *(const bf16x4*)(Y + (size_t)r * DM + c); return (f32x4){bf2f((u16)y[0]), bf2f((u16)y[1]), bf2f((u16)y[2]), bf2f((u16)y[3])}; }
	s_mov_b32 s0, s4
	v_add_f32_e32 v34, v34, v226
	v_add_f32_e32 v35, v35, v227
	v_mul_f32_e32 v34, 0xbfb8aa3b, v34
	v_mul_f32_e32 v35, 0xbfb8aa3b, v35
	v_exp_f32_e32 v34, v34
	v_exp_f32_e32 v35, v35
	v_and_b32_e32 v43, 0xffff0000, v68
	v_lshlrev_b32_e32 v42, 16, v68
	v_add_f32_e32 v34, 1.0, v34
	v_add_f32_e32 v35, 1.0, v35
	v_rcp_f32_e32 v34, v34
	v_rcp_f32_e32 v35, v35
	v_add_f32_e32 v38, v38, v222
	v_add_f32_e32 v39, v39, v223
	v_mul_f32_e32 v38, 0xbfb8aa3b, v38
	v_pk_mul_f32 v[42:43], v[34:35], v[42:43]
	v_add_f32_e32 v35, v36, v228
	v_mul_f32_e32 v35, 0xbfb8aa3b, v35
	v_exp_f32_e32 v35, v35
	v_add_f32_e32 v34, v40, v224
	v_mul_f32_e32 v34, 0xbfb8aa3b, v34
	v_exp_f32_e32 v34, v34
	v_add_f32_e32 v35, 1.0, v35
	v_rcp_f32_e32 v36, v35
	v_add_f32_e32 v35, v41, v225
	v_mul_f32_e32 v35, 0xbfb8aa3b, v35
	v_exp_f32_e32 v35, v35
	v_add_f32_e32 v34, 1.0, v34
	v_rcp_f32_e32 v34, v34
	v_and_b32_e32 v41, 0xffff0000, v67
	v_add_f32_e32 v35, 1.0, v35
	v_rcp_f32_e32 v35, v35
	v_lshlrev_b32_e32 v40, 16, v67
	v_mul_f32_e32 v39, 0xbfb8aa3b, v39
	v_exp_f32_e32 v38, v38
	v_pk_mul_f32 v[40:41], v[34:35], v[40:41]
	v_add_f32_e32 v34, v37, v229
	v_mul_f32_e32 v34, 0xbfb8aa3b, v34
	v_exp_f32_e32 v39, v39
	v_exp_f32_e32 v34, v34
	v_add_f32_e32 v38, 1.0, v38
	v_rcp_f32_e32 v38, v38
	v_add_f32_e32 v39, 1.0, v39
	v_add_f32_e32 v34, 1.0, v34
	v_rcp_f32_e32 v39, v39
	v_rcp_f32_e32 v37, v34
	v_and_b32_e32 v49, 0xffff0000, v66
	v_lshlrev_b32_e32 v48, 16, v66
	v_and_b32_e32 v35, 0xffff0000, v69
	v_lshlrev_b32_e32 v34, 16, v69
	v_pk_mul_f32 v[38:39], v[38:39], v[48:49]
	v_pk_mul_f32 v[44:45], v[36:37], v[34:35]
	v_cvt_pk_bf16_f32 v34, v38, v39
	v_cvt_pk_bf16_f32 v35, v40, v41
	v_cvt_pk_bf16_f32 v36, v42, v43
	v_cvt_pk_bf16_f32 v37, v44, v45
	global_store_dwordx4 v[46:47], v[34:37], off offset:256
	s_nop 1
	v_lshl_add_u64 v[34:35], s[24:25], 0, v[56:57]
	v_lshl_add_u64 v[34:35], v[34:35], 0, v[176:177]
	global_load_dwordx4 v[46:49], v[34:35], off
	global_load_dwordx4 v[42:45], v[34:35], off offset:256
	v_lshl_add_u64 v[34:35], s[24:25], 0, v[54:55]
	v_lshl_add_u64 v[34:35], v[34:35], 0, v[176:177]
	global_load_dwordx4 v[38:41], v[34:35], off
	s_nop 0
	global_load_dwordx4 v[34:37], v[34:35], off offset:256
	s_nop 0
	s_waitcnt vmcnt(0)
	v_add_f32_e32 v26, v26, v218
	v_add_f32_e32 v27, v27, v219
	v_mul_f32_e32 v26, 0xbfb8aa3b, v26
	v_mul_f32_e32 v27, 0xbfb8aa3b, v27
	v_exp_f32_e32 v26, v26
	v_exp_f32_e32 v27, v27
	v_and_b32_e32 v51, 0xffff0000, v48
	v_lshlrev_b32_e32 v50, 16, v48
	v_add_f32_e32 v26, 1.0, v26
	v_add_f32_e32 v27, 1.0, v27
	v_rcp_f32_e32 v26, v26
	v_rcp_f32_e32 v27, v27
	v_add_f32_e32 v30, v30, v214
	v_add_f32_e32 v31, v31, v215
	v_mul_f32_e32 v30, 0xbfb8aa3b, v30
	v_pk_mul_f32 v[50:51], v[26:27], v[50:51]
	v_add_f32_e32 v27, v28, v220
	v_mul_f32_e32 v27, 0xbfb8aa3b, v27
	v_exp_f32_e32 v27, v27
	v_add_f32_e32 v26, v32, v216
	v_mul_f32_e32 v26, 0xbfb8aa3b, v26
	v_exp_f32_e32 v26, v26
	v_add_f32_e32 v27, 1.0, v27
	v_rcp_f32_e32 v28, v27
	v_add_f32_e32 v27, v33, v217
	v_mul_f32_e32 v27, 0xbfb8aa3b, v27
	v_exp_f32_e32 v27, v27
	v_add_f32_e32 v26, 1.0, v26
	v_rcp_f32_e32 v26, v26
	v_and_b32_e32 v33, 0xffff0000, v47
	v_add_f32_e32 v27, 1.0, v27
	v_rcp_f32_e32 v27, v27
	v_lshlrev_b32_e32 v32, 16, v47
	v_mul_f32_e32 v31, 0xbfb8aa3b, v31
	v_exp_f32_e32 v30, v30
	v_pk_mul_f32 v[32:33], v[26:27], v[32:33]
	v_add_f32_e32 v26, v29, v221
	v_exp_f32_e32 v31, v31
	v_mul_f32_e32 v26, 0xbfb8aa3b, v26
	v_exp_f32_e32 v26, v26
	v_add_f32_e32 v30, 1.0, v30
	v_add_f32_e32 v31, 1.0, v31
	v_rcp_f32_e32 v30, v30
	v_rcp_f32_e32 v31, v31
	v_add_f32_e32 v26, 1.0, v26
	v_rcp_f32_e32 v29, v26
	v_and_b32_e32 v59, 0xffff0000, v46
	v_lshlrev_b32_e32 v58, 16, v46
	v_pk_mul_f32 v[30:31], v[30:31], v[58:59]
	v_and_b32_e32 v27, 0xffff0000, v49
	v_lshlrev_b32_e32 v26, 16, v49
	v_pk_mul_f32 v[46:47], v[28:29], v[26:27]
	v_cvt_pk_bf16_f32 v26, v30, v31
	v_lshl_add_u64 v[30:31], s[64:65], 0, v[56:57]
	v_cvt_pk_bf16_f32 v27, v32, v33
	v_cvt_pk_bf16_f32 v28, v50, v51
	v_cvt_pk_bf16_f32 v29, v46, v47
	v_lshl_add_u64 v[30:31], v[30:31], 0, v[176:177]
	global_store_dwordx4 v[30:31], v[26:29], off
	s_nop 0
	v_and_b32_e32 v33, 0xffff0000, v42
	v_lshlrev_b32_e32 v32, 16, v42
	v_add_f32_e32 v18, v18, v226
	v_add_f32_e32 v19, v19, v227
	v_mul_f32_e32 v18, 0xbfb8aa3b, v18
	v_mul_f32_e32 v19, 0xbfb8aa3b, v19
	v_add_f32_e32 v24, v24, v224
	v_add_f32_e32 v25, v25, v225
	v_add_f32_e32 v22, v22, v222
	v_exp_f32_e32 v18, v18
	v_add_f32_e32 v23, v23, v223
	v_exp_f32_e32 v19, v19
	v_mul_f32_e32 v24, 0xbfb8aa3b, v24
	v_add_f32_e32 v20, v20, v228
	v_mul_f32_e32 v25, 0xbfb8aa3b, v25
	v_add_f32_e32 v21, v21, v229
	v_mul_f32_e32 v22, 0xbfb8aa3b, v22
	v_mul_f32_e32 v23, 0xbfb8aa3b, v23
	v_exp_f32_e32 v24, v24
	v_mul_f32_e32 v20, 0xbfb8aa3b, v20
	v_exp_f32_e32 v25, v25
; #define PG8_WAIT_V(n) asm volatile("s_waitcnt vmcnt(" #n ")" ::: "memory")
; #define PG8_BAR __builtin_amdgcn_s_barrier()
; template <class Epi>
; DEVI void gemm_phase(LAS unsigned char* lds, const Gemm g, const Epi& E) {
;     ...
;         if (!has_next) break;
; #pragma unroll
;         for (int a = 0; a < 2; ++a)
; #pragma unroll
;             for (int b = 0; b < 2; ++b)
; #pragma unroll
;                 for (int m = 0; m < 4; ++m)
; #pragma unroll
;                     for (int n = 0; n < 2; ++n) acc[a][b][m][n] = (f32x4){0.f, 0.f, 0.f, 0.f};
;         cur = nxt; cA = nA; cB = nB; ++ui;
;     }
;     PG8_WAIT_V(0);
;     if (wr == 0) PG8_BAR;
;     PG8_BAR;
	v_mul_f32_e32 v21, 0xbfb8aa3b, v21
	v_exp_f32_e32 v22, v22
	v_exp_f32_e32 v23, v23
	v_exp_f32_e32 v20, v20
	v_exp_f32_e32 v21, v21
	v_add_f32_e32 v18, 1.0, v18
	v_add_f32_e32 v19, 1.0, v19
	v_rcp_f32_e32 v18, v18
	v_rcp_f32_e32 v19, v19
	v_add_f32_e32 v24, 1.0, v24
	v_add_f32_e32 v25, 1.0, v25
	v_add_f32_e32 v22, 1.0, v22
	v_add_f32_e32 v23, 1.0, v23
	v_rcp_f32_e32 v24, v24
	v_add_f32_e32 v20, 1.0, v20
	v_rcp_f32_e32 v25, v25
	v_add_f32_e32 v21, 1.0, v21
	v_rcp_f32_e32 v22, v22
	v_rcp_f32_e32 v23, v23
	v_rcp_f32_e32 v20, v20
	v_rcp_f32_e32 v21, v21
	v_and_b32_e32 v27, 0xffff0000, v44
	v_lshlrev_b32_e32 v26, 16, v44
	v_pk_mul_f32 v[18:19], v[18:19], v[26:27]
	v_and_b32_e32 v27, 0xffff0000, v43
	v_lshlrev_b32_e32 v26, 16, v43
	v_pk_mul_f32 v[24:25], v[24:25], v[26:27]
	v_and_b32_e32 v27, 0xffff0000, v45
	v_lshlrev_b32_e32 v26, 16, v45
	v_pk_mul_f32 v[22:23], v[22:23], v[32:33]
	v_pk_mul_f32 v[26:27], v[20:21], v[26:27]
	v_cvt_pk_bf16_f32 v20, v22, v23
	v_cvt_pk_bf16_f32 v21, v24, v25
	v_cvt_pk_bf16_f32 v22, v18, v19
	v_cvt_pk_bf16_f32 v23, v26, v27
	global_store_dwordx4 v[30:31], v[20:23], off offset:256
	s_nop 0
	v_add_f32_e32 v10, v10, v218
	v_add_f32_e32 v11, v11, v219
	v_mul_f32_e32 v10, 0xbfb8aa3b, v10
	v_mul_f32_e32 v11, 0xbfb8aa3b, v11
	v_exp_f32_e32 v10, v10
	v_exp_f32_e32 v11, v11
	v_and_b32_e32 v19, 0xffff0000, v40
	v_lshlrev_b32_e32 v18, 16, v40
	v_add_f32_e32 v10, 1.0, v10
	v_add_f32_e32 v11, 1.0, v11
	v_rcp_f32_e32 v10, v10
	v_rcp_f32_e32 v11, v11
	v_add_f32_e32 v14, v14, v214
	v_add_f32_e32 v15, v15, v215
	v_mul_f32_e32 v14, 0xbfb8aa3b, v14
	v_pk_mul_f32 v[18:19], v[10:11], v[18:19]
	v_add_f32_e32 v11, v12, v220
	v_mul_f32_e32 v11, 0xbfb8aa3b, v11
	v_exp_f32_e32 v11, v11
	v_add_f32_e32 v10, v16, v216
	v_mul_f32_e32 v10, 0xbfb8aa3b, v10
	v_exp_f32_e32 v10, v10
	v_add_f32_e32 v11, 1.0, v11
	v_rcp_f32_e32 v12, v11
	v_add_f32_e32 v11, v17, v217
	v_mul_f32_e32 v11, 0xbfb8aa3b, v11
	v_exp_f32_e32 v11, v11
	v_add_f32_e32 v10, 1.0, v10
	v_rcp_f32_e32 v10, v10
	v_and_b32_e32 v17, 0xffff0000, v39
	v_add_f32_e32 v11, 1.0, v11
	v_rcp_f32_e32 v11, v11
	v_lshlrev_b32_e32 v16, 16, v39
	v_mul_f32_e32 v15, 0xbfb8aa3b, v15
	v_exp_f32_e32 v14, v14
	v_pk_mul_f32 v[16:17], v[10:11], v[16:17]
	v_add_f32_e32 v10, v13, v221
	v_exp_f32_e32 v15, v15
	v_mul_f32_e32 v10, 0xbfb8aa3b, v10
	v_exp_f32_e32 v10, v10
	v_add_f32_e32 v14, 1.0, v14
	v_add_f32_e32 v15, 1.0, v15
	v_rcp_f32_e32 v14, v14
	v_rcp_f32_e32 v15, v15
	v_add_f32_e32 v10, 1.0, v10
	v_rcp_f32_e32 v13, v10
	v_and_b32_e32 v23, 0xffff0000, v38
	v_lshlrev_b32_e32 v22, 16, v38
	v_pk_mul_f32 v[14:15], v[14:15], v[22:23]
	v_and_b32_e32 v11, 0xffff0000, v41
	v_lshlrev_b32_e32 v10, 16, v41
	v_pk_mul_f32 v[20:21], v[12:13], v[10:11]
	v_cvt_pk_bf16_f32 v10, v14, v15
	v_lshl_add_u64 v[14:15], s[64:65], 0, v[54:55]
	v_cvt_pk_bf16_f32 v11, v16, v17
	v_cvt_pk_bf16_f32 v12, v18, v19
	v_cvt_pk_bf16_f32 v13, v20, v21
	v_lshl_add_u64 v[14:15], v[14:15], 0, v[176:177]
	global_store_dwordx4 v[14:15], v[10:13], off
	s_nop 0
	v_add_f32_e32 v0, v0, v226
	v_add_f32_e32 v1, v1, v227
	v_mul_f32_e32 v0, 0xbfb8aa3b, v0
	v_mul_f32_e32 v1, 0xbfb8aa3b, v1
	v_exp_f32_e32 v0, v0
	v_exp_f32_e32 v1, v1
	v_and_b32_e32 v11, 0xffff0000, v36
	v_lshlrev_b32_e32 v10, 16, v36
	v_add_f32_e32 v0, 1.0, v0
	v_add_f32_e32 v1, 1.0, v1
	v_rcp_f32_e32 v0, v0
	v_rcp_f32_e32 v1, v1
	v_add_f32_e32 v4, v4, v222
	v_add_f32_e32 v5, v5, v223
	v_mul_f32_e32 v4, 0xbfb8aa3b, v4
	v_pk_mul_f32 v[10:11], v[0:1], v[10:11]
	v_add_f32_e32 v1, v2, v228
	v_mul_f32_e32 v1, 0xbfb8aa3b, v1
	v_exp_f32_e32 v1, v1
	v_add_f32_e32 v0, v6, v224
	v_mul_f32_e32 v0, 0xbfb8aa3b, v0
	v_exp_f32_e32 v0, v0
	v_add_f32_e32 v1, 1.0, v1
	v_rcp_f32_e32 v2, v1
	v_add_f32_e32 v1, v7, v225
	v_mul_f32_e32 v1, 0xbfb8aa3b, v1
	v_exp_f32_e32 v1, v1
	v_add_f32_e32 v0, 1.0, v0
	v_rcp_f32_e32 v0, v0
	v_and_b32_e32 v7, 0xffff0000, v35
	v_add_f32_e32 v1, 1.0, v1
	v_rcp_f32_e32 v1, v1
	v_lshlrev_b32_e32 v6, 16, v35
	v_mul_f32_e32 v5, 0xbfb8aa3b, v5
	v_exp_f32_e32 v4, v4
	v_pk_mul_f32 v[6:7], v[0:1], v[6:7]
	v_add_f32_e32 v0, v3, v229
	v_mul_f32_e32 v0, 0xbfb8aa3b, v0
	v_exp_f32_e32 v5, v5
	v_exp_f32_e32 v0, v0
	v_add_f32_e32 v4, 1.0, v4
	v_rcp_f32_e32 v4, v4
	v_add_f32_e32 v5, 1.0, v5
	v_add_f32_e32 v0, 1.0, v0
	v_rcp_f32_e32 v5, v5
	v_rcp_f32_e32 v3, v0
	v_and_b32_e32 v17, 0xffff0000, v34
	v_lshlrev_b32_e32 v16, 16, v34
	v_and_b32_e32 v1, 0xffff0000, v37
	v_lshlrev_b32_e32 v0, 16, v37
	v_pk_mul_f32 v[4:5], v[4:5], v[16:17]
	v_pk_mul_f32 v[12:13], v[2:3], v[0:1]
	v_cvt_pk_bf16_f32 v0, v4, v5
	v_cvt_pk_bf16_f32 v1, v6, v7
	v_cvt_pk_bf16_f32 v2, v10, v11
	v_cvt_pk_bf16_f32 v3, v12, v13
	global_store_dwordx4 v[14:15], v[0:3], off offset:256
	s_cbranch_vccz .LBB0_1339
	s_waitcnt vmcnt(0)
	s_cmpk_gt_u32 s46, 0xff
	s_cbranch_scc1 .LBB0_1350
	s_barrier

; #define PG8_STAGE(bufoff, gbase, voff) do { _Pragma("unroll") for (int _i = 0; _i < 2; ++_i) \
;         __builtin_amdgcn_global_load_lds((const unsigned*)((const char*)(gbase) + (voff)[_i]), (LAS unsigned*)(lds + (bufoff) + ldsw + _i * 8192), 16, 0, 0); } while (0)
; #define PG8_LDA(dst, b, h) do { _Pragma("unroll") for (int m = 0; m < 4; ++m) _Pragma("unroll") for (int k = 0; k < 2; ++k) dst[m][k] = *(const LAS bf16x8*)(lds + PG8_SA(b, h) + aoff + m * 2048 + k * 1024); } while (0)
; #define PG8_LDB(dst, b, h) do { _Pragma("unroll") for (int n = 0; n < 2; ++n) _Pragma("unroll") for (int k = 0; k < 2; ++k) dst[n][k] = *(const LAS bf16x8*)(lds + PG8_SB(b, h) + boff + n * 2048 + k * 1024); } while (0)
; #define PG8_MMA(ai, bj, At, Bt) do { __builtin_amdgcn_s_setprio(1); _Pragma("unroll") for (int m = 0; m < 4; ++m) _Pragma("unroll") for (int n = 0; n < 2; ++n) _Pragma("unroll") for (int k = 0; k < 2; ++k) \
;         acc[ai][bj][m][n] = __builtin_amdgcn_mfma_f32_16x16x32_bf16(Bt[n][k], At[m][k], acc[ai][bj][m][n], 0, 0, 0); __builtin_amdgcn_s_setprio(0); } while (0)
; #define PG8_WAIT_V(n) asm volatile("s_waitcnt vmcnt(" #n ")" ::: "memory")
; #define PG8_WAIT_L(n) asm volatile("s_waitcnt lgkmcnt(" #n ")" ::: "memory")
; #define PG8_BAR __builtin_amdgcn_s_barrier()
; #define PG8_SCHED __builtin_amdgcn_sched_barrier(0)
; template <class Epi>
; DEVI void gemm_phase(LAS unsigned char* lds, const Gemm g, const Epi& E) {
;     ...
;             const bool last = (t == nt - 2);
;             const char* a1 = cA + (size_t)(t + 1) * kstep;
;             const char* a2 = last ? nA : cA + (size_t)(t + 2) * kstep; const char* b2 = last ? nB : cB + (size_t)(t + 2) * kstep;
;             const char* a3 = a2 + kstep; const char* b3 = b2 + kstep;
;             PG8_LDB(B0, 0, 0); PG8_SCHED; PG8_LDA(At, 0, 0); PG8_STAGE(PG8_SA(1, 1), a1 + hstepA, voffA);
;             PG8_WAIT_L(8); PG8_BAR; PG8_WAIT_L(0); PG8_MMA(0, 0, At, B0); PG8_BAR; PG8_SCHED;
;             PG8_LDB(B1, 0, 1); PG8_STAGE(PG8_SB(0, 0), b2, voffB);
;             PG8_BAR; PG8_WAIT_L(0); PG8_MMA(0, 1, At, B1); PG8_BAR;
;             PG8_LDA(At, 0, 1); PG8_STAGE(PG8_SA(0, 0), a2, voffA);
;             PG8_BAR; PG8_WAIT_L(0); PG8_MMA(1, 0, At, B0); PG8_BAR; PG8_SCHED;
;             PG8_STAGE(PG8_SB(0, 1), b2 + hstepB, voffB);
;             PG8_WAIT_V(6); PG8_BAR; PG8_MMA(1, 1, At, B1); PG8_BAR;
.LBB0_1507:
	s_add_u32 s19, s6, 0xfffc0080
	s_addc_u32 s26, s7, -1
	s_add_i32 s27, 0, 0x10000
	v_add_u32_e32 v142, s27, v199
	ds_read_b128 v[130:133], v142
	ds_read_b128 v[134:137], v142 offset:1024
	ds_read_b128 v[138:141], v142 offset:2048
	ds_read_b128 v[142:145], v142 offset:3072
	s_cmp_eq_u32 s18, 12
	s_cselect_b32 s79, s0, s26
	s_cselect_b32 s78, s1, s19
	s_cselect_b32 s69, s15, s13
	s_cselect_b32 s68, s14, s11
	v_lshl_add_u64 v[162:163], s[6:7], 0, v[182:183]
	s_add_i32 m0, s37, 0xc000
	ds_read_b128 v[146:149], v202
	ds_read_b128 v[150:153], v202 offset:1024
	ds_read_b128 v[186:189], v202 offset:2048
	ds_read_b128 v[190:193], v202 offset:3072
	ds_read_b128 v[194:197], v202 offset:4096
	ds_read_b128 v[204:207], v202 offset:5120
	ds_read_b128 v[214:217], v202 offset:6144
	ds_read_b128 v[218:221], v202 offset:7168
	global_load_lds_dwordx4 v[162:163], off
	s_add_i32 m0, s37, 0xe000
	v_lshl_add_u64 v[162:163], s[6:7], 0, v[184:185]
	global_load_lds_dwordx4 v[162:163], off
	s_waitcnt lgkmcnt(0)
	s_barrier
	v_mfma_f32_16x16x32_bf16 v[126:129], v[130:133], v[146:149], v[126:129]
	v_mfma_f32_16x16x32_bf16 v[122:125], v[138:141], v[146:149], v[122:125]
	v_mfma_f32_16x16x32_bf16 v[110:113], v[130:133], v[186:189], v[110:113]
	v_mfma_f32_16x16x32_bf16 v[106:109], v[138:141], v[186:189], v[106:109]
	v_mfma_f32_16x16x32_bf16 v[94:97], v[130:133], v[194:197], v[94:97]
	v_mfma_f32_16x16x32_bf16 v[90:93], v[138:141], v[194:197], v[90:93]
	v_mfma_f32_16x16x32_bf16 v[78:81], v[130:133], v[214:217], v[78:81]
	v_mfma_f32_16x16x32_bf16 v[74:77], v[138:141], v[214:217], v[74:77]
	v_mfma_f32_16x16x32_bf16 v[126:129], v[134:137], v[150:153], v[126:129]
	v_mfma_f32_16x16x32_bf16 v[122:125], v[142:145], v[150:153], v[122:125]
	v_mfma_f32_16x16x32_bf16 v[110:113], v[134:137], v[190:193], v[110:113]
	v_mfma_f32_16x16x32_bf16 v[106:109], v[142:145], v[190:193], v[106:109]
	v_mfma_f32_16x16x32_bf16 v[94:97], v[134:137], v[204:207], v[94:97]
	v_mfma_f32_16x16x32_bf16 v[90:93], v[142:145], v[204:207], v[90:93]
	v_mfma_f32_16x16x32_bf16 v[78:81], v[134:137], v[218:221], v[78:81]
	v_mfma_f32_16x16x32_bf16 v[74:77], v[142:145], v[218:221], v[74:77]
	s_barrier
	s_add_i32 s19, 0, 0x14000
	v_add_u32_e32 v162, s19, v199
	s_add_i32 s26, s27, s80
	ds_read_b128 v[222:225], v162
	ds_read_b128 v[226:229], v162 offset:1024
	ds_read_b128 v[230:233], v162 offset:2048
	ds_read_b128 v[234:237], v162 offset:3072
	v_lshl_add_u64 v[162:163], s[68:69], 0, v[8:9]
	s_mov_b32 m0, s26
	v_lshl_add_u64 v[164:165], s[68:69], 0, v[180:181]
	global_load_lds_dwordx4 v[162:163], off
	s_add_i32 m0, s26, 0x2000
	s_nop 0
	global_load_lds_dwordx4 v[164:165], off
	s_waitcnt lgkmcnt(0)
	s_barrier
	v_mfma_f32_16x16x32_bf16 v[118:121], v[222:225], v[146:149], v[118:121]
	v_mfma_f32_16x16x32_bf16 v[114:117], v[230:233], v[146:149], v[114:117]
	v_mfma_f32_16x16x32_bf16 v[102:105], v[222:225], v[186:189], v[102:105]
	v_mfma_f32_16x16x32_bf16 v[98:101], v[230:233], v[186:189], v[98:101]
	v_mfma_f32_16x16x32_bf16 v[86:89], v[222:225], v[194:197], v[86:89]
	v_mfma_f32_16x16x32_bf16 v[82:85], v[230:233], v[194:197], v[82:85]
	v_mfma_f32_16x16x32_bf16 v[70:73], v[222:225], v[214:217], v[70:73]
	v_mfma_f32_16x16x32_bf16 v[62:65], v[230:233], v[214:217], v[62:65]
	v_mfma_f32_16x16x32_bf16 v[118:121], v[226:229], v[150:153], v[118:121]
	v_mfma_f32_16x16x32_bf16 v[114:117], v[234:237], v[150:153], v[114:117]
	v_mfma_f32_16x16x32_bf16 v[102:105], v[226:229], v[190:193], v[102:105]
	v_mfma_f32_16x16x32_bf16 v[98:101], v[234:237], v[190:193], v[98:101]
	v_mfma_f32_16x16x32_bf16 v[86:89], v[226:229], v[204:207], v[86:89]
	v_mfma_f32_16x16x32_bf16 v[82:85], v[234:237], v[204:207], v[82:85]
	v_mfma_f32_16x16x32_bf16 v[70:73], v[226:229], v[218:221], v[70:73]
	v_mfma_f32_16x16x32_bf16 v[62:65], v[234:237], v[218:221], v[62:65]
	s_mov_b32 m0, s37
	v_lshl_add_u64 v[208:209], s[78:79], 0, v[176:177]
	s_barrier
	ds_read_b128 v[146:149], v202 offset:16384
	ds_read_b128 v[150:153], v202 offset:17408
	ds_read_b128 v[186:189], v202 offset:18432
	ds_read_b128 v[190:193], v202 offset:19456
	ds_read_b128 v[194:197], v202 offset:20480
	ds_read_b128 v[204:207], v202 offset:21504
	ds_read_b128 v[214:217], v202 offset:22528
	ds_read_b128 v[218:221], v202 offset:23552
	global_load_lds_dwordx4 v[208:209], off
	s_mov_b32 m0, s47
	v_lshl_add_u64 v[238:239], s[78:79], 0, v[178:179]
	global_load_lds_dwordx4 v[238:239], off
	s_waitcnt lgkmcnt(0)
	s_barrier
	v_mfma_f32_16x16x32_bf16 v[66:69], v[130:133], v[146:149], v[66:69]
	v_mfma_f32_16x16x32_bf16 v[54:57], v[138:141], v[146:149], v[54:57]
	v_mfma_f32_16x16x32_bf16 v[46:49], v[130:133], v[186:189], v[46:49]
	v_mfma_f32_16x16x32_bf16 v[38:41], v[138:141], v[186:189], v[38:41]
	v_mfma_f32_16x16x32_bf16 v[30:33], v[130:133], v[194:197], v[30:33]
	v_mfma_f32_16x16x32_bf16 v[22:25], v[138:141], v[194:197], v[22:25]
	v_mfma_f32_16x16x32_bf16 v[14:17], v[130:133], v[214:217], v[14:17]
	v_mfma_f32_16x16x32_bf16 v[4:7], v[138:141], v[214:217], v[4:7]
	v_mfma_f32_16x16x32_bf16 v[66:69], v[134:137], v[150:153], v[66:69]
	v_mfma_f32_16x16x32_bf16 v[54:57], v[142:145], v[150:153], v[54:57]
	v_mfma_f32_16x16x32_bf16 v[46:49], v[134:137], v[190:193], v[46:49]
	v_mfma_f32_16x16x32_bf16 v[38:41], v[142:145], v[190:193], v[38:41]
	v_mfma_f32_16x16x32_bf16 v[30:33], v[134:137], v[204:207], v[30:33]
	v_mfma_f32_16x16x32_bf16 v[22:25], v[142:145], v[204:207], v[22:25]
	v_mfma_f32_16x16x32_bf16 v[14:17], v[134:137], v[218:221], v[14:17]
	v_mfma_f32_16x16x32_bf16 v[4:7], v[142:145], v[218:221], v[4:7]
	s_barrier
; #define PG8_STAGE(bufoff, gbase, voff) do { _Pragma("unroll") for (int _i = 0; _i < 2; ++_i) \
;         __builtin_amdgcn_global_load_lds((const unsigned*)((const char*)(gbase) + (voff)[_i]), (LAS unsigned*)(lds + (bufoff) + ldsw + _i * 8192), 16, 0, 0); } while (0)
; #define PG8_LDA(dst, b, h) do { _Pragma("unroll") for (int m = 0; m < 4; ++m) _Pragma("unroll") for (int k = 0; k < 2; ++k) dst[m][k] = *(const LAS bf16x8*)(lds + PG8_SA(b, h) + aoff + m * 2048 + k * 1024); } while (0)
; #define PG8_LDB(dst, b, h) do { _Pragma("unroll") for (int n = 0; n < 2; ++n) _Pragma("unroll") for (int k = 0; k < 2; ++k) dst[n][k] = *(const LAS bf16x8*)(lds + PG8_SB(b, h) + boff + n * 2048 + k * 1024); } while (0)
; #define PG8_MMA(ai, bj, At, Bt) do { __builtin_amdgcn_s_setprio(1); _Pragma("unroll") for (int m = 0; m < 4; ++m) _Pragma("unroll") for (int n = 0; n < 2; ++n) _Pragma("unroll") for (int k = 0; k < 2; ++k) \
;         acc[ai][bj][m][n] = __builtin_amdgcn_mfma_f32_16x16x32_bf16(Bt[n][k], At[m][k], acc[ai][bj][m][n], 0, 0, 0); __builtin_amdgcn_s_setprio(0); } while (0)
; #define PG8_WAIT_V(n) asm volatile("s_waitcnt vmcnt(" #n ")" ::: "memory")
; #define PG8_WAIT_L(n) asm volatile("s_waitcnt lgkmcnt(" #n ")" ::: "memory")
; #define PG8_BAR __builtin_amdgcn_s_barrier()
; #define PG8_SCHED __builtin_amdgcn_sched_barrier(0)
; template <class Epi>
; DEVI void gemm_phase(LAS unsigned char* lds, const Gemm g, const Epi& E) {
;     ...
;             PG8_WAIT_V(6); PG8_BAR; PG8_MMA(1, 1, At, B1); PG8_BAR;
;             PG8_LDB(B0, 1, 0); PG8_SCHED; PG8_LDA(At, 1, 0); PG8_STAGE(PG8_SA(0, 1), a2 + hstepA, voffA);
;             PG8_WAIT_L(8); PG8_BAR; PG8_WAIT_L(0); PG8_MMA(0, 0, At, B0); PG8_BAR; PG8_SCHED;
;             PG8_LDB(B1, 1, 1); PG8_STAGE(PG8_SB(1, 0), b3, voffB);
;             PG8_BAR; PG8_WAIT_L(0); PG8_MMA(0, 1, At, B1); PG8_BAR;
;             PG8_LDA(At, 1, 1); PG8_STAGE(PG8_SA(1, 0), a3, voffA);
;             PG8_BAR; PG8_WAIT_L(0); PG8_MMA(1, 0, At, B0); PG8_BAR; PG8_SCHED;
	s_add_u32 s26, s68, 0x40000
	s_addc_u32 s27, s69, 0
	s_add_i32 s19, s19, s80
	s_mov_b32 m0, s19
	v_lshl_add_u64 v[130:131], s[26:27], 0, v[8:9]
	global_load_lds_dwordx4 v[130:131], off
	s_add_i32 m0, s19, 0x2000
	v_lshl_add_u64 v[130:131], s[26:27], 0, v[180:181]
	global_load_lds_dwordx4 v[130:131], off
	s_waitcnt vmcnt(6)
	s_barrier
	v_mfma_f32_16x16x32_bf16 v[58:61], v[222:225], v[146:149], v[58:61]
	v_mfma_f32_16x16x32_bf16 v[50:53], v[230:233], v[146:149], v[50:53]
	v_mfma_f32_16x16x32_bf16 v[42:45], v[222:225], v[186:189], v[42:45]
	v_mfma_f32_16x16x32_bf16 v[34:37], v[230:233], v[186:189], v[34:37]
	v_mfma_f32_16x16x32_bf16 v[26:29], v[222:225], v[194:197], v[26:29]
	v_mfma_f32_16x16x32_bf16 v[18:21], v[230:233], v[194:197], v[18:21]
	v_mfma_f32_16x16x32_bf16 v[10:13], v[222:225], v[214:217], v[10:13]
	v_mfma_f32_16x16x32_bf16 v[0:3], v[230:233], v[214:217], v[0:3]
	v_mfma_f32_16x16x32_bf16 v[58:61], v[226:229], v[150:153], v[58:61]
	v_mfma_f32_16x16x32_bf16 v[50:53], v[234:237], v[150:153], v[50:53]
	v_mfma_f32_16x16x32_bf16 v[42:45], v[226:229], v[190:193], v[42:45]
	v_mfma_f32_16x16x32_bf16 v[34:37], v[234:237], v[190:193], v[34:37]
	v_mfma_f32_16x16x32_bf16 v[26:29], v[226:229], v[204:207], v[26:29]
	v_mfma_f32_16x16x32_bf16 v[18:21], v[234:237], v[204:207], v[18:21]
	v_mfma_f32_16x16x32_bf16 v[10:13], v[226:229], v[218:221], v[10:13]
	v_mfma_f32_16x16x32_bf16 v[0:3], v[234:237], v[218:221], v[0:3]
	s_add_i32 s19, 0, 0x18000
	v_add_u32_e32 v142, s19, v199
	s_barrier
	ds_read_b128 v[130:133], v142
	ds_read_b128 v[134:137], v142 offset:1024
	ds_read_b128 v[138:141], v142 offset:2048
	ds_read_b128 v[142:145], v142 offset:3072
	s_add_u32 s26, s78, 0x40000
	s_addc_u32 s27, s79, 0
	s_mov_b32 m0, s81
	v_lshl_add_u64 v[222:223], s[26:27], 0, v[176:177]
	ds_read_b128 v[146:149], v202 offset:32768
	ds_read_b128 v[150:153], v202 offset:33792
	ds_read_b128 v[186:189], v202 offset:34816
	ds_read_b128 v[190:193], v202 offset:35840
	ds_read_b128 v[194:197], v202 offset:36864
	ds_read_b128 v[204:207], v202 offset:37888
	ds_read_b128 v[214:217], v202 offset:38912
	ds_read_b128 v[218:221], v202 offset:39936
	global_load_lds_dwordx4 v[222:223], off
	s_mov_b32 m0, s82
	v_lshl_add_u64 v[222:223], s[26:27], 0, v[178:179]
	global_load_lds_dwordx4 v[222:223], off
	s_waitcnt lgkmcnt(0)
	s_barrier
	v_mfma_f32_16x16x32_bf16 v[126:129], v[130:133], v[146:149], v[126:129]
	v_mfma_f32_16x16x32_bf16 v[122:125], v[138:141], v[146:149], v[122:125]
	v_mfma_f32_16x16x32_bf16 v[110:113], v[130:133], v[186:189], v[110:113]
	v_mfma_f32_16x16x32_bf16 v[106:109], v[138:141], v[186:189], v[106:109]
	v_mfma_f32_16x16x32_bf16 v[94:97], v[130:133], v[194:197], v[94:97]
	v_mfma_f32_16x16x32_bf16 v[90:93], v[138:141], v[194:197], v[90:93]
	v_mfma_f32_16x16x32_bf16 v[78:81], v[130:133], v[214:217], v[78:81]
	v_mfma_f32_16x16x32_bf16 v[74:77], v[138:141], v[214:217], v[74:77]
	v_mfma_f32_16x16x32_bf16 v[126:129], v[134:137], v[150:153], v[126:129]
	v_mfma_f32_16x16x32_bf16 v[122:125], v[142:145], v[150:153], v[122:125]
	v_mfma_f32_16x16x32_bf16 v[110:113], v[134:137], v[190:193], v[110:113]
	v_mfma_f32_16x16x32_bf16 v[106:109], v[142:145], v[190:193], v[106:109]
	v_mfma_f32_16x16x32_bf16 v[94:97], v[134:137], v[204:207], v[94:97]
	v_mfma_f32_16x16x32_bf16 v[90:93], v[142:145], v[204:207], v[90:93]
	v_mfma_f32_16x16x32_bf16 v[78:81], v[134:137], v[218:221], v[78:81]
	v_mfma_f32_16x16x32_bf16 v[74:77], v[142:145], v[218:221], v[74:77]
	s_barrier
	s_add_i32 s38, 0, 0x1c000
	s_add_i32 s19, s19, s80
	v_add_u32_e32 v213, s38, v199
	v_lshl_add_u64 v[162:163], v[162:163], 0, s[70:71]
	s_mov_b32 m0, s19
	ds_read_b128 v[222:225], v213
	ds_read_b128 v[226:229], v213 offset:1024
	ds_read_b128 v[230:233], v213 offset:2048
	ds_read_b128 v[234:237], v213 offset:3072
	global_load_lds_dwordx4 v[162:163], off
	s_add_i32 m0, s19, 0x2000
	v_lshl_add_u64 v[162:163], v[164:165], 0, s[70:71]
	global_load_lds_dwordx4 v[162:163], off
	s_waitcnt lgkmcnt(0)
	s_barrier
	v_mfma_f32_16x16x32_bf16 v[118:121], v[222:225], v[146:149], v[118:121]
	v_mfma_f32_16x16x32_bf16 v[114:117], v[230:233], v[146:149], v[114:117]
	v_mfma_f32_16x16x32_bf16 v[102:105], v[222:225], v[186:189], v[102:105]
	v_mfma_f32_16x16x32_bf16 v[98:101], v[230:233], v[186:189], v[98:101]
	v_mfma_f32_16x16x32_bf16 v[86:89], v[222:225], v[194:197], v[86:89]
	v_mfma_f32_16x16x32_bf16 v[82:85], v[230:233], v[194:197], v[82:85]
	v_mfma_f32_16x16x32_bf16 v[70:73], v[222:225], v[214:217], v[70:73]
	v_mfma_f32_16x16x32_bf16 v[62:65], v[230:233], v[214:217], v[62:65]
	v_mfma_f32_16x16x32_bf16 v[118:121], v[226:229], v[150:153], v[118:121]
	v_mfma_f32_16x16x32_bf16 v[114:117], v[234:237], v[150:153], v[114:117]
	v_mfma_f32_16x16x32_bf16 v[102:105], v[226:229], v[190:193], v[102:105]
	v_mfma_f32_16x16x32_bf16 v[98:101], v[234:237], v[190:193], v[98:101]
	v_mfma_f32_16x16x32_bf16 v[86:89], v[226:229], v[204:207], v[86:89]
	v_mfma_f32_16x16x32_bf16 v[82:85], v[234:237], v[204:207], v[82:85]
	v_mfma_f32_16x16x32_bf16 v[70:73], v[226:229], v[218:221], v[70:73]
	v_mfma_f32_16x16x32_bf16 v[62:65], v[234:237], v[218:221], v[62:65]
	s_mov_b32 m0, s83
	v_lshl_add_u64 v[162:163], v[208:209], 0, s[70:71]
	s_barrier
	ds_read_b128 v[146:149], v202 offset:49152
	ds_read_b128 v[150:153], v202 offset:50176
	ds_read_b128 v[186:189], v202 offset:51200
	ds_read_b128 v[190:193], v202 offset:52224
	ds_read_b128 v[194:197], v202 offset:53248
	ds_read_b128 v[204:207], v202 offset:54272
	ds_read_b128 v[214:217], v202 offset:55296
	ds_read_b128 v[218:221], v202 offset:56320
	global_load_lds_dwordx4 v[162:163], off
	s_mov_b32 m0, s84
	v_lshl_add_u64 v[162:163], v[238:239], 0, s[70:71]
	global_load_lds_dwordx4 v[162:163], off
	s_waitcnt lgkmcnt(0)
	s_barrier
; #define PG8_STAGE(bufoff, gbase, voff) do { _Pragma("unroll") for (int _i = 0; _i < 2; ++_i) \
;         __builtin_amdgcn_global_load_lds((const unsigned*)((const char*)(gbase) + (voff)[_i]), (LAS unsigned*)(lds + (bufoff) + ldsw + _i * 8192), 16, 0, 0); } while (0)
; #define PG8_MMA(ai, bj, At, Bt) do { __builtin_amdgcn_s_setprio(1); _Pragma("unroll") for (int m = 0; m < 4; ++m) _Pragma("unroll") for (int n = 0; n < 2; ++n) _Pragma("unroll") for (int k = 0; k < 2; ++k) \
;         acc[ai][bj][m][n] = __builtin_amdgcn_mfma_f32_16x16x32_bf16(Bt[n][k], At[m][k], acc[ai][bj][m][n], 0, 0, 0); __builtin_amdgcn_s_setprio(0); } while (0)
; #define PG8_WAIT_V(n) asm volatile("s_waitcnt vmcnt(" #n ")" ::: "memory")
; #define PG8_WAIT_L(n) asm volatile("s_waitcnt lgkmcnt(" #n ")" ::: "memory")
; #define PG8_BAR __builtin_amdgcn_s_barrier()
; #define PG8_SCHED __builtin_amdgcn_sched_barrier(0)
; template <class Epi>
; DEVI void gemm_phase(LAS unsigned char* lds, const Gemm g, const Epi& E) {
;     ...
;             PG8_BAR; PG8_WAIT_L(0); PG8_MMA(1, 0, At, B0); PG8_BAR; PG8_SCHED;
;             PG8_STAGE(PG8_SB(1, 1), b3 + hstepB, voffB);
;             PG8_WAIT_V(6); PG8_BAR; PG8_MMA(1, 1, At, B1); PG8_BAR;
;         }
	v_mfma_f32_16x16x32_bf16 v[66:69], v[130:133], v[146:149], v[66:69]
	v_mfma_f32_16x16x32_bf16 v[54:57], v[138:141], v[146:149], v[54:57]
	v_mfma_f32_16x16x32_bf16 v[46:49], v[130:133], v[186:189], v[46:49]
	v_mfma_f32_16x16x32_bf16 v[38:41], v[138:141], v[186:189], v[38:41]
	v_mfma_f32_16x16x32_bf16 v[30:33], v[130:133], v[194:197], v[30:33]
	v_mfma_f32_16x16x32_bf16 v[22:25], v[138:141], v[194:197], v[22:25]
	v_mfma_f32_16x16x32_bf16 v[14:17], v[130:133], v[214:217], v[14:17]
	v_mfma_f32_16x16x32_bf16 v[4:7], v[138:141], v[214:217], v[4:7]
	v_mfma_f32_16x16x32_bf16 v[66:69], v[134:137], v[150:153], v[66:69]
	v_mfma_f32_16x16x32_bf16 v[54:57], v[142:145], v[150:153], v[54:57]
	v_mfma_f32_16x16x32_bf16 v[46:49], v[134:137], v[190:193], v[46:49]
	v_mfma_f32_16x16x32_bf16 v[38:41], v[142:145], v[190:193], v[38:41]
	v_mfma_f32_16x16x32_bf16 v[30:33], v[134:137], v[204:207], v[30:33]
	v_mfma_f32_16x16x32_bf16 v[22:25], v[142:145], v[204:207], v[22:25]
	v_mfma_f32_16x16x32_bf16 v[14:17], v[134:137], v[218:221], v[14:17]
	v_mfma_f32_16x16x32_bf16 v[4:7], v[142:145], v[218:221], v[4:7]
	s_barrier
	s_add_u32 s26, s68, 0x40080
	s_addc_u32 s27, s69, 0
	s_add_i32 s19, s38, s80
	s_mov_b32 m0, s19
	v_lshl_add_u64 v[130:131], s[26:27], 0, v[8:9]
	global_load_lds_dwordx4 v[130:131], off
	s_add_i32 m0, s19, 0x2000
	v_lshl_add_u64 v[130:131], s[26:27], 0, v[180:181]
	global_load_lds_dwordx4 v[130:131], off
	s_waitcnt vmcnt(6)
	s_barrier
	v_mfma_f32_16x16x32_bf16 v[58:61], v[222:225], v[146:149], v[58:61]
	v_mfma_f32_16x16x32_bf16 v[50:53], v[230:233], v[146:149], v[50:53]
	v_mfma_f32_16x16x32_bf16 v[42:45], v[222:225], v[186:189], v[42:45]
	v_mfma_f32_16x16x32_bf16 v[34:37], v[230:233], v[186:189], v[34:37]
	v_mfma_f32_16x16x32_bf16 v[26:29], v[222:225], v[194:197], v[26:29]
	v_mfma_f32_16x16x32_bf16 v[18:21], v[230:233], v[194:197], v[18:21]
	v_mfma_f32_16x16x32_bf16 v[10:13], v[222:225], v[214:217], v[10:13]
	v_mfma_f32_16x16x32_bf16 v[0:3], v[230:233], v[214:217], v[0:3]
	v_mfma_f32_16x16x32_bf16 v[58:61], v[226:229], v[150:153], v[58:61]
	v_mfma_f32_16x16x32_bf16 v[50:53], v[234:237], v[150:153], v[50:53]
	v_mfma_f32_16x16x32_bf16 v[42:45], v[226:229], v[190:193], v[42:45]
	v_mfma_f32_16x16x32_bf16 v[34:37], v[234:237], v[190:193], v[34:37]
	v_mfma_f32_16x16x32_bf16 v[26:29], v[226:229], v[204:207], v[26:29]
	v_mfma_f32_16x16x32_bf16 v[18:21], v[234:237], v[204:207], v[18:21]
	v_mfma_f32_16x16x32_bf16 v[10:13], v[226:229], v[218:221], v[10:13]
	v_mfma_f32_16x16x32_bf16 v[0:3], v[234:237], v[218:221], v[0:3]
	s_add_i32 s18, s18, 2
	s_add_u32 s6, s6, 0x100
	s_addc_u32 s7, s7, 0
	s_add_u32 s11, s11, 0x100
	s_addc_u32 s13, s13, 0
	s_cmp_gt_u32 s18, 13
	s_barrier
	s_cbranch_scc0 .LBB0_1507
; #define LAS __attribute__((address_space(3)))
; template <class Epi>
; DEVI void gemm_phase(LAS unsigned char* lds, const Gemm g, const Epi& E) {
;     ...
;             if constexpr (Epi::RS) { f32x4 q4[8];
; #pragma unroll
;                 for (int i = 0; i < 8; ++i) q4[i] = *(const f32x4*)(E.ssq_in + (size_t)(row0 + (i >> 2) * HALF + (i & 3) * 16) * 4);
; #pragma unroll
;                 for (int i = 0; i < 8; ++i) rsv[i] = rsqrtf((((q4[i][0] + q4[i][1]) + q4[i][2]) + q4[i][3]) * (1.f / DM) + 1e-6f); }
;             if constexpr (Epi::SOFTMAX) {
;                 LAS float* red = (LAS float*)(lds + 131072);
; #pragma unroll
;                 for (int ai = 0; ai < 2; ++ai)
; #pragma unroll
;                     for (int m = 0; m < 4; ++m) { const float sc = rsv[ai * 4 + m] * 0.0625f; float part = 0.f;
; #pragma unroll
;                         for (int bj = 0; bj < 2; ++bj)
; #pragma unroll
;                             for (int n = 0; n < 2; ++n)
; #pragma unroll
;                                 for (int j = 0; j < 4; ++j) { const float e = __expf(fmaxf(fminf(acc[ai][bj][m][n][j] * sc, 80.f), -80.f)); acc[ai][bj][m][n][j] = e; part += e; }
;                         part += __shfl_xor(part, 16); part += __shfl_xor(part, 32);
;                         if (fq == 0) red[(wr * 4 + wc) * 128 + ai * 64 + m * 16 + fr] = part; }
	s_setprio 0
	v_lshl_add_u32 v194, s46, 8, v198
	v_or_b32_e32 v192, 16, v194
	v_ashrrev_i32_e32 v195, 31, v194
	v_ashrrev_i32_e32 v193, 31, v192
	v_lshl_add_u64 v[130:131], v[194:195], 4, s[8:9]
	v_lshl_add_u64 v[134:135], v[192:193], 4, s[8:9]
	global_load_dwordx4 v[130:133], v[130:131], off
	v_and_b32_e32 v139, 64, v155
	global_load_dwordx4 v[134:137], v[134:135], off
	v_add_u32_e32 v138, 0x90, v194
	v_add_u32_e32 v140, 0xa0, v194
	v_add_u32_e32 v205, 64, v139
	v_ashrrev_i32_e32 v139, 31, v138
	v_ashrrev_i32_e32 v141, 31, v140
	v_lshl_add_u64 v[164:165], v[138:139], 4, s[8:9]
	v_lshl_add_u64 v[206:207], v[140:141], 4, s[8:9]
	v_xor_b32_e32 v144, 16, v155
	v_or_b32_e32 v190, 32, v194
	v_or_b32_e32 v188, 48, v194
	v_add_u32_e32 v186, 0x80, v194
	v_cmp_lt_i32_e32 vcc, v144, v205
	v_add_u32_e32 v142, 0xb0, v194
	v_ashrrev_i32_e32 v191, 31, v190
	v_ashrrev_i32_e32 v189, 31, v188
	v_ashrrev_i32_e32 v187, 31, v186
	v_cndmask_b32_e32 v146, v155, v144, vcc
	v_ashrrev_i32_e32 v143, 31, v142
	v_lshl_add_u64 v[144:145], v[190:191], 4, s[8:9]
	v_lshl_add_u64 v[150:151], v[188:189], 4, s[8:9]
	v_lshl_add_u64 v[162:163], v[186:187], 4, s[8:9]
	v_lshl_add_u64 v[208:209], v[142:143], 4, s[8:9]
	v_lshlrev_b32_e32 v204, 2, v146
	global_load_dwordx4 v[146:149], v[144:145], off
	s_nop 0
	global_load_dwordx4 v[150:153], v[150:151], off
	s_waitcnt vmcnt(0)
	v_mov_b32_e32 v139, v130
	v_mov_b32_e32 v141, v132
	v_mov_b32_e32 v138, v134
	v_mov_b32_e32 v130, v135
	v_mov_b32_e32 v140, v136
	v_pk_add_f32 v[130:131], v[138:139], v[130:131]
	v_mov_b32_e32 v132, v137
	v_pk_add_f32 v[130:131], v[140:141], v[130:131]
	s_nop 0
	v_pk_add_f32 v[130:131], v[132:133], v[130:131]
	s_nop 0
	v_pk_fma_f32 v[196:197], v[130:131], s[72:73], v[160:161] op_sel_hi:[1,0,0]
	s_nop 0
	v_mul_f32_e32 v130, 0x4b800000, v197
	v_cmp_gt_f32_e32 vcc, s94, v197
	s_nop 1
	v_cndmask_b32_e32 v130, v197, v130, vcc
	v_rsq_f32_e32 v197, v130
	global_load_dwordx4 v[138:141], v[162:163], off
	global_load_dwordx4 v[142:145], v[164:165], off
	global_load_dwordx4 v[130:133], v[206:207], off
	global_load_dwordx4 v[134:137], v[208:209], off
	v_mul_f32_e32 v162, 0x45800000, v197
	v_cndmask_b32_e32 v162, v197, v162, vcc
	v_mul_f32_e32 v162, 0x3d800000, v162
	v_mul_f32_e32 v126, v126, v162
	v_mul_f32_e32 v127, v127, v162
	v_mul_f32_e32 v124, v124, v162
	v_min_f32_e32 v126, 0x42a00000, v126
	v_mul_f32_e32 v128, v128, v162
	v_mul_f32_e32 v125, v125, v162
	v_min_f32_e32 v127, 0x42a00000, v127
	v_min_f32_e32 v124, 0x42a00000, v124
	v_max_f32_e32 v126, 0xc2a00000, v126
	v_mul_f32_e32 v129, v129, v162
	v_min_f32_e32 v128, 0x42a00000, v128
	v_min_f32_e32 v125, 0x42a00000, v125
	v_max_f32_e32 v127, 0xc2a00000, v127
	v_max_f32_e32 v124, 0xc2a00000, v124
	v_mul_f32_e32 v126, 0x3fb8aa3b, v126
	v_mul_f32_e32 v122, v122, v162
	v_min_f32_e32 v129, 0x42a00000, v129
	v_max_f32_e32 v128, 0xc2a00000, v128
	v_max_f32_e32 v125, 0xc2a00000, v125
	v_mul_f32_e32 v127, 0x3fb8aa3b, v127
	v_mul_f32_e32 v163, 0x3fb8aa3b, v124
	v_exp_f32_e32 v124, v126
	v_mul_f32_e32 v123, v123, v162
	v_min_f32_e32 v122, 0x42a00000, v122
	v_max_f32_e32 v129, 0xc2a00000, v129
	v_mul_f32_e32 v128, 0x3fb8aa3b, v128
	v_mul_f32_e32 v164, 0x3fb8aa3b, v125
	v_exp_f32_e32 v125, v127
	v_min_f32_e32 v123, 0x42a00000, v123
	v_max_f32_e32 v122, 0xc2a00000, v122
	v_mul_f32_e32 v129, 0x3fb8aa3b, v129
	v_exp_f32_e32 v128, v128
	v_max_f32_e32 v123, 0xc2a00000, v123
	v_mul_f32_e32 v122, 0x3fb8aa3b, v122
	v_exp_f32_e32 v129, v129
	v_mul_f32_e32 v118, v118, v162
	v_mul_f32_e32 v123, 0x3fb8aa3b, v123
	v_exp_f32_e32 v122, v122
	v_exp_f32_e32 v126, v163
	v_add_f32_e32 v163, 0, v124
	v_mul_f32_e32 v119, v119, v162
	v_min_f32_e32 v118, 0x42a00000, v118
	v_exp_f32_e32 v123, v123
	v_add_f32_e32 v163, v125, v163
	v_mul_f32_e32 v120, v120, v162
	v_min_f32_e32 v119, 0x42a00000, v119
	v_max_f32_e32 v118, 0xc2a00000, v118
	v_add_f32_e32 v163, v128, v163
	v_max_f32_e32 v119, 0xc2a00000, v119
	v_mul_f32_e32 v118, 0x3fb8aa3b, v118
	v_exp_f32_e32 v127, v164
	v_add_f32_e32 v163, v129, v163
	v_min_f32_e32 v120, 0x42a00000, v120
	v_mul_f32_e32 v121, v121, v162
	v_mul_f32_e32 v119, 0x3fb8aa3b, v119
	v_exp_f32_e32 v118, v118
	v_add_f32_e32 v163, v122, v163
	v_max_f32_e32 v120, 0xc2a00000, v120
	v_min_f32_e32 v121, 0x42a00000, v121
	v_mul_f32_e32 v114, v114, v162
	v_exp_f32_e32 v119, v119
	v_add_f32_e32 v163, v123, v163
	v_mul_f32_e32 v120, 0x3fb8aa3b, v120
	v_max_f32_e32 v121, 0xc2a00000, v121
	v_min_f32_e32 v114, 0x42a00000, v114
	v_mul_f32_e32 v115, v115, v162
	v_add_f32_e32 v163, v126, v163
	v_exp_f32_e32 v120, v120
	v_mul_f32_e32 v121, 0x3fb8aa3b, v121
	v_max_f32_e32 v114, 0xc2a00000, v114
	v_min_f32_e32 v115, 0x42a00000, v115
	v_mul_f32_e32 v116, v116, v162
	v_add_f32_e32 v163, v127, v163
	v_exp_f32_e32 v121, v121
	v_mul_f32_e32 v114, 0x3fb8aa3b, v114
	v_max_f32_e32 v115, 0xc2a00000, v115
	v_min_f32_e32 v116, 0x42a00000, v116
	v_mul_f32_e32 v117, v117, v162
	v_add_f32_e32 v163, v118, v163
	v_exp_f32_e32 v114, v114
	v_mul_f32_e32 v115, 0x3fb8aa3b, v115
	v_max_f32_e32 v116, 0xc2a00000, v116
	v_min_f32_e32 v117, 0x42a00000, v117
	v_add_f32_e32 v163, v119, v163
	v_exp_f32_e32 v115, v115
	v_mul_f32_e32 v116, 0x3fb8aa3b, v116
	v_max_f32_e32 v117, 0xc2a00000, v117
	v_add_f32_e32 v163, v120, v163
	v_exp_f32_e32 v116, v116
	v_mul_f32_e32 v117, 0x3fb8aa3b, v117
	v_add_f32_e32 v163, v121, v163
	v_exp_f32_e32 v117, v117
	v_add_f32_e32 v162, v114, v163
	v_add_f32_e32 v162, v115, v162
	v_add_f32_e32 v162, v116, v162
	v_add_f32_e32 v162, v117, v162
	ds_bpermute_b32 v163, v204, v162
	v_xor_b32_e32 v164, 32, v155
	v_cmp_lt_i32_e32 vcc, v164, v205
	s_waitcnt lgkmcnt(0)
	v_add_f32_e32 v205, v162, v163
	v_cndmask_b32_e32 v164, v155, v164, vcc
	v_lshlrev_b32_e32 v197, 2, v164
	ds_bpermute_b32 v206, v197, v205
	v_cmp_gt_f32_e32 vcc, s94, v196
	s_and_saveexec_b64 s[6:7], s[2:3]
	s_cbranch_execz .LBB0_1510
	s_waitcnt lgkmcnt(0)
	v_add_f32_e32 v162, v205, v206
	ds_write_b32 v201, v162

; #define PG8_STAGE(bufoff, gbase, voff) do { _Pragma("unroll") for (int _i = 0; _i < 2; ++_i) \
;         __builtin_amdgcn_global_load_lds((const unsigned*)((const char*)(gbase) + (voff)[_i]), (LAS unsigned*)(lds + (bufoff) + ldsw + _i * 8192), 16, 0, 0); } while (0)
; #define PG8_LDA(dst, b, h) do { _Pragma("unroll") for (int m = 0; m < 4; ++m) _Pragma("unroll") for (int k = 0; k < 2; ++k) dst[m][k] = *(const LAS bf16x8*)(lds + PG8_SA(b, h) + aoff + m * 2048 + k * 1024); } while (0)
; #define PG8_LDB(dst, b, h) do { _Pragma("unroll") for (int n = 0; n < 2; ++n) _Pragma("unroll") for (int k = 0; k < 2; ++k) dst[n][k] = *(const LAS bf16x8*)(lds + PG8_SB(b, h) + boff + n * 2048 + k * 1024); } while (0)
; #define PG8_MMA(ai, bj, At, Bt) do { __builtin_amdgcn_s_setprio(1); _Pragma("unroll") for (int m = 0; m < 4; ++m) _Pragma("unroll") for (int n = 0; n < 2; ++n) _Pragma("unroll") for (int k = 0; k < 2; ++k) \
;         acc[ai][bj][m][n] = __builtin_amdgcn_mfma_f32_16x16x32_bf16(Bt[n][k], At[m][k], acc[ai][bj][m][n], 0, 0, 0); __builtin_amdgcn_s_setprio(0); } while (0)
; #define PG8_WAIT_V(n) asm volatile("s_waitcnt vmcnt(" #n ")" ::: "memory")
; #define PG8_WAIT_L(n) asm volatile("s_waitcnt lgkmcnt(" #n ")" ::: "memory")
; #define PG8_BAR __builtin_amdgcn_s_barrier()
; #define PG8_SCHED __builtin_amdgcn_sched_barrier(0)
; template <class Epi>
; DEVI void gemm_phase(LAS unsigned char* lds, const Gemm g, const Epi& E) {
;     ...
;             const bool last = (t == nt - 2);
;             const char* a1 = cA + (size_t)(t + 1) * kstep;
;             const char* a2 = last ? nA : cA + (size_t)(t + 2) * kstep; const char* b2 = last ? nB : cB + (size_t)(t + 2) * kstep;
;             const char* a3 = a2 + kstep; const char* b3 = b2 + kstep;
;             PG8_LDB(B0, 0, 0); PG8_SCHED; PG8_LDA(At, 0, 0); PG8_STAGE(PG8_SA(1, 1), a1 + hstepA, voffA);
;             PG8_WAIT_L(8); PG8_BAR; PG8_WAIT_L(0); PG8_MMA(0, 0, At, B0); PG8_BAR; PG8_SCHED;
;             PG8_LDB(B1, 0, 1); PG8_STAGE(PG8_SB(0, 0), b2, voffB);
;             PG8_BAR; PG8_WAIT_L(0); PG8_MMA(0, 1, At, B1); PG8_BAR;
;             PG8_LDA(At, 0, 1); PG8_STAGE(PG8_SA(0, 0), a2, voffA);
;             PG8_BAR; PG8_WAIT_L(0); PG8_MMA(1, 0, At, B0); PG8_BAR; PG8_SCHED;
;             PG8_STAGE(PG8_SB(0, 1), b2 + hstepB, voffB);
;             PG8_WAIT_V(6); PG8_BAR; PG8_MMA(1, 1, At, B1); PG8_BAR;
.LBB0_1595:
	s_add_u32 s18, s8, 0xfffc0080
	s_addc_u32 s19, s9, -1
	s_add_i32 s26, 0, 0x10000
	v_add_u32_e32 v142, s26, v191
	ds_read_b128 v[130:133], v142
	ds_read_b128 v[134:137], v142 offset:1024
	ds_read_b128 v[138:141], v142 offset:2048
	ds_read_b128 v[142:145], v142 offset:3072
	s_cmp_eq_u32 s17, 12
	s_cselect_b32 s81, s0, s19
	s_cselect_b32 s80, s1, s18
	s_cselect_b32 s79, s37, s15
	s_cselect_b32 s78, s36, s13
	v_lshl_add_u64 v[162:163], s[8:9], 0, v[152:153]
	s_add_i32 m0, s69, 0xc000
	ds_read_b128 v[178:181], v196
	ds_read_b128 v[182:185], v196 offset:1024
	ds_read_b128 v[186:189], v196 offset:2048
	ds_read_b128 v[198:201], v196 offset:3072
	ds_read_b128 v[202:205], v196 offset:4096
	ds_read_b128 v[206:209], v196 offset:5120
	ds_read_b128 v[214:217], v196 offset:6144
	ds_read_b128 v[218:221], v196 offset:7168
	global_load_lds_dwordx4 v[162:163], off
	s_add_i32 m0, s69, 0xe000
	v_lshl_add_u64 v[162:163], s[8:9], 0, v[176:177]
	global_load_lds_dwordx4 v[162:163], off
	s_waitcnt lgkmcnt(0)
	s_barrier
	v_mfma_f32_16x16x32_bf16 v[126:129], v[130:133], v[178:181], v[126:129]
	v_mfma_f32_16x16x32_bf16 v[122:125], v[138:141], v[178:181], v[122:125]
	v_mfma_f32_16x16x32_bf16 v[110:113], v[130:133], v[186:189], v[110:113]
	v_mfma_f32_16x16x32_bf16 v[106:109], v[138:141], v[186:189], v[106:109]
	v_mfma_f32_16x16x32_bf16 v[94:97], v[130:133], v[202:205], v[94:97]
	v_mfma_f32_16x16x32_bf16 v[90:93], v[138:141], v[202:205], v[90:93]
	v_mfma_f32_16x16x32_bf16 v[78:81], v[130:133], v[214:217], v[78:81]
	v_mfma_f32_16x16x32_bf16 v[74:77], v[138:141], v[214:217], v[74:77]
	v_mfma_f32_16x16x32_bf16 v[126:129], v[134:137], v[182:185], v[126:129]
	v_mfma_f32_16x16x32_bf16 v[122:125], v[142:145], v[182:185], v[122:125]
	v_mfma_f32_16x16x32_bf16 v[110:113], v[134:137], v[198:201], v[110:113]
	v_mfma_f32_16x16x32_bf16 v[106:109], v[142:145], v[198:201], v[106:109]
	v_mfma_f32_16x16x32_bf16 v[94:97], v[134:137], v[206:209], v[94:97]
	v_mfma_f32_16x16x32_bf16 v[90:93], v[142:145], v[206:209], v[90:93]
	v_mfma_f32_16x16x32_bf16 v[78:81], v[134:137], v[218:221], v[78:81]
	v_mfma_f32_16x16x32_bf16 v[74:77], v[142:145], v[218:221], v[74:77]
	s_barrier
	s_add_i32 s27, 0, 0x14000
	v_add_u32_e32 v162, s27, v191
	s_add_i32 s18, s26, s82
	ds_read_b128 v[222:225], v162
	ds_read_b128 v[226:229], v162 offset:1024
	ds_read_b128 v[230:233], v162 offset:2048
	ds_read_b128 v[234:237], v162 offset:3072
	v_lshl_add_u64 v[162:163], s[78:79], 0, v[8:9]
	s_mov_b32 m0, s18
	v_lshl_add_u64 v[164:165], s[78:79], 0, v[150:151]
	global_load_lds_dwordx4 v[162:163], off
	s_add_i32 m0, s18, 0x2000
	s_nop 0
	global_load_lds_dwordx4 v[164:165], off
	s_waitcnt lgkmcnt(0)
	s_barrier
	v_mfma_f32_16x16x32_bf16 v[118:121], v[222:225], v[178:181], v[118:121]
	v_mfma_f32_16x16x32_bf16 v[114:117], v[230:233], v[178:181], v[114:117]
	v_mfma_f32_16x16x32_bf16 v[102:105], v[222:225], v[186:189], v[102:105]
	v_mfma_f32_16x16x32_bf16 v[98:101], v[230:233], v[186:189], v[98:101]
	v_mfma_f32_16x16x32_bf16 v[86:89], v[222:225], v[202:205], v[86:89]
	v_mfma_f32_16x16x32_bf16 v[82:85], v[230:233], v[202:205], v[82:85]
	v_mfma_f32_16x16x32_bf16 v[70:73], v[222:225], v[214:217], v[70:73]
	v_mfma_f32_16x16x32_bf16 v[66:69], v[230:233], v[214:217], v[66:69]
	v_mfma_f32_16x16x32_bf16 v[118:121], v[226:229], v[182:185], v[118:121]
	v_mfma_f32_16x16x32_bf16 v[114:117], v[234:237], v[182:185], v[114:117]
	v_mfma_f32_16x16x32_bf16 v[102:105], v[226:229], v[198:201], v[102:105]
	v_mfma_f32_16x16x32_bf16 v[98:101], v[234:237], v[198:201], v[98:101]
	v_mfma_f32_16x16x32_bf16 v[86:89], v[226:229], v[206:209], v[86:89]
	v_mfma_f32_16x16x32_bf16 v[82:85], v[234:237], v[206:209], v[82:85]
	v_mfma_f32_16x16x32_bf16 v[70:73], v[226:229], v[218:221], v[70:73]
	v_mfma_f32_16x16x32_bf16 v[66:69], v[234:237], v[218:221], v[66:69]
	s_mov_b32 m0, s69
	v_lshl_add_u64 v[238:239], s[80:81], 0, v[146:147]
	s_barrier
	ds_read_b128 v[178:181], v196 offset:16384
	ds_read_b128 v[182:185], v196 offset:17408
	ds_read_b128 v[186:189], v196 offset:18432
	ds_read_b128 v[198:201], v196 offset:19456
	ds_read_b128 v[202:205], v196 offset:20480
	ds_read_b128 v[206:209], v196 offset:21504
	ds_read_b128 v[214:217], v196 offset:22528
	ds_read_b128 v[218:221], v196 offset:23552
	global_load_lds_dwordx4 v[238:239], off
	s_mov_b32 m0, s83
	v_lshl_add_u64 v[240:241], s[80:81], 0, v[148:149]
	global_load_lds_dwordx4 v[240:241], off
	s_waitcnt lgkmcnt(0)
	s_barrier
	v_mfma_f32_16x16x32_bf16 v[62:65], v[130:133], v[178:181], v[62:65]
	v_mfma_f32_16x16x32_bf16 v[58:61], v[138:141], v[178:181], v[58:61]
	v_mfma_f32_16x16x32_bf16 v[46:49], v[130:133], v[186:189], v[46:49]
	v_mfma_f32_16x16x32_bf16 v[42:45], v[138:141], v[186:189], v[42:45]
	v_mfma_f32_16x16x32_bf16 v[30:33], v[130:133], v[202:205], v[30:33]
	v_mfma_f32_16x16x32_bf16 v[26:29], v[138:141], v[202:205], v[26:29]
	v_mfma_f32_16x16x32_bf16 v[14:17], v[130:133], v[214:217], v[14:17]
	v_mfma_f32_16x16x32_bf16 v[10:13], v[138:141], v[214:217], v[10:13]
	v_mfma_f32_16x16x32_bf16 v[62:65], v[134:137], v[182:185], v[62:65]
	v_mfma_f32_16x16x32_bf16 v[58:61], v[142:145], v[182:185], v[58:61]
	v_mfma_f32_16x16x32_bf16 v[46:49], v[134:137], v[198:201], v[46:49]
	v_mfma_f32_16x16x32_bf16 v[42:45], v[142:145], v[198:201], v[42:45]
	v_mfma_f32_16x16x32_bf16 v[30:33], v[134:137], v[206:209], v[30:33]
	v_mfma_f32_16x16x32_bf16 v[26:29], v[142:145], v[206:209], v[26:29]
	v_mfma_f32_16x16x32_bf16 v[14:17], v[134:137], v[218:221], v[14:17]
	v_mfma_f32_16x16x32_bf16 v[10:13], v[142:145], v[218:221], v[10:13]
	s_barrier
; #define PG8_STAGE(bufoff, gbase, voff) do { _Pragma("unroll") for (int _i = 0; _i < 2; ++_i) \
;         __builtin_amdgcn_global_load_lds((const unsigned*)((const char*)(gbase) + (voff)[_i]), (LAS unsigned*)(lds + (bufoff) + ldsw + _i * 8192), 16, 0, 0); } while (0)
; #define PG8_LDA(dst, b, h) do { _Pragma("unroll") for (int m = 0; m < 4; ++m) _Pragma("unroll") for (int k = 0; k < 2; ++k) dst[m][k] = *(const LAS bf16x8*)(lds + PG8_SA(b, h) + aoff + m * 2048 + k * 1024); } while (0)
; #define PG8_LDB(dst, b, h) do { _Pragma("unroll") for (int n = 0; n < 2; ++n) _Pragma("unroll") for (int k = 0; k < 2; ++k) dst[n][k] = *(const LAS bf16x8*)(lds + PG8_SB(b, h) + boff + n * 2048 + k * 1024); } while (0)
; #define PG8_MMA(ai, bj, At, Bt) do { __builtin_amdgcn_s_setprio(1); _Pragma("unroll") for (int m = 0; m < 4; ++m) _Pragma("unroll") for (int n = 0; n < 2; ++n) _Pragma("unroll") for (int k = 0; k < 2; ++k) \
;         acc[ai][bj][m][n] = __builtin_amdgcn_mfma_f32_16x16x32_bf16(Bt[n][k], At[m][k], acc[ai][bj][m][n], 0, 0, 0); __builtin_amdgcn_s_setprio(0); } while (0)
; #define PG8_WAIT_V(n) asm volatile("s_waitcnt vmcnt(" #n ")" ::: "memory")
; #define PG8_WAIT_L(n) asm volatile("s_waitcnt lgkmcnt(" #n ")" ::: "memory")
; #define PG8_BAR __builtin_amdgcn_s_barrier()
; #define PG8_SCHED __builtin_amdgcn_sched_barrier(0)
; template <class Epi>
; DEVI void gemm_phase(LAS unsigned char* lds, const Gemm g, const Epi& E) {
;     ...
;             PG8_WAIT_V(6); PG8_BAR; PG8_MMA(1, 1, At, B1); PG8_BAR;
;             PG8_LDB(B0, 1, 0); PG8_SCHED; PG8_LDA(At, 1, 0); PG8_STAGE(PG8_SA(0, 1), a2 + hstepA, voffA);
;             PG8_WAIT_L(8); PG8_BAR; PG8_WAIT_L(0); PG8_MMA(0, 0, At, B0); PG8_BAR; PG8_SCHED;
;             PG8_LDB(B1, 1, 1); PG8_STAGE(PG8_SB(1, 0), b3, voffB);
;             PG8_BAR; PG8_WAIT_L(0); PG8_MMA(0, 1, At, B1); PG8_BAR;
;             PG8_LDA(At, 1, 1); PG8_STAGE(PG8_SA(1, 0), a3, voffA);
;             PG8_BAR; PG8_WAIT_L(0); PG8_MMA(1, 0, At, B0); PG8_BAR; PG8_SCHED;
	s_add_u32 s18, s78, 0x40000
	s_addc_u32 s19, s79, 0
	s_add_i32 s26, s27, s82
	s_mov_b32 m0, s26
	v_lshl_add_u64 v[130:131], s[18:19], 0, v[8:9]
	global_load_lds_dwordx4 v[130:131], off
	s_add_i32 m0, s26, 0x2000
	v_lshl_add_u64 v[130:131], s[18:19], 0, v[150:151]
	global_load_lds_dwordx4 v[130:131], off
	s_waitcnt vmcnt(6)
	s_barrier
	v_mfma_f32_16x16x32_bf16 v[54:57], v[222:225], v[178:181], v[54:57]
	v_mfma_f32_16x16x32_bf16 v[50:53], v[230:233], v[178:181], v[50:53]
	v_mfma_f32_16x16x32_bf16 v[38:41], v[222:225], v[186:189], v[38:41]
	v_mfma_f32_16x16x32_bf16 v[34:37], v[230:233], v[186:189], v[34:37]
	v_mfma_f32_16x16x32_bf16 v[22:25], v[222:225], v[202:205], v[22:25]
	v_mfma_f32_16x16x32_bf16 v[18:21], v[230:233], v[202:205], v[18:21]
	v_mfma_f32_16x16x32_bf16 v[4:7], v[222:225], v[214:217], v[4:7]
	v_mfma_f32_16x16x32_bf16 v[0:3], v[230:233], v[214:217], v[0:3]
	v_mfma_f32_16x16x32_bf16 v[54:57], v[226:229], v[182:185], v[54:57]
	v_mfma_f32_16x16x32_bf16 v[50:53], v[234:237], v[182:185], v[50:53]
	v_mfma_f32_16x16x32_bf16 v[38:41], v[226:229], v[198:201], v[38:41]
	v_mfma_f32_16x16x32_bf16 v[34:37], v[234:237], v[198:201], v[34:37]
	v_mfma_f32_16x16x32_bf16 v[22:25], v[226:229], v[206:209], v[22:25]
	v_mfma_f32_16x16x32_bf16 v[18:21], v[234:237], v[206:209], v[18:21]
	v_mfma_f32_16x16x32_bf16 v[4:7], v[226:229], v[218:221], v[4:7]
	v_mfma_f32_16x16x32_bf16 v[0:3], v[234:237], v[218:221], v[0:3]
	s_add_i32 s26, 0, 0x18000
	v_add_u32_e32 v142, s26, v191
	s_barrier
	ds_read_b128 v[130:133], v142
	ds_read_b128 v[134:137], v142 offset:1024
	ds_read_b128 v[138:141], v142 offset:2048
	ds_read_b128 v[142:145], v142 offset:3072
	s_add_u32 s18, s80, 0x40000
	s_addc_u32 s19, s81, 0
	s_mov_b32 m0, s84
	v_lshl_add_u64 v[222:223], s[18:19], 0, v[146:147]
	ds_read_b128 v[178:181], v196 offset:32768
	ds_read_b128 v[182:185], v196 offset:33792
	ds_read_b128 v[186:189], v196 offset:34816
	ds_read_b128 v[198:201], v196 offset:35840
	ds_read_b128 v[202:205], v196 offset:36864
	ds_read_b128 v[206:209], v196 offset:37888
	ds_read_b128 v[214:217], v196 offset:38912
	ds_read_b128 v[218:221], v196 offset:39936
	global_load_lds_dwordx4 v[222:223], off
	s_mov_b32 m0, s85
	v_lshl_add_u64 v[222:223], s[18:19], 0, v[148:149]
	global_load_lds_dwordx4 v[222:223], off
	s_waitcnt lgkmcnt(0)
	s_barrier
	v_mfma_f32_16x16x32_bf16 v[126:129], v[130:133], v[178:181], v[126:129]
	v_mfma_f32_16x16x32_bf16 v[122:125], v[138:141], v[178:181], v[122:125]
	v_mfma_f32_16x16x32_bf16 v[110:113], v[130:133], v[186:189], v[110:113]
	v_mfma_f32_16x16x32_bf16 v[106:109], v[138:141], v[186:189], v[106:109]
	v_mfma_f32_16x16x32_bf16 v[94:97], v[130:133], v[202:205], v[94:97]
	v_mfma_f32_16x16x32_bf16 v[90:93], v[138:141], v[202:205], v[90:93]
	v_mfma_f32_16x16x32_bf16 v[78:81], v[130:133], v[214:217], v[78:81]
	v_mfma_f32_16x16x32_bf16 v[74:77], v[138:141], v[214:217], v[74:77]
	v_mfma_f32_16x16x32_bf16 v[126:129], v[134:137], v[182:185], v[126:129]
	v_mfma_f32_16x16x32_bf16 v[122:125], v[142:145], v[182:185], v[122:125]
	v_mfma_f32_16x16x32_bf16 v[110:113], v[134:137], v[198:201], v[110:113]
	v_mfma_f32_16x16x32_bf16 v[106:109], v[142:145], v[198:201], v[106:109]
	v_mfma_f32_16x16x32_bf16 v[94:97], v[134:137], v[206:209], v[94:97]
	v_mfma_f32_16x16x32_bf16 v[90:93], v[142:145], v[206:209], v[90:93]
	v_mfma_f32_16x16x32_bf16 v[78:81], v[134:137], v[218:221], v[78:81]
	v_mfma_f32_16x16x32_bf16 v[74:77], v[142:145], v[218:221], v[74:77]
	s_barrier
	s_add_i32 s27, 0, 0x1c000
	s_add_i32 s18, s26, s82
	v_add_u32_e32 v197, s27, v191
	v_lshl_add_u64 v[162:163], v[162:163], 0, s[70:71]
	s_mov_b32 m0, s18
	ds_read_b128 v[222:225], v197
	ds_read_b128 v[226:229], v197 offset:1024
	ds_read_b128 v[230:233], v197 offset:2048
	ds_read_b128 v[234:237], v197 offset:3072
	global_load_lds_dwordx4 v[162:163], off
	s_add_i32 m0, s18, 0x2000
	v_lshl_add_u64 v[162:163], v[164:165], 0, s[70:71]
	global_load_lds_dwordx4 v[162:163], off
	s_waitcnt lgkmcnt(0)
	s_barrier
	v_mfma_f32_16x16x32_bf16 v[118:121], v[222:225], v[178:181], v[118:121]
	v_mfma_f32_16x16x32_bf16 v[114:117], v[230:233], v[178:181], v[114:117]
	v_mfma_f32_16x16x32_bf16 v[102:105], v[222:225], v[186:189], v[102:105]
	v_mfma_f32_16x16x32_bf16 v[98:101], v[230:233], v[186:189], v[98:101]
	v_mfma_f32_16x16x32_bf16 v[86:89], v[222:225], v[202:205], v[86:89]
	v_mfma_f32_16x16x32_bf16 v[82:85], v[230:233], v[202:205], v[82:85]
	v_mfma_f32_16x16x32_bf16 v[70:73], v[222:225], v[214:217], v[70:73]
	v_mfma_f32_16x16x32_bf16 v[66:69], v[230:233], v[214:217], v[66:69]
	v_mfma_f32_16x16x32_bf16 v[118:121], v[226:229], v[182:185], v[118:121]
	v_mfma_f32_16x16x32_bf16 v[114:117], v[234:237], v[182:185], v[114:117]
	v_mfma_f32_16x16x32_bf16 v[102:105], v[226:229], v[198:201], v[102:105]
	v_mfma_f32_16x16x32_bf16 v[98:101], v[234:237], v[198:201], v[98:101]
	v_mfma_f32_16x16x32_bf16 v[86:89], v[226:229], v[206:209], v[86:89]
	v_mfma_f32_16x16x32_bf16 v[82:85], v[234:237], v[206:209], v[82:85]
	v_mfma_f32_16x16x32_bf16 v[70:73], v[226:229], v[218:221], v[70:73]
	v_mfma_f32_16x16x32_bf16 v[66:69], v[234:237], v[218:221], v[66:69]
	s_mov_b32 m0, s86
	v_lshl_add_u64 v[162:163], v[238:239], 0, s[70:71]
	s_barrier
	ds_read_b128 v[178:181], v196 offset:49152
	ds_read_b128 v[182:185], v196 offset:50176
	ds_read_b128 v[186:189], v196 offset:51200
	ds_read_b128 v[198:201], v196 offset:52224
	ds_read_b128 v[202:205], v196 offset:53248
	ds_read_b128 v[206:209], v196 offset:54272
	ds_read_b128 v[214:217], v196 offset:55296
	ds_read_b128 v[218:221], v196 offset:56320
	global_load_lds_dwordx4 v[162:163], off
	s_mov_b32 m0, s87
	v_lshl_add_u64 v[162:163], v[240:241], 0, s[70:71]
	global_load_lds_dwordx4 v[162:163], off
	s_waitcnt lgkmcnt(0)
	s_barrier
; #define LAS __attribute__((address_space(3)))
; #define PG8_STAGE(bufoff, gbase, voff) do { _Pragma("unroll") for (int _i = 0; _i < 2; ++_i) \
;         __builtin_amdgcn_global_load_lds((const unsigned*)((const char*)(gbase) + (voff)[_i]), (LAS unsigned*)(lds + (bufoff) + ldsw + _i * 8192), 16, 0, 0); } while (0)
; #define PG8_WAIT_V(n) asm volatile("s_waitcnt vmcnt(" #n ")" ::: "memory")
; #define PG8_WAIT_L(n) asm volatile("s_waitcnt lgkmcnt(" #n ")" ::: "memory")
; #define PG8_BAR __builtin_amdgcn_s_barrier()
; #define PG8_SCHED __builtin_amdgcn_sched_barrier(0)
; template <class Epi>
; DEVI void gemm_phase(LAS unsigned char* lds, const Gemm g, const Epi& E) {
;     ...
;             PG8_BAR; PG8_WAIT_L(0); PG8_MMA(1, 0, At, B0); PG8_BAR; PG8_SCHED;
;             PG8_STAGE(PG8_SB(1, 1), b3 + hstepB, voffB);
;             PG8_WAIT_V(6); PG8_BAR; PG8_MMA(1, 1, At, B1); PG8_BAR;
;         }
;     ...
;                             for (int n = 0; n < 2; ++n) pre[m][bj][n] = E.load(row0 + ai * HALF + (m0 + m) * 16, col0 + bj * HALF + n * NST);
;                 }
; #pragma unroll
;                 for (int mm = 0; mm < 2; ++mm) {
;                     const int m = m0 + mm;
;                     const int r = row0 + ai * HALF + m * 16; float rs = 1.f, part = 0.f;
;                     if constexpr (Epi::RS) rs = rsv[ai * 4 + m];
;                     if constexpr (Epi::PAIR) E.pair8(cur.b, r, cur.pn * HALF + wc * 32 + 8 * fq, acc[ai][0][m][0] * rs, acc[ai][0][m][1] * rs, acc[ai][1][m][0] * rs, acc[ai][1][m][1] * rs);
;                     else
; #pragma unroll
;                     for (int bj = 0; bj < 2; ++bj) {
;                         const int c = col0 + bj * HALF; f32x4 v0 = acc[ai][bj][m][0], v1 = acc[ai][bj][m][1];
;                         if constexpr (Epi::RS) { v0 = v0 * rs; v1 = v1 * rs; }
;                         if constexpr (Epi::PRE) part += E.frag_pre8(cur.b, r, c, v0, v1, pre[mm][bj][0], pre[mm][bj][1]);
;                         else if constexpr (Epi::PERM) E.frag8(cur.b, r, c, v0, v1);
;                         else { E.frag(cur.b, r, c, v0); E.frag(cur.b, r, c + 16, v1); }
;                     }
;                     if constexpr (Epi::SSQ) { part += __shfl_xor(part, 16); part += __shfl_xor(part, 32); if (fq == 0) ((LAS float*)(lds + 131072))[(wr * 4 + wc) * 128 + ai * 64 + m * 16 + fr] = part; }
	v_mfma_f32_16x16x32_bf16 v[62:65], v[130:133], v[178:181], v[62:65]
	v_mfma_f32_16x16x32_bf16 v[58:61], v[138:141], v[178:181], v[58:61]
	v_mfma_f32_16x16x32_bf16 v[46:49], v[130:133], v[186:189], v[46:49]
	v_mfma_f32_16x16x32_bf16 v[42:45], v[138:141], v[186:189], v[42:45]
	v_mfma_f32_16x16x32_bf16 v[30:33], v[130:133], v[202:205], v[30:33]
	v_mfma_f32_16x16x32_bf16 v[26:29], v[138:141], v[202:205], v[26:29]
	v_mfma_f32_16x16x32_bf16 v[14:17], v[130:133], v[214:217], v[14:17]
	v_mfma_f32_16x16x32_bf16 v[10:13], v[138:141], v[214:217], v[10:13]
	v_mfma_f32_16x16x32_bf16 v[62:65], v[134:137], v[182:185], v[62:65]
	v_mfma_f32_16x16x32_bf16 v[58:61], v[142:145], v[182:185], v[58:61]
	v_mfma_f32_16x16x32_bf16 v[46:49], v[134:137], v[198:201], v[46:49]
	v_mfma_f32_16x16x32_bf16 v[42:45], v[142:145], v[198:201], v[42:45]
	v_mfma_f32_16x16x32_bf16 v[30:33], v[134:137], v[206:209], v[30:33]
	v_mfma_f32_16x16x32_bf16 v[26:29], v[142:145], v[206:209], v[26:29]
	v_mfma_f32_16x16x32_bf16 v[14:17], v[134:137], v[218:221], v[14:17]
	v_mfma_f32_16x16x32_bf16 v[10:13], v[142:145], v[218:221], v[10:13]
	s_barrier
	s_add_u32 s18, s78, 0x40080
	s_addc_u32 s19, s79, 0
	s_add_i32 s26, s27, s82
	s_mov_b32 m0, s26
	v_lshl_add_u64 v[130:131], s[18:19], 0, v[8:9]
	global_load_lds_dwordx4 v[130:131], off
	s_add_i32 m0, s26, 0x2000
	v_lshl_add_u64 v[130:131], s[18:19], 0, v[150:151]
	global_load_lds_dwordx4 v[130:131], off
	s_waitcnt vmcnt(6)
	s_barrier
	v_mfma_f32_16x16x32_bf16 v[54:57], v[222:225], v[178:181], v[54:57]
	v_mfma_f32_16x16x32_bf16 v[50:53], v[230:233], v[178:181], v[50:53]
	v_mfma_f32_16x16x32_bf16 v[38:41], v[222:225], v[186:189], v[38:41]
	v_mfma_f32_16x16x32_bf16 v[34:37], v[230:233], v[186:189], v[34:37]
	v_mfma_f32_16x16x32_bf16 v[22:25], v[222:225], v[202:205], v[22:25]
	v_mfma_f32_16x16x32_bf16 v[18:21], v[230:233], v[202:205], v[18:21]
	v_mfma_f32_16x16x32_bf16 v[4:7], v[222:225], v[214:217], v[4:7]
	v_mfma_f32_16x16x32_bf16 v[0:3], v[230:233], v[214:217], v[0:3]
	v_mfma_f32_16x16x32_bf16 v[54:57], v[226:229], v[182:185], v[54:57]
	v_mfma_f32_16x16x32_bf16 v[50:53], v[234:237], v[182:185], v[50:53]
	v_mfma_f32_16x16x32_bf16 v[38:41], v[226:229], v[198:201], v[38:41]
	v_mfma_f32_16x16x32_bf16 v[34:37], v[234:237], v[198:201], v[34:37]
	v_mfma_f32_16x16x32_bf16 v[22:25], v[226:229], v[206:209], v[22:25]
	v_mfma_f32_16x16x32_bf16 v[18:21], v[234:237], v[206:209], v[18:21]
	v_mfma_f32_16x16x32_bf16 v[4:7], v[226:229], v[218:221], v[4:7]
	v_mfma_f32_16x16x32_bf16 v[0:3], v[234:237], v[218:221], v[0:3]
	s_add_i32 s17, s17, 2
	s_add_u32 s8, s8, 0x100
	s_addc_u32 s9, s9, 0
	s_add_u32 s13, s13, 0x100
	s_addc_u32 s15, s15, 0
	s_cmp_gt_u32 s17, 13
	s_barrier
	s_cbranch_scc0 .LBB0_1595
	s_setprio 0
	s_lshl_b32 s0, s68, 8
	v_add_u32_e32 v182, s0, v190
	v_lshl_or_b32 v180, s12, 8, v195
	v_ashrrev_i32_e32 v183, 31, v182
	v_lshlrev_b64 v[130:131], 12, v[182:183]
	v_ashrrev_i32_e32 v181, 31, v180
	v_lshl_add_u64 v[130:131], s[30:31], 0, v[130:131]
	v_lshlrev_b64 v[184:185], 2, v[180:181]
	v_lshl_add_u64 v[162:163], v[130:131], 0, v[184:185]
	global_load_dwordx4 v[200:203], v[162:163], off
	global_load_dwordx4 v[204:207], v[162:163], off offset:16
	global_load_dwordx4 v[214:217], v[162:163], off offset:512
	global_load_dwordx4 v[218:221], v[162:163], off offset:528
	v_or_b32_e32 v188, 16, v182
	v_ashrrev_i32_e32 v189, 31, v188
	v_lshlrev_b64 v[130:131], 12, v[188:189]
	v_lshl_add_u64 v[130:131], s[30:31], 0, v[130:131]
	v_lshl_add_u64 v[186:187], v[130:131], 0, v[184:185]
	global_load_dwordx4 v[138:141], v[186:187], off offset:16
	global_load_dwordx4 v[142:145], v[186:187], off
	global_load_dwordx4 v[130:133], v[186:187], off offset:528
	global_load_dwordx4 v[134:137], v[186:187], off offset:512
	v_and_b32_e32 v165, 64, v155
	v_xor_b32_e32 v164, 16, v155
	v_add_u32_e32 v165, 64, v165
	v_xor_b32_e32 v179, 32, v155
	v_cmp_lt_i32_e32 vcc, v164, v165
	v_or_b32_e32 v178, 0x80, v180
	s_waitcnt vmcnt(0)
	v_pk_add_f32 v[128:129], v[128:129], v[202:203]
	v_cndmask_b32_e32 v164, v155, v164, vcc
	v_cmp_lt_i32_e32 vcc, v179, v165
	v_lshlrev_b32_e32 v198, 2, v164
	v_pk_add_f32 v[126:127], v[126:127], v[200:201]
	v_cndmask_b32_e32 v165, v155, v179, vcc
	v_lshlrev_b32_e32 v197, 2, v165
	v_lshlrev_b64 v[164:165], 10, v[182:183]
	v_pk_add_f32 v[124:125], v[124:125], v[206:207]
	v_pk_add_f32 v[122:123], v[122:123], v[204:205]
	v_pk_add_f32 v[120:121], v[120:121], v[216:217]
	v_pk_add_f32 v[118:119], v[118:119], v[214:215]
	v_pk_add_f32 v[202:203], v[116:117], v[220:221]
	v_pk_add_f32 v[200:201], v[114:115], v[218:219]
	v_lshl_add_u64 v[208:209], v[164:165], 0, v[180:181]
	global_store_dwordx4 v[162:163], v[126:129], off
	global_store_dwordx4 v[162:163], v[122:125], off offset:16
	v_cvt_pk_bf16_f32 v114, v126, v127
	v_cvt_pk_bf16_f32 v115, v128, v129
	v_cvt_pk_bf16_f32 v116, v122, v123
	v_cvt_pk_bf16_f32 v117, v124, v125
	v_mul_f32_e32 v127, v127, v127
	v_mul_f32_e32 v129, v129, v129
	v_mul_f32_e32 v123, v123, v123
	v_mul_f32_e32 v125, v125, v125
	v_mul_f32_e32 v183, v119, v119
	v_mul_f32_e32 v199, v121, v121
	v_mul_f32_e32 v204, v201, v201
	v_mul_f32_e32 v205, v203, v203
	v_lshl_add_u64 v[208:209], v[208:209], 1, s[24:25]
	v_fmac_f32_e32 v127, v126, v126
	v_fmac_f32_e32 v129, v128, v128
	v_fmac_f32_e32 v123, v122, v122
	v_fmac_f32_e32 v125, v124, v124
	v_fmac_f32_e32 v183, v118, v118
	v_fmac_f32_e32 v199, v120, v120
	v_fmac_f32_e32 v204, v200, v200
	v_fmac_f32_e32 v205, v202, v202
	global_store_dwordx4 v[208:209], v[114:117], off
	v_ashrrev_i32_e32 v179, 31, v178
	v_lshl_add_u64 v[164:165], v[164:165], 0, v[178:179]
	v_add_f32_e32 v114, v127, v129
	v_add_f32_e32 v115, v123, v125
	v_add_f32_e32 v116, v183, v199
	v_add_f32_e32 v117, v204, v205
	v_add_f32_e32 v114, v114, v115
	v_add_f32_e32 v115, v116, v117
	v_add_f32_e32 v114, v114, v115
	ds_bpermute_b32 v115, v198, v114
	global_store_dwordx4 v[162:163], v[118:121], off offset:512
	global_store_dwordx4 v[162:163], v[200:203], off offset:528
	v_cvt_pk_bf16_f32 v116, v118, v119
	v_cvt_pk_bf16_f32 v117, v120, v121
	v_cvt_pk_bf16_f32 v118, v200, v201
	s_waitcnt lgkmcnt(0)
	v_add_f32_e32 v114, v114, v115
	ds_bpermute_b32 v115, v197, v114
	v_cvt_pk_bf16_f32 v119, v202, v203
	v_lshl_add_u64 v[120:121], v[164:165], 1, s[24:25]
	global_store_dwordx4 v[120:121], v[116:119], off
	s_and_saveexec_b64 s[8:9], s[2:3]
	s_cbranch_execz .LBB0_1598
	s_waitcnt lgkmcnt(0)
	v_add_f32_e32 v114, v114, v115
	ds_write_b32 v192, v114

; #define PG8_STAGE(bufoff, gbase, voff) do { _Pragma("unroll") for (int _i = 0; _i < 2; ++_i) \
;         __builtin_amdgcn_global_load_lds((const unsigned*)((const char*)(gbase) + (voff)[_i]), (LAS unsigned*)(lds + (bufoff) + ldsw + _i * 8192), 16, 0, 0); } while (0)
; #define PG8_LDA(dst, b, h) do { _Pragma("unroll") for (int m = 0; m < 4; ++m) _Pragma("unroll") for (int k = 0; k < 2; ++k) dst[m][k] = *(const LAS bf16x8*)(lds + PG8_SA(b, h) + aoff + m * 2048 + k * 1024); } while (0)
; #define PG8_LDB(dst, b, h) do { _Pragma("unroll") for (int n = 0; n < 2; ++n) _Pragma("unroll") for (int k = 0; k < 2; ++k) dst[n][k] = *(const LAS bf16x8*)(lds + PG8_SB(b, h) + boff + n * 2048 + k * 1024); } while (0)
; #define PG8_MMA(ai, bj, At, Bt) do { __builtin_amdgcn_s_setprio(1); _Pragma("unroll") for (int m = 0; m < 4; ++m) _Pragma("unroll") for (int n = 0; n < 2; ++n) _Pragma("unroll") for (int k = 0; k < 2; ++k) \
;         acc[ai][bj][m][n] = __builtin_amdgcn_mfma_f32_16x16x32_bf16(Bt[n][k], At[m][k], acc[ai][bj][m][n], 0, 0, 0); __builtin_amdgcn_s_setprio(0); } while (0)
; #define PG8_WAIT_V(n) asm volatile("s_waitcnt vmcnt(" #n ")" ::: "memory")
; #define PG8_WAIT_L(n) asm volatile("s_waitcnt lgkmcnt(" #n ")" ::: "memory")
; #define PG8_BAR __builtin_amdgcn_s_barrier()
; #define PG8_SCHED __builtin_amdgcn_sched_barrier(0)
; template <class Epi>
; DEVI void gemm_phase(LAS unsigned char* lds, const Gemm g, const Epi& E) {
;     ...
;             const bool last = (t == nt - 2);
;             const char* a1 = cA + (size_t)(t + 1) * kstep;
;             const char* a2 = last ? nA : cA + (size_t)(t + 2) * kstep; const char* b2 = last ? nB : cB + (size_t)(t + 2) * kstep;
;             const char* a3 = a2 + kstep; const char* b3 = b2 + kstep;
;             PG8_LDB(B0, 0, 0); PG8_SCHED; PG8_LDA(At, 0, 0); PG8_STAGE(PG8_SA(1, 1), a1 + hstepA, voffA);
;             PG8_WAIT_L(8); PG8_BAR; PG8_WAIT_L(0); PG8_MMA(0, 0, At, B0); PG8_BAR; PG8_SCHED;
;             PG8_LDB(B1, 0, 1); PG8_STAGE(PG8_SB(0, 0), b2, voffB);
;             PG8_BAR; PG8_WAIT_L(0); PG8_MMA(0, 1, At, B1); PG8_BAR;
;             PG8_LDA(At, 0, 1); PG8_STAGE(PG8_SA(0, 0), a2, voffA);
;             PG8_BAR; PG8_WAIT_L(0); PG8_MMA(1, 0, At, B0); PG8_BAR; PG8_SCHED;
;             PG8_STAGE(PG8_SB(0, 1), b2 + hstepB, voffB);
;             PG8_WAIT_V(6); PG8_BAR; PG8_MMA(1, 1, At, B1); PG8_BAR;
.LBB0_1672:
	s_add_u32 s26, s16, 0xfffc0080
	s_addc_u32 s27, s17, -1
	s_add_i32 s38, 0, 0x10000
	v_add_u32_e32 v142, s38, v197
	ds_read_b128 v[130:133], v142
	ds_read_b128 v[134:137], v142 offset:1024
	ds_read_b128 v[138:141], v142 offset:2048
	ds_read_b128 v[142:145], v142 offset:3072
	s_cmp_eq_u32 s19, 12
	s_cselect_b32 s47, s0, s27
	s_cselect_b32 s46, s1, s26
	s_cselect_b32 s37, s5, s18
	s_cselect_b32 s36, s7, s9
	v_lshl_add_u64 v[162:163], s[16:17], 0, v[152:153]
	s_add_i32 m0, s79, 0xc000
	ds_read_b128 v[178:181], v201
	ds_read_b128 v[182:185], v201 offset:1024
	ds_read_b128 v[186:189], v201 offset:2048
	ds_read_b128 v[202:205], v201 offset:3072
	ds_read_b128 v[206:209], v201 offset:4096
	ds_read_b128 v[214:217], v201 offset:5120
	ds_read_b128 v[218:221], v201 offset:6144
	ds_read_b128 v[222:225], v201 offset:7168
	global_load_lds_dwordx4 v[162:163], off
	s_add_i32 m0, s79, 0xe000
	v_lshl_add_u64 v[162:163], s[16:17], 0, v[176:177]
	global_load_lds_dwordx4 v[162:163], off
	s_waitcnt lgkmcnt(0)
	s_barrier
	v_mfma_f32_16x16x32_bf16 v[126:129], v[130:133], v[178:181], v[126:129]
	v_mfma_f32_16x16x32_bf16 v[122:125], v[138:141], v[178:181], v[122:125]
	v_mfma_f32_16x16x32_bf16 v[110:113], v[130:133], v[186:189], v[110:113]
	v_mfma_f32_16x16x32_bf16 v[106:109], v[138:141], v[186:189], v[106:109]
	v_mfma_f32_16x16x32_bf16 v[94:97], v[130:133], v[206:209], v[94:97]
	v_mfma_f32_16x16x32_bf16 v[90:93], v[138:141], v[206:209], v[90:93]
	v_mfma_f32_16x16x32_bf16 v[78:81], v[130:133], v[218:221], v[78:81]
	v_mfma_f32_16x16x32_bf16 v[74:77], v[138:141], v[218:221], v[74:77]
	v_mfma_f32_16x16x32_bf16 v[126:129], v[134:137], v[182:185], v[126:129]
	v_mfma_f32_16x16x32_bf16 v[122:125], v[142:145], v[182:185], v[122:125]
	v_mfma_f32_16x16x32_bf16 v[110:113], v[134:137], v[202:205], v[110:113]
	v_mfma_f32_16x16x32_bf16 v[106:109], v[142:145], v[202:205], v[106:109]
	v_mfma_f32_16x16x32_bf16 v[94:97], v[134:137], v[214:217], v[94:97]
	v_mfma_f32_16x16x32_bf16 v[90:93], v[142:145], v[214:217], v[90:93]
	v_mfma_f32_16x16x32_bf16 v[78:81], v[134:137], v[222:225], v[78:81]
	v_mfma_f32_16x16x32_bf16 v[74:77], v[142:145], v[222:225], v[74:77]
	s_barrier
	s_add_i32 s39, 0, 0x14000
	v_add_u32_e32 v162, s39, v197
	s_add_i32 s26, s38, s78
	ds_read_b128 v[226:229], v162
	ds_read_b128 v[230:233], v162 offset:1024
	ds_read_b128 v[234:237], v162 offset:2048
	ds_read_b128 v[238:241], v162 offset:3072
	v_lshl_add_u64 v[162:163], s[36:37], 0, v[8:9]
	s_mov_b32 m0, s26
	v_lshl_add_u64 v[164:165], s[36:37], 0, v[146:147]
	global_load_lds_dwordx4 v[162:163], off
	s_add_i32 m0, s26, 0x2000
	s_nop 0
	global_load_lds_dwordx4 v[164:165], off
	s_waitcnt lgkmcnt(0)
	s_barrier
	v_mfma_f32_16x16x32_bf16 v[118:121], v[226:229], v[178:181], v[118:121]
	v_mfma_f32_16x16x32_bf16 v[114:117], v[234:237], v[178:181], v[114:117]
	v_mfma_f32_16x16x32_bf16 v[102:105], v[226:229], v[186:189], v[102:105]
	v_mfma_f32_16x16x32_bf16 v[98:101], v[234:237], v[186:189], v[98:101]
	v_mfma_f32_16x16x32_bf16 v[86:89], v[226:229], v[206:209], v[86:89]
	v_mfma_f32_16x16x32_bf16 v[82:85], v[234:237], v[206:209], v[82:85]
	v_mfma_f32_16x16x32_bf16 v[70:73], v[226:229], v[218:221], v[70:73]
	v_mfma_f32_16x16x32_bf16 v[66:69], v[234:237], v[218:221], v[66:69]
	v_mfma_f32_16x16x32_bf16 v[118:121], v[230:233], v[182:185], v[118:121]
	v_mfma_f32_16x16x32_bf16 v[114:117], v[238:241], v[182:185], v[114:117]
	v_mfma_f32_16x16x32_bf16 v[102:105], v[230:233], v[202:205], v[102:105]
	v_mfma_f32_16x16x32_bf16 v[98:101], v[238:241], v[202:205], v[98:101]
	v_mfma_f32_16x16x32_bf16 v[86:89], v[230:233], v[214:217], v[86:89]
	v_mfma_f32_16x16x32_bf16 v[82:85], v[238:241], v[214:217], v[82:85]
	v_mfma_f32_16x16x32_bf16 v[70:73], v[230:233], v[222:225], v[70:73]
	v_mfma_f32_16x16x32_bf16 v[66:69], v[238:241], v[222:225], v[66:69]
	s_mov_b32 m0, s79
	v_lshl_add_u64 v[190:191], s[46:47], 0, v[150:151]
	s_barrier
	ds_read_b128 v[178:181], v201 offset:16384
	ds_read_b128 v[182:185], v201 offset:17408
	ds_read_b128 v[186:189], v201 offset:18432
	ds_read_b128 v[202:205], v201 offset:19456
	ds_read_b128 v[206:209], v201 offset:20480
	ds_read_b128 v[214:217], v201 offset:21504
	ds_read_b128 v[218:221], v201 offset:22528
	ds_read_b128 v[222:225], v201 offset:23552
	global_load_lds_dwordx4 v[190:191], off
	s_mov_b32 m0, s80
	v_lshl_add_u64 v[194:195], s[46:47], 0, v[148:149]
	global_load_lds_dwordx4 v[194:195], off
	s_waitcnt lgkmcnt(0)
	s_barrier
	v_mfma_f32_16x16x32_bf16 v[50:53], v[130:133], v[178:181], v[50:53]
	v_mfma_f32_16x16x32_bf16 v[54:57], v[138:141], v[178:181], v[54:57]
	v_mfma_f32_16x16x32_bf16 v[34:37], v[130:133], v[186:189], v[34:37]
	v_mfma_f32_16x16x32_bf16 v[38:41], v[138:141], v[186:189], v[38:41]
	v_mfma_f32_16x16x32_bf16 v[18:21], v[130:133], v[206:209], v[18:21]
	v_mfma_f32_16x16x32_bf16 v[22:25], v[138:141], v[206:209], v[22:25]
	v_mfma_f32_16x16x32_bf16 v[0:3], v[130:133], v[218:221], v[0:3]
	v_mfma_f32_16x16x32_bf16 v[4:7], v[138:141], v[218:221], v[4:7]
	v_mfma_f32_16x16x32_bf16 v[50:53], v[134:137], v[182:185], v[50:53]
	v_mfma_f32_16x16x32_bf16 v[54:57], v[142:145], v[182:185], v[54:57]
	v_mfma_f32_16x16x32_bf16 v[34:37], v[134:137], v[202:205], v[34:37]
	v_mfma_f32_16x16x32_bf16 v[38:41], v[142:145], v[202:205], v[38:41]
	v_mfma_f32_16x16x32_bf16 v[18:21], v[134:137], v[214:217], v[18:21]
	v_mfma_f32_16x16x32_bf16 v[22:25], v[142:145], v[214:217], v[22:25]
	v_mfma_f32_16x16x32_bf16 v[0:3], v[134:137], v[222:225], v[0:3]
	v_mfma_f32_16x16x32_bf16 v[4:7], v[142:145], v[222:225], v[4:7]
	s_barrier
; #define PG8_STAGE(bufoff, gbase, voff) do { _Pragma("unroll") for (int _i = 0; _i < 2; ++_i) \
;         __builtin_amdgcn_global_load_lds((const unsigned*)((const char*)(gbase) + (voff)[_i]), (LAS unsigned*)(lds + (bufoff) + ldsw + _i * 8192), 16, 0, 0); } while (0)
; #define PG8_LDA(dst, b, h) do { _Pragma("unroll") for (int m = 0; m < 4; ++m) _Pragma("unroll") for (int k = 0; k < 2; ++k) dst[m][k] = *(const LAS bf16x8*)(lds + PG8_SA(b, h) + aoff + m * 2048 + k * 1024); } while (0)
; #define PG8_LDB(dst, b, h) do { _Pragma("unroll") for (int n = 0; n < 2; ++n) _Pragma("unroll") for (int k = 0; k < 2; ++k) dst[n][k] = *(const LAS bf16x8*)(lds + PG8_SB(b, h) + boff + n * 2048 + k * 1024); } while (0)
; #define PG8_MMA(ai, bj, At, Bt) do { __builtin_amdgcn_s_setprio(1); _Pragma("unroll") for (int m = 0; m < 4; ++m) _Pragma("unroll") for (int n = 0; n < 2; ++n) _Pragma("unroll") for (int k = 0; k < 2; ++k) \
;         acc[ai][bj][m][n] = __builtin_amdgcn_mfma_f32_16x16x32_bf16(Bt[n][k], At[m][k], acc[ai][bj][m][n], 0, 0, 0); __builtin_amdgcn_s_setprio(0); } while (0)
; #define PG8_WAIT_V(n) asm volatile("s_waitcnt vmcnt(" #n ")" ::: "memory")
; #define PG8_WAIT_L(n) asm volatile("s_waitcnt lgkmcnt(" #n ")" ::: "memory")
; #define PG8_BAR __builtin_amdgcn_s_barrier()
; #define PG8_SCHED __builtin_amdgcn_sched_barrier(0)
; template <class Epi>
; DEVI void gemm_phase(LAS unsigned char* lds, const Gemm g, const Epi& E) {
;     ...
;             PG8_WAIT_V(6); PG8_BAR; PG8_MMA(1, 1, At, B1); PG8_BAR;
;             PG8_LDB(B0, 1, 0); PG8_SCHED; PG8_LDA(At, 1, 0); PG8_STAGE(PG8_SA(0, 1), a2 + hstepA, voffA);
;             PG8_WAIT_L(8); PG8_BAR; PG8_WAIT_L(0); PG8_MMA(0, 0, At, B0); PG8_BAR; PG8_SCHED;
;             PG8_LDB(B1, 1, 1); PG8_STAGE(PG8_SB(1, 0), b3, voffB);
;             PG8_BAR; PG8_WAIT_L(0); PG8_MMA(0, 1, At, B1); PG8_BAR;
;             PG8_LDA(At, 1, 1); PG8_STAGE(PG8_SA(1, 0), a3, voffA);
;             PG8_BAR; PG8_WAIT_L(0); PG8_MMA(1, 0, At, B0); PG8_BAR; PG8_SCHED;
	s_add_u32 s26, s36, 0x40000
	s_addc_u32 s27, s37, 0
	s_add_i32 s38, s39, s78
	s_mov_b32 m0, s38
	v_lshl_add_u64 v[130:131], s[26:27], 0, v[8:9]
	global_load_lds_dwordx4 v[130:131], off
	s_add_i32 m0, s38, 0x2000
	v_lshl_add_u64 v[130:131], s[26:27], 0, v[146:147]
	global_load_lds_dwordx4 v[130:131], off
	s_waitcnt vmcnt(6)
	s_barrier
	v_mfma_f32_16x16x32_bf16 v[58:61], v[226:229], v[178:181], v[58:61]
	v_mfma_f32_16x16x32_bf16 v[62:65], v[234:237], v[178:181], v[62:65]
	v_mfma_f32_16x16x32_bf16 v[42:45], v[226:229], v[186:189], v[42:45]
	v_mfma_f32_16x16x32_bf16 v[46:49], v[234:237], v[186:189], v[46:49]
	v_mfma_f32_16x16x32_bf16 v[26:29], v[226:229], v[206:209], v[26:29]
	v_mfma_f32_16x16x32_bf16 v[30:33], v[234:237], v[206:209], v[30:33]
	v_mfma_f32_16x16x32_bf16 v[10:13], v[226:229], v[218:221], v[10:13]
	v_mfma_f32_16x16x32_bf16 v[14:17], v[234:237], v[218:221], v[14:17]
	v_mfma_f32_16x16x32_bf16 v[58:61], v[230:233], v[182:185], v[58:61]
	v_mfma_f32_16x16x32_bf16 v[62:65], v[238:241], v[182:185], v[62:65]
	v_mfma_f32_16x16x32_bf16 v[42:45], v[230:233], v[202:205], v[42:45]
	v_mfma_f32_16x16x32_bf16 v[46:49], v[238:241], v[202:205], v[46:49]
	v_mfma_f32_16x16x32_bf16 v[26:29], v[230:233], v[214:217], v[26:29]
	v_mfma_f32_16x16x32_bf16 v[30:33], v[238:241], v[214:217], v[30:33]
	v_mfma_f32_16x16x32_bf16 v[10:13], v[230:233], v[222:225], v[10:13]
	v_mfma_f32_16x16x32_bf16 v[14:17], v[238:241], v[222:225], v[14:17]
	s_add_i32 s38, 0, 0x18000
	v_add_u32_e32 v142, s38, v197
	s_barrier
	ds_read_b128 v[130:133], v142
	ds_read_b128 v[134:137], v142 offset:1024
	ds_read_b128 v[138:141], v142 offset:2048
	ds_read_b128 v[142:145], v142 offset:3072
	s_add_u32 s26, s46, 0x40000
	s_addc_u32 s27, s47, 0
	s_mov_b32 m0, s81
	v_lshl_add_u64 v[226:227], s[26:27], 0, v[150:151]
	ds_read_b128 v[178:181], v201 offset:32768
	ds_read_b128 v[182:185], v201 offset:33792
	ds_read_b128 v[186:189], v201 offset:34816
	ds_read_b128 v[202:205], v201 offset:35840
	ds_read_b128 v[206:209], v201 offset:36864
	ds_read_b128 v[214:217], v201 offset:37888
	ds_read_b128 v[218:221], v201 offset:38912
	ds_read_b128 v[222:225], v201 offset:39936
	global_load_lds_dwordx4 v[226:227], off
	s_mov_b32 m0, s82
	v_lshl_add_u64 v[226:227], s[26:27], 0, v[148:149]
	global_load_lds_dwordx4 v[226:227], off
	s_waitcnt lgkmcnt(0)
	s_barrier
	v_mfma_f32_16x16x32_bf16 v[126:129], v[130:133], v[178:181], v[126:129]
	v_mfma_f32_16x16x32_bf16 v[122:125], v[138:141], v[178:181], v[122:125]
	v_mfma_f32_16x16x32_bf16 v[110:113], v[130:133], v[186:189], v[110:113]
	v_mfma_f32_16x16x32_bf16 v[106:109], v[138:141], v[186:189], v[106:109]
	v_mfma_f32_16x16x32_bf16 v[94:97], v[130:133], v[206:209], v[94:97]
	v_mfma_f32_16x16x32_bf16 v[90:93], v[138:141], v[206:209], v[90:93]
	v_mfma_f32_16x16x32_bf16 v[78:81], v[130:133], v[218:221], v[78:81]
	v_mfma_f32_16x16x32_bf16 v[74:77], v[138:141], v[218:221], v[74:77]
	v_mfma_f32_16x16x32_bf16 v[126:129], v[134:137], v[182:185], v[126:129]
	v_mfma_f32_16x16x32_bf16 v[122:125], v[142:145], v[182:185], v[122:125]
	v_mfma_f32_16x16x32_bf16 v[110:113], v[134:137], v[202:205], v[110:113]
	v_mfma_f32_16x16x32_bf16 v[106:109], v[142:145], v[202:205], v[106:109]
	v_mfma_f32_16x16x32_bf16 v[94:97], v[134:137], v[214:217], v[94:97]
	v_mfma_f32_16x16x32_bf16 v[90:93], v[142:145], v[214:217], v[90:93]
	v_mfma_f32_16x16x32_bf16 v[78:81], v[134:137], v[222:225], v[78:81]
	v_mfma_f32_16x16x32_bf16 v[74:77], v[142:145], v[222:225], v[74:77]
	s_barrier
	s_add_i32 s39, 0, 0x1c000
	s_add_i32 s26, s38, s78
	v_add_u32_e32 v192, s39, v197
	v_lshl_add_u64 v[162:163], v[162:163], 0, s[70:71]
	s_mov_b32 m0, s26
	ds_read_b128 v[226:229], v192
	ds_read_b128 v[230:233], v192 offset:1024
	ds_read_b128 v[234:237], v192 offset:2048
	ds_read_b128 v[238:241], v192 offset:3072
	global_load_lds_dwordx4 v[162:163], off
	s_add_i32 m0, s26, 0x2000
	v_lshl_add_u64 v[162:163], v[164:165], 0, s[70:71]
	global_load_lds_dwordx4 v[162:163], off
	s_waitcnt lgkmcnt(0)
	s_barrier
	v_mfma_f32_16x16x32_bf16 v[118:121], v[226:229], v[178:181], v[118:121]
	v_mfma_f32_16x16x32_bf16 v[114:117], v[234:237], v[178:181], v[114:117]
	v_mfma_f32_16x16x32_bf16 v[102:105], v[226:229], v[186:189], v[102:105]
	v_mfma_f32_16x16x32_bf16 v[98:101], v[234:237], v[186:189], v[98:101]
	v_mfma_f32_16x16x32_bf16 v[86:89], v[226:229], v[206:209], v[86:89]
	v_mfma_f32_16x16x32_bf16 v[82:85], v[234:237], v[206:209], v[82:85]
	v_mfma_f32_16x16x32_bf16 v[70:73], v[226:229], v[218:221], v[70:73]
	v_mfma_f32_16x16x32_bf16 v[66:69], v[234:237], v[218:221], v[66:69]
	v_mfma_f32_16x16x32_bf16 v[118:121], v[230:233], v[182:185], v[118:121]
	v_mfma_f32_16x16x32_bf16 v[114:117], v[238:241], v[182:185], v[114:117]
	v_mfma_f32_16x16x32_bf16 v[102:105], v[230:233], v[202:205], v[102:105]
	v_mfma_f32_16x16x32_bf16 v[98:101], v[238:241], v[202:205], v[98:101]
	v_mfma_f32_16x16x32_bf16 v[86:89], v[230:233], v[214:217], v[86:89]
	v_mfma_f32_16x16x32_bf16 v[82:85], v[238:241], v[214:217], v[82:85]
	v_mfma_f32_16x16x32_bf16 v[70:73], v[230:233], v[222:225], v[70:73]
	v_mfma_f32_16x16x32_bf16 v[66:69], v[238:241], v[222:225], v[66:69]
	s_mov_b32 m0, s83
	v_lshl_add_u64 v[162:163], v[190:191], 0, s[70:71]
	s_barrier
	ds_read_b128 v[178:181], v201 offset:49152
	ds_read_b128 v[182:185], v201 offset:50176
	ds_read_b128 v[186:189], v201 offset:51200
	ds_read_b128 v[202:205], v201 offset:52224
	ds_read_b128 v[206:209], v201 offset:53248
	ds_read_b128 v[214:217], v201 offset:54272
	ds_read_b128 v[218:221], v201 offset:55296
	ds_read_b128 v[222:225], v201 offset:56320
	global_load_lds_dwordx4 v[162:163], off
	s_mov_b32 m0, s84
	v_lshl_add_u64 v[162:163], v[194:195], 0, s[70:71]
	global_load_lds_dwordx4 v[162:163], off
	s_waitcnt lgkmcnt(0)
	s_barrier
; #define PG8_STAGE(bufoff, gbase, voff) do { _Pragma("unroll") for (int _i = 0; _i < 2; ++_i) \
;         __builtin_amdgcn_global_load_lds((const unsigned*)((const char*)(gbase) + (voff)[_i]), (LAS unsigned*)(lds + (bufoff) + ldsw + _i * 8192), 16, 0, 0); } while (0)
; #define PG8_MMA(ai, bj, At, Bt) do { __builtin_amdgcn_s_setprio(1); _Pragma("unroll") for (int m = 0; m < 4; ++m) _Pragma("unroll") for (int n = 0; n < 2; ++n) _Pragma("unroll") for (int k = 0; k < 2; ++k) \
;         acc[ai][bj][m][n] = __builtin_amdgcn_mfma_f32_16x16x32_bf16(Bt[n][k], At[m][k], acc[ai][bj][m][n], 0, 0, 0); __builtin_amdgcn_s_setprio(0); } while (0)
; #define PG8_WAIT_V(n) asm volatile("s_waitcnt vmcnt(" #n ")" ::: "memory")
; #define PG8_WAIT_L(n) asm volatile("s_waitcnt lgkmcnt(" #n ")" ::: "memory")
; #define PG8_BAR __builtin_amdgcn_s_barrier()
; #define PG8_SCHED __builtin_amdgcn_sched_barrier(0)
; template <class Epi>
; DEVI void gemm_phase(LAS unsigned char* lds, const Gemm g, const Epi& E) {
;     ...
;             PG8_BAR; PG8_WAIT_L(0); PG8_MMA(1, 0, At, B0); PG8_BAR; PG8_SCHED;
;             PG8_STAGE(PG8_SB(1, 1), b3 + hstepB, voffB);
;             PG8_WAIT_V(6); PG8_BAR; PG8_MMA(1, 1, At, B1); PG8_BAR;
;         }
;     ...
;             if constexpr (Epi::RS) { f32x4 q4[8];
; #pragma unroll
;                 for (int i = 0; i < 8; ++i) q4[i] = *(const f32x4*)(E.ssq_in + (size_t)(row0 + (i >> 2) * HALF + (i & 3) * 16) * 4);
; #pragma unroll
;                 for (int i = 0; i < 8; ++i) rsv[i] = rsqrtf((((q4[i][0] + q4[i][1]) + q4[i][2]) + q4[i][3]) * (1.f / DM) + 1e-6f); }
	v_mfma_f32_16x16x32_bf16 v[50:53], v[130:133], v[178:181], v[50:53]
	v_mfma_f32_16x16x32_bf16 v[54:57], v[138:141], v[178:181], v[54:57]
	v_mfma_f32_16x16x32_bf16 v[34:37], v[130:133], v[186:189], v[34:37]
	v_mfma_f32_16x16x32_bf16 v[38:41], v[138:141], v[186:189], v[38:41]
	v_mfma_f32_16x16x32_bf16 v[18:21], v[130:133], v[206:209], v[18:21]
	v_mfma_f32_16x16x32_bf16 v[22:25], v[138:141], v[206:209], v[22:25]
	v_mfma_f32_16x16x32_bf16 v[0:3], v[130:133], v[218:221], v[0:3]
	v_mfma_f32_16x16x32_bf16 v[4:7], v[138:141], v[218:221], v[4:7]
	v_mfma_f32_16x16x32_bf16 v[50:53], v[134:137], v[182:185], v[50:53]
	v_mfma_f32_16x16x32_bf16 v[54:57], v[142:145], v[182:185], v[54:57]
	v_mfma_f32_16x16x32_bf16 v[34:37], v[134:137], v[202:205], v[34:37]
	v_mfma_f32_16x16x32_bf16 v[38:41], v[142:145], v[202:205], v[38:41]
	v_mfma_f32_16x16x32_bf16 v[18:21], v[134:137], v[214:217], v[18:21]
	v_mfma_f32_16x16x32_bf16 v[22:25], v[142:145], v[214:217], v[22:25]
	v_mfma_f32_16x16x32_bf16 v[0:3], v[134:137], v[222:225], v[0:3]
	v_mfma_f32_16x16x32_bf16 v[4:7], v[142:145], v[222:225], v[4:7]
	s_barrier
	s_add_u32 s26, s36, 0x40080
	s_addc_u32 s27, s37, 0
	s_add_i32 s36, s39, s78
	s_mov_b32 m0, s36
	v_lshl_add_u64 v[130:131], s[26:27], 0, v[8:9]
	global_load_lds_dwordx4 v[130:131], off
	s_add_i32 m0, s36, 0x2000
	v_lshl_add_u64 v[130:131], s[26:27], 0, v[146:147]
	global_load_lds_dwordx4 v[130:131], off
	s_waitcnt vmcnt(6)
	s_barrier
	v_mfma_f32_16x16x32_bf16 v[58:61], v[226:229], v[178:181], v[58:61]
	v_mfma_f32_16x16x32_bf16 v[62:65], v[234:237], v[178:181], v[62:65]
	v_mfma_f32_16x16x32_bf16 v[42:45], v[226:229], v[186:189], v[42:45]
	v_mfma_f32_16x16x32_bf16 v[46:49], v[234:237], v[186:189], v[46:49]
	v_mfma_f32_16x16x32_bf16 v[26:29], v[226:229], v[206:209], v[26:29]
	v_mfma_f32_16x16x32_bf16 v[30:33], v[234:237], v[206:209], v[30:33]
	v_mfma_f32_16x16x32_bf16 v[10:13], v[226:229], v[218:221], v[10:13]
	v_mfma_f32_16x16x32_bf16 v[14:17], v[234:237], v[218:221], v[14:17]
	v_mfma_f32_16x16x32_bf16 v[58:61], v[230:233], v[182:185], v[58:61]
	v_mfma_f32_16x16x32_bf16 v[62:65], v[238:241], v[182:185], v[62:65]
	v_mfma_f32_16x16x32_bf16 v[42:45], v[230:233], v[202:205], v[42:45]
	v_mfma_f32_16x16x32_bf16 v[46:49], v[238:241], v[202:205], v[46:49]
	v_mfma_f32_16x16x32_bf16 v[26:29], v[230:233], v[214:217], v[26:29]
	v_mfma_f32_16x16x32_bf16 v[30:33], v[238:241], v[214:217], v[30:33]
	v_mfma_f32_16x16x32_bf16 v[10:13], v[230:233], v[222:225], v[10:13]
	v_mfma_f32_16x16x32_bf16 v[14:17], v[238:241], v[222:225], v[14:17]
	s_add_i32 s19, s19, 2
	s_add_u32 s16, s16, 0x100
	s_addc_u32 s17, s17, 0
	s_add_u32 s9, s9, 0x100
	s_addc_u32 s18, s18, 0
	s_cmp_gt_u32 s19, 13
	s_barrier
	s_cbranch_scc0 .LBB0_1672
	s_setprio 0
	v_lshl_add_u32 v194, s4, 8, v193
	v_add_u32_e32 v178, 0xb0, v194
	v_ashrrev_i32_e32 v195, 31, v194
	v_or_b32_e32 v190, 16, v194
	v_ashrrev_i32_e32 v179, 31, v178
	v_lshl_add_u64 v[130:131], v[194:195], 4, s[10:11]
	v_ashrrev_i32_e32 v191, 31, v190
	v_lshl_add_u64 v[134:135], v[178:179], 4, s[10:11]
	global_load_dwordx4 v[202:205], v[130:131], off
	v_or_b32_e32 v188, 32, v194
	global_load_dwordx4 v[134:137], v[134:135], off
	v_lshl_add_u64 v[130:131], v[190:191], 4, s[10:11]
	global_load_dwordx4 v[206:209], v[130:131], off
	v_ashrrev_i32_e32 v189, 31, v188
	v_or_b32_e32 v186, 48, v194
	v_lshl_add_u64 v[130:131], v[188:189], 4, s[10:11]
	v_ashrrev_i32_e32 v187, 31, v186
	global_load_dwordx4 v[214:217], v[130:131], off
	v_lshl_add_u64 v[130:131], v[186:187], 4, s[10:11]
	global_load_dwordx4 v[218:221], v[130:131], off
	v_add_u32_e32 v184, 0x80, v194
	v_ashrrev_i32_e32 v185, 31, v184
	v_add_u32_e32 v182, 0x90, v194
	v_lshl_add_u64 v[130:131], v[184:185], 4, s[10:11]
	v_ashrrev_i32_e32 v183, 31, v182
	global_load_dwordx4 v[138:141], v[130:131], off
	v_lshl_add_u64 v[130:131], v[182:183], 4, s[10:11]
	v_add_u32_e32 v180, 0xa0, v194
	global_load_dwordx4 v[142:145], v[130:131], off
	v_ashrrev_i32_e32 v181, 31, v180
	v_lshl_add_u64 v[130:131], v[180:181], 4, s[10:11]
	global_load_dwordx4 v[130:133], v[130:131], off
	s_mov_b32 s0, 0x358637bd
	s_mov_b64 s[36:37], s[14:15]
	s_mov_b64 s[16:17], s[12:13]
	s_waitcnt vmcnt(0)
	v_mov_b32_e32 v163, v202
	v_mov_b32_e32 v165, v204
	v_mov_b32_e32 v162, v206
	v_mov_b32_e32 v202, v207
	v_pk_add_f32 v[162:163], v[162:163], v[202:203]
	v_mov_b32_e32 v164, v208
	v_pk_add_f32 v[162:163], v[164:165], v[162:163]
	v_mov_b32_e32 v204, v209
	v_pk_add_f32 v[162:163], v[204:205], v[162:163]
	v_mov_b64_e32 v[202:203], s[0:1]
	v_pk_fma_f32 v[162:163], v[162:163], s[72:73], v[202:203] op_sel_hi:[1,0,0]
	v_mov_b32_e32 v165, v216
	v_mul_f32_e32 v164, 0x4b800000, v163
	v_cmp_gt_f32_e64 s[4:5], s94, v163
	v_cmp_gt_f32_e32 vcc, s94, v162
	v_mov_b32_e32 v216, v221
	v_cndmask_b32_e64 v163, v163, v164, s[4:5]
	v_rsq_f32_e32 v163, v163
	s_nop 0
	v_mul_f32_e32 v164, 0x45800000, v163
	v_cndmask_b32_e64 v200, v163, v164, s[4:5]
	v_mul_f32_e32 v163, 0x4b800000, v162
	v_cndmask_b32_e32 v162, v162, v163, vcc
	v_rsq_f32_e32 v162, v162
	v_mov_b32_e32 v164, v220
	v_pk_mul_f32 v[126:127], v[126:127], v[200:201] op_sel_hi:[1,0]
	v_pk_mul_f32 v[122:123], v[122:123], v[200:201] op_sel_hi:[1,0]
	v_mul_f32_e32 v163, 0x45800000, v162
	v_cndmask_b32_e32 v198, v162, v163, vcc
	v_mov_b32_e32 v162, v218
	v_mov_b32_e32 v163, v214
	v_mov_b32_e32 v214, v219
	v_pk_add_f32 v[162:163], v[162:163], v[214:215]
	v_pk_mul_f32 v[118:119], v[118:119], v[200:201] op_sel_hi:[1,0]
	v_pk_add_f32 v[162:163], v[164:165], v[162:163]
	v_pk_mul_f32 v[124:125], v[124:125], v[200:201] op_sel_hi:[1,0]
	v_pk_add_f32 v[162:163], v[216:217], v[162:163]
	v_pk_mul_f32 v[114:115], v[114:115], v[200:201] op_sel_hi:[1,0]
; template <class Epi>
; DEVI void gemm_phase(LAS unsigned char* lds, const Gemm g, const Epi& E) {
;     ...
;             if constexpr (Epi::RS) { f32x4 q4[8];
; #pragma unroll
;                 for (int i = 0; i < 8; ++i) q4[i] = *(const f32x4*)(E.ssq_in + (size_t)(row0 + (i >> 2) * HALF + (i & 3) * 16) * 4);
; #pragma unroll
;                 for (int i = 0; i < 8; ++i) rsv[i] = rsqrtf((((q4[i][0] + q4[i][1]) + q4[i][2]) + q4[i][3]) * (1.f / DM) + 1e-6f); }
	v_pk_fma_f32 v[162:163], v[162:163], s[72:73], v[202:203] op_sel_hi:[1,0,0]
	v_pk_mul_f32 v[128:129], v[128:129], v[200:201] op_sel_hi:[1,0]
	v_mul_f32_e32 v164, 0x4b800000, v163
	v_cmp_gt_f32_e64 s[4:5], s94, v163
	v_cmp_gt_f32_e32 vcc, s94, v162
	v_pk_mul_f32 v[120:121], v[120:121], v[200:201] op_sel_hi:[1,0]
	v_cndmask_b32_e64 v163, v163, v164, s[4:5]
	v_rsq_f32_e32 v163, v163
	v_pk_mul_f32 v[116:117], v[116:117], v[200:201] op_sel_hi:[1,0]
	v_pk_mul_f32 v[106:107], v[106:107], v[198:199] op_sel_hi:[1,0]
	v_pk_mul_f32 v[110:111], v[110:111], v[198:199] op_sel_hi:[1,0]
	v_mul_f32_e32 v164, 0x45800000, v163
	v_cndmask_b32_e64 v196, v163, v164, s[4:5]
	v_mul_f32_e32 v163, 0x4b800000, v162
	v_cndmask_b32_e32 v162, v162, v163, vcc
	v_rsq_f32_e32 v162, v162
	v_pk_mul_f32 v[102:103], v[102:103], v[198:199] op_sel_hi:[1,0]
	v_pk_mul_f32 v[108:109], v[108:109], v[198:199] op_sel_hi:[1,0]
	v_pk_mul_f32 v[98:99], v[98:99], v[198:199] op_sel_hi:[1,0]
	v_mul_f32_e32 v163, 0x45800000, v162
	v_cndmask_b32_e32 v192, v162, v163, vcc
	v_mov_b32_e32 v162, v142
	v_mov_b32_e32 v163, v138
	v_mov_b32_e32 v138, v143
	v_pk_add_f32 v[138:139], v[162:163], v[138:139]
	v_mov_b32_e32 v142, v144
	v_mov_b32_e32 v143, v140
	v_pk_add_f32 v[138:139], v[142:143], v[138:139]
	v_mov_b32_e32 v142, v134
	v_mov_b32_e32 v143, v130
	v_mov_b32_e32 v130, v135
	v_pk_add_f32 v[130:131], v[142:143], v[130:131]
	v_mov_b32_e32 v134, v136
	v_mov_b32_e32 v135, v132
	v_pk_add_f32 v[130:131], v[134:135], v[130:131]
	v_mov_b32_e32 v132, v137
	v_pk_add_f32 v[130:131], v[132:133], v[130:131]
	v_mul_f32_e32 v133, 0xbfb8aa3b, v126
	v_exp_f32_e32 v133, v133
	v_mov_b32_e32 v140, v145
	v_pk_add_f32 v[138:139], v[140:141], v[138:139]
	v_pk_fma_f32 v[130:131], v[130:131], s[72:73], v[202:203] op_sel_hi:[1,0,0]
	v_add_f32_e32 v133, 1.0, v133
	v_rcp_f32_e32 v136, v133
	v_mul_f32_e32 v133, 0xbfb8aa3b, v122
	v_exp_f32_e32 v133, v133
	v_pk_fma_f32 v[138:139], v[138:139], s[72:73], v[202:203] op_sel_hi:[1,0,0]
	v_mul_f32_e32 v132, 0x4b800000, v131
	v_mul_f32_e32 v140, 0x4b800000, v139
	v_add_f32_e32 v133, 1.0, v133
	v_rcp_f32_e32 v142, v133
	v_mul_f32_e32 v133, 0xbfb8aa3b, v127
	v_exp_f32_e32 v133, v133
	v_cmp_gt_f32_e64 s[4:5], s94, v139
	v_cmp_gt_f32_e32 vcc, s94, v138
	v_pk_mul_f32 v[112:113], v[112:113], v[198:199] op_sel_hi:[1,0]
	v_add_f32_e32 v133, 1.0, v133
	v_rcp_f32_e32 v137, v133
	v_cndmask_b32_e64 v139, v139, v140, s[4:5]
	v_rsq_f32_e32 v139, v139
	v_pk_mul_f32 v[104:105], v[104:105], v[198:199] op_sel_hi:[1,0]
	v_pk_mul_f32 v[126:127], v[126:127], v[136:137]
	v_pk_mul_f32 v[100:101], v[100:101], v[198:199] op_sel_hi:[1,0]
	v_pk_mul_f32 v[118:119], v[118:119], v[126:127]
	v_mul_f32_e32 v126, 0xbfb8aa3b, v123
	v_exp_f32_e32 v126, v126
	v_mul_f32_e32 v140, 0x45800000, v139
	v_cndmask_b32_e64 v140, v139, v140, s[4:5]
	v_mul_f32_e32 v139, 0x4b800000, v138
	v_add_f32_e32 v126, 1.0, v126
	v_rcp_f32_e32 v143, v126
	v_cmp_gt_f32_e64 s[4:5], s94, v131
	v_cndmask_b32_e32 v138, v138, v139, vcc
	v_rsq_f32_e32 v138, v138
	v_pk_mul_f32 v[122:123], v[122:123], v[142:143]
	v_cndmask_b32_e64 v131, v131, v132, s[4:5]
	v_pk_mul_f32 v[122:123], v[114:115], v[122:123]
	v_mul_f32_e32 v115, 0xbfb8aa3b, v124
	v_exp_f32_e32 v115, v115
	v_mul_f32_e32 v114, 0xbfb8aa3b, v128
	v_exp_f32_e32 v114, v114
	v_rsq_f32_e32 v131, v131
	v_add_f32_e32 v115, 1.0, v115
	v_rcp_f32_e32 v126, v115
	v_mul_f32_e32 v115, 0xbfb8aa3b, v129
	v_exp_f32_e32 v115, v115
	v_add_f32_e32 v114, 1.0, v114
	v_rcp_f32_e32 v114, v114
	v_mul_f32_e32 v139, 0x45800000, v138
	v_add_f32_e32 v115, 1.0, v115
	v_rcp_f32_e32 v115, v115
	v_mul_f32_e32 v132, 0x45800000, v131
	v_cndmask_b32_e32 v138, v138, v139, vcc
	v_cmp_gt_f32_e32 vcc, s94, v130
	v_pk_mul_f32 v[114:115], v[128:129], v[114:115]
	v_cndmask_b32_e64 v134, v131, v132, s[4:5]
	v_pk_mul_f32 v[120:121], v[120:121], v[114:115]
	v_mul_f32_e32 v114, 0xbfb8aa3b, v125
	v_exp_f32_e32 v114, v114
	v_mul_f32_e32 v131, 0x4b800000, v130
	v_cndmask_b32_e32 v130, v130, v131, vcc
	v_rsq_f32_e32 v130, v130
	v_add_f32_e32 v114, 1.0, v114
	v_rcp_f32_e32 v127, v114
	v_pk_mul_f32 v[90:91], v[90:91], v[196:197] op_sel_hi:[1,0]
	v_mul_f32_e32 v131, 0x45800000, v130
	v_cndmask_b32_e32 v132, v130, v131, vcc
	v_lshl_or_b32 v130, s86, 7, v199
	v_ashrrev_i32_e32 v131, 31, v130
	v_pk_mul_f32 v[114:115], v[124:125], v[126:127]
	v_lshl_add_u64 v[130:131], v[130:131], 1, s[28:29]
	v_pk_mul_f32 v[124:125], v[116:117], v[114:115]
	v_cvt_pk_bf16_f32 v114, v118, v119
	v_cvt_pk_bf16_f32 v115, v120, v121
	v_cvt_pk_bf16_f32 v116, v122, v123
	v_cvt_pk_bf16_f32 v117, v124, v125
	v_mad_i64_i32 v[118:119], s[0:1], v194, s35, v[130:131]
	global_store_dwordx4 v[118:119], v[114:117], off
	v_pk_mul_f32 v[94:95], v[94:95], v[196:197] op_sel_hi:[1,0]
	v_pk_mul_f32 v[86:87], v[86:87], v[196:197] op_sel_hi:[1,0]
	v_mul_f32_e32 v115, 0xbfb8aa3b, v106
	v_exp_f32_e32 v115, v115
	v_mul_f32_e32 v114, 0xbfb8aa3b, v110
	v_exp_f32_e32 v114, v114
	v_pk_mul_f32 v[92:93], v[92:93], v[196:197] op_sel_hi:[1,0]
	v_add_f32_e32 v115, 1.0, v115
	v_rcp_f32_e32 v116, v115
	v_mul_f32_e32 v115, 0xbfb8aa3b, v111
	v_exp_f32_e32 v115, v115
	v_add_f32_e32 v114, 1.0, v114
	v_rcp_f32_e32 v114, v114
	v_pk_mul_f32 v[82:83], v[82:83], v[196:197] op_sel_hi:[1,0]
	v_add_f32_e32 v115, 1.0, v115
	v_rcp_f32_e32 v115, v115
	v_pk_mul_f32 v[96:97], v[96:97], v[196:197] op_sel_hi:[1,0]
	v_pk_mul_f32 v[88:89], v[88:89], v[196:197] op_sel_hi:[1,0]
	v_pk_mul_f32 v[84:85], v[84:85], v[196:197] op_sel_hi:[1,0]
	v_pk_mul_f32 v[110:111], v[110:111], v[114:115]
	v_pk_mul_f32 v[74:75], v[74:75], v[192:193] op_sel_hi:[1,0]
	v_pk_mul_f32 v[102:103], v[102:103], v[110:111]
	v_mul_f32_e32 v110, 0xbfb8aa3b, v107
; template <class Epi>
; DEVI void gemm_phase(LAS unsigned char* lds, const Gemm g, const Epi& E) {
;     ...
;                     const int r = row0 + ai * HALF + m * 16; float rs = 1.f, part = 0.f;
;                     if constexpr (Epi::RS) rs = rsv[ai * 4 + m];
;                     if constexpr (Epi::PAIR) E.pair8(cur.b, r, cur.pn * HALF + wc * 32 + 8 * fq, acc[ai][0][m][0] * rs, acc[ai][0][m][1] * rs, acc[ai][1][m][0] * rs, acc[ai][1][m][1] * rs);
	v_exp_f32_e32 v110, v110
	v_pk_mul_f32 v[78:79], v[78:79], v[192:193] op_sel_hi:[1,0]
	v_pk_mul_f32 v[70:71], v[70:71], v[192:193] op_sel_hi:[1,0]
	v_pk_mul_f32 v[76:77], v[76:77], v[192:193] op_sel_hi:[1,0]
	v_add_f32_e32 v110, 1.0, v110
	v_rcp_f32_e32 v117, v110
	v_pk_mul_f32 v[66:67], v[66:67], v[192:193] op_sel_hi:[1,0]
	v_pk_mul_f32 v[80:81], v[80:81], v[192:193] op_sel_hi:[1,0]
	v_pk_mul_f32 v[72:73], v[72:73], v[192:193] op_sel_hi:[1,0]
	v_pk_mul_f32 v[106:107], v[106:107], v[116:117]
	v_pk_mul_f32 v[68:69], v[68:69], v[192:193] op_sel_hi:[1,0]
	v_pk_mul_f32 v[106:107], v[98:99], v[106:107]
	v_mul_f32_e32 v99, 0xbfb8aa3b, v108
	v_exp_f32_e32 v99, v99
	v_mul_f32_e32 v98, 0xbfb8aa3b, v112
	v_exp_f32_e32 v98, v98
	v_pk_mul_f32 v[54:55], v[54:55], v[140:141] op_sel_hi:[1,0]
	v_add_f32_e32 v99, 1.0, v99
	v_rcp_f32_e32 v110, v99
	v_mul_f32_e32 v99, 0xbfb8aa3b, v113
	v_exp_f32_e32 v99, v99
	v_add_f32_e32 v98, 1.0, v98
	v_rcp_f32_e32 v98, v98
	v_pk_mul_f32 v[50:51], v[50:51], v[140:141] op_sel_hi:[1,0]
	v_add_f32_e32 v99, 1.0, v99
	v_rcp_f32_e32 v99, v99
	v_pk_mul_f32 v[58:59], v[58:59], v[140:141] op_sel_hi:[1,0]
	v_pk_mul_f32 v[56:57], v[56:57], v[140:141] op_sel_hi:[1,0]
	v_pk_mul_f32 v[52:53], v[52:53], v[140:141] op_sel_hi:[1,0]
	v_pk_mul_f32 v[98:99], v[112:113], v[98:99]
	v_pk_mul_f32 v[62:63], v[62:63], v[140:141] op_sel_hi:[1,0]
	v_pk_mul_f32 v[104:105], v[104:105], v[98:99]
	v_mul_f32_e32 v98, 0xbfb8aa3b, v109
	v_exp_f32_e32 v98, v98
	v_pk_mul_f32 v[60:61], v[60:61], v[140:141] op_sel_hi:[1,0]
	v_pk_mul_f32 v[64:65], v[64:65], v[140:141] op_sel_hi:[1,0]
	v_pk_mul_f32 v[38:39], v[38:39], v[138:139] op_sel_hi:[1,0]
	v_add_f32_e32 v98, 1.0, v98
	v_rcp_f32_e32 v111, v98
	v_pk_mul_f32 v[34:35], v[34:35], v[138:139] op_sel_hi:[1,0]
	v_pk_mul_f32 v[42:43], v[42:43], v[138:139] op_sel_hi:[1,0]
	v_pk_mul_f32 v[40:41], v[40:41], v[138:139] op_sel_hi:[1,0]
	v_pk_mul_f32 v[98:99], v[108:109], v[110:111]
	v_pk_mul_f32 v[36:37], v[36:37], v[138:139] op_sel_hi:[1,0]
	v_pk_mul_f32 v[108:109], v[100:101], v[98:99]
	v_cvt_pk_bf16_f32 v98, v102, v103
	v_cvt_pk_bf16_f32 v99, v104, v105
	v_cvt_pk_bf16_f32 v100, v106, v107
	v_cvt_pk_bf16_f32 v101, v108, v109
	v_mad_i64_i32 v[102:103], s[0:1], v190, s35, v[130:131]
	global_store_dwordx4 v[102:103], v[98:101], off
	v_pk_mul_f32 v[46:47], v[46:47], v[138:139] op_sel_hi:[1,0]
	v_pk_mul_f32 v[44:45], v[44:45], v[138:139] op_sel_hi:[1,0]
	v_mul_f32_e32 v99, 0xbfb8aa3b, v90
	v_exp_f32_e32 v99, v99
	v_mul_f32_e32 v98, 0xbfb8aa3b, v94
	v_exp_f32_e32 v98, v98
	v_pk_mul_f32 v[48:49], v[48:49], v[138:139] op_sel_hi:[1,0]
	v_add_f32_e32 v99, 1.0, v99
	v_rcp_f32_e32 v100, v99
	v_mul_f32_e32 v99, 0xbfb8aa3b, v95
	v_exp_f32_e32 v99, v99
	v_add_f32_e32 v98, 1.0, v98
	v_rcp_f32_e32 v98, v98
	v_pk_mul_f32 v[22:23], v[22:23], v[134:135] op_sel_hi:[1,0]
	v_add_f32_e32 v99, 1.0, v99
	v_rcp_f32_e32 v99, v99
	v_pk_mul_f32 v[18:19], v[18:19], v[134:135] op_sel_hi:[1,0]
	v_pk_mul_f32 v[26:27], v[26:27], v[134:135] op_sel_hi:[1,0]
	v_pk_mul_f32 v[24:25], v[24:25], v[134:135] op_sel_hi:[1,0]
	v_pk_mul_f32 v[94:95], v[94:95], v[98:99]
	v_pk_mul_f32 v[20:21], v[20:21], v[134:135] op_sel_hi:[1,0]
	v_pk_mul_f32 v[86:87], v[86:87], v[94:95]
	v_mul_f32_e32 v94, 0xbfb8aa3b, v91
	v_exp_f32_e32 v94, v94
	v_pk_mul_f32 v[30:31], v[30:31], v[134:135] op_sel_hi:[1,0]
	v_pk_mul_f32 v[28:29], v[28:29], v[134:135] op_sel_hi:[1,0]
	v_pk_mul_f32 v[32:33], v[32:33], v[134:135] op_sel_hi:[1,0]
	v_add_f32_e32 v94, 1.0, v94
	v_rcp_f32_e32 v101, v94
	v_pk_mul_f32 v[4:5], v[4:5], v[132:133] op_sel_hi:[1,0]
	v_pk_mul_f32 v[0:1], v[0:1], v[132:133] op_sel_hi:[1,0]
	v_pk_mul_f32 v[10:11], v[10:11], v[132:133] op_sel_hi:[1,0]
	v_pk_mul_f32 v[90:91], v[90:91], v[100:101]
	v_pk_mul_f32 v[6:7], v[6:7], v[132:133] op_sel_hi:[1,0]
	v_pk_mul_f32 v[90:91], v[82:83], v[90:91]
	v_mul_f32_e32 v83, 0xbfb8aa3b, v92
	v_exp_f32_e32 v83, v83
	v_mul_f32_e32 v82, 0xbfb8aa3b, v96
	v_exp_f32_e32 v82, v82
	v_pk_mul_f32 v[2:3], v[2:3], v[132:133] op_sel_hi:[1,0]
	v_add_f32_e32 v83, 1.0, v83
	v_rcp_f32_e32 v94, v83
	v_mul_f32_e32 v83, 0xbfb8aa3b, v97
	v_exp_f32_e32 v83, v83
	v_add_f32_e32 v82, 1.0, v82
	v_rcp_f32_e32 v82, v82
	v_pk_mul_f32 v[14:15], v[14:15], v[132:133] op_sel_hi:[1,0]
	v_add_f32_e32 v83, 1.0, v83
	v_rcp_f32_e32 v83, v83
	v_pk_mul_f32 v[12:13], v[12:13], v[132:133] op_sel_hi:[1,0]
	v_pk_mul_f32 v[16:17], v[16:17], v[132:133] op_sel_hi:[1,0]
	s_and_b64 vcc, exec, s[2:3]
	v_pk_mul_f32 v[82:83], v[96:97], v[82:83]
	s_mov_b32 s86, s8
	v_pk_mul_f32 v[88:89], v[88:89], v[82:83]
	v_mul_f32_e32 v82, 0xbfb8aa3b, v93
	v_exp_f32_e32 v82, v82
	s_mov_b32 s4, s6
	v_add_f32_e32 v82, 1.0, v82
	v_rcp_f32_e32 v95, v82
	s_nop 0
	v_pk_mul_f32 v[82:83], v[92:93], v[94:95]
	s_nop 0
	v_pk_mul_f32 v[92:93], v[84:85], v[82:83]
	v_cvt_pk_bf16_f32 v82, v86, v87
	v_cvt_pk_bf16_f32 v83, v88, v89
	v_cvt_pk_bf16_f32 v84, v90, v91
	v_cvt_pk_bf16_f32 v85, v92, v93
	v_mad_i64_i32 v[86:87], s[0:1], v188, s35, v[130:131]
	global_store_dwordx4 v[86:87], v[82:85], off
	s_nop 1
	v_mul_f32_e32 v83, 0xbfb8aa3b, v74
	v_exp_f32_e32 v83, v83
	v_mul_f32_e32 v82, 0xbfb8aa3b, v78
	v_exp_f32_e32 v82, v82
	v_add_f32_e32 v83, 1.0, v83
	v_rcp_f32_e32 v84, v83
	v_mul_f32_e32 v83, 0xbfb8aa3b, v79
	v_exp_f32_e32 v83, v83
	v_add_f32_e32 v82, 1.0, v82
	v_rcp_f32_e32 v82, v82
	v_add_f32_e32 v83, 1.0, v83
	v_rcp_f32_e32 v83, v83
	s_nop 0
	v_pk_mul_f32 v[78:79], v[78:79], v[82:83]
	s_nop 0
	v_pk_mul_f32 v[70:71], v[70:71], v[78:79]
	v_mul_f32_e32 v78, 0xbfb8aa3b, v75
	v_exp_f32_e32 v78, v78
	s_nop 0
	v_add_f32_e32 v78, 1.0, v78
	v_rcp_f32_e32 v85, v78
	s_nop 0
	v_pk_mul_f32 v[74:75], v[74:75], v[84:85]
	s_nop 0
	v_pk_mul_f32 v[74:75], v[66:67], v[74:75]
	v_mul_f32_e32 v67, 0xbfb8aa3b, v76
	v_exp_f32_e32 v67, v67
	v_mul_f32_e32 v66, 0xbfb8aa3b, v80
	v_exp_f32_e32 v66, v66
	v_add_f32_e32 v67, 1.0, v67
	v_rcp_f32_e32 v78, v67
	v_mul_f32_e32 v67, 0xbfb8aa3b, v81
	v_exp_f32_e32 v67, v67
	v_add_f32_e32 v66, 1.0, v66
	v_rcp_f32_e32 v66, v66
	v_add_f32_e32 v67, 1.0, v67
	v_rcp_f32_e32 v67, v67
	s_nop 0
	v_pk_mul_f32 v[66:67], v[80:81], v[66:67]
	s_nop 0
	v_pk_mul_f32 v[72:73], v[72:73], v[66:67]
	v_mul_f32_e32 v66, 0xbfb8aa3b, v77
	v_exp_f32_e32 v66, v66
	s_nop 0
	v_add_f32_e32 v66, 1.0, v66
	v_rcp_f32_e32 v79, v66
	s_nop 0
	v_pk_mul_f32 v[66:67], v[76:77], v[78:79]
	s_nop 0
	v_pk_mul_f32 v[76:77], v[68:69], v[66:67]
	v_cvt_pk_bf16_f32 v66, v70, v71
	v_cvt_pk_bf16_f32 v67, v72, v73
	v_cvt_pk_bf16_f32 v68, v74, v75
	v_cvt_pk_bf16_f32 v69, v76, v77
	v_mad_i64_i32 v[70:71], s[0:1], v186, s35, v[130:131]
	global_store_dwordx4 v[70:71], v[66:69], off
	s_nop 1
	v_mul_f32_e32 v67, 0xbfb8aa3b, v54
	v_exp_f32_e32 v67, v67
	v_mul_f32_e32 v66, 0xbfb8aa3b, v50
	v_exp_f32_e32 v66, v66
	v_add_f32_e32 v67, 1.0, v67
	v_rcp_f32_e32 v68, v67
	v_mul_f32_e32 v67, 0xbfb8aa3b, v51
	v_exp_f32_e32 v67, v67
	v_add_f32_e32 v66, 1.0, v66
	v_rcp_f32_e32 v66, v66
	v_add_f32_e32 v67, 1.0, v67
	v_rcp_f32_e32 v67, v67
	s_nop 0
	v_pk_mul_f32 v[50:51], v[50:51], v[66:67]
	s_nop 0
	v_pk_mul_f32 v[50:51], v[58:59], v[50:51]
	v_mul_f32_e32 v58, 0xbfb8aa3b, v55
	v_exp_f32_e32 v58, v58
	v_mul_f32_e32 v59, 0xbfb8aa3b, v56
	v_exp_f32_e32 v59, v59
	v_cvt_pk_bf16_f32 v50, v50, v51
	v_add_f32_e32 v58, 1.0, v58
	v_rcp_f32_e32 v69, v58
	v_add_f32_e32 v59, 1.0, v59
	v_mul_f32_e32 v58, 0xbfb8aa3b, v52
	v_exp_f32_e32 v58, v58
	v_pk_mul_f32 v[54:55], v[54:55], v[68:69]
	v_add_f32_e32 v58, 1.0, v58
	v_pk_mul_f32 v[54:55], v[62:63], v[54:55]
	v_rcp_f32_e32 v62, v59
	v_mul_f32_e32 v59, 0xbfb8aa3b, v53
	v_exp_f32_e32 v59, v59
	v_rcp_f32_e32 v58, v58
	v_add_f32_e32 v59, 1.0, v59
	v_rcp_f32_e32 v59, v59
	s_nop 0
	v_pk_mul_f32 v[52:53], v[52:53], v[58:59]
	v_mul_f32_e32 v58, 0xbfb8aa3b, v57
	v_exp_f32_e32 v58, v58
	v_pk_mul_f32 v[52:53], v[60:61], v[52:53]
	v_add_f32_e32 v58, 1.0, v58
	v_rcp_f32_e32 v63, v58
	v_cvt_pk_bf16_f32 v51, v52, v53
	v_cvt_pk_bf16_f32 v52, v54, v55
	v_mad_i64_i32 v[54:55], s[0:1], v184, s35, v[130:131]
	v_pk_mul_f32 v[56:57], v[56:57], v[62:63]
	s_nop 0
	v_pk_mul_f32 v[56:57], v[64:65], v[56:57]
	s_nop 0
	v_cvt_pk_bf16_f32 v53, v56, v57
	global_store_dwordx4 v[54:55], v[50:53], off
	s_nop 1
	v_mul_f32_e32 v51, 0xbfb8aa3b, v38
	v_exp_f32_e32 v51, v51
	v_mul_f32_e32 v50, 0xbfb8aa3b, v34
	v_exp_f32_e32 v50, v50
	v_add_f32_e32 v51, 1.0, v51
	v_rcp_f32_e32 v52, v51
	v_mul_f32_e32 v51, 0xbfb8aa3b, v35
	v_exp_f32_e32 v51, v51
	v_add_f32_e32 v50, 1.0, v50
	v_rcp_f32_e32 v50, v50
	v_add_f32_e32 v51, 1.0, v51
	v_rcp_f32_e32 v51, v51
	s_nop 0
	v_pk_mul_f32 v[34:35], v[34:35], v[50:51]
	s_nop 0
	v_pk_mul_f32 v[34:35], v[42:43], v[34:35]
	v_mul_f32_e32 v42, 0xbfb8aa3b, v39
	v_exp_f32_e32 v42, v42
	v_mul_f32_e32 v43, 0xbfb8aa3b, v40
	v_exp_f32_e32 v43, v43
	v_cvt_pk_bf16_f32 v34, v34, v35
	v_add_f32_e32 v42, 1.0, v42
	v_rcp_f32_e32 v53, v42
	v_add_f32_e32 v43, 1.0, v43
	v_mul_f32_e32 v42, 0xbfb8aa3b, v36
	v_exp_f32_e32 v42, v42
	v_pk_mul_f32 v[38:39], v[38:39], v[52:53]
	v_add_f32_e32 v42, 1.0, v42
	v_pk_mul_f32 v[38:39], v[46:47], v[38:39]
	v_rcp_f32_e32 v46, v43
	v_mul_f32_e32 v43, 0xbfb8aa3b, v37
	v_exp_f32_e32 v43, v43
	v_rcp_f32_e32 v42, v42
	v_add_f32_e32 v43, 1.0, v43
	v_rcp_f32_e32 v43, v43
	s_nop 0
	v_pk_mul_f32 v[36:37], v[36:37], v[42:43]
; #define PG8_WAIT_V(n) asm volatile("s_waitcnt vmcnt(" #n ")" ::: "memory")
; #define PG8_BAR __builtin_amdgcn_s_barrier()
; template <class Epi>
; DEVI void gemm_phase(LAS unsigned char* lds, const Gemm g, const Epi& E) {
;     ...
;         if (!has_next) break;
; #pragma unroll
;         for (int a = 0; a < 2; ++a)
; #pragma unroll
;             for (int b = 0; b < 2; ++b)
; #pragma unroll
;                 for (int m = 0; m < 4; ++m)
; #pragma unroll
;                     for (int n = 0; n < 2; ++n) acc[a][b][m][n] = (f32x4){0.f, 0.f, 0.f, 0.f};
;         cur = nxt; cA = nA; cB = nB; ++ui;
;     }
;     PG8_WAIT_V(0);
;     if (wr == 0) PG8_BAR;
;     PG8_BAR;
	v_mul_f32_e32 v42, 0xbfb8aa3b, v41
	v_exp_f32_e32 v42, v42
	v_pk_mul_f32 v[36:37], v[44:45], v[36:37]
	v_add_f32_e32 v42, 1.0, v42
	v_rcp_f32_e32 v47, v42
	v_cvt_pk_bf16_f32 v35, v36, v37
	v_cvt_pk_bf16_f32 v36, v38, v39
	v_mad_i64_i32 v[38:39], s[0:1], v182, s35, v[130:131]
	v_pk_mul_f32 v[40:41], v[40:41], v[46:47]
	s_nop 0
	v_pk_mul_f32 v[40:41], v[48:49], v[40:41]
	s_nop 0
	v_cvt_pk_bf16_f32 v37, v40, v41
	global_store_dwordx4 v[38:39], v[34:37], off
	s_nop 1
	v_mul_f32_e32 v35, 0xbfb8aa3b, v22
	v_exp_f32_e32 v35, v35
	v_mul_f32_e32 v34, 0xbfb8aa3b, v18
	v_exp_f32_e32 v34, v34
	v_add_f32_e32 v35, 1.0, v35
	v_rcp_f32_e32 v36, v35
	v_mul_f32_e32 v35, 0xbfb8aa3b, v19
	v_exp_f32_e32 v35, v35
	v_add_f32_e32 v34, 1.0, v34
	v_rcp_f32_e32 v34, v34
	v_add_f32_e32 v35, 1.0, v35
	v_rcp_f32_e32 v35, v35
	s_nop 0
	v_pk_mul_f32 v[18:19], v[18:19], v[34:35]
	s_nop 0
	v_pk_mul_f32 v[18:19], v[26:27], v[18:19]
	v_mul_f32_e32 v26, 0xbfb8aa3b, v23
	v_exp_f32_e32 v26, v26
	v_mul_f32_e32 v27, 0xbfb8aa3b, v24
	v_exp_f32_e32 v27, v27
	v_cvt_pk_bf16_f32 v18, v18, v19
	v_add_f32_e32 v26, 1.0, v26
	v_rcp_f32_e32 v37, v26
	v_add_f32_e32 v27, 1.0, v27
	v_mul_f32_e32 v26, 0xbfb8aa3b, v20
	v_exp_f32_e32 v26, v26
	v_pk_mul_f32 v[22:23], v[22:23], v[36:37]
	v_add_f32_e32 v26, 1.0, v26
	v_pk_mul_f32 v[22:23], v[30:31], v[22:23]
	v_rcp_f32_e32 v30, v27
	v_mul_f32_e32 v27, 0xbfb8aa3b, v21
	v_exp_f32_e32 v27, v27
	v_rcp_f32_e32 v26, v26
	v_add_f32_e32 v27, 1.0, v27
	v_rcp_f32_e32 v27, v27
	s_nop 0
	v_pk_mul_f32 v[20:21], v[20:21], v[26:27]
	v_mul_f32_e32 v26, 0xbfb8aa3b, v25
	v_exp_f32_e32 v26, v26
	v_pk_mul_f32 v[20:21], v[28:29], v[20:21]
	v_add_f32_e32 v26, 1.0, v26
	v_rcp_f32_e32 v31, v26
	v_cvt_pk_bf16_f32 v19, v20, v21
	v_cvt_pk_bf16_f32 v20, v22, v23
	v_mad_i64_i32 v[22:23], s[0:1], v180, s35, v[130:131]
	v_pk_mul_f32 v[24:25], v[24:25], v[30:31]
	s_nop 0
	v_pk_mul_f32 v[24:25], v[32:33], v[24:25]
	s_nop 0
	v_cvt_pk_bf16_f32 v21, v24, v25
	global_store_dwordx4 v[22:23], v[18:21], off
	s_nop 1
	v_mul_f32_e32 v19, 0xbfb8aa3b, v4
	v_exp_f32_e32 v19, v19
	v_mul_f32_e32 v18, 0xbfb8aa3b, v0
	v_exp_f32_e32 v18, v18
	v_add_f32_e32 v19, 1.0, v19
	v_rcp_f32_e32 v20, v19
	v_mul_f32_e32 v19, 0xbfb8aa3b, v1
	v_exp_f32_e32 v19, v19
	v_add_f32_e32 v18, 1.0, v18
	v_rcp_f32_e32 v18, v18
	v_add_f32_e32 v19, 1.0, v19
	v_rcp_f32_e32 v19, v19
	s_nop 0
	v_pk_mul_f32 v[0:1], v[0:1], v[18:19]
	s_nop 0
	v_pk_mul_f32 v[0:1], v[10:11], v[0:1]
	v_mul_f32_e32 v10, 0xbfb8aa3b, v5
	v_exp_f32_e32 v10, v10
	v_mul_f32_e32 v11, 0xbfb8aa3b, v6
	v_exp_f32_e32 v11, v11
	v_cvt_pk_bf16_f32 v0, v0, v1
	v_add_f32_e32 v10, 1.0, v10
	v_rcp_f32_e32 v21, v10
	v_add_f32_e32 v11, 1.0, v11
	v_mul_f32_e32 v10, 0xbfb8aa3b, v2
	v_exp_f32_e32 v10, v10
	v_pk_mul_f32 v[4:5], v[4:5], v[20:21]
	v_add_f32_e32 v10, 1.0, v10
	v_pk_mul_f32 v[4:5], v[14:15], v[4:5]
	v_rcp_f32_e32 v14, v11
	v_mul_f32_e32 v11, 0xbfb8aa3b, v3
	v_exp_f32_e32 v11, v11
	v_rcp_f32_e32 v10, v10
	v_add_f32_e32 v11, 1.0, v11
	v_rcp_f32_e32 v11, v11
	s_nop 0
	v_pk_mul_f32 v[2:3], v[2:3], v[10:11]
	v_mul_f32_e32 v10, 0xbfb8aa3b, v7
	v_exp_f32_e32 v10, v10
	v_pk_mul_f32 v[2:3], v[12:13], v[2:3]
	v_add_f32_e32 v10, 1.0, v10
	v_rcp_f32_e32 v15, v10
	v_cvt_pk_bf16_f32 v1, v2, v3
	v_cvt_pk_bf16_f32 v2, v4, v5
	v_mad_i64_i32 v[4:5], s[0:1], v178, s35, v[130:131]
	v_pk_mul_f32 v[6:7], v[6:7], v[14:15]
	s_nop 0
	v_pk_mul_f32 v[6:7], v[16:17], v[6:7]
	s_nop 0
	v_cvt_pk_bf16_f32 v3, v6, v7
	global_store_dwordx4 v[4:5], v[0:3], off
	s_cbranch_vccz .LBB0_1669
	s_waitcnt vmcnt(0)
	s_cmpk_gt_u32 s66, 0xff
	s_cbranch_scc1 .LBB0_1676
	s_barrier

; #define PG8_STAGE(bufoff, gbase, voff) do { _Pragma("unroll") for (int _i = 0; _i < 2; ++_i) \
;         __builtin_amdgcn_global_load_lds((const unsigned*)((const char*)(gbase) + (voff)[_i]), (LAS unsigned*)(lds + (bufoff) + ldsw + _i * 8192), 16, 0, 0); } while (0)
; #define PG8_LDA(dst, b, h) do { _Pragma("unroll") for (int m = 0; m < 4; ++m) _Pragma("unroll") for (int k = 0; k < 2; ++k) dst[m][k] = *(const LAS bf16x8*)(lds + PG8_SA(b, h) + aoff + m * 2048 + k * 1024); } while (0)
; #define PG8_LDB(dst, b, h) do { _Pragma("unroll") for (int n = 0; n < 2; ++n) _Pragma("unroll") for (int k = 0; k < 2; ++k) dst[n][k] = *(const LAS bf16x8*)(lds + PG8_SB(b, h) + boff + n * 2048 + k * 1024); } while (0)
; #define PG8_MMA(ai, bj, At, Bt) do { __builtin_amdgcn_s_setprio(1); _Pragma("unroll") for (int m = 0; m < 4; ++m) _Pragma("unroll") for (int n = 0; n < 2; ++n) _Pragma("unroll") for (int k = 0; k < 2; ++k) \
;         acc[ai][bj][m][n] = __builtin_amdgcn_mfma_f32_16x16x32_bf16(Bt[n][k], At[m][k], acc[ai][bj][m][n], 0, 0, 0); __builtin_amdgcn_s_setprio(0); } while (0)
; #define PG8_WAIT_V(n) asm volatile("s_waitcnt vmcnt(" #n ")" ::: "memory")
; #define PG8_WAIT_L(n) asm volatile("s_waitcnt lgkmcnt(" #n ")" ::: "memory")
; #define PG8_BAR __builtin_amdgcn_s_barrier()
; #define PG8_SCHED __builtin_amdgcn_sched_barrier(0)
; template <class Epi>
; DEVI void gemm_phase(LAS unsigned char* lds, const Gemm g, const Epi& E) {
;     ...
;             const bool last = (t == nt - 2);
;             const char* a1 = cA + (size_t)(t + 1) * kstep;
;             const char* a2 = last ? nA : cA + (size_t)(t + 2) * kstep; const char* b2 = last ? nB : cB + (size_t)(t + 2) * kstep;
;             const char* a3 = a2 + kstep; const char* b3 = b2 + kstep;
;             PG8_LDB(B0, 0, 0); PG8_SCHED; PG8_LDA(At, 0, 0); PG8_STAGE(PG8_SA(1, 1), a1 + hstepA, voffA);
;             PG8_WAIT_L(8); PG8_BAR; PG8_WAIT_L(0); PG8_MMA(0, 0, At, B0); PG8_BAR; PG8_SCHED;
;             PG8_LDB(B1, 0, 1); PG8_STAGE(PG8_SB(0, 0), b2, voffB);
;             PG8_BAR; PG8_WAIT_L(0); PG8_MMA(0, 1, At, B1); PG8_BAR;
;             PG8_LDA(At, 0, 1); PG8_STAGE(PG8_SA(0, 0), a2, voffA);
;             PG8_BAR; PG8_WAIT_L(0); PG8_MMA(1, 0, At, B0); PG8_BAR; PG8_SCHED;
;             PG8_STAGE(PG8_SB(0, 1), b2 + hstepB, voffB);
;             PG8_WAIT_V(6); PG8_BAR; PG8_MMA(1, 1, At, B1); PG8_BAR;
.LBB0_1747:
	s_add_u32 s36, s16, 0x100
	s_addc_u32 s37, s17, 0
	s_add_i32 s19, 0, 0x10000
	v_add_u32_e32 v142, s19, v191
	ds_read_b128 v[130:133], v142
	ds_read_b128 v[134:137], v142 offset:1024
	ds_read_b128 v[138:141], v142 offset:2048
	ds_read_b128 v[142:145], v142 offset:3072
	s_cmp_eq_u32 s18, 40
	s_cselect_b32 s69, s9, s37
	s_cselect_b32 s68, s8, s36
	s_cselect_b32 s47, s11, s13
	s_cselect_b32 s46, s10, s1
	v_lshl_add_u64 v[162:163], s[16:17], 0, v[152:153]
	s_add_i32 m0, s81, 0xc000
	ds_read_b128 v[178:181], v196
	ds_read_b128 v[182:185], v196 offset:1024
	ds_read_b128 v[186:189], v196 offset:2048
	ds_read_b128 v[198:201], v196 offset:3072
	ds_read_b128 v[202:205], v196 offset:4096
	ds_read_b128 v[206:209], v196 offset:5120
	ds_read_b128 v[214:217], v196 offset:6144
	ds_read_b128 v[218:221], v196 offset:7168
	global_load_lds_dwordx4 v[162:163], off
	s_add_i32 m0, s81, 0xe000
	v_lshl_add_u64 v[162:163], s[16:17], 0, v[176:177]
	global_load_lds_dwordx4 v[162:163], off
	s_waitcnt lgkmcnt(0)
	s_barrier
	v_mfma_f32_16x16x32_bf16 v[126:129], v[130:133], v[178:181], v[126:129]
	v_mfma_f32_16x16x32_bf16 v[122:125], v[138:141], v[178:181], v[122:125]
	v_mfma_f32_16x16x32_bf16 v[110:113], v[130:133], v[186:189], v[110:113]
	v_mfma_f32_16x16x32_bf16 v[106:109], v[138:141], v[186:189], v[106:109]
	v_mfma_f32_16x16x32_bf16 v[94:97], v[130:133], v[202:205], v[94:97]
	v_mfma_f32_16x16x32_bf16 v[90:93], v[138:141], v[202:205], v[90:93]
	v_mfma_f32_16x16x32_bf16 v[78:81], v[130:133], v[214:217], v[78:81]
	v_mfma_f32_16x16x32_bf16 v[74:77], v[138:141], v[214:217], v[74:77]
	v_mfma_f32_16x16x32_bf16 v[126:129], v[134:137], v[182:185], v[126:129]
	v_mfma_f32_16x16x32_bf16 v[122:125], v[142:145], v[182:185], v[122:125]
	v_mfma_f32_16x16x32_bf16 v[110:113], v[134:137], v[198:201], v[110:113]
	v_mfma_f32_16x16x32_bf16 v[106:109], v[142:145], v[198:201], v[106:109]
	v_mfma_f32_16x16x32_bf16 v[94:97], v[134:137], v[206:209], v[94:97]
	v_mfma_f32_16x16x32_bf16 v[90:93], v[142:145], v[206:209], v[90:93]
	v_mfma_f32_16x16x32_bf16 v[78:81], v[134:137], v[218:221], v[78:81]
	v_mfma_f32_16x16x32_bf16 v[74:77], v[142:145], v[218:221], v[74:77]
	s_barrier
	s_add_i32 s26, 0, 0x14000
	v_add_u32_e32 v162, s26, v191
	s_add_i32 s16, s19, s80
	ds_read_b128 v[222:225], v162
	ds_read_b128 v[226:229], v162 offset:1024
	ds_read_b128 v[230:233], v162 offset:2048
	ds_read_b128 v[234:237], v162 offset:3072
	v_lshl_add_u64 v[162:163], s[46:47], 0, v[8:9]
	s_mov_b32 m0, s16
	v_lshl_add_u64 v[164:165], s[46:47], 0, v[150:151]
	global_load_lds_dwordx4 v[162:163], off
	s_add_i32 m0, s16, 0x2000
	s_nop 0
	global_load_lds_dwordx4 v[164:165], off
	s_waitcnt lgkmcnt(0)
	s_barrier
	v_mfma_f32_16x16x32_bf16 v[118:121], v[222:225], v[178:181], v[118:121]
	v_mfma_f32_16x16x32_bf16 v[114:117], v[230:233], v[178:181], v[114:117]
	v_mfma_f32_16x16x32_bf16 v[102:105], v[222:225], v[186:189], v[102:105]
	v_mfma_f32_16x16x32_bf16 v[98:101], v[230:233], v[186:189], v[98:101]
	v_mfma_f32_16x16x32_bf16 v[86:89], v[222:225], v[202:205], v[86:89]
	v_mfma_f32_16x16x32_bf16 v[82:85], v[230:233], v[202:205], v[82:85]
	v_mfma_f32_16x16x32_bf16 v[70:73], v[222:225], v[214:217], v[70:73]
	v_mfma_f32_16x16x32_bf16 v[66:69], v[230:233], v[214:217], v[66:69]
	v_mfma_f32_16x16x32_bf16 v[118:121], v[226:229], v[182:185], v[118:121]
	v_mfma_f32_16x16x32_bf16 v[114:117], v[234:237], v[182:185], v[114:117]
	v_mfma_f32_16x16x32_bf16 v[102:105], v[226:229], v[198:201], v[102:105]
	v_mfma_f32_16x16x32_bf16 v[98:101], v[234:237], v[198:201], v[98:101]
	v_mfma_f32_16x16x32_bf16 v[86:89], v[226:229], v[206:209], v[86:89]
	v_mfma_f32_16x16x32_bf16 v[82:85], v[234:237], v[206:209], v[82:85]
	v_mfma_f32_16x16x32_bf16 v[70:73], v[226:229], v[218:221], v[70:73]
	v_mfma_f32_16x16x32_bf16 v[66:69], v[234:237], v[218:221], v[66:69]
	s_mov_b32 m0, s81
	v_lshl_add_u64 v[238:239], s[68:69], 0, v[146:147]
	s_barrier
	ds_read_b128 v[178:181], v196 offset:16384
	ds_read_b128 v[182:185], v196 offset:17408
	ds_read_b128 v[186:189], v196 offset:18432
	ds_read_b128 v[198:201], v196 offset:19456
	ds_read_b128 v[202:205], v196 offset:20480
	ds_read_b128 v[206:209], v196 offset:21504
	ds_read_b128 v[214:217], v196 offset:22528
	ds_read_b128 v[218:221], v196 offset:23552
	global_load_lds_dwordx4 v[238:239], off
	s_mov_b32 m0, s82
	v_lshl_add_u64 v[240:241], s[68:69], 0, v[148:149]
	global_load_lds_dwordx4 v[240:241], off
	s_waitcnt lgkmcnt(0)
	s_barrier
	v_mfma_f32_16x16x32_bf16 v[62:65], v[130:133], v[178:181], v[62:65]
	v_mfma_f32_16x16x32_bf16 v[58:61], v[138:141], v[178:181], v[58:61]
	v_mfma_f32_16x16x32_bf16 v[46:49], v[130:133], v[186:189], v[46:49]
	v_mfma_f32_16x16x32_bf16 v[42:45], v[138:141], v[186:189], v[42:45]
	v_mfma_f32_16x16x32_bf16 v[30:33], v[130:133], v[202:205], v[30:33]
	v_mfma_f32_16x16x32_bf16 v[26:29], v[138:141], v[202:205], v[26:29]
	v_mfma_f32_16x16x32_bf16 v[14:17], v[130:133], v[214:217], v[14:17]
	v_mfma_f32_16x16x32_bf16 v[10:13], v[138:141], v[214:217], v[10:13]
	v_mfma_f32_16x16x32_bf16 v[62:65], v[134:137], v[182:185], v[62:65]
	v_mfma_f32_16x16x32_bf16 v[58:61], v[142:145], v[182:185], v[58:61]
	v_mfma_f32_16x16x32_bf16 v[46:49], v[134:137], v[198:201], v[46:49]
	v_mfma_f32_16x16x32_bf16 v[42:45], v[142:145], v[198:201], v[42:45]
	v_mfma_f32_16x16x32_bf16 v[30:33], v[134:137], v[206:209], v[30:33]
	v_mfma_f32_16x16x32_bf16 v[26:29], v[142:145], v[206:209], v[26:29]
	v_mfma_f32_16x16x32_bf16 v[14:17], v[134:137], v[218:221], v[14:17]
	v_mfma_f32_16x16x32_bf16 v[10:13], v[142:145], v[218:221], v[10:13]
	s_barrier
; #define PG8_STAGE(bufoff, gbase, voff) do { _Pragma("unroll") for (int _i = 0; _i < 2; ++_i) \
;         __builtin_amdgcn_global_load_lds((const unsigned*)((const char*)(gbase) + (voff)[_i]), (LAS unsigned*)(lds + (bufoff) + ldsw + _i * 8192), 16, 0, 0); } while (0)
; #define PG8_LDA(dst, b, h) do { _Pragma("unroll") for (int m = 0; m < 4; ++m) _Pragma("unroll") for (int k = 0; k < 2; ++k) dst[m][k] = *(const LAS bf16x8*)(lds + PG8_SA(b, h) + aoff + m * 2048 + k * 1024); } while (0)
; #define PG8_LDB(dst, b, h) do { _Pragma("unroll") for (int n = 0; n < 2; ++n) _Pragma("unroll") for (int k = 0; k < 2; ++k) dst[n][k] = *(const LAS bf16x8*)(lds + PG8_SB(b, h) + boff + n * 2048 + k * 1024); } while (0)
; #define PG8_MMA(ai, bj, At, Bt) do { __builtin_amdgcn_s_setprio(1); _Pragma("unroll") for (int m = 0; m < 4; ++m) _Pragma("unroll") for (int n = 0; n < 2; ++n) _Pragma("unroll") for (int k = 0; k < 2; ++k) \
;         acc[ai][bj][m][n] = __builtin_amdgcn_mfma_f32_16x16x32_bf16(Bt[n][k], At[m][k], acc[ai][bj][m][n], 0, 0, 0); __builtin_amdgcn_s_setprio(0); } while (0)
; #define PG8_WAIT_V(n) asm volatile("s_waitcnt vmcnt(" #n ")" ::: "memory")
; #define PG8_WAIT_L(n) asm volatile("s_waitcnt lgkmcnt(" #n ")" ::: "memory")
; #define PG8_BAR __builtin_amdgcn_s_barrier()
; #define PG8_SCHED __builtin_amdgcn_sched_barrier(0)
; template <class Epi>
; DEVI void gemm_phase(LAS unsigned char* lds, const Gemm g, const Epi& E) {
;     ...
;             PG8_WAIT_V(6); PG8_BAR; PG8_MMA(1, 1, At, B1); PG8_BAR;
;             PG8_LDB(B0, 1, 0); PG8_SCHED; PG8_LDA(At, 1, 0); PG8_STAGE(PG8_SA(0, 1), a2 + hstepA, voffA);
;             PG8_WAIT_L(8); PG8_BAR; PG8_WAIT_L(0); PG8_MMA(0, 0, At, B0); PG8_BAR; PG8_SCHED;
;             PG8_LDB(B1, 1, 1); PG8_STAGE(PG8_SB(1, 0), b3, voffB);
;             PG8_BAR; PG8_WAIT_L(0); PG8_MMA(0, 1, At, B1); PG8_BAR;
;             PG8_LDA(At, 1, 1); PG8_STAGE(PG8_SA(1, 0), a3, voffA);
;             PG8_BAR; PG8_WAIT_L(0); PG8_MMA(1, 0, At, B0); PG8_BAR; PG8_SCHED;
	s_add_u32 s16, s46, 0xb0000
	s_addc_u32 s17, s47, 0
	s_add_i32 s19, s26, s80
	s_mov_b32 m0, s19
	v_lshl_add_u64 v[130:131], s[16:17], 0, v[8:9]
	global_load_lds_dwordx4 v[130:131], off
	s_add_i32 m0, s19, 0x2000
	v_lshl_add_u64 v[130:131], s[16:17], 0, v[150:151]
	global_load_lds_dwordx4 v[130:131], off
	s_waitcnt vmcnt(6)
	s_barrier
	v_mfma_f32_16x16x32_bf16 v[54:57], v[222:225], v[178:181], v[54:57]
	v_mfma_f32_16x16x32_bf16 v[50:53], v[230:233], v[178:181], v[50:53]
	v_mfma_f32_16x16x32_bf16 v[38:41], v[222:225], v[186:189], v[38:41]
	v_mfma_f32_16x16x32_bf16 v[34:37], v[230:233], v[186:189], v[34:37]
	v_mfma_f32_16x16x32_bf16 v[22:25], v[222:225], v[202:205], v[22:25]
	v_mfma_f32_16x16x32_bf16 v[18:21], v[230:233], v[202:205], v[18:21]
	v_mfma_f32_16x16x32_bf16 v[4:7], v[222:225], v[214:217], v[4:7]
	v_mfma_f32_16x16x32_bf16 v[0:3], v[230:233], v[214:217], v[0:3]
	v_mfma_f32_16x16x32_bf16 v[54:57], v[226:229], v[182:185], v[54:57]
	v_mfma_f32_16x16x32_bf16 v[50:53], v[234:237], v[182:185], v[50:53]
	v_mfma_f32_16x16x32_bf16 v[38:41], v[226:229], v[198:201], v[38:41]
	v_mfma_f32_16x16x32_bf16 v[34:37], v[234:237], v[198:201], v[34:37]
	v_mfma_f32_16x16x32_bf16 v[22:25], v[226:229], v[206:209], v[22:25]
	v_mfma_f32_16x16x32_bf16 v[18:21], v[234:237], v[206:209], v[18:21]
	v_mfma_f32_16x16x32_bf16 v[4:7], v[226:229], v[218:221], v[4:7]
	v_mfma_f32_16x16x32_bf16 v[0:3], v[234:237], v[218:221], v[0:3]
	s_add_i32 s19, 0, 0x18000
	v_add_u32_e32 v142, s19, v191
	s_barrier
	ds_read_b128 v[130:133], v142
	ds_read_b128 v[134:137], v142 offset:1024
	ds_read_b128 v[138:141], v142 offset:2048
	ds_read_b128 v[142:145], v142 offset:3072
	s_add_u32 s16, s68, 0xb0000
	s_addc_u32 s17, s69, 0
	s_mov_b32 m0, s83
	v_lshl_add_u64 v[222:223], s[16:17], 0, v[146:147]
	ds_read_b128 v[178:181], v196 offset:32768
	ds_read_b128 v[182:185], v196 offset:33792
	ds_read_b128 v[186:189], v196 offset:34816
	ds_read_b128 v[198:201], v196 offset:35840
	ds_read_b128 v[202:205], v196 offset:36864
	ds_read_b128 v[206:209], v196 offset:37888
	ds_read_b128 v[214:217], v196 offset:38912
	ds_read_b128 v[218:221], v196 offset:39936
	global_load_lds_dwordx4 v[222:223], off
	s_mov_b32 m0, s84
	v_lshl_add_u64 v[222:223], s[16:17], 0, v[148:149]
	global_load_lds_dwordx4 v[222:223], off
	s_waitcnt lgkmcnt(0)
	s_barrier
	v_mfma_f32_16x16x32_bf16 v[126:129], v[130:133], v[178:181], v[126:129]
	v_mfma_f32_16x16x32_bf16 v[122:125], v[138:141], v[178:181], v[122:125]
	v_mfma_f32_16x16x32_bf16 v[110:113], v[130:133], v[186:189], v[110:113]
	v_mfma_f32_16x16x32_bf16 v[106:109], v[138:141], v[186:189], v[106:109]
	v_mfma_f32_16x16x32_bf16 v[94:97], v[130:133], v[202:205], v[94:97]
	v_mfma_f32_16x16x32_bf16 v[90:93], v[138:141], v[202:205], v[90:93]
	v_mfma_f32_16x16x32_bf16 v[78:81], v[130:133], v[214:217], v[78:81]
	v_mfma_f32_16x16x32_bf16 v[74:77], v[138:141], v[214:217], v[74:77]
	v_mfma_f32_16x16x32_bf16 v[126:129], v[134:137], v[182:185], v[126:129]
	v_mfma_f32_16x16x32_bf16 v[122:125], v[142:145], v[182:185], v[122:125]
	v_mfma_f32_16x16x32_bf16 v[110:113], v[134:137], v[198:201], v[110:113]
	v_mfma_f32_16x16x32_bf16 v[106:109], v[142:145], v[198:201], v[106:109]
	v_mfma_f32_16x16x32_bf16 v[94:97], v[134:137], v[206:209], v[94:97]
	v_mfma_f32_16x16x32_bf16 v[90:93], v[142:145], v[206:209], v[90:93]
	v_mfma_f32_16x16x32_bf16 v[78:81], v[134:137], v[218:221], v[78:81]
	v_mfma_f32_16x16x32_bf16 v[74:77], v[142:145], v[218:221], v[74:77]
	s_barrier
	s_add_i32 s26, 0, 0x1c000
	s_add_i32 s16, s19, s80
	v_add_u32_e32 v197, s26, v191
	v_lshl_add_u64 v[162:163], v[162:163], 0, s[70:71]
	s_mov_b32 m0, s16
	ds_read_b128 v[222:225], v197
	ds_read_b128 v[226:229], v197 offset:1024
	ds_read_b128 v[230:233], v197 offset:2048
	ds_read_b128 v[234:237], v197 offset:3072
	global_load_lds_dwordx4 v[162:163], off
	s_add_i32 m0, s16, 0x2000
	v_lshl_add_u64 v[162:163], v[164:165], 0, s[70:71]
	global_load_lds_dwordx4 v[162:163], off
	s_waitcnt lgkmcnt(0)
	s_barrier
	v_mfma_f32_16x16x32_bf16 v[118:121], v[222:225], v[178:181], v[118:121]
	v_mfma_f32_16x16x32_bf16 v[114:117], v[230:233], v[178:181], v[114:117]
	v_mfma_f32_16x16x32_bf16 v[102:105], v[222:225], v[186:189], v[102:105]
	v_mfma_f32_16x16x32_bf16 v[98:101], v[230:233], v[186:189], v[98:101]
	v_mfma_f32_16x16x32_bf16 v[86:89], v[222:225], v[202:205], v[86:89]
	v_mfma_f32_16x16x32_bf16 v[82:85], v[230:233], v[202:205], v[82:85]
	v_mfma_f32_16x16x32_bf16 v[70:73], v[222:225], v[214:217], v[70:73]
	v_mfma_f32_16x16x32_bf16 v[66:69], v[230:233], v[214:217], v[66:69]
	v_mfma_f32_16x16x32_bf16 v[118:121], v[226:229], v[182:185], v[118:121]
	v_mfma_f32_16x16x32_bf16 v[114:117], v[234:237], v[182:185], v[114:117]
	v_mfma_f32_16x16x32_bf16 v[102:105], v[226:229], v[198:201], v[102:105]
	v_mfma_f32_16x16x32_bf16 v[98:101], v[234:237], v[198:201], v[98:101]
	v_mfma_f32_16x16x32_bf16 v[86:89], v[226:229], v[206:209], v[86:89]
	v_mfma_f32_16x16x32_bf16 v[82:85], v[234:237], v[206:209], v[82:85]
	v_mfma_f32_16x16x32_bf16 v[70:73], v[226:229], v[218:221], v[70:73]
	v_mfma_f32_16x16x32_bf16 v[66:69], v[234:237], v[218:221], v[66:69]
	s_mov_b32 m0, s76
	v_lshl_add_u64 v[162:163], v[238:239], 0, s[70:71]
	s_barrier
	ds_read_b128 v[178:181], v196 offset:49152
	ds_read_b128 v[182:185], v196 offset:50176
	ds_read_b128 v[186:189], v196 offset:51200
	ds_read_b128 v[198:201], v196 offset:52224
	ds_read_b128 v[202:205], v196 offset:53248
	ds_read_b128 v[206:209], v196 offset:54272
	ds_read_b128 v[214:217], v196 offset:55296
	ds_read_b128 v[218:221], v196 offset:56320
	global_load_lds_dwordx4 v[162:163], off
	s_mov_b32 m0, s77
	v_lshl_add_u64 v[162:163], v[240:241], 0, s[70:71]
	global_load_lds_dwordx4 v[162:163], off
	s_waitcnt lgkmcnt(0)
	s_barrier
; #define LAS __attribute__((address_space(3)))
; #define PG8_STAGE(bufoff, gbase, voff) do { _Pragma("unroll") for (int _i = 0; _i < 2; ++_i) \
;         __builtin_amdgcn_global_load_lds((const unsigned*)((const char*)(gbase) + (voff)[_i]), (LAS unsigned*)(lds + (bufoff) + ldsw + _i * 8192), 16, 0, 0); } while (0)
; #define PG8_WAIT_V(n) asm volatile("s_waitcnt vmcnt(" #n ")" ::: "memory")
; #define PG8_WAIT_L(n) asm volatile("s_waitcnt lgkmcnt(" #n ")" ::: "memory")
; #define PG8_BAR __builtin_amdgcn_s_barrier()
; #define PG8_SCHED __builtin_amdgcn_sched_barrier(0)
; template <class Epi>
; DEVI void gemm_phase(LAS unsigned char* lds, const Gemm g, const Epi& E) {
;     ...
;             PG8_BAR; PG8_WAIT_L(0); PG8_MMA(1, 0, At, B0); PG8_BAR; PG8_SCHED;
;             PG8_STAGE(PG8_SB(1, 1), b3 + hstepB, voffB);
;             PG8_WAIT_V(6); PG8_BAR; PG8_MMA(1, 1, At, B1); PG8_BAR;
;         }
;     ...
;                             for (int n = 0; n < 2; ++n) pre[m][bj][n] = E.load(row0 + ai * HALF + (m0 + m) * 16, col0 + bj * HALF + n * NST);
;                 }
; #pragma unroll
;                 for (int mm = 0; mm < 2; ++mm) {
;                     const int m = m0 + mm;
;                     const int r = row0 + ai * HALF + m * 16; float rs = 1.f, part = 0.f;
;                     if constexpr (Epi::RS) rs = rsv[ai * 4 + m];
;                     if constexpr (Epi::PAIR) E.pair8(cur.b, r, cur.pn * HALF + wc * 32 + 8 * fq, acc[ai][0][m][0] * rs, acc[ai][0][m][1] * rs, acc[ai][1][m][0] * rs, acc[ai][1][m][1] * rs);
;                     else
; #pragma unroll
;                     for (int bj = 0; bj < 2; ++bj) {
;                         const int c = col0 + bj * HALF; f32x4 v0 = acc[ai][bj][m][0], v1 = acc[ai][bj][m][1];
;                         if constexpr (Epi::RS) { v0 = v0 * rs; v1 = v1 * rs; }
;                         if constexpr (Epi::PRE) part += E.frag_pre8(cur.b, r, c, v0, v1, pre[mm][bj][0], pre[mm][bj][1]);
;                         else if constexpr (Epi::PERM) E.frag8(cur.b, r, c, v0, v1);
;                         else { E.frag(cur.b, r, c, v0); E.frag(cur.b, r, c + 16, v1); }
;                     }
;                     if constexpr (Epi::SSQ) { part += __shfl_xor(part, 16); part += __shfl_xor(part, 32); if (fq == 0) ((LAS float*)(lds + 131072))[(wr * 4 + wc) * 128 + ai * 64 + m * 16 + fr] = part; }
	v_mfma_f32_16x16x32_bf16 v[62:65], v[130:133], v[178:181], v[62:65]
	v_mfma_f32_16x16x32_bf16 v[58:61], v[138:141], v[178:181], v[58:61]
	v_mfma_f32_16x16x32_bf16 v[46:49], v[130:133], v[186:189], v[46:49]
	v_mfma_f32_16x16x32_bf16 v[42:45], v[138:141], v[186:189], v[42:45]
	v_mfma_f32_16x16x32_bf16 v[30:33], v[130:133], v[202:205], v[30:33]
	v_mfma_f32_16x16x32_bf16 v[26:29], v[138:141], v[202:205], v[26:29]
	v_mfma_f32_16x16x32_bf16 v[14:17], v[130:133], v[214:217], v[14:17]
	v_mfma_f32_16x16x32_bf16 v[10:13], v[138:141], v[214:217], v[10:13]
	v_mfma_f32_16x16x32_bf16 v[62:65], v[134:137], v[182:185], v[62:65]
	v_mfma_f32_16x16x32_bf16 v[58:61], v[142:145], v[182:185], v[58:61]
	v_mfma_f32_16x16x32_bf16 v[46:49], v[134:137], v[198:201], v[46:49]
	v_mfma_f32_16x16x32_bf16 v[42:45], v[142:145], v[198:201], v[42:45]
	v_mfma_f32_16x16x32_bf16 v[30:33], v[134:137], v[206:209], v[30:33]
	v_mfma_f32_16x16x32_bf16 v[26:29], v[142:145], v[206:209], v[26:29]
	v_mfma_f32_16x16x32_bf16 v[14:17], v[134:137], v[218:221], v[14:17]
	v_mfma_f32_16x16x32_bf16 v[10:13], v[142:145], v[218:221], v[10:13]
	s_barrier
	s_add_u32 s16, s46, 0xb0080
	s_addc_u32 s17, s47, 0
	s_add_i32 s19, s26, s80
	s_mov_b32 m0, s19
	v_lshl_add_u64 v[130:131], s[16:17], 0, v[8:9]
	global_load_lds_dwordx4 v[130:131], off
	s_add_i32 m0, s19, 0x2000
	v_lshl_add_u64 v[130:131], s[16:17], 0, v[150:151]
	global_load_lds_dwordx4 v[130:131], off
	s_waitcnt vmcnt(6)
	s_barrier
	v_mfma_f32_16x16x32_bf16 v[54:57], v[222:225], v[178:181], v[54:57]
	v_mfma_f32_16x16x32_bf16 v[50:53], v[230:233], v[178:181], v[50:53]
	v_mfma_f32_16x16x32_bf16 v[38:41], v[222:225], v[186:189], v[38:41]
	v_mfma_f32_16x16x32_bf16 v[34:37], v[230:233], v[186:189], v[34:37]
	v_mfma_f32_16x16x32_bf16 v[22:25], v[222:225], v[202:205], v[22:25]
	v_mfma_f32_16x16x32_bf16 v[18:21], v[230:233], v[202:205], v[18:21]
	v_mfma_f32_16x16x32_bf16 v[4:7], v[222:225], v[214:217], v[4:7]
	v_mfma_f32_16x16x32_bf16 v[0:3], v[230:233], v[214:217], v[0:3]
	v_mfma_f32_16x16x32_bf16 v[54:57], v[226:229], v[182:185], v[54:57]
	v_mfma_f32_16x16x32_bf16 v[50:53], v[234:237], v[182:185], v[50:53]
	v_mfma_f32_16x16x32_bf16 v[38:41], v[226:229], v[198:201], v[38:41]
	v_mfma_f32_16x16x32_bf16 v[34:37], v[234:237], v[198:201], v[34:37]
	v_mfma_f32_16x16x32_bf16 v[22:25], v[226:229], v[206:209], v[22:25]
	v_mfma_f32_16x16x32_bf16 v[18:21], v[234:237], v[206:209], v[18:21]
	v_mfma_f32_16x16x32_bf16 v[4:7], v[226:229], v[218:221], v[4:7]
	v_mfma_f32_16x16x32_bf16 v[0:3], v[234:237], v[218:221], v[0:3]
	s_add_i32 s18, s18, 2
	s_add_u32 s1, s1, 0x100
	s_addc_u32 s13, s13, 0
	s_cmp_gt_u32 s18, 41
	s_mov_b64 s[16:17], s[36:37]
	s_barrier
	s_cbranch_scc0 .LBB0_1747
	s_setprio 0
	s_lshl_b32 s0, s0, 8
	v_add_u32_e32 v182, s0, v190
	v_lshl_or_b32 v180, s12, 8, v195
	v_ashrrev_i32_e32 v183, 31, v182
	v_lshlrev_b64 v[130:131], 12, v[182:183]
	v_ashrrev_i32_e32 v181, 31, v180
	v_lshl_add_u64 v[130:131], s[30:31], 0, v[130:131]
	v_lshlrev_b64 v[184:185], 2, v[180:181]
	v_lshl_add_u64 v[162:163], v[130:131], 0, v[184:185]
	global_load_dwordx4 v[200:203], v[162:163], off
	global_load_dwordx4 v[204:207], v[162:163], off offset:16
	global_load_dwordx4 v[214:217], v[162:163], off offset:512
	global_load_dwordx4 v[218:221], v[162:163], off offset:528
	v_or_b32_e32 v188, 16, v182
	v_ashrrev_i32_e32 v189, 31, v188
	v_lshlrev_b64 v[130:131], 12, v[188:189]
	v_lshl_add_u64 v[130:131], s[30:31], 0, v[130:131]
	v_lshl_add_u64 v[186:187], v[130:131], 0, v[184:185]
	global_load_dwordx4 v[138:141], v[186:187], off offset:16
	global_load_dwordx4 v[142:145], v[186:187], off
	global_load_dwordx4 v[130:133], v[186:187], off offset:528
	global_load_dwordx4 v[134:137], v[186:187], off offset:512
	v_and_b32_e32 v165, 64, v155
	v_xor_b32_e32 v164, 16, v155
	v_add_u32_e32 v165, 64, v165
	v_xor_b32_e32 v179, 32, v155
	v_cmp_lt_i32_e32 vcc, v164, v165
	v_or_b32_e32 v178, 0x80, v180
	s_waitcnt vmcnt(0)
	v_pk_add_f32 v[128:129], v[128:129], v[202:203]
	v_cndmask_b32_e32 v164, v155, v164, vcc
	v_cmp_lt_i32_e32 vcc, v179, v165
	v_lshlrev_b32_e32 v198, 2, v164
	v_pk_add_f32 v[126:127], v[126:127], v[200:201]
	v_cndmask_b32_e32 v165, v155, v179, vcc
	v_lshlrev_b32_e32 v197, 2, v165
	v_lshlrev_b64 v[164:165], 10, v[182:183]
	v_pk_add_f32 v[124:125], v[124:125], v[206:207]
	v_pk_add_f32 v[122:123], v[122:123], v[204:205]
	v_pk_add_f32 v[120:121], v[120:121], v[216:217]
	v_pk_add_f32 v[118:119], v[118:119], v[214:215]
	v_pk_add_f32 v[202:203], v[116:117], v[220:221]
	v_pk_add_f32 v[200:201], v[114:115], v[218:219]
	v_lshl_add_u64 v[208:209], v[164:165], 0, v[180:181]
	global_store_dwordx4 v[162:163], v[126:129], off
	global_store_dwordx4 v[162:163], v[122:125], off offset:16
	v_cvt_pk_bf16_f32 v114, v126, v127
	v_cvt_pk_bf16_f32 v115, v128, v129
	v_cvt_pk_bf16_f32 v116, v122, v123
	v_cvt_pk_bf16_f32 v117, v124, v125
	v_mul_f32_e32 v127, v127, v127
	v_mul_f32_e32 v129, v129, v129
	v_mul_f32_e32 v123, v123, v123
	v_mul_f32_e32 v125, v125, v125
	v_mul_f32_e32 v183, v119, v119
	v_mul_f32_e32 v199, v121, v121
	v_mul_f32_e32 v204, v201, v201
	v_mul_f32_e32 v205, v203, v203
	v_lshl_add_u64 v[208:209], v[208:209], 1, s[24:25]
	v_fmac_f32_e32 v127, v126, v126
	v_fmac_f32_e32 v129, v128, v128
	v_fmac_f32_e32 v123, v122, v122
	v_fmac_f32_e32 v125, v124, v124
	v_fmac_f32_e32 v183, v118, v118
	v_fmac_f32_e32 v199, v120, v120
	v_fmac_f32_e32 v204, v200, v200
	v_fmac_f32_e32 v205, v202, v202
	global_store_dwordx4 v[208:209], v[114:117], off
	v_ashrrev_i32_e32 v179, 31, v178
	v_lshl_add_u64 v[164:165], v[164:165], 0, v[178:179]
	v_add_f32_e32 v114, v127, v129
	v_add_f32_e32 v115, v123, v125
	v_add_f32_e32 v116, v183, v199
	v_add_f32_e32 v117, v204, v205
	v_add_f32_e32 v114, v114, v115
	v_add_f32_e32 v115, v116, v117
	v_add_f32_e32 v114, v114, v115
	ds_bpermute_b32 v115, v198, v114
	global_store_dwordx4 v[162:163], v[118:121], off offset:512
	global_store_dwordx4 v[162:163], v[200:203], off offset:528
	v_cvt_pk_bf16_f32 v116, v118, v119
	v_cvt_pk_bf16_f32 v117, v120, v121
	v_cvt_pk_bf16_f32 v118, v200, v201
	s_waitcnt lgkmcnt(0)
	v_add_f32_e32 v114, v114, v115
	ds_bpermute_b32 v115, v197, v114
	v_cvt_pk_bf16_f32 v119, v202, v203
	v_lshl_add_u64 v[120:121], v[164:165], 1, s[24:25]
	global_store_dwordx4 v[120:121], v[116:119], off
	s_and_saveexec_b64 s[16:17], s[2:3]
	s_cbranch_execz .LBB0_1750
	s_waitcnt lgkmcnt(0)
	v_add_f32_e32 v114, v114, v115
	ds_write_b32 v192, v114
